# all remaining flat_load/flat_store converted to global_load/global_store (same addresses; no lgkmcnt coupling of epilogue memory ops)
# baseline (speedup 1.0000x reference)
;     __device__ __forceinline__ void operator()(const f32x4 (&acc)[2][2][4][2], const Unit& u, int wr, int wc, int fr, int fq) const {
;     ...
; #pragma unroll
;             for (int bj = 0; bj < 2; ++bj)
; #pragma unroll
;                 for (int n = 0; n < 2; ++n) *(f32x4*)(op + ro + 128 * bj + 4 * n) = pre[g & 1][bj][n] + mv[bj][n] * acc[ai][bj][m][n];
.LBB0_69:
	s_andn2_b64 vcc, exec, s[0:1]
	s_mov_b64 s[14:15], -1
	global_store_dwordx4 v[184:185], v[144:147], off offset:528
	s_cbranch_vccnz .LBB0_49
	s_branch .LBB0_72

; #define FOR_AI_M _Pragma("unroll") for (int ai = 0; ai < 2; ++ai) _Pragma("unroll") for (int m = 0; m < 4; ++m)
;     __device__ __forceinline__ void operator()(const f32x4 (&acc)[2][2][4][2], const Unit& u, int wr, int wc, int fr, int fq) const {
;     ...
;         if (u.mode > 0) {
;             float* pp = part + (size_t)(u.mode - 1) * NCTX * 1024 + (size_t)(row0 - NLAT) * 1024;
;             FOR_AI_M {
;                 const size_t ro = (size_t)(128 * ai + 64 * wr + 16 * m + fr) * 1024 + cb0;
; #pragma unroll
;                 for (int bj = 0; bj < 2; ++bj)
; #pragma unroll
;                     for (int n = 0; n < 2; ++n) *(f32x4*)(pp + ro + 128 * bj + 4 * n) = mv[bj][n] * acc[ai][bj][m][n];
;             }
;             return;
.LBB0_71:
	v_readlane_b32 s2, v253, 15
	v_readlane_b32 s3, v253, 16
	s_mov_b32 s9, s3
	s_add_i32 s8, s64, -1
	v_writelane_b32 v253, s2, 15
	v_lshlrev_b64 v[146:147], 12, v[180:181]
	s_waitcnt vmcnt(0) lgkmcnt(0)
	v_pk_mul_f32 v[106:107], v[106:107], v[130:131]
	v_writelane_b32 v253, s3, 16
	s_lshl_b64 s[2:3], s[8:9], 22
	v_readlane_b32 s8, v254, 55
	s_add_u32 s16, s8, s2
	v_readlane_b32 s2, v254, 60
	s_addc_u32 s17, s2, s3
	s_ashr_i32 s19, s18, 31
	s_lshl_b64 s[2:3], s[18:19], 12
	s_add_u32 s2, s16, s2
	s_addc_u32 s3, s17, s3
	v_lshl_add_u64 v[144:145], v[182:183], 2, s[2:3]
	s_brev_b32 s2, 31
	s_mov_b32 s3, -1
	v_lshl_add_u64 v[144:145], v[144:145], 0, s[2:3]
	v_lshl_add_u64 v[146:147], v[144:145], 0, v[146:147]
	v_pk_mul_f32 v[104:105], v[104:105], v[128:129]
	v_pk_mul_f32 v[114:115], v[114:115], v[134:135]
	v_pk_mul_f32 v[112:113], v[112:113], v[132:133]
	global_store_dwordx4 v[146:147], v[104:107], off offset:528
	global_store_dwordx4 v[146:147], v[112:115], off offset:512
	v_pk_mul_f32 v[90:91], v[90:91], v[130:131]
	v_lshlrev_b64 v[104:105], 12, v[178:179]
	v_lshl_add_u64 v[112:113], v[144:145], 0, v[104:105]
	v_pk_mul_f32 v[88:89], v[88:89], v[128:129]
	v_pk_mul_f32 v[98:99], v[98:99], v[134:135]
	v_pk_mul_f32 v[96:97], v[96:97], v[132:133]
	global_store_dwordx4 v[112:113], v[88:91], off offset:528
	global_store_dwordx4 v[112:113], v[96:99], off offset:512
	v_pk_mul_f32 v[74:75], v[74:75], v[130:131]
	v_lshlrev_b64 v[88:89], 12, v[176:177]
	v_lshl_add_u64 v[96:97], v[144:145], 0, v[88:89]
	v_pk_mul_f32 v[72:73], v[72:73], v[128:129]
	v_pk_mul_f32 v[82:83], v[82:83], v[134:135]
	v_pk_mul_f32 v[80:81], v[80:81], v[132:133]
	global_store_dwordx4 v[96:97], v[72:75], off offset:528
	global_store_dwordx4 v[96:97], v[80:83], off offset:512
	v_pk_mul_f32 v[66:67], v[66:67], v[130:131]
	v_lshlrev_b64 v[72:73], 12, v[174:175]
	v_lshl_add_u64 v[80:81], v[144:145], 0, v[72:73]
	v_pk_mul_f32 v[64:65], v[64:65], v[128:129]
	global_store_dwordx4 v[80:81], v[64:67], off offset:528
	v_pk_mul_f32 v[42:43], v[42:43], v[130:131]
	v_pk_mul_f32 v[40:41], v[40:41], v[128:129]
	v_lshlrev_b64 v[64:65], 12, v[172:173]
	v_lshl_add_u64 v[64:65], v[144:145], 0, v[64:65]
	v_pk_mul_f32 v[50:51], v[50:51], v[134:135]
	v_pk_mul_f32 v[48:49], v[48:49], v[132:133]
	global_store_dwordx4 v[64:65], v[40:43], off offset:528
	global_store_dwordx4 v[64:65], v[48:51], off offset:512
	v_pk_mul_f32 v[26:27], v[26:27], v[130:131]
	v_lshlrev_b64 v[40:41], 12, v[170:171]
	v_lshl_add_u64 v[48:49], v[144:145], 0, v[40:41]
	v_pk_mul_f32 v[24:25], v[24:25], v[128:129]
	v_ashrrev_i32_e32 v169, 31, v168
	v_pk_mul_f32 v[34:35], v[34:35], v[134:135]
	v_pk_mul_f32 v[32:33], v[32:33], v[132:133]
	global_store_dwordx4 v[48:49], v[24:27], off offset:528
	global_store_dwordx4 v[48:49], v[32:35], off offset:512
	v_pk_mul_f32 v[10:11], v[10:11], v[130:131]
	v_lshlrev_b64 v[24:25], 12, v[168:169]
	v_lshl_add_u64 v[32:33], v[144:145], 0, v[24:25]
	v_pk_mul_f32 v[8:9], v[8:9], v[128:129]
	v_ashrrev_i32_e32 v167, 31, v166
	global_store_dwordx4 v[32:33], v[8:11], off offset:528
	v_pk_mul_f32 v[126:127], v[126:127], v[142:143]
	v_pk_mul_f32 v[124:125], v[124:125], v[140:141]
	v_lshlrev_b64 v[8:9], 12, v[166:167]
	v_pk_mul_f32 v[122:123], v[122:123], v[138:139]
	v_pk_mul_f32 v[120:121], v[120:121], v[136:137]
	v_pk_mul_f32 v[106:107], v[118:119], v[142:143]
	v_pk_mul_f32 v[104:105], v[116:117], v[140:141]
	v_pk_mul_f32 v[90:91], v[102:103], v[142:143]
	v_pk_mul_f32 v[88:89], v[100:101], v[140:141]
	v_pk_mul_f32 v[74:75], v[86:87], v[142:143]
	v_pk_mul_f32 v[72:73], v[84:85], v[140:141]
	v_pk_mul_f32 v[42:43], v[54:55], v[142:143]
	v_pk_mul_f32 v[40:41], v[52:53], v[140:141]
	v_pk_mul_f32 v[26:27], v[38:39], v[142:143]
	v_pk_mul_f32 v[24:25], v[36:37], v[140:141]
	v_lshl_add_u64 v[184:185], v[144:145], 0, v[8:9]
	v_pk_mul_f32 v[10:11], v[22:23], v[142:143]
	v_pk_mul_f32 v[8:9], v[20:21], v[140:141]
	global_store_dwordx4 v[146:147], v[124:127], off
	global_store_dwordx4 v[146:147], v[120:123], off offset:16
	global_store_dwordx4 v[112:113], v[104:107], off
	global_store_dwordx4 v[96:97], v[88:91], off
	global_store_dwordx4 v[80:81], v[72:75], off
	v_pk_mul_f32 v[106:107], v[110:111], v[138:139]
	v_pk_mul_f32 v[104:105], v[108:109], v[136:137]
	v_pk_mul_f32 v[90:91], v[94:95], v[138:139]
	v_pk_mul_f32 v[88:89], v[92:93], v[136:137]
	v_pk_mul_f32 v[74:75], v[78:79], v[138:139]
	v_pk_mul_f32 v[72:73], v[76:77], v[136:137]
	v_pk_mul_f32 v[70:71], v[70:71], v[134:135]
	v_pk_mul_f32 v[68:69], v[68:69], v[132:133]
	v_pk_mul_f32 v[62:63], v[62:63], v[142:143]
	v_pk_mul_f32 v[60:61], v[60:61], v[140:141]
	v_pk_mul_f32 v[58:59], v[58:59], v[138:139]
	v_pk_mul_f32 v[56:57], v[56:57], v[136:137]
	global_store_dwordx4 v[48:49], v[40:43], off
	global_store_dwordx4 v[32:33], v[24:27], off
	v_pk_mul_f32 v[18:19], v[18:19], v[134:135]
	v_pk_mul_f32 v[42:43], v[46:47], v[138:139]
	v_pk_mul_f32 v[40:41], v[44:45], v[136:137]
	v_pk_mul_f32 v[26:27], v[30:31], v[138:139]
	v_pk_mul_f32 v[24:25], v[28:29], v[136:137]
	v_pk_mul_f32 v[16:17], v[16:17], v[132:133]
	global_store_dwordx4 v[184:185], v[8:11], off
	v_pk_mul_f32 v[6:7], v[6:7], v[134:135]
	v_pk_mul_f32 v[4:5], v[4:5], v[132:133]
	v_pk_mul_f32 v[10:11], v[14:15], v[138:139]
	v_pk_mul_f32 v[8:9], v[12:13], v[136:137]
	v_pk_mul_f32 v[146:147], v[2:3], v[130:131]
	v_pk_mul_f32 v[144:145], v[0:1], v[128:129]
	global_store_dwordx4 v[112:113], v[104:107], off offset:16
	global_store_dwordx4 v[96:97], v[88:91], off offset:16
	global_store_dwordx4 v[80:81], v[72:75], off offset:16
	global_store_dwordx4 v[80:81], v[68:71], off offset:512
	global_store_dwordx4 v[64:65], v[60:63], off
	global_store_dwordx4 v[64:65], v[56:59], off offset:16
	global_store_dwordx4 v[48:49], v[40:43], off offset:16
	global_store_dwordx4 v[32:33], v[24:27], off offset:16
	global_store_dwordx4 v[32:33], v[16:19], off offset:512
	global_store_dwordx4 v[184:185], v[8:11], off offset:16
	global_store_dwordx4 v[184:185], v[4:7], off offset:512
	s_andn2_b64 vcc, exec, s[0:1]
	s_mov_b64 s[14:15], -1
	global_store_dwordx4 v[184:185], v[144:147], off offset:528
	s_cbranch_vccnz .LBB0_49

; __device__ __forceinline__ unsigned cvt_pk_bf16(float lo, float hi) { f32x2 v = {lo, hi}; bf16x2_t b = __builtin_convertvector(v, bf16x2_t); return __builtin_bit_cast(unsigned, b); }
; __device__ __forceinline__ float sigmoidf_(float v) { return __builtin_amdgcn_rcpf(1.0f + __builtin_amdgcn_exp2f(-1.4426950408889634f * v)); }
; __device__ __forceinline__ float dpp_shr1(float v) { return __builtin_bit_cast(float, __builtin_amdgcn_update_dpp(0, __builtin_bit_cast(int, v), 0x111, 0xf, 0xf, true)); }
;     __device__ __forceinline__ void operator()(const f32x4 (&acc)[2][2][4][2], const Unit& u, int wr, int wc, int fr, int fq) const {
;     ...
;         const size_t row0 = (size_t)256 * u.pm + 128 * wr + 8 * fr;
; #pragma unroll
;         for (int n = 0; n < 2; ++n) {
;             const int f0 = 128 * u.pn + 32 * wc + 8 * fq + 4 * n;
;             f32x4 wa[3], wg[3];
; #pragma unroll
;             for (int j = 0; j < 3; ++j) { wa[j] = *(const f32x4*)(cw + j * 5632 + f0); wg[j] = *(const f32x4*)(cw + j * 5632 + 2816 + f0); }
;             const f32x4 ba = *(const f32x4*)(cb + f0), bg = *(const f32x4*)(cb + 2816 + f0);
;             f32x4 pa, pg, na, ng;
; #pragma unroll
;             for (int e = 0; e < 4; ++e) { pa[e] = dpp_shr1(acc[1][0][3][n][e]); pg[e] = dpp_shr1(acc[1][1][3][n][e]); na[e] = dpp_shl1(acc[0][0][0][n][e]); ng[e] = dpp_shl1(acc[0][1][0][n][e]); }
; #pragma unroll
;             for (int k = 0; k < 8; ++k) {
;                 const f32x4 ua0 = (k == 0) ? pa : acc[(k - 1) >> 2][0][(k - 1) & 3][n], ua1 = acc[k >> 2][0][k & 3][n], ua2 = (k == 7) ? na : acc[(k + 1) >> 2][0][(k + 1) & 3][n];
;                 const f32x4 ug0 = (k == 0) ? pg : acc[(k - 1) >> 2][1][(k - 1) & 3][n], ug1 = acc[k >> 2][1][k & 3][n], ug2 = (k == 7) ? ng : acc[(k + 1) >> 2][1][(k + 1) & 3][n];
;                 const f32x4 ca = wa[0] * ua0 + wa[1] * ua1 + wa[2] * ua2 + ba, cg = wg[0] * ug0 + wg[1] * ug1 + wg[2] * ug2 + bg;
;                 u32x2 w; w.x = cvt_pk_bf16(cg[0] * sigmoidf_(cg[0]) * ca[0], cg[1] * sigmoidf_(cg[1]) * ca[1]); w.y = cvt_pk_bf16(cg[2] * sigmoidf_(cg[2]) * ca[2], cg[3] * sigmoidf_(cg[3]) * ca[3]);
;                 const bool edge = (k == 0 && fr == 0) || (k == 7 && fr == 15);
;                 if (!edge) *(u32x2*)(ACT + (row0 + k) * 2816 + f0) = w;
.LBB0_118:
	v_mov_b32_e32 v128, v212
	v_mov_b32_e32 v192, v197
	s_mov_b64 s[6:7], -1
	s_cmp_lg_u32 s2, 1
	v_lshl_add_u32 v215, v128, 3, s94
	s_cbranch_scc0 .LBB0_131
	s_ashr_i32 s1, s0, 31
	s_lshl_b64 s[2:3], s[0:1], 8
	s_add_u32 s2, s2, s35
	v_readlane_b32 s1, v254, 63
	s_addc_u32 s3, s3, s1
	s_lshl_b32 s1, s18, 7
	v_add_u32_e32 v172, s1, v215
	v_ashrrev_i32_e32 v173, 31, v172
	v_readlane_b32 s6, v253, 48
	v_lshlrev_b64 v[144:145], 2, v[172:173]
	v_readlane_b32 s7, v253, 49
	v_lshlrev_b32_e32 v174, 3, v192
	v_ashrrev_i32_e32 v175, 31, v174
	v_lshl_add_u64 v[128:129], s[6:7], 0, v[144:145]
	v_readlane_b32 s6, v253, 40
	v_readlane_b32 s7, v253, 41
	v_lshl_add_u64 v[174:175], s[2:3], 0, v[174:175]
	v_mov_b32_dpp v178, v76 row_shr:1 row_mask:0xf bank_mask:0xf bound_ctrl:1
	v_lshl_add_u64 v[132:133], s[6:7], 0, v[144:145]
	v_readlane_b32 s6, v253, 42
	v_readlane_b32 s7, v253, 43
	global_load_dwordx4 v[128:131], v[128:129], off
	s_nop 0
	global_load_dwordx4 v[136:139], v[132:133], off
	v_lshl_add_u64 v[132:133], s[6:7], 0, v[144:145]
	v_readlane_b32 s6, v253, 44
	v_readlane_b32 s7, v253, 45
	v_mov_b32_dpp v182, v60 row_shr:1 row_mask:0xf bank_mask:0xf bound_ctrl:1
	v_mov_b32_dpp v188, v124 row_shl:1 row_mask:0xf bank_mask:0xf bound_ctrl:1
	v_lshl_add_u64 v[134:135], s[6:7], 0, v[144:145]
	v_readlane_b32 s6, v253, 46
	v_readlane_b32 s7, v253, 47
	global_load_dwordx4 v[140:143], v[132:133], off
	global_load_dwordx4 v[152:155], v[134:135], off
	v_lshl_add_u64 v[132:133], s[6:7], 0, v[144:145]
	v_readlane_b32 s6, v253, 50
	v_readlane_b32 s7, v253, 51
	v_mov_b32_dpp v198, v120 row_shl:1 row_mask:0xf bank_mask:0xf bound_ctrl:1
	v_mov_b32_dpp v179, v77 row_shr:1 row_mask:0xf bank_mask:0xf bound_ctrl:1
	v_lshl_add_u64 v[146:147], s[6:7], 0, v[144:145]
	v_readlane_b32 s6, v253, 52
	v_readlane_b32 s7, v253, 53
	global_load_dwordx4 v[132:135], v[132:133], off
	s_nop 0
	global_load_dwordx4 v[148:151], v[146:147], off
	v_lshl_add_u64 v[146:147], s[6:7], 0, v[144:145]
	v_readlane_b32 s6, v253, 54
	v_readlane_b32 s7, v253, 55
	v_mov_b32_dpp v183, v61 row_shr:1 row_mask:0xf bank_mask:0xf bound_ctrl:1
	v_mov_b32_dpp v189, v125 row_shl:1 row_mask:0xf bank_mask:0xf bound_ctrl:1
	v_lshl_add_u64 v[156:157], s[6:7], 0, v[144:145]
	global_load_dwordx4 v[144:147], v[146:147], off
	s_nop 0
	global_load_dwordx4 v[156:159], v[156:157], off
	v_mov_b32_dpp v199, v121 row_shl:1 row_mask:0xf bank_mask:0xf bound_ctrl:1
	v_mov_b32_dpp v180, v78 row_shr:1 row_mask:0xf bank_mask:0xf bound_ctrl:1
	v_mov_b32_dpp v184, v62 row_shr:1 row_mask:0xf bank_mask:0xf bound_ctrl:1
	v_mov_b32_dpp v186, v126 row_shl:1 row_mask:0xf bank_mask:0xf bound_ctrl:1
	v_mov_b32_dpp v190, v122 row_shl:1 row_mask:0xf bank_mask:0xf bound_ctrl:1
	v_mov_b32_dpp v181, v79 row_shr:1 row_mask:0xf bank_mask:0xf bound_ctrl:1
	v_mov_b32_dpp v185, v63 row_shr:1 row_mask:0xf bank_mask:0xf bound_ctrl:1
	v_mov_b32_dpp v187, v127 row_shl:1 row_mask:0xf bank_mask:0xf bound_ctrl:1
	v_mov_b32_dpp v191, v123 row_shl:1 row_mask:0xf bank_mask:0xf bound_ctrl:1
	v_cmp_ne_u32_e64 s[8:9], 0, v192
	s_and_saveexec_b64 s[2:3], s[8:9]
	s_xor_b64 s[6:7], exec, s[2:3]
	s_cbranch_execz .LBB0_121
	s_waitcnt vmcnt(0)
	v_pk_mul_f32 v[182:183], v[136:137], v[182:183]
	v_pk_mul_f32 v[176:177], v[138:139], v[184:185]
	v_pk_fma_f32 v[182:183], v[120:121], v[152:153], v[182:183]
	v_pk_mul_f32 v[178:179], v[128:129], v[178:179]
	v_pk_fma_f32 v[182:183], v[104:105], v[148:149], v[182:183]
	v_pk_fma_f32 v[178:179], v[124:125], v[140:141], v[178:179]
	v_pk_add_f32 v[182:183], v[156:157], v[182:183]
	v_pk_fma_f32 v[176:177], v[122:123], v[154:155], v[176:177]
	v_mul_f32_e32 v184, 0xbfb8aa3b, v182
	v_mul_f32_e32 v185, 0xbfb8aa3b, v183
	v_exp_f32_e32 v184, v184
	v_exp_f32_e32 v185, v185
	v_pk_fma_f32 v[178:179], v[116:117], v[132:133], v[178:179]
	v_pk_fma_f32 v[176:177], v[106:107], v[150:151], v[176:177]
	v_add_f32_e32 v184, 1.0, v184
	v_add_f32_e32 v185, 1.0, v185
	v_rcp_f32_e32 v184, v184
	v_rcp_f32_e32 v185, v185
	v_pk_add_f32 v[178:179], v[144:145], v[178:179]
	v_pk_add_f32 v[176:177], v[158:159], v[176:177]
	v_pk_mul_f32 v[180:181], v[130:131], v[180:181]
	v_pk_mul_f32 v[182:183], v[182:183], v[184:185]
	v_pk_fma_f32 v[180:181], v[126:127], v[142:143], v[180:181]
	v_pk_mul_f32 v[178:179], v[178:179], v[182:183]
	v_pk_fma_f32 v[180:181], v[118:119], v[134:135], v[180:181]
	v_cvt_pk_bf16_f32 v178, v178, v179
	v_mul_f32_e32 v179, 0xbfb8aa3b, v176
	v_exp_f32_e32 v179, v179
	v_pk_add_f32 v[180:181], v[146:147], v[180:181]
	s_movk_i32 s19, 0x1600
	v_add_f32_e32 v179, 1.0, v179
	v_rcp_f32_e32 v182, v179
	v_mul_f32_e32 v179, 0xbfb8aa3b, v177
	v_exp_f32_e32 v179, v179
	s_nop 0
	v_add_f32_e32 v179, 1.0, v179
	v_rcp_f32_e32 v183, v179
	s_nop 0
	v_pk_mul_f32 v[176:177], v[176:177], v[182:183]
	s_nop 0
	v_pk_mul_f32 v[176:177], v[180:181], v[176:177]
	s_nop 0
	v_cvt_pk_bf16_f32 v179, v176, v177
	v_mad_u64_u32 v[176:177], s[2:3], v174, s19, 0
	v_readlane_b32 s2, v254, 38
	v_readlane_b32 s3, v254, 39
	v_mad_i32_i24 v177, v175, s19, v177
	s_nop 0
	v_mov_b64_e32 v[180:181], s[2:3]
	v_mad_u64_u32 v[180:181], s[2:3], v174, s19, v[180:181]
	v_mad_i32_i24 v181, v175, s19, v181
	v_lshl_add_u64 v[174:175], v[172:173], 1, v[180:181]
	global_store_dwordx2 v[174:175], v[178:179], off
; __device__ __forceinline__ unsigned cvt_pk_bf16(float lo, float hi) { f32x2 v = {lo, hi}; bf16x2_t b = __builtin_convertvector(v, bf16x2_t); return __builtin_bit_cast(unsigned, b); }
; __device__ __forceinline__ float sigmoidf_(float v) { return __builtin_amdgcn_rcpf(1.0f + __builtin_amdgcn_exp2f(-1.4426950408889634f * v)); }
;     __device__ __forceinline__ void operator()(const f32x4 (&acc)[2][2][4][2], const Unit& u, int wr, int wc, int fr, int fq) const {
;     ...
;             for (int k = 0; k < 8; ++k) {
;                 const f32x4 ua0 = (k == 0) ? pa : acc[(k - 1) >> 2][0][(k - 1) & 3][n], ua1 = acc[k >> 2][0][k & 3][n], ua2 = (k == 7) ? na : acc[(k + 1) >> 2][0][(k + 1) & 3][n];
;                 const f32x4 ug0 = (k == 0) ? pg : acc[(k - 1) >> 2][1][(k - 1) & 3][n], ug1 = acc[k >> 2][1][k & 3][n], ug2 = (k == 7) ? ng : acc[(k + 1) >> 2][1][(k + 1) & 3][n];
;                 const f32x4 ca = wa[0] * ua0 + wa[1] * ua1 + wa[2] * ua2 + ba, cg = wg[0] * ug0 + wg[1] * ug1 + wg[2] * ug2 + bg;
;                 u32x2 w; w.x = cvt_pk_bf16(cg[0] * sigmoidf_(cg[0]) * ca[0], cg[1] * sigmoidf_(cg[1]) * ca[1]); w.y = cvt_pk_bf16(cg[2] * sigmoidf_(cg[2]) * ca[2], cg[3] * sigmoidf_(cg[3]) * ca[3]);
;                 const bool edge = (k == 0 && fr == 0) || (k == 7 && fr == 15);
;                 if (!edge) *(u32x2*)(ACT + (row0 + k) * 2816 + f0) = w;
.LBB0_121:
	s_andn2_saveexec_b64 s[6:7], s[6:7]
	s_movk_i32 s19, 0x1600
	v_mad_u64_u32 v[176:177], s[2:3], v174, s19, 0
	v_mad_i32_i24 v177, v175, s19, v177
	s_or_b64 exec, exec, s[6:7]
	s_waitcnt vmcnt(0)
	v_pk_mul_f32 v[178:179], v[104:105], v[152:153]
	v_pk_mul_f32 v[184:185], v[116:117], v[140:141]
	v_pk_fma_f32 v[178:179], v[120:121], v[136:137], v[178:179]
	v_pk_mul_f32 v[174:175], v[106:107], v[154:155]
	v_pk_fma_f32 v[178:179], v[100:101], v[148:149], v[178:179]
	v_pk_fma_f32 v[184:185], v[124:125], v[128:129], v[184:185]
	v_pk_add_f32 v[178:179], v[156:157], v[178:179]
	v_pk_fma_f32 v[174:175], v[122:123], v[138:139], v[174:175]
	v_mul_f32_e32 v180, 0xbfb8aa3b, v178
	v_mul_f32_e32 v181, 0xbfb8aa3b, v179
	v_exp_f32_e32 v180, v180
	v_exp_f32_e32 v181, v181
	v_pk_fma_f32 v[184:185], v[112:113], v[132:133], v[184:185]
	v_pk_fma_f32 v[174:175], v[102:103], v[150:151], v[174:175]
	v_add_f32_e32 v180, 1.0, v180
	v_add_f32_e32 v181, 1.0, v181
	v_rcp_f32_e32 v180, v180
	v_rcp_f32_e32 v181, v181
	v_pk_add_f32 v[184:185], v[144:145], v[184:185]
	v_pk_add_f32 v[174:175], v[158:159], v[174:175]
	v_pk_mul_f32 v[182:183], v[118:119], v[142:143]
	v_pk_mul_f32 v[178:179], v[178:179], v[180:181]
	v_pk_fma_f32 v[182:183], v[126:127], v[130:131], v[182:183]
	v_pk_mul_f32 v[178:179], v[184:185], v[178:179]
	v_pk_fma_f32 v[182:183], v[114:115], v[134:135], v[182:183]
	v_cvt_pk_bf16_f32 v178, v178, v179
	v_mul_f32_e32 v179, 0xbfb8aa3b, v174
	v_exp_f32_e32 v179, v179
	v_readlane_b32 s2, v254, 38
	v_pk_add_f32 v[182:183], v[146:147], v[182:183]
	v_readlane_b32 s3, v254, 39
	v_add_f32_e32 v179, 1.0, v179
	v_rcp_f32_e32 v180, v179
	v_mul_f32_e32 v179, 0xbfb8aa3b, v175
	v_exp_f32_e32 v179, v179
	v_lshl_add_u64 v[200:201], s[2:3], 0, v[176:177]
	s_mov_b64 s[2:3], 0x1600
	v_lshlrev_b64 v[202:203], 1, v[172:173]
	v_add_f32_e32 v179, 1.0, v179
	v_rcp_f32_e32 v181, v179
	v_pk_mul_f32 v[184:185], v[112:113], v[140:141]
	v_pk_mul_f32 v[204:205], v[108:109], v[140:141]
	v_pk_fma_f32 v[184:185], v[116:117], v[128:129], v[184:185]
	v_pk_mul_f32 v[174:175], v[174:175], v[180:181]
	v_pk_fma_f32 v[184:185], v[108:109], v[132:133], v[184:185]
	v_pk_mul_f32 v[174:175], v[182:183], v[174:175]
	v_pk_add_f32 v[184:185], v[144:145], v[184:185]
	v_cvt_pk_bf16_f32 v179, v174, v175
	v_lshl_add_u64 v[174:175], v[200:201], 0, s[2:3]
	v_lshl_add_u64 v[176:177], v[174:175], 0, v[202:203]
	global_store_dwordx2 v[176:177], v[178:179], off
	v_pk_mul_f32 v[178:179], v[100:101], v[152:153]
	v_pk_mul_f32 v[176:177], v[102:103], v[154:155]
	v_pk_fma_f32 v[178:179], v[104:105], v[136:137], v[178:179]
	v_pk_fma_f32 v[176:177], v[106:107], v[138:139], v[176:177]
	v_pk_fma_f32 v[178:179], v[96:97], v[148:149], v[178:179]
	v_pk_fma_f32 v[176:177], v[98:99], v[150:151], v[176:177]
	v_pk_add_f32 v[178:179], v[156:157], v[178:179]
	v_pk_add_f32 v[176:177], v[158:159], v[176:177]
	v_mul_f32_e32 v180, 0xbfb8aa3b, v178
	v_mul_f32_e32 v181, 0xbfb8aa3b, v179
	v_exp_f32_e32 v180, v180
	v_exp_f32_e32 v181, v181
	v_pk_mul_f32 v[182:183], v[114:115], v[142:143]
	s_mov_b64 s[2:3], 0x2c00
	v_add_f32_e32 v180, 1.0, v180
	v_add_f32_e32 v181, 1.0, v181
	v_rcp_f32_e32 v180, v180
	v_rcp_f32_e32 v181, v181
	v_pk_fma_f32 v[182:183], v[118:119], v[130:131], v[182:183]
	v_pk_fma_f32 v[204:205], v[112:113], v[128:129], v[204:205]
	v_pk_fma_f32 v[182:183], v[110:111], v[134:135], v[182:183]
	v_pk_mul_f32 v[178:179], v[178:179], v[180:181]
	v_pk_add_f32 v[182:183], v[146:147], v[182:183]
	v_pk_mul_f32 v[178:179], v[184:185], v[178:179]
	v_pk_fma_f32 v[204:205], v[92:93], v[132:133], v[204:205]
	v_cvt_pk_bf16_f32 v178, v178, v179
	v_mul_f32_e32 v179, 0xbfb8aa3b, v176
	v_exp_f32_e32 v179, v179
	v_pk_add_f32 v[204:205], v[144:145], v[204:205]
	v_pk_mul_f32 v[184:185], v[110:111], v[142:143]
	v_pk_mul_f32 v[206:207], v[92:93], v[140:141]
	v_add_f32_e32 v179, 1.0, v179
	v_rcp_f32_e32 v180, v179
	v_mul_f32_e32 v179, 0xbfb8aa3b, v177
	v_exp_f32_e32 v179, v179
	v_pk_fma_f32 v[184:185], v[114:115], v[130:131], v[184:185]
	v_pk_fma_f32 v[206:207], v[108:109], v[128:129], v[206:207]
	v_pk_fma_f32 v[184:185], v[94:95], v[134:135], v[184:185]
	v_add_f32_e32 v179, 1.0, v179
	v_rcp_f32_e32 v181, v179
	v_pk_add_f32 v[184:185], v[146:147], v[184:185]
	v_pk_fma_f32 v[206:207], v[84:85], v[132:133], v[206:207]
	v_pk_mul_f32 v[208:209], v[84:85], v[140:141]
	v_pk_mul_f32 v[176:177], v[176:177], v[180:181]
	v_pk_add_f32 v[206:207], v[144:145], v[206:207]
	v_pk_mul_f32 v[176:177], v[182:183], v[176:177]
	v_pk_fma_f32 v[208:209], v[92:93], v[128:129], v[208:209]
	v_cvt_pk_bf16_f32 v179, v176, v177
	v_lshl_add_u64 v[176:177], v[200:201], 0, s[2:3]
	v_lshl_add_u64 v[180:181], v[176:177], 0, v[202:203]
	global_store_dwordx2 v[180:181], v[178:179], off
	v_pk_mul_f32 v[180:181], v[96:97], v[152:153]
	v_pk_mul_f32 v[178:179], v[98:99], v[154:155]
	v_pk_fma_f32 v[180:181], v[100:101], v[136:137], v[180:181]
	v_pk_fma_f32 v[178:179], v[102:103], v[138:139], v[178:179]
	v_pk_fma_f32 v[180:181], v[88:89], v[148:149], v[180:181]
	v_pk_fma_f32 v[178:179], v[90:91], v[150:151], v[178:179]
	v_pk_add_f32 v[180:181], v[156:157], v[180:181]
	v_pk_add_f32 v[178:179], v[158:159], v[178:179]
	v_mul_f32_e32 v182, 0xbfb8aa3b, v180
	v_mul_f32_e32 v183, 0xbfb8aa3b, v181
	v_exp_f32_e32 v182, v182
	v_exp_f32_e32 v183, v183
	s_mov_b64 s[2:3], 0x4200
	v_pk_fma_f32 v[208:209], v[80:81], v[132:133], v[208:209]
	v_add_f32_e32 v182, 1.0, v182
	v_add_f32_e32 v183, 1.0, v183
	v_rcp_f32_e32 v182, v182
	v_rcp_f32_e32 v183, v183
	v_pk_add_f32 v[208:209], v[144:145], v[208:209]
	v_pk_mul_f32 v[210:211], v[80:81], v[140:141]
	v_cmp_ne_u32_e64 s[6:7], 15, v192
; __device__ __forceinline__ unsigned cvt_pk_bf16(float lo, float hi) { f32x2 v = {lo, hi}; bf16x2_t b = __builtin_convertvector(v, bf16x2_t); return __builtin_bit_cast(unsigned, b); }
; __device__ __forceinline__ float sigmoidf_(float v) { return __builtin_amdgcn_rcpf(1.0f + __builtin_amdgcn_exp2f(-1.4426950408889634f * v)); }
;     __device__ __forceinline__ void operator()(const f32x4 (&acc)[2][2][4][2], const Unit& u, int wr, int wc, int fr, int fq) const {
;     ...
;             for (int k = 0; k < 8; ++k) {
;                 const f32x4 ua0 = (k == 0) ? pa : acc[(k - 1) >> 2][0][(k - 1) & 3][n], ua1 = acc[k >> 2][0][k & 3][n], ua2 = (k == 7) ? na : acc[(k + 1) >> 2][0][(k + 1) & 3][n];
;                 const f32x4 ug0 = (k == 0) ? pg : acc[(k - 1) >> 2][1][(k - 1) & 3][n], ug1 = acc[k >> 2][1][k & 3][n], ug2 = (k == 7) ? ng : acc[(k + 1) >> 2][1][(k + 1) & 3][n];
;                 const f32x4 ca = wa[0] * ua0 + wa[1] * ua1 + wa[2] * ua2 + ba, cg = wg[0] * ug0 + wg[1] * ug1 + wg[2] * ug2 + bg;
;                 u32x2 w; w.x = cvt_pk_bf16(cg[0] * sigmoidf_(cg[0]) * ca[0], cg[1] * sigmoidf_(cg[1]) * ca[1]); w.y = cvt_pk_bf16(cg[2] * sigmoidf_(cg[2]) * ca[2], cg[3] * sigmoidf_(cg[3]) * ca[3]);
;                 const bool edge = (k == 0 && fr == 0) || (k == 7 && fr == 15);
;                 if (!edge) *(u32x2*)(ACT + (row0 + k) * 2816 + f0) = w;
	v_pk_mul_f32 v[180:181], v[180:181], v[182:183]
	v_pk_fma_f32 v[210:211], v[84:85], v[128:129], v[210:211]
	v_pk_mul_f32 v[180:181], v[204:205], v[180:181]
	v_pk_mul_f32 v[204:205], v[94:95], v[142:143]
	v_cvt_pk_bf16_f32 v180, v180, v181
	v_mul_f32_e32 v181, 0xbfb8aa3b, v178
	v_exp_f32_e32 v181, v181
	v_pk_fma_f32 v[204:205], v[110:111], v[130:131], v[204:205]
	v_pk_fma_f32 v[210:211], v[76:77], v[132:133], v[210:211]
	v_pk_fma_f32 v[204:205], v[86:87], v[134:135], v[204:205]
	v_add_f32_e32 v181, 1.0, v181
	v_rcp_f32_e32 v182, v181
	v_mul_f32_e32 v181, 0xbfb8aa3b, v179
	v_exp_f32_e32 v181, v181
	v_pk_add_f32 v[204:205], v[146:147], v[204:205]
	v_pk_add_f32 v[210:211], v[144:145], v[210:211]
	v_add_f32_e32 v181, 1.0, v181
	v_rcp_f32_e32 v183, v181
	s_nop 0
	v_pk_mul_f32 v[178:179], v[178:179], v[182:183]
	s_nop 0
	v_pk_mul_f32 v[178:179], v[184:185], v[178:179]
	s_nop 0
	v_cvt_pk_bf16_f32 v181, v178, v179
	v_lshl_add_u64 v[178:179], v[200:201], 0, s[2:3]
	v_lshl_add_u64 v[182:183], v[178:179], 0, v[202:203]
	global_store_dwordx2 v[182:183], v[180:181], off
	v_pk_mul_f32 v[182:183], v[88:89], v[152:153]
	v_pk_mul_f32 v[180:181], v[90:91], v[154:155]
	v_pk_fma_f32 v[182:183], v[96:97], v[136:137], v[182:183]
	v_pk_fma_f32 v[180:181], v[98:99], v[138:139], v[180:181]
	v_pk_fma_f32 v[182:183], v[72:73], v[148:149], v[182:183]
	v_pk_fma_f32 v[180:181], v[74:75], v[150:151], v[180:181]
	v_pk_add_f32 v[182:183], v[156:157], v[182:183]
	v_pk_add_f32 v[180:181], v[158:159], v[180:181]
	v_mul_f32_e32 v184, 0xbfb8aa3b, v182
	v_mul_f32_e32 v185, 0xbfb8aa3b, v183
	v_exp_f32_e32 v184, v184
	v_exp_f32_e32 v185, v185
	s_mov_b64 s[2:3], 0x5800
	v_add_f32_e32 v184, 1.0, v184
	v_add_f32_e32 v185, 1.0, v185
	v_rcp_f32_e32 v184, v184
	v_rcp_f32_e32 v185, v185
	s_nop 0
	v_pk_mul_f32 v[182:183], v[182:183], v[184:185]
	s_nop 0
	v_pk_mul_f32 v[182:183], v[206:207], v[182:183]
	v_pk_mul_f32 v[206:207], v[86:87], v[142:143]
	v_cvt_pk_bf16_f32 v182, v182, v183
	v_mul_f32_e32 v183, 0xbfb8aa3b, v180
	v_exp_f32_e32 v183, v183
	v_pk_fma_f32 v[206:207], v[94:95], v[130:131], v[206:207]
	v_add_f32_e32 v183, 1.0, v183
	v_rcp_f32_e32 v184, v183
	v_mul_f32_e32 v183, 0xbfb8aa3b, v181
	v_exp_f32_e32 v183, v183
	v_pk_fma_f32 v[206:207], v[82:83], v[134:135], v[206:207]
	v_add_f32_e32 v183, 1.0, v183
	v_rcp_f32_e32 v185, v183
	v_pk_add_f32 v[206:207], v[146:147], v[206:207]
	v_pk_mul_f32 v[180:181], v[180:181], v[184:185]
	s_nop 0
	v_pk_mul_f32 v[180:181], v[204:205], v[180:181]
	s_nop 0
	v_cvt_pk_bf16_f32 v183, v180, v181
	v_lshl_add_u64 v[180:181], v[200:201], 0, s[2:3]
	v_lshl_add_u64 v[184:185], v[180:181], 0, v[202:203]
	global_store_dwordx2 v[184:185], v[182:183], off
	v_pk_mul_f32 v[184:185], v[72:73], v[152:153]
	v_pk_mul_f32 v[182:183], v[74:75], v[154:155]
	v_pk_fma_f32 v[184:185], v[88:89], v[136:137], v[184:185]
	v_pk_fma_f32 v[182:183], v[90:91], v[138:139], v[182:183]
	v_pk_fma_f32 v[184:185], v[68:69], v[148:149], v[184:185]
	v_pk_fma_f32 v[182:183], v[70:71], v[150:151], v[182:183]
	v_pk_add_f32 v[184:185], v[156:157], v[184:185]
	v_pk_add_f32 v[182:183], v[158:159], v[182:183]
	v_mul_f32_e32 v204, 0xbfb8aa3b, v184
	v_mul_f32_e32 v205, 0xbfb8aa3b, v185
	v_exp_f32_e32 v204, v204
	v_exp_f32_e32 v205, v205
	s_mov_b64 s[2:3], 0x6e00
	v_add_f32_e32 v204, 1.0, v204
	v_add_f32_e32 v205, 1.0, v205
	v_rcp_f32_e32 v204, v204
	v_rcp_f32_e32 v205, v205
	s_nop 0
	v_pk_mul_f32 v[184:185], v[184:185], v[204:205]
	s_nop 0
	v_pk_mul_f32 v[184:185], v[208:209], v[184:185]
	v_pk_mul_f32 v[208:209], v[82:83], v[142:143]
	v_cvt_pk_bf16_f32 v184, v184, v185
	v_mul_f32_e32 v185, 0xbfb8aa3b, v182
	v_exp_f32_e32 v185, v185
	v_pk_fma_f32 v[208:209], v[86:87], v[130:131], v[208:209]
	v_add_f32_e32 v185, 1.0, v185
	v_rcp_f32_e32 v204, v185
	v_mul_f32_e32 v185, 0xbfb8aa3b, v183
	v_exp_f32_e32 v185, v185
	v_pk_fma_f32 v[208:209], v[78:79], v[134:135], v[208:209]
	v_add_f32_e32 v185, 1.0, v185
	v_rcp_f32_e32 v205, v185
	v_pk_add_f32 v[208:209], v[146:147], v[208:209]
	v_pk_mul_f32 v[182:183], v[182:183], v[204:205]
	s_nop 0
	v_pk_mul_f32 v[182:183], v[206:207], v[182:183]
	s_nop 0
	v_cvt_pk_bf16_f32 v185, v182, v183
	v_lshl_add_u64 v[182:183], v[200:201], 0, s[2:3]
	v_lshl_add_u64 v[204:205], v[182:183], 0, v[202:203]
	global_store_dwordx2 v[204:205], v[184:185], off
	v_pk_mul_f32 v[204:205], v[68:69], v[152:153]
	v_pk_mul_f32 v[184:185], v[70:71], v[154:155]
	v_pk_fma_f32 v[204:205], v[72:73], v[136:137], v[204:205]
	v_pk_fma_f32 v[184:185], v[74:75], v[138:139], v[184:185]
	v_pk_fma_f32 v[204:205], v[60:61], v[148:149], v[204:205]
	v_pk_fma_f32 v[184:185], v[62:63], v[150:151], v[184:185]
	v_pk_add_f32 v[204:205], v[156:157], v[204:205]
	v_pk_add_f32 v[184:185], v[158:159], v[184:185]
	v_mul_f32_e32 v206, 0xbfb8aa3b, v204
	v_mul_f32_e32 v207, 0xbfb8aa3b, v205
	v_exp_f32_e32 v206, v206
	v_exp_f32_e32 v207, v207
	s_mov_b64 s[2:3], 0x8400
	v_add_f32_e32 v206, 1.0, v206
	v_add_f32_e32 v207, 1.0, v207
	v_rcp_f32_e32 v206, v206
	v_rcp_f32_e32 v207, v207
	s_nop 0
	v_pk_mul_f32 v[204:205], v[204:205], v[206:207]
	s_nop 0
	v_pk_mul_f32 v[204:205], v[210:211], v[204:205]
	s_nop 0
	v_cvt_pk_bf16_f32 v204, v204, v205
	v_mul_f32_e32 v205, 0xbfb8aa3b, v184
	v_exp_f32_e32 v205, v205
	s_nop 0
	v_add_f32_e32 v205, 1.0, v205
	v_rcp_f32_e32 v206, v205
	v_mul_f32_e32 v205, 0xbfb8aa3b, v185
	v_exp_f32_e32 v205, v205
	s_nop 0
	v_add_f32_e32 v205, 1.0, v205
	v_rcp_f32_e32 v207, v205
	s_nop 0
	v_pk_mul_f32 v[184:185], v[184:185], v[206:207]
	s_nop 0
	v_pk_mul_f32 v[184:185], v[208:209], v[184:185]
	s_nop 0
	v_cvt_pk_bf16_f32 v205, v184, v185
	v_lshl_add_u64 v[184:185], v[200:201], 0, s[2:3]
	v_lshl_add_u64 v[202:203], v[184:185], 0, v[202:203]
	global_store_dwordx2 v[202:203], v[204:205], off
	s_and_saveexec_b64 s[28:29], s[6:7]
	s_cbranch_execz .LBB0_125
; __device__ __forceinline__ unsigned cvt_pk_bf16(float lo, float hi) { f32x2 v = {lo, hi}; bf16x2_t b = __builtin_convertvector(v, bf16x2_t); return __builtin_bit_cast(unsigned, b); }
; __device__ __forceinline__ float sigmoidf_(float v) { return __builtin_amdgcn_rcpf(1.0f + __builtin_amdgcn_exp2f(-1.4426950408889634f * v)); }
; __device__ __forceinline__ float dpp_shr1(float v) { return __builtin_bit_cast(float, __builtin_amdgcn_update_dpp(0, __builtin_bit_cast(int, v), 0x111, 0xf, 0xf, true)); }
; __device__ __forceinline__ float dpp_shl1(float v) { return __builtin_bit_cast(float, __builtin_amdgcn_update_dpp(0, __builtin_bit_cast(int, v), 0x101, 0xf, 0xf, true)); }
;     __device__ __forceinline__ void operator()(const f32x4 (&acc)[2][2][4][2], const Unit& u, int wr, int wc, int fr, int fq) const {
;     ...
;         for (int n = 0; n < 2; ++n) {
;             const int f0 = 128 * u.pn + 32 * wc + 8 * fq + 4 * n;
;             f32x4 wa[3], wg[3];
; #pragma unroll
;             for (int j = 0; j < 3; ++j) { wa[j] = *(const f32x4*)(cw + j * 5632 + f0); wg[j] = *(const f32x4*)(cw + j * 5632 + 2816 + f0); }
;             const f32x4 ba = *(const f32x4*)(cb + f0), bg = *(const f32x4*)(cb + 2816 + f0);
;             f32x4 pa, pg, na, ng;
; #pragma unroll
;             for (int e = 0; e < 4; ++e) { pa[e] = dpp_shr1(acc[1][0][3][n][e]); pg[e] = dpp_shr1(acc[1][1][3][n][e]); na[e] = dpp_shl1(acc[0][0][0][n][e]); ng[e] = dpp_shl1(acc[0][1][0][n][e]); }
; #pragma unroll
;             for (int k = 0; k < 8; ++k) {
;                 const f32x4 ua0 = (k == 0) ? pa : acc[(k - 1) >> 2][0][(k - 1) & 3][n], ua1 = acc[k >> 2][0][k & 3][n], ua2 = (k == 7) ? na : acc[(k + 1) >> 2][0][(k + 1) & 3][n];
;                 const f32x4 ug0 = (k == 0) ? pg : acc[(k - 1) >> 2][1][(k - 1) & 3][n], ug1 = acc[k >> 2][1][k & 3][n], ug2 = (k == 7) ? ng : acc[(k + 1) >> 2][1][(k + 1) & 3][n];
;                 const f32x4 ca = wa[0] * ua0 + wa[1] * ua1 + wa[2] * ua2 + ba, cg = wg[0] * ug0 + wg[1] * ug1 + wg[2] * ug2 + bg;
;                 u32x2 w; w.x = cvt_pk_bf16(cg[0] * sigmoidf_(cg[0]) * ca[0], cg[1] * sigmoidf_(cg[1]) * ca[1]); w.y = cvt_pk_bf16(cg[2] * sigmoidf_(cg[2]) * ca[2], cg[3] * sigmoidf_(cg[3]) * ca[3]);
;                 const bool edge = (k == 0 && fr == 0) || (k == 7 && fr == 15);
;                 if (!edge) *(u32x2*)(ACT + (row0 + k) * 2816 + f0) = w;
	v_pk_mul_f32 v[152:153], v[60:61], v[152:153]
	v_pk_mul_f32 v[154:155], v[62:63], v[154:155]
	v_pk_fma_f32 v[136:137], v[68:69], v[136:137], v[152:153]
	v_pk_fma_f32 v[138:139], v[70:71], v[138:139], v[154:155]
	v_pk_fma_f32 v[136:137], v[148:149], v[198:199], v[136:137]
	v_pk_mul_f32 v[140:141], v[76:77], v[140:141]
	v_pk_add_f32 v[136:137], v[156:157], v[136:137]
	v_pk_fma_f32 v[138:139], v[150:151], v[190:191], v[138:139]
	v_pk_mul_f32 v[142:143], v[78:79], v[142:143]
	v_pk_fma_f32 v[128:129], v[80:81], v[128:129], v[140:141]
	v_pk_add_f32 v[138:139], v[158:159], v[138:139]
	v_pk_fma_f32 v[130:131], v[82:83], v[130:131], v[142:143]
	v_pk_fma_f32 v[128:129], v[132:133], v[188:189], v[128:129]
	v_mul_f32_e32 v132, 0xbfb8aa3b, v137
	v_mul_f32_e32 v148, 0xbfb8aa3b, v136
	v_exp_f32_e32 v132, v132
	v_pk_fma_f32 v[130:131], v[134:135], v[186:187], v[130:131]
	v_mul_f32_e32 v133, 0xbfb8aa3b, v138
	v_mul_f32_e32 v134, 0xbfb8aa3b, v139
	v_exp_f32_e32 v148, v148
	v_exp_f32_e32 v133, v133
	v_exp_f32_e32 v134, v134
	v_add_f32_e32 v132, 1.0, v132
	v_add_f32_e32 v148, 1.0, v148
	v_rcp_f32_e32 v149, v132
	v_add_f32_e32 v132, 1.0, v133
	v_add_f32_e32 v133, 1.0, v134
	v_rcp_f32_e32 v148, v148
	v_rcp_f32_e32 v132, v132
	v_rcp_f32_e32 v133, v133
	v_pk_add_f32 v[130:131], v[146:147], v[130:131]
	v_pk_add_f32 v[128:129], v[144:145], v[128:129]
	v_pk_mul_f32 v[134:135], v[136:137], v[148:149]
	v_pk_mul_f32 v[132:133], v[138:139], v[132:133]
	v_pk_mul_f32 v[128:129], v[128:129], v[134:135]
	v_pk_mul_f32 v[130:131], v[130:131], v[132:133]
	v_cvt_pk_bf16_f32 v128, v128, v129
	v_cvt_pk_bf16_f32 v129, v130, v131
	v_lshl_add_u64 v[130:131], v[172:173], 1, v[200:201]
	v_add_co_u32_e32 v130, vcc, 0x9000, v130
	s_nop 1
	v_addc_co_u32_e32 v131, vcc, 0, v131, vcc
	global_store_dwordx2 v[130:131], v[128:129], off offset:2560
.LBB0_125:
	s_or_b64 exec, exec, s[28:29]
	v_add3_u32 v202, v215, s1, 4
	v_ashrrev_i32_e32 v203, 31, v202
	v_readlane_b32 s2, v253, 48
	v_lshlrev_b64 v[144:145], 2, v[202:203]
	v_readlane_b32 s3, v253, 49
	v_mov_b32_dpp v204, v12 row_shr:1 row_mask:0xf bank_mask:0xf bound_ctrl:1
	v_mov_b32_dpp v208, v0 row_shr:1 row_mask:0xf bank_mask:0xf bound_ctrl:1
	v_lshl_add_u64 v[128:129], s[2:3], 0, v[144:145]
	v_readlane_b32 s2, v253, 40
	v_readlane_b32 s3, v253, 41
	v_mov_b32_dpp v188, v64 row_shl:1 row_mask:0xf bank_mask:0xf bound_ctrl:1
	v_mov_b32_dpp v198, v56 row_shl:1 row_mask:0xf bank_mask:0xf bound_ctrl:1
	v_lshl_add_u64 v[132:133], s[2:3], 0, v[144:145]
	v_readlane_b32 s2, v253, 42
	v_readlane_b32 s3, v253, 43
	global_load_dwordx4 v[128:131], v[128:129], off
	s_nop 0
	global_load_dwordx4 v[136:139], v[132:133], off
	v_lshl_add_u64 v[132:133], s[2:3], 0, v[144:145]
	v_readlane_b32 s2, v253, 44
	v_readlane_b32 s3, v253, 45
	v_mov_b32_dpp v205, v13 row_shr:1 row_mask:0xf bank_mask:0xf bound_ctrl:1
	v_mov_b32_dpp v209, v1 row_shr:1 row_mask:0xf bank_mask:0xf bound_ctrl:1
	v_lshl_add_u64 v[134:135], s[2:3], 0, v[144:145]
	v_readlane_b32 s2, v253, 46
	v_readlane_b32 s3, v253, 47
	global_load_dwordx4 v[140:143], v[132:133], off
	global_load_dwordx4 v[152:155], v[134:135], off
	v_lshl_add_u64 v[132:133], s[2:3], 0, v[144:145]
	v_readlane_b32 s2, v253, 50
	v_readlane_b32 s3, v253, 51
	v_mov_b32_dpp v189, v65 row_shl:1 row_mask:0xf bank_mask:0xf bound_ctrl:1
	v_mov_b32_dpp v199, v57 row_shl:1 row_mask:0xf bank_mask:0xf bound_ctrl:1
	v_lshl_add_u64 v[146:147], s[2:3], 0, v[144:145]
	v_readlane_b32 s2, v253, 52
	v_readlane_b32 s3, v253, 53
	global_load_dwordx4 v[132:135], v[132:133], off
	s_nop 0
	global_load_dwordx4 v[148:151], v[146:147], off
	v_lshl_add_u64 v[146:147], s[2:3], 0, v[144:145]
	v_readlane_b32 s2, v253, 54
	v_readlane_b32 s3, v253, 55
	v_mov_b32_dpp v206, v14 row_shr:1 row_mask:0xf bank_mask:0xf bound_ctrl:1
	v_mov_b32_dpp v210, v2 row_shr:1 row_mask:0xf bank_mask:0xf bound_ctrl:1
	v_lshl_add_u64 v[156:157], s[2:3], 0, v[144:145]
	global_load_dwordx4 v[144:147], v[146:147], off
	s_nop 0
	global_load_dwordx4 v[156:159], v[156:157], off
	v_mov_b32_dpp v186, v66 row_shl:1 row_mask:0xf bank_mask:0xf bound_ctrl:1
	v_mov_b32_dpp v190, v58 row_shl:1 row_mask:0xf bank_mask:0xf bound_ctrl:1
	v_mov_b32_dpp v207, v15 row_shr:1 row_mask:0xf bank_mask:0xf bound_ctrl:1
	v_mov_b32_dpp v211, v3 row_shr:1 row_mask:0xf bank_mask:0xf bound_ctrl:1
	v_mov_b32_dpp v187, v67 row_shl:1 row_mask:0xf bank_mask:0xf bound_ctrl:1
	v_mov_b32_dpp v191, v59 row_shl:1 row_mask:0xf bank_mask:0xf bound_ctrl:1
	v_lshl_add_u64 v[172:173], v[202:203], 1, v[200:201]
	s_and_saveexec_b64 s[28:29], s[8:9]
	s_cbranch_execz .LBB0_127
	s_waitcnt vmcnt(0)
	v_pk_mul_f32 v[208:209], v[136:137], v[208:209]
	v_pk_mul_f32 v[200:201], v[138:139], v[210:211]
	v_pk_fma_f32 v[208:209], v[56:57], v[152:153], v[208:209]
	v_pk_mul_f32 v[204:205], v[128:129], v[204:205]
	v_pk_fma_f32 v[208:209], v[40:41], v[148:149], v[208:209]
	v_pk_fma_f32 v[204:205], v[64:65], v[140:141], v[204:205]
	v_pk_add_f32 v[208:209], v[156:157], v[208:209]
	v_pk_fma_f32 v[200:201], v[58:59], v[154:155], v[200:201]
	v_mul_f32_e32 v210, 0xbfb8aa3b, v208
	v_mul_f32_e32 v211, 0xbfb8aa3b, v209
	v_exp_f32_e32 v210, v210
	v_exp_f32_e32 v211, v211
	v_pk_fma_f32 v[204:205], v[52:53], v[132:133], v[204:205]
	v_pk_fma_f32 v[200:201], v[42:43], v[150:151], v[200:201]
	v_add_f32_e32 v210, 1.0, v210
	v_add_f32_e32 v211, 1.0, v211
	v_rcp_f32_e32 v210, v210
	v_rcp_f32_e32 v211, v211
	v_pk_add_f32 v[204:205], v[144:145], v[204:205]
	v_pk_add_f32 v[200:201], v[158:159], v[200:201]
	v_pk_mul_f32 v[206:207], v[130:131], v[206:207]
	v_pk_mul_f32 v[208:209], v[208:209], v[210:211]
	v_pk_fma_f32 v[206:207], v[66:67], v[142:143], v[206:207]
	v_pk_mul_f32 v[204:205], v[204:205], v[208:209]
	v_pk_fma_f32 v[206:207], v[54:55], v[134:135], v[206:207]
	v_cvt_pk_bf16_f32 v204, v204, v205
	v_mul_f32_e32 v205, 0xbfb8aa3b, v200
	v_exp_f32_e32 v205, v205
	v_pk_add_f32 v[206:207], v[146:147], v[206:207]
	v_add_f32_e32 v205, 1.0, v205
	v_rcp_f32_e32 v208, v205
	v_mul_f32_e32 v205, 0xbfb8aa3b, v201
	v_exp_f32_e32 v205, v205
	s_nop 0
	v_add_f32_e32 v205, 1.0, v205
	v_rcp_f32_e32 v209, v205
	s_nop 0
	v_pk_mul_f32 v[200:201], v[200:201], v[208:209]
	s_nop 0
	v_pk_mul_f32 v[200:201], v[206:207], v[200:201]
	s_nop 0
	v_cvt_pk_bf16_f32 v205, v200, v201
	global_store_dwordx2 v[172:173], v[204:205], off
; __device__ __forceinline__ unsigned cvt_pk_bf16(float lo, float hi) { f32x2 v = {lo, hi}; bf16x2_t b = __builtin_convertvector(v, bf16x2_t); return __builtin_bit_cast(unsigned, b); }
; __device__ __forceinline__ float sigmoidf_(float v) { return __builtin_amdgcn_rcpf(1.0f + __builtin_amdgcn_exp2f(-1.4426950408889634f * v)); }
;     __device__ __forceinline__ void operator()(const f32x4 (&acc)[2][2][4][2], const Unit& u, int wr, int wc, int fr, int fq) const {
;     ...
;             for (int k = 0; k < 8; ++k) {
;                 const f32x4 ua0 = (k == 0) ? pa : acc[(k - 1) >> 2][0][(k - 1) & 3][n], ua1 = acc[k >> 2][0][k & 3][n], ua2 = (k == 7) ? na : acc[(k + 1) >> 2][0][(k + 1) & 3][n];
;                 const f32x4 ug0 = (k == 0) ? pg : acc[(k - 1) >> 2][1][(k - 1) & 3][n], ug1 = acc[k >> 2][1][k & 3][n], ug2 = (k == 7) ? ng : acc[(k + 1) >> 2][1][(k + 1) & 3][n];
;                 const f32x4 ca = wa[0] * ua0 + wa[1] * ua1 + wa[2] * ua2 + ba, cg = wg[0] * ug0 + wg[1] * ug1 + wg[2] * ug2 + bg;
;                 u32x2 w; w.x = cvt_pk_bf16(cg[0] * sigmoidf_(cg[0]) * ca[0], cg[1] * sigmoidf_(cg[1]) * ca[1]); w.y = cvt_pk_bf16(cg[2] * sigmoidf_(cg[2]) * ca[2], cg[3] * sigmoidf_(cg[3]) * ca[3]);
;                 const bool edge = (k == 0 && fr == 0) || (k == 7 && fr == 15);
;                 if (!edge) *(u32x2*)(ACT + (row0 + k) * 2816 + f0) = w;
.LBB0_127:
	s_or_b64 exec, exec, s[28:29]
	s_waitcnt vmcnt(0)
	v_pk_mul_f32 v[204:205], v[40:41], v[152:153]
	v_pk_mul_f32 v[210:211], v[52:53], v[140:141]
	v_pk_fma_f32 v[204:205], v[56:57], v[136:137], v[204:205]
	v_pk_mul_f32 v[200:201], v[42:43], v[154:155]
	v_pk_fma_f32 v[204:205], v[36:37], v[148:149], v[204:205]
	v_pk_fma_f32 v[210:211], v[64:65], v[128:129], v[210:211]
	v_pk_add_f32 v[204:205], v[156:157], v[204:205]
	v_pk_fma_f32 v[200:201], v[58:59], v[138:139], v[200:201]
	v_mul_f32_e32 v206, 0xbfb8aa3b, v204
	v_mul_f32_e32 v207, 0xbfb8aa3b, v205
	v_exp_f32_e32 v206, v206
	v_exp_f32_e32 v207, v207
	v_pk_fma_f32 v[210:211], v[48:49], v[132:133], v[210:211]
	v_pk_fma_f32 v[200:201], v[38:39], v[150:151], v[200:201]
	v_add_f32_e32 v206, 1.0, v206
	v_add_f32_e32 v207, 1.0, v207
	v_rcp_f32_e32 v206, v206
	v_rcp_f32_e32 v207, v207
	v_pk_add_f32 v[210:211], v[144:145], v[210:211]
	v_pk_add_f32 v[200:201], v[158:159], v[200:201]
	v_pk_mul_f32 v[208:209], v[54:55], v[142:143]
	v_pk_mul_f32 v[204:205], v[204:205], v[206:207]
	v_pk_fma_f32 v[208:209], v[66:67], v[130:131], v[208:209]
	v_pk_mul_f32 v[204:205], v[210:211], v[204:205]
	v_pk_fma_f32 v[208:209], v[50:51], v[134:135], v[208:209]
	v_cvt_pk_bf16_f32 v204, v204, v205
	v_mul_f32_e32 v205, 0xbfb8aa3b, v200
	v_exp_f32_e32 v205, v205
	v_pk_add_f32 v[208:209], v[146:147], v[208:209]
	v_add_f32_e32 v205, 1.0, v205
	v_rcp_f32_e32 v206, v205
	v_mul_f32_e32 v205, 0xbfb8aa3b, v201
	v_exp_f32_e32 v205, v205
	s_nop 0
	v_add_f32_e32 v205, 1.0, v205
	v_rcp_f32_e32 v207, v205
	s_nop 0
	v_pk_mul_f32 v[200:201], v[200:201], v[206:207]
	s_nop 0
	v_pk_mul_f32 v[200:201], v[208:209], v[200:201]
	v_pk_mul_f32 v[208:209], v[48:49], v[140:141]
	v_cvt_pk_bf16_f32 v205, v200, v201
	v_lshlrev_b64 v[200:201], 1, v[202:203]
	v_pk_mul_f32 v[202:203], v[36:37], v[152:153]
	v_lshl_add_u64 v[174:175], v[174:175], 0, v[200:201]
	v_pk_fma_f32 v[202:203], v[40:41], v[136:137], v[202:203]
	global_store_dwordx2 v[174:175], v[204:205], off
	v_pk_fma_f32 v[202:203], v[32:33], v[148:149], v[202:203]
	v_pk_mul_f32 v[174:175], v[38:39], v[154:155]
	v_pk_add_f32 v[202:203], v[156:157], v[202:203]
	v_pk_fma_f32 v[208:209], v[52:53], v[128:129], v[208:209]
	v_mul_f32_e32 v204, 0xbfb8aa3b, v202
	v_mul_f32_e32 v205, 0xbfb8aa3b, v203
	v_exp_f32_e32 v204, v204
	v_exp_f32_e32 v205, v205
	v_pk_fma_f32 v[174:175], v[42:43], v[138:139], v[174:175]
	v_pk_fma_f32 v[208:209], v[44:45], v[132:133], v[208:209]
	v_add_f32_e32 v204, 1.0, v204
	v_add_f32_e32 v205, 1.0, v205
	v_rcp_f32_e32 v204, v204
	v_rcp_f32_e32 v205, v205
	v_pk_fma_f32 v[174:175], v[34:35], v[150:151], v[174:175]
	v_pk_add_f32 v[208:209], v[144:145], v[208:209]
	v_pk_add_f32 v[174:175], v[158:159], v[174:175]
	v_pk_mul_f32 v[202:203], v[202:203], v[204:205]
	v_pk_mul_f32 v[206:207], v[50:51], v[142:143]
	v_pk_mul_f32 v[202:203], v[208:209], v[202:203]
	v_pk_fma_f32 v[206:207], v[54:55], v[130:131], v[206:207]
	v_cvt_pk_bf16_f32 v202, v202, v203
	v_mul_f32_e32 v203, 0xbfb8aa3b, v174
	v_exp_f32_e32 v203, v203
	v_pk_fma_f32 v[206:207], v[46:47], v[134:135], v[206:207]
	v_add_f32_e32 v203, 1.0, v203
	v_rcp_f32_e32 v204, v203
	v_mul_f32_e32 v203, 0xbfb8aa3b, v175
	v_exp_f32_e32 v203, v203
	v_pk_add_f32 v[206:207], v[146:147], v[206:207]
	v_add_f32_e32 v203, 1.0, v203
	v_rcp_f32_e32 v205, v203
	s_nop 0
	v_pk_mul_f32 v[174:175], v[174:175], v[204:205]
	s_nop 0
	v_pk_mul_f32 v[174:175], v[206:207], v[174:175]
	v_pk_mul_f32 v[206:207], v[44:45], v[140:141]
	v_cvt_pk_bf16_f32 v203, v174, v175
	v_lshl_add_u64 v[174:175], v[176:177], 0, v[200:201]
	v_pk_mul_f32 v[176:177], v[32:33], v[152:153]
	global_store_dwordx2 v[174:175], v[202:203], off
	v_pk_fma_f32 v[176:177], v[36:37], v[136:137], v[176:177]
	v_pk_mul_f32 v[174:175], v[34:35], v[154:155]
	v_pk_fma_f32 v[176:177], v[24:25], v[148:149], v[176:177]
	v_pk_fma_f32 v[206:207], v[48:49], v[128:129], v[206:207]
	v_pk_add_f32 v[176:177], v[156:157], v[176:177]
	v_pk_fma_f32 v[174:175], v[38:39], v[138:139], v[174:175]
	v_mul_f32_e32 v202, 0xbfb8aa3b, v176
	v_mul_f32_e32 v203, 0xbfb8aa3b, v177
	v_exp_f32_e32 v202, v202
	v_exp_f32_e32 v203, v203
	v_pk_fma_f32 v[206:207], v[28:29], v[132:133], v[206:207]
	v_pk_fma_f32 v[174:175], v[26:27], v[150:151], v[174:175]
	v_add_f32_e32 v202, 1.0, v202
	v_add_f32_e32 v203, 1.0, v203
	v_rcp_f32_e32 v202, v202
	v_rcp_f32_e32 v203, v203
	v_pk_add_f32 v[206:207], v[144:145], v[206:207]
	v_pk_add_f32 v[174:175], v[158:159], v[174:175]
	v_pk_mul_f32 v[204:205], v[46:47], v[142:143]
	v_pk_mul_f32 v[176:177], v[176:177], v[202:203]
	v_pk_fma_f32 v[204:205], v[50:51], v[130:131], v[204:205]
	v_pk_mul_f32 v[176:177], v[206:207], v[176:177]
	v_pk_fma_f32 v[204:205], v[30:31], v[134:135], v[204:205]
	v_cvt_pk_bf16_f32 v176, v176, v177
	v_mul_f32_e32 v177, 0xbfb8aa3b, v174
	v_exp_f32_e32 v177, v177
	v_pk_add_f32 v[204:205], v[146:147], v[204:205]
	v_add_f32_e32 v177, 1.0, v177
	v_rcp_f32_e32 v202, v177
	v_mul_f32_e32 v177, 0xbfb8aa3b, v175
	v_exp_f32_e32 v177, v177
	s_nop 0
	v_add_f32_e32 v177, 1.0, v177
	v_rcp_f32_e32 v203, v177
	s_nop 0
	v_pk_mul_f32 v[174:175], v[174:175], v[202:203]
	s_nop 0
	v_pk_mul_f32 v[174:175], v[204:205], v[174:175]
	v_pk_mul_f32 v[204:205], v[28:29], v[140:141]
	v_cvt_pk_bf16_f32 v177, v174, v175
	v_lshl_add_u64 v[174:175], v[178:179], 0, v[200:201]
	global_store_dwordx2 v[174:175], v[176:177], off
	v_pk_mul_f32 v[176:177], v[24:25], v[152:153]
	v_pk_mul_f32 v[174:175], v[26:27], v[154:155]
	v_pk_fma_f32 v[176:177], v[32:33], v[136:137], v[176:177]
	v_pk_fma_f32 v[204:205], v[44:45], v[128:129], v[204:205]
	v_pk_fma_f32 v[176:177], v[8:9], v[148:149], v[176:177]
; __device__ __forceinline__ unsigned cvt_pk_bf16(float lo, float hi) { f32x2 v = {lo, hi}; bf16x2_t b = __builtin_convertvector(v, bf16x2_t); return __builtin_bit_cast(unsigned, b); }
; __device__ __forceinline__ float sigmoidf_(float v) { return __builtin_amdgcn_rcpf(1.0f + __builtin_amdgcn_exp2f(-1.4426950408889634f * v)); }
;     __device__ __forceinline__ void operator()(const f32x4 (&acc)[2][2][4][2], const Unit& u, int wr, int wc, int fr, int fq) const {
;     ...
;             for (int k = 0; k < 8; ++k) {
;                 const f32x4 ua0 = (k == 0) ? pa : acc[(k - 1) >> 2][0][(k - 1) & 3][n], ua1 = acc[k >> 2][0][k & 3][n], ua2 = (k == 7) ? na : acc[(k + 1) >> 2][0][(k + 1) & 3][n];
;                 const f32x4 ug0 = (k == 0) ? pg : acc[(k - 1) >> 2][1][(k - 1) & 3][n], ug1 = acc[k >> 2][1][k & 3][n], ug2 = (k == 7) ? ng : acc[(k + 1) >> 2][1][(k + 1) & 3][n];
;                 const f32x4 ca = wa[0] * ua0 + wa[1] * ua1 + wa[2] * ua2 + ba, cg = wg[0] * ug0 + wg[1] * ug1 + wg[2] * ug2 + bg;
;                 u32x2 w; w.x = cvt_pk_bf16(cg[0] * sigmoidf_(cg[0]) * ca[0], cg[1] * sigmoidf_(cg[1]) * ca[1]); w.y = cvt_pk_bf16(cg[2] * sigmoidf_(cg[2]) * ca[2], cg[3] * sigmoidf_(cg[3]) * ca[3]);
;                 const bool edge = (k == 0 && fr == 0) || (k == 7 && fr == 15);
;                 if (!edge) *(u32x2*)(ACT + (row0 + k) * 2816 + f0) = w;
	v_pk_fma_f32 v[174:175], v[34:35], v[138:139], v[174:175]
	v_pk_add_f32 v[176:177], v[156:157], v[176:177]
	v_pk_fma_f32 v[204:205], v[20:21], v[132:133], v[204:205]
	v_mul_f32_e32 v178, 0xbfb8aa3b, v176
	v_mul_f32_e32 v179, 0xbfb8aa3b, v177
	v_exp_f32_e32 v178, v178
	v_exp_f32_e32 v179, v179
	v_pk_fma_f32 v[174:175], v[10:11], v[150:151], v[174:175]
	v_pk_add_f32 v[204:205], v[144:145], v[204:205]
	v_add_f32_e32 v178, 1.0, v178
	v_add_f32_e32 v179, 1.0, v179
	v_rcp_f32_e32 v178, v178
	v_rcp_f32_e32 v179, v179
	v_pk_add_f32 v[174:175], v[158:159], v[174:175]
	v_pk_mul_f32 v[202:203], v[30:31], v[142:143]
	v_pk_mul_f32 v[176:177], v[176:177], v[178:179]
	s_nop 0
	v_pk_mul_f32 v[176:177], v[204:205], v[176:177]
	v_pk_fma_f32 v[202:203], v[46:47], v[130:131], v[202:203]
	v_cvt_pk_bf16_f32 v176, v176, v177
	v_mul_f32_e32 v177, 0xbfb8aa3b, v174
	v_exp_f32_e32 v177, v177
	v_pk_fma_f32 v[202:203], v[22:23], v[134:135], v[202:203]
	v_add_f32_e32 v177, 1.0, v177
	v_rcp_f32_e32 v178, v177
	v_mul_f32_e32 v177, 0xbfb8aa3b, v175
	v_exp_f32_e32 v177, v177
	v_pk_add_f32 v[202:203], v[146:147], v[202:203]
	v_add_f32_e32 v177, 1.0, v177
	v_rcp_f32_e32 v179, v177
	s_nop 0
	v_pk_mul_f32 v[174:175], v[174:175], v[178:179]
	s_nop 0
	v_pk_mul_f32 v[174:175], v[202:203], v[174:175]
	v_pk_mul_f32 v[202:203], v[20:21], v[140:141]
	v_cvt_pk_bf16_f32 v177, v174, v175
	v_lshl_add_u64 v[174:175], v[180:181], 0, v[200:201]
	global_store_dwordx2 v[174:175], v[176:177], off
	v_pk_mul_f32 v[176:177], v[8:9], v[152:153]
	v_pk_mul_f32 v[174:175], v[10:11], v[154:155]
	v_pk_fma_f32 v[176:177], v[24:25], v[136:137], v[176:177]
	v_pk_fma_f32 v[202:203], v[28:29], v[128:129], v[202:203]
	v_pk_fma_f32 v[176:177], v[4:5], v[148:149], v[176:177]
	v_pk_fma_f32 v[174:175], v[26:27], v[138:139], v[174:175]
	v_pk_add_f32 v[176:177], v[156:157], v[176:177]
	v_pk_fma_f32 v[202:203], v[16:17], v[132:133], v[202:203]
	v_mul_f32_e32 v178, 0xbfb8aa3b, v176
	v_mul_f32_e32 v179, 0xbfb8aa3b, v177
	v_exp_f32_e32 v178, v178
	v_exp_f32_e32 v179, v179
	v_pk_fma_f32 v[174:175], v[6:7], v[150:151], v[174:175]
	v_pk_add_f32 v[202:203], v[144:145], v[202:203]
	v_add_f32_e32 v178, 1.0, v178
	v_add_f32_e32 v179, 1.0, v179
	v_rcp_f32_e32 v178, v178
	v_rcp_f32_e32 v179, v179
	v_pk_add_f32 v[174:175], v[158:159], v[174:175]
	v_pk_mul_f32 v[180:181], v[22:23], v[142:143]
	v_pk_mul_f32 v[176:177], v[176:177], v[178:179]
	s_nop 0
	v_pk_mul_f32 v[176:177], v[202:203], v[176:177]
	v_pk_fma_f32 v[180:181], v[30:31], v[130:131], v[180:181]
	v_cvt_pk_bf16_f32 v176, v176, v177
	v_mul_f32_e32 v177, 0xbfb8aa3b, v174
	v_exp_f32_e32 v177, v177
	v_pk_fma_f32 v[180:181], v[18:19], v[134:135], v[180:181]
	v_add_f32_e32 v177, 1.0, v177
	v_rcp_f32_e32 v178, v177
	v_mul_f32_e32 v177, 0xbfb8aa3b, v175
	v_exp_f32_e32 v177, v177
	v_pk_add_f32 v[180:181], v[146:147], v[180:181]
	v_add_f32_e32 v177, 1.0, v177
	v_rcp_f32_e32 v179, v177
	s_nop 0
	v_pk_mul_f32 v[174:175], v[174:175], v[178:179]
	s_nop 0
	v_pk_mul_f32 v[174:175], v[180:181], v[174:175]
	v_pk_mul_f32 v[180:181], v[18:19], v[142:143]
	v_cvt_pk_bf16_f32 v177, v174, v175
	v_lshl_add_u64 v[174:175], v[182:183], 0, v[200:201]
	global_store_dwordx2 v[174:175], v[176:177], off
	v_pk_mul_f32 v[176:177], v[4:5], v[152:153]
	v_pk_mul_f32 v[182:183], v[16:17], v[140:141]
	v_pk_fma_f32 v[176:177], v[8:9], v[136:137], v[176:177]
	v_pk_mul_f32 v[174:175], v[6:7], v[154:155]
	v_pk_fma_f32 v[176:177], v[0:1], v[148:149], v[176:177]
	v_pk_fma_f32 v[182:183], v[20:21], v[128:129], v[182:183]
	v_pk_add_f32 v[176:177], v[156:157], v[176:177]
	v_pk_fma_f32 v[174:175], v[10:11], v[138:139], v[174:175]
	v_mul_f32_e32 v178, 0xbfb8aa3b, v176
	v_mul_f32_e32 v179, 0xbfb8aa3b, v177
	v_exp_f32_e32 v178, v178
	v_exp_f32_e32 v179, v179
	v_pk_fma_f32 v[182:183], v[12:13], v[132:133], v[182:183]
	v_pk_fma_f32 v[174:175], v[2:3], v[150:151], v[174:175]
	v_add_f32_e32 v178, 1.0, v178
	v_add_f32_e32 v179, 1.0, v179
	v_rcp_f32_e32 v178, v178
	v_rcp_f32_e32 v179, v179
	v_pk_add_f32 v[182:183], v[144:145], v[182:183]
	v_pk_add_f32 v[174:175], v[158:159], v[174:175]
	v_pk_fma_f32 v[180:181], v[22:23], v[130:131], v[180:181]
	v_pk_mul_f32 v[176:177], v[176:177], v[178:179]
	v_pk_fma_f32 v[180:181], v[14:15], v[134:135], v[180:181]
	v_pk_mul_f32 v[176:177], v[182:183], v[176:177]
	v_pk_add_f32 v[180:181], v[146:147], v[180:181]
	v_cvt_pk_bf16_f32 v176, v176, v177
	v_mul_f32_e32 v177, 0xbfb8aa3b, v174
	v_exp_f32_e32 v177, v177
	s_nop 0
	v_add_f32_e32 v177, 1.0, v177
	v_rcp_f32_e32 v178, v177
	v_mul_f32_e32 v177, 0xbfb8aa3b, v175
	v_exp_f32_e32 v177, v177
	s_nop 0
	v_add_f32_e32 v177, 1.0, v177
	v_rcp_f32_e32 v179, v177
	s_nop 0
	v_pk_mul_f32 v[174:175], v[174:175], v[178:179]
	s_nop 0
	v_pk_mul_f32 v[174:175], v[180:181], v[174:175]
	s_nop 0
	v_cvt_pk_bf16_f32 v177, v174, v175
	v_lshl_add_u64 v[174:175], v[184:185], 0, v[200:201]
	global_store_dwordx2 v[174:175], v[176:177], off
	s_and_saveexec_b64 s[8:9], s[6:7]
	s_cbranch_execz .LBB0_129
	v_pk_mul_f32 v[152:153], v[0:1], v[152:153]
	v_pk_mul_f32 v[154:155], v[2:3], v[154:155]
	v_pk_fma_f32 v[136:137], v[4:5], v[136:137], v[152:153]
	v_pk_fma_f32 v[138:139], v[6:7], v[138:139], v[154:155]
	v_pk_fma_f32 v[136:137], v[148:149], v[198:199], v[136:137]
	v_pk_mul_f32 v[140:141], v[12:13], v[140:141]
	v_pk_add_f32 v[136:137], v[156:157], v[136:137]
	v_pk_fma_f32 v[138:139], v[150:151], v[190:191], v[138:139]
	v_pk_mul_f32 v[142:143], v[14:15], v[142:143]
	v_pk_fma_f32 v[128:129], v[16:17], v[128:129], v[140:141]
	v_pk_add_f32 v[138:139], v[158:159], v[138:139]
	v_pk_fma_f32 v[130:131], v[18:19], v[130:131], v[142:143]
	v_pk_fma_f32 v[128:129], v[132:133], v[188:189], v[128:129]
	v_mul_f32_e32 v132, 0xbfb8aa3b, v137
	v_mul_f32_e32 v148, 0xbfb8aa3b, v136
	v_exp_f32_e32 v132, v132
	v_pk_fma_f32 v[130:131], v[134:135], v[186:187], v[130:131]
	v_mul_f32_e32 v133, 0xbfb8aa3b, v138
	v_mul_f32_e32 v134, 0xbfb8aa3b, v139
	v_exp_f32_e32 v148, v148
	v_exp_f32_e32 v133, v133
	v_exp_f32_e32 v134, v134
	v_add_f32_e32 v132, 1.0, v132
	v_add_f32_e32 v148, 1.0, v148
	v_rcp_f32_e32 v149, v132
	v_add_f32_e32 v132, 1.0, v133
	v_add_f32_e32 v133, 1.0, v134
	v_rcp_f32_e32 v148, v148
	v_rcp_f32_e32 v132, v132
	v_rcp_f32_e32 v133, v133
	v_pk_add_f32 v[130:131], v[146:147], v[130:131]
	v_pk_add_f32 v[128:129], v[144:145], v[128:129]
	v_pk_mul_f32 v[134:135], v[136:137], v[148:149]
	v_pk_mul_f32 v[132:133], v[138:139], v[132:133]
	v_pk_mul_f32 v[128:129], v[128:129], v[134:135]
	v_pk_mul_f32 v[130:131], v[130:131], v[132:133]
	v_cvt_pk_bf16_f32 v128, v128, v129
	v_cvt_pk_bf16_f32 v129, v130, v131
	v_add_co_u32_e32 v130, vcc, 0x9000, v172
	s_nop 1
	v_addc_co_u32_e32 v131, vcc, 0, v173, vcc
	global_store_dwordx2 v[130:131], v[128:129], off offset:2560

;     __device__ __forceinline__ void operator()(const f32x4 (&acc)[2][2][4][2], const Unit& u, int wr, int wc, int fr, int fq) const {
;         if (u.mode == 1) {
; #pragma unroll
;             for (int n = 0; n < 2; ++n) {
;                 const int f0 = 128 * u.pn + 32 * wc + 8 * fq + 4 * n;
;                 f32x4 wa[3], wg[3];
; #pragma unroll
;                 for (int j = 0; j < 3; ++j) { wa[j] = *(const f32x4*)(cw + j * 5632 + f0); wg[j] = *(const f32x4*)(cw + j * 5632 + 2816 + f0); }
;                 const f32x4 ba = *(const f32x4*)(cb + f0), bg = *(const f32x4*)(cb + 2816 + f0);
; #pragma unroll
;                 for (int ai = 0; ai < 2; ++ai) {
;                     const int j = 64 * u.pm + 32 * wr + 2 * fr + ai;
;                     const bool seqb = (j < 256) ? ((j & 63) == 0) : ((j & 1) == 0);
;                     const f32x4 z4 = (f32x4){0.f, 0.f, 0.f, 0.f};
;                     const int rowL = 128 * j - 1, rowR = 128 * j;
;                     if (j >= 1 && j < NBGRP && rowL < nrows) {
;                         const f32x4 ca = wa[0] * acc[ai][0][0][n] + wa[1] * acc[ai][0][1][n] + wa[2] * (seqb ? z4 : acc[ai][0][2][n]) + ba;
;                         const f32x4 cg = wg[0] * acc[ai][1][0][n] + wg[1] * acc[ai][1][1][n] + wg[2] * (seqb ? z4 : acc[ai][1][2][n]) + bg;
;                         u32x2 w; w.x = cvt_pk_bf16(cg[0] * sigmoidf_(cg[0]) * ca[0], cg[1] * sigmoidf_(cg[1]) * ca[1]); w.y = cvt_pk_bf16(cg[2] * sigmoidf_(cg[2]) * ca[2], cg[3] * sigmoidf_(cg[3]) * ca[3]);
;                         *(u32x2*)(ACT + (size_t)rowL * 2816 + f0) = w;
;                     }
;                     if (j < NBGRP && rowR < nrows) {
;                         const f32x4 ca = wa[0] * (seqb ? z4 : acc[ai][0][1][n]) + wa[1] * acc[ai][0][2][n] + wa[2] * acc[ai][0][3][n] + ba;
;                         const f32x4 cg = wg[0] * (seqb ? z4 : acc[ai][1][1][n]) + wg[1] * acc[ai][1][2][n] + wg[2] * acc[ai][1][3][n] + bg;
;                         u32x2 w; w.x = cvt_pk_bf16(cg[0] * sigmoidf_(cg[0]) * ca[0], cg[1] * sigmoidf_(cg[1]) * ca[1]); w.y = cvt_pk_bf16(cg[2] * sigmoidf_(cg[2]) * ca[2], cg[3] * sigmoidf_(cg[3]) * ca[3]);
;                         *(u32x2*)(ACT + (size_t)rowR * 2816 + f0) = w;
;                     }
.LBB0_131:
	s_and_b64 vcc, exec, s[6:7]
	s_cbranch_vccz .LBB0_130
	s_lshl_b32 s2, s18, 7
	v_add_u32_e32 v172, s2, v215
	v_ashrrev_i32_e32 v173, 31, v172
	v_readlane_b32 s6, v253, 48
	v_lshlrev_b64 v[132:133], 2, v[172:173]
	v_readlane_b32 s7, v253, 49
	v_readlane_b32 s1, v255, 1
	s_lshl_b32 s3, s0, 6
	v_lshl_add_u64 v[128:129], s[6:7], 0, v[132:133]
	v_readlane_b32 s6, v253, 40
	v_readlane_b32 s7, v253, 41
	v_lshl_add_u32 v175, v192, 1, s1
	v_add_u32_e32 v176, s3, v175
	v_lshl_add_u64 v[130:131], s[6:7], 0, v[132:133]
	v_readlane_b32 s6, v253, 42
	v_readlane_b32 s7, v253, 43
	global_load_dwordx4 v[144:147], v[128:129], off
	s_nop 0
	global_load_dwordx4 v[128:131], v[130:131], off
	v_lshl_add_u64 v[134:135], s[6:7], 0, v[132:133]
	v_readlane_b32 s6, v253, 44
	v_readlane_b32 s7, v253, 45
	s_movk_i32 s0, 0xff
	v_and_b32_e32 v174, 62, v175
	v_lshl_add_u64 v[136:137], s[6:7], 0, v[132:133]
	v_readlane_b32 s6, v253, 46
	v_readlane_b32 s7, v253, 47
	global_load_dwordx4 v[152:155], v[134:135], off
	global_load_dwordx4 v[140:143], v[136:137], off
	v_lshl_add_u64 v[134:135], s[6:7], 0, v[132:133]
	v_readlane_b32 s6, v253, 50
	v_readlane_b32 s7, v253, 51
	v_cmp_lt_i32_e32 vcc, s0, v176
	v_cmp_eq_u32_e64 s[0:1], 0, v174
	v_lshl_add_u64 v[136:137], s[6:7], 0, v[132:133]
	v_readlane_b32 s6, v253, 52
	v_readlane_b32 s7, v253, 53
	global_load_dwordx4 v[148:151], v[134:135], off
	s_nop 0
	global_load_dwordx4 v[136:139], v[136:137], off
	v_lshl_add_u64 v[134:135], s[6:7], 0, v[132:133]
	v_readlane_b32 s6, v253, 54
	v_readlane_b32 s7, v253, 55
	v_add_u32_e32 v177, 0xfffffef7, v176
	v_lshlrev_b32_e32 v174, 7, v176
	v_lshl_add_u64 v[132:133], s[6:7], 0, v[132:133]
	global_load_dwordx4 v[156:159], v[134:135], off
	s_nop 0
	global_load_dwordx4 v[132:135], v[132:133], off
	s_or_b64 s[6:7], vcc, s[0:1]
	s_movk_i32 s0, 0xfef7
	v_cmp_lt_u32_e32 vcc, s0, v177
	v_readlane_b32 s0, v253, 35
	s_nop 1
	v_cmp_ge_i32_e64 s[0:1], s0, v174
	s_and_b64 s[8:9], vcc, s[0:1]
	s_mov_b32 s0, 0x58000
	v_mul_lo_u32 v192, v176, s0
	s_and_saveexec_b64 s[0:1], s[8:9]
	s_cbranch_execz .LBB0_134
	s_waitcnt vmcnt(0)
	v_pk_mul_f32 v[180:181], v[116:117], v[152:153]
	v_pk_mul_f32 v[178:179], v[118:119], v[154:155]
	v_pk_fma_f32 v[124:125], v[124:125], v[144:145], v[180:181]
	v_cndmask_b32_e64 v181, v113, 0, s[6:7]
	v_cndmask_b32_e64 v180, v112, 0, s[6:7]
	v_pk_fma_f32 v[124:125], v[180:181], v[148:149], v[124:125]
	v_pk_mul_f32 v[180:181], v[104:105], v[140:141]
	v_pk_fma_f32 v[126:127], v[126:127], v[146:147], v[178:179]
	v_pk_fma_f32 v[120:121], v[120:121], v[128:129], v[180:181]
	v_cndmask_b32_e64 v181, v101, 0, s[6:7]
	v_cndmask_b32_e64 v180, v100, 0, s[6:7]
	v_cndmask_b32_e64 v179, v115, 0, s[6:7]
	v_cndmask_b32_e64 v178, v114, 0, s[6:7]
	v_pk_fma_f32 v[120:121], v[180:181], v[136:137], v[120:121]
	v_pk_fma_f32 v[126:127], v[178:179], v[150:151], v[126:127]
	v_pk_mul_f32 v[178:179], v[106:107], v[142:143]
	v_pk_add_f32 v[120:121], v[132:133], v[120:121]
	v_pk_fma_f32 v[122:123], v[122:123], v[130:131], v[178:179]
	v_cndmask_b32_e64 v179, v103, 0, s[6:7]
	v_cndmask_b32_e64 v178, v102, 0, s[6:7]
	v_mul_f32_e32 v177, 0xbfb8aa3b, v120
	v_pk_fma_f32 v[122:123], v[178:179], v[138:139], v[122:123]
	v_exp_f32_e32 v177, v177
	v_mul_f32_e32 v178, 0xbfb8aa3b, v121
	v_exp_f32_e32 v179, v178
	v_pk_add_f32 v[122:123], v[134:135], v[122:123]
	v_add_f32_e32 v177, 1.0, v177
	v_rcp_f32_e32 v178, v177
	v_add_f32_e32 v177, 1.0, v179
	v_mul_f32_e32 v179, 0xbfb8aa3b, v122
	v_exp_f32_e32 v180, v179
	v_mul_f32_e32 v179, 0xbfb8aa3b, v123
	v_exp_f32_e32 v181, v179
	v_rcp_f32_e32 v179, v177
	v_add_f32_e32 v177, 1.0, v180
	v_rcp_f32_e32 v180, v177
	v_add_f32_e32 v177, 1.0, v181
	v_rcp_f32_e32 v181, v177
	v_pk_add_f32 v[126:127], v[158:159], v[126:127]
	v_pk_add_f32 v[124:125], v[156:157], v[124:125]
	v_pk_mul_f32 v[120:121], v[120:121], v[178:179]
	v_pk_mul_f32 v[122:123], v[122:123], v[180:181]
	v_readlane_b32 s18, v254, 38
	v_pk_mul_f32 v[120:121], v[124:125], v[120:121]
	v_pk_mul_f32 v[122:123], v[126:127], v[122:123]
	v_readlane_b32 s19, v254, 39
	v_cvt_pk_bf16_f32 v120, v120, v121
	v_cvt_pk_bf16_f32 v121, v122, v123
	v_lshl_add_u64 v[122:123], v[192:193], 1, s[18:19]
	v_lshl_add_u64 v[122:123], v[172:173], 1, v[122:123]
	v_add_co_u32_e32 v122, vcc, 0xffffea00, v122
	s_nop 1
	v_addc_co_u32_e32 v123, vcc, -1, v123, vcc
	global_store_dwordx2 v[122:123], v[120:121], off
.LBB0_134:
	s_or_b64 exec, exec, s[0:1]
	s_movk_i32 s0, 0x109
	v_cmp_gt_i32_e32 vcc, s0, v176
	v_readlane_b32 s0, v253, 35
	s_nop 1
	v_cmp_gt_i32_e64 s[0:1], s0, v174
	s_and_b64 s[18:19], vcc, s[0:1]
	s_and_saveexec_b64 s[0:1], s[18:19]
	s_cbranch_execz .LBB0_136
	v_cndmask_b32_e64 v105, v105, 0, s[6:7]
	v_cndmask_b32_e64 v104, v104, 0, s[6:7]
	v_cndmask_b32_e64 v107, v107, 0, s[6:7]
	v_cndmask_b32_e64 v106, v106, 0, s[6:7]
	s_waitcnt vmcnt(0)
	v_pk_mul_f32 v[102:103], v[102:103], v[142:143]
	v_pk_mul_f32 v[100:101], v[100:101], v[140:141]
	v_pk_fma_f32 v[102:103], v[106:107], v[130:131], v[102:103]
	v_pk_fma_f32 v[100:101], v[104:105], v[128:129], v[100:101]
	v_pk_fma_f32 v[98:99], v[98:99], v[138:139], v[102:103]
	v_pk_fma_f32 v[96:97], v[96:97], v[136:137], v[100:101]
	v_pk_add_f32 v[98:99], v[134:135], v[98:99]
	v_pk_add_f32 v[96:97], v[132:133], v[96:97]
	v_mul_f32_e32 v102, 0xbfb8aa3b, v98
	v_mul_f32_e32 v100, 0xbfb8aa3b, v96
	v_mul_f32_e32 v101, 0xbfb8aa3b, v97
	v_mul_f32_e32 v103, 0xbfb8aa3b, v99
	v_exp_f32_e32 v100, v100
	v_exp_f32_e32 v101, v101
	v_exp_f32_e32 v102, v102
	v_exp_f32_e32 v103, v103
	v_add_f32_e32 v100, 1.0, v100
	v_add_f32_e32 v101, 1.0, v101
	v_add_f32_e32 v102, 1.0, v102
	v_add_f32_e32 v103, 1.0, v103
	v_rcp_f32_e32 v100, v100
	v_rcp_f32_e32 v101, v101
	v_rcp_f32_e32 v102, v102
	v_rcp_f32_e32 v103, v103
	v_cndmask_b32_e64 v117, v117, 0, s[6:7]
	v_cndmask_b32_e64 v116, v116, 0, s[6:7]
	v_cndmask_b32_e64 v119, v119, 0, s[6:7]
	v_cndmask_b32_e64 v118, v118, 0, s[6:7]
	v_pk_mul_f32 v[114:115], v[114:115], v[154:155]
	v_pk_mul_f32 v[112:113], v[112:113], v[152:153]
	v_pk_fma_f32 v[114:115], v[118:119], v[146:147], v[114:115]
	v_pk_fma_f32 v[112:113], v[116:117], v[144:145], v[112:113]
	v_pk_fma_f32 v[110:111], v[110:111], v[150:151], v[114:115]
	v_pk_fma_f32 v[108:109], v[108:109], v[148:149], v[112:113]
	v_pk_add_f32 v[110:111], v[158:159], v[110:111]
	v_pk_add_f32 v[108:109], v[156:157], v[108:109]
	v_pk_mul_f32 v[96:97], v[96:97], v[100:101]
	v_pk_mul_f32 v[98:99], v[98:99], v[102:103]
	v_readlane_b32 s28, v254, 38
	v_pk_mul_f32 v[96:97], v[108:109], v[96:97]
	v_pk_mul_f32 v[98:99], v[110:111], v[98:99]
	v_readlane_b32 s29, v254, 39
	v_cvt_pk_bf16_f32 v96, v96, v97
	v_cvt_pk_bf16_f32 v97, v98, v99
	v_mov_b64_e32 v[98:99], s[28:29]
	s_movk_i32 s25, 0x1600
	v_mad_i64_i32 v[98:99], s[28:29], v174, s25, v[98:99]
	v_lshl_add_u64 v[98:99], v[172:173], 1, v[98:99]
	global_store_dwordx2 v[98:99], v[96:97], off
; __device__ __forceinline__ unsigned cvt_pk_bf16(float lo, float hi) { f32x2 v = {lo, hi}; bf16x2_t b = __builtin_convertvector(v, bf16x2_t); return __builtin_bit_cast(unsigned, b); }
; __device__ __forceinline__ float sigmoidf_(float v) { return __builtin_amdgcn_rcpf(1.0f + __builtin_amdgcn_exp2f(-1.4426950408889634f * v)); }
;     __device__ __forceinline__ void operator()(const f32x4 (&acc)[2][2][4][2], const Unit& u, int wr, int wc, int fr, int fq) const {
;     ...
;                 for (int ai = 0; ai < 2; ++ai) {
;                     const int j = 64 * u.pm + 32 * wr + 2 * fr + ai;
;                     const bool seqb = (j < 256) ? ((j & 63) == 0) : ((j & 1) == 0);
;                     const f32x4 z4 = (f32x4){0.f, 0.f, 0.f, 0.f};
;                     const int rowL = 128 * j - 1, rowR = 128 * j;
;                     if (j >= 1 && j < NBGRP && rowL < nrows) {
;                         const f32x4 ca = wa[0] * acc[ai][0][0][n] + wa[1] * acc[ai][0][1][n] + wa[2] * (seqb ? z4 : acc[ai][0][2][n]) + ba;
;                         const f32x4 cg = wg[0] * acc[ai][1][0][n] + wg[1] * acc[ai][1][1][n] + wg[2] * (seqb ? z4 : acc[ai][1][2][n]) + bg;
;                         u32x2 w; w.x = cvt_pk_bf16(cg[0] * sigmoidf_(cg[0]) * ca[0], cg[1] * sigmoidf_(cg[1]) * ca[1]); w.y = cvt_pk_bf16(cg[2] * sigmoidf_(cg[2]) * ca[2], cg[3] * sigmoidf_(cg[3]) * ca[3]);
;                         *(u32x2*)(ACT + (size_t)rowL * 2816 + f0) = w;
;                     }
;                     if (j < NBGRP && rowR < nrows) {
;                         const f32x4 ca = wa[0] * (seqb ? z4 : acc[ai][0][1][n]) + wa[1] * acc[ai][0][2][n] + wa[2] * acc[ai][0][3][n] + ba;
;                         const f32x4 cg = wg[0] * (seqb ? z4 : acc[ai][1][1][n]) + wg[1] * acc[ai][1][2][n] + wg[2] * acc[ai][1][3][n] + bg;
;                         u32x2 w; w.x = cvt_pk_bf16(cg[0] * sigmoidf_(cg[0]) * ca[0], cg[1] * sigmoidf_(cg[1]) * ca[1]); w.y = cvt_pk_bf16(cg[2] * sigmoidf_(cg[2]) * ca[2], cg[3] * sigmoidf_(cg[3]) * ca[3]);
;                         *(u32x2*)(ACT + (size_t)rowR * 2816 + f0) = w;
;                     }
.LBB0_136:
	s_or_b64 exec, exec, s[0:1]
	v_or_b32_e32 v96, 1, v175
	v_add_u32_e32 v98, s3, v96
	v_add_u32_e32 v96, 0xfffffef7, v98
	s_movk_i32 s0, 0xfef7
	v_lshlrev_b32_e32 v100, 7, v98
	v_cmp_lt_u32_e32 vcc, s0, v96
	v_readlane_b32 s0, v253, 35
	s_nop 1
	v_cmp_ge_i32_e64 s[0:1], s0, v100
	s_and_b64 s[28:29], vcc, s[0:1]
	s_mov_b32 s0, 0x58000
	v_mul_lo_u32 v96, v98, s0
	s_and_saveexec_b64 s[0:1], s[28:29]
	s_cbranch_execz .LBB0_138
	s_waitcnt vmcnt(0)
	v_pk_mul_f32 v[104:105], v[84:85], v[152:153]
	v_pk_mul_f32 v[102:103], v[86:87], v[154:155]
	v_pk_fma_f32 v[92:93], v[92:93], v[144:145], v[104:105]
	v_pk_mul_f32 v[104:105], v[72:73], v[140:141]
	v_pk_fma_f32 v[94:95], v[94:95], v[146:147], v[102:103]
	v_pk_fma_f32 v[88:89], v[88:89], v[128:129], v[104:105]
	v_pk_mul_f32 v[102:103], v[74:75], v[142:143]
	v_pk_fma_f32 v[88:89], v[68:69], v[136:137], v[88:89]
	v_pk_fma_f32 v[90:91], v[90:91], v[130:131], v[102:103]
	v_pk_add_f32 v[88:89], v[132:133], v[88:89]
	v_pk_fma_f32 v[90:91], v[70:71], v[138:139], v[90:91]
	v_mul_f32_e32 v97, 0xbfb8aa3b, v88
	v_exp_f32_e32 v97, v97
	v_mul_f32_e32 v99, 0xbfb8aa3b, v89
	v_exp_f32_e32 v99, v99
	v_pk_add_f32 v[90:91], v[134:135], v[90:91]
	v_add_f32_e32 v97, 1.0, v97
	v_rcp_f32_e32 v102, v97
	v_add_f32_e32 v97, 1.0, v99
	v_mul_f32_e32 v99, 0xbfb8aa3b, v90
	v_exp_f32_e32 v99, v99
	v_mul_f32_e32 v101, 0xbfb8aa3b, v91
	v_exp_f32_e32 v101, v101
	v_rcp_f32_e32 v103, v97
	v_add_f32_e32 v97, 1.0, v99
	v_rcp_f32_e32 v104, v97
	v_add_f32_e32 v97, 1.0, v101
	v_rcp_f32_e32 v105, v97
	v_pk_fma_f32 v[94:95], v[82:83], v[150:151], v[94:95]
	v_pk_fma_f32 v[92:93], v[80:81], v[148:149], v[92:93]
	v_pk_add_f32 v[94:95], v[158:159], v[94:95]
	v_pk_add_f32 v[92:93], v[156:157], v[92:93]
	v_pk_mul_f32 v[88:89], v[88:89], v[102:103]
	v_pk_mul_f32 v[90:91], v[90:91], v[104:105]
	v_readlane_b32 s30, v254, 38
	v_pk_mul_f32 v[88:89], v[92:93], v[88:89]
	v_pk_mul_f32 v[90:91], v[94:95], v[90:91]
	v_mov_b32_e32 v97, v193
	v_readlane_b32 s31, v254, 39
	v_cvt_pk_bf16_f32 v88, v88, v89
	v_cvt_pk_bf16_f32 v89, v90, v91
	v_lshl_add_u64 v[90:91], v[96:97], 1, s[30:31]
	v_lshl_add_u64 v[90:91], v[172:173], 1, v[90:91]
	v_add_co_u32_e32 v90, vcc, 0xffffea00, v90
	s_nop 1
	v_addc_co_u32_e32 v91, vcc, -1, v91, vcc
	global_store_dwordx2 v[90:91], v[88:89], off
.LBB0_138:
	s_or_b64 exec, exec, s[0:1]
	s_movk_i32 s0, 0x109
	v_cmp_gt_i32_e32 vcc, s0, v98
	v_readlane_b32 s0, v253, 35
	s_nop 1
	v_cmp_gt_i32_e64 s[0:1], s0, v100
	s_and_b64 s[0:1], vcc, s[0:1]
	s_and_saveexec_b64 s[30:31], s[0:1]
	s_cbranch_execz .LBB0_140
	s_waitcnt vmcnt(0)
	v_pk_mul_f32 v[70:71], v[70:71], v[142:143]
	v_pk_mul_f32 v[68:69], v[68:69], v[140:141]
	v_pk_fma_f32 v[70:71], v[74:75], v[130:131], v[70:71]
	v_pk_fma_f32 v[68:69], v[72:73], v[128:129], v[68:69]
	v_pk_fma_f32 v[62:63], v[62:63], v[138:139], v[70:71]
	v_pk_fma_f32 v[60:61], v[60:61], v[136:137], v[68:69]
	v_pk_add_f32 v[62:63], v[134:135], v[62:63]
	v_pk_add_f32 v[60:61], v[132:133], v[60:61]
	v_mul_f32_e32 v70, 0xbfb8aa3b, v62
	v_mul_f32_e32 v68, 0xbfb8aa3b, v60
	v_mul_f32_e32 v69, 0xbfb8aa3b, v61
	v_mul_f32_e32 v71, 0xbfb8aa3b, v63
	v_exp_f32_e32 v68, v68
	v_exp_f32_e32 v69, v69
	v_exp_f32_e32 v70, v70
	v_exp_f32_e32 v71, v71
	v_add_f32_e32 v68, 1.0, v68
	v_add_f32_e32 v69, 1.0, v69
	v_add_f32_e32 v70, 1.0, v70
	v_add_f32_e32 v71, 1.0, v71
	v_rcp_f32_e32 v68, v68
	v_rcp_f32_e32 v69, v69
	v_rcp_f32_e32 v70, v70
	v_rcp_f32_e32 v71, v71
	v_pk_mul_f32 v[82:83], v[82:83], v[154:155]
	v_pk_mul_f32 v[80:81], v[80:81], v[152:153]
	v_pk_fma_f32 v[82:83], v[86:87], v[146:147], v[82:83]
	v_pk_fma_f32 v[80:81], v[84:85], v[144:145], v[80:81]
	v_pk_fma_f32 v[78:79], v[78:79], v[150:151], v[82:83]
	v_pk_fma_f32 v[76:77], v[76:77], v[148:149], v[80:81]
	v_pk_add_f32 v[78:79], v[158:159], v[78:79]
	v_pk_add_f32 v[76:77], v[156:157], v[76:77]
	v_pk_mul_f32 v[60:61], v[60:61], v[68:69]
	v_pk_mul_f32 v[62:63], v[62:63], v[70:71]
	v_readlane_b32 s60, v254, 38
	v_pk_mul_f32 v[60:61], v[76:77], v[60:61]
	v_pk_mul_f32 v[62:63], v[78:79], v[62:63]
	v_readlane_b32 s61, v254, 39
	v_cvt_pk_bf16_f32 v60, v60, v61
	v_cvt_pk_bf16_f32 v61, v62, v63
	v_mov_b64_e32 v[62:63], s[60:61]
	s_movk_i32 s3, 0x1600
	v_mad_i64_i32 v[62:63], s[60:61], v100, s3, v[62:63]
	v_lshl_add_u64 v[62:63], v[172:173], 1, v[62:63]
	global_store_dwordx2 v[62:63], v[60:61], off
; __device__ __forceinline__ unsigned cvt_pk_bf16(float lo, float hi) { f32x2 v = {lo, hi}; bf16x2_t b = __builtin_convertvector(v, bf16x2_t); return __builtin_bit_cast(unsigned, b); }
; __device__ __forceinline__ float sigmoidf_(float v) { return __builtin_amdgcn_rcpf(1.0f + __builtin_amdgcn_exp2f(-1.4426950408889634f * v)); }
;     __device__ __forceinline__ void operator()(const f32x4 (&acc)[2][2][4][2], const Unit& u, int wr, int wc, int fr, int fq) const {
;     ...
;             for (int n = 0; n < 2; ++n) {
;                 const int f0 = 128 * u.pn + 32 * wc + 8 * fq + 4 * n;
;                 f32x4 wa[3], wg[3];
; #pragma unroll
;                 for (int j = 0; j < 3; ++j) { wa[j] = *(const f32x4*)(cw + j * 5632 + f0); wg[j] = *(const f32x4*)(cw + j * 5632 + 2816 + f0); }
;                 const f32x4 ba = *(const f32x4*)(cb + f0), bg = *(const f32x4*)(cb + 2816 + f0);
; #pragma unroll
;                 for (int ai = 0; ai < 2; ++ai) {
;                     const int j = 64 * u.pm + 32 * wr + 2 * fr + ai;
;                     const bool seqb = (j < 256) ? ((j & 63) == 0) : ((j & 1) == 0);
;                     const f32x4 z4 = (f32x4){0.f, 0.f, 0.f, 0.f};
;                     const int rowL = 128 * j - 1, rowR = 128 * j;
;                     if (j >= 1 && j < NBGRP && rowL < nrows) {
;                         const f32x4 ca = wa[0] * acc[ai][0][0][n] + wa[1] * acc[ai][0][1][n] + wa[2] * (seqb ? z4 : acc[ai][0][2][n]) + ba;
;                         const f32x4 cg = wg[0] * acc[ai][1][0][n] + wg[1] * acc[ai][1][1][n] + wg[2] * (seqb ? z4 : acc[ai][1][2][n]) + bg;
;                         u32x2 w; w.x = cvt_pk_bf16(cg[0] * sigmoidf_(cg[0]) * ca[0], cg[1] * sigmoidf_(cg[1]) * ca[1]); w.y = cvt_pk_bf16(cg[2] * sigmoidf_(cg[2]) * ca[2], cg[3] * sigmoidf_(cg[3]) * ca[3]);
;                         *(u32x2*)(ACT + (size_t)rowL * 2816 + f0) = w;
;                     }
.LBB0_140:
	s_or_b64 exec, exec, s[30:31]
	v_add3_u32 v98, v215, s2, 4
	v_ashrrev_i32_e32 v99, 31, v98
	v_readlane_b32 s2, v253, 48
	v_lshlrev_b64 v[68:69], 2, v[98:99]
	v_readlane_b32 s3, v253, 49
	s_nop 1
	v_lshl_add_u64 v[60:61], s[2:3], 0, v[68:69]
	v_readlane_b32 s2, v253, 40
	v_readlane_b32 s3, v253, 41
	s_nop 1
	v_lshl_add_u64 v[62:63], s[2:3], 0, v[68:69]
	v_readlane_b32 s2, v253, 42
	v_readlane_b32 s3, v253, 43
	global_load_dwordx4 v[80:83], v[60:61], off
	s_nop 0
	global_load_dwordx4 v[60:63], v[62:63], off
	v_lshl_add_u64 v[70:71], s[2:3], 0, v[68:69]
	v_readlane_b32 s2, v253, 44
	v_readlane_b32 s3, v253, 45
	s_nop 1
	v_lshl_add_u64 v[72:73], s[2:3], 0, v[68:69]
	v_readlane_b32 s2, v253, 46
	v_readlane_b32 s3, v253, 47
	global_load_dwordx4 v[88:91], v[70:71], off
	global_load_dwordx4 v[76:79], v[72:73], off
	v_lshl_add_u64 v[70:71], s[2:3], 0, v[68:69]
	v_readlane_b32 s2, v253, 50
	v_readlane_b32 s3, v253, 51
	s_nop 1
	v_lshl_add_u64 v[72:73], s[2:3], 0, v[68:69]
	v_readlane_b32 s2, v253, 52
	v_readlane_b32 s3, v253, 53
	global_load_dwordx4 v[84:87], v[70:71], off
	s_nop 0
	global_load_dwordx4 v[72:75], v[72:73], off
	v_lshl_add_u64 v[70:71], s[2:3], 0, v[68:69]
	v_readlane_b32 s2, v253, 54
	v_readlane_b32 s3, v253, 55
	s_nop 1
	v_lshl_add_u64 v[68:69], s[2:3], 0, v[68:69]
	global_load_dwordx4 v[92:95], v[70:71], off
	s_nop 0
	global_load_dwordx4 v[68:71], v[68:69], off
	s_and_saveexec_b64 s[30:31], s[8:9]
	s_cbranch_execz .LBB0_144
	s_waitcnt vmcnt(0)
	v_pk_mul_f32 v[104:105], v[52:53], v[88:89]
	v_pk_mul_f32 v[102:103], v[54:55], v[90:91]
	v_pk_fma_f32 v[64:65], v[64:65], v[80:81], v[104:105]
	v_cndmask_b32_e64 v105, v49, 0, s[6:7]
	v_cndmask_b32_e64 v104, v48, 0, s[6:7]
	v_pk_fma_f32 v[64:65], v[104:105], v[84:85], v[64:65]
	v_pk_mul_f32 v[104:105], v[40:41], v[76:77]
	v_pk_fma_f32 v[66:67], v[66:67], v[82:83], v[102:103]
	v_pk_fma_f32 v[56:57], v[56:57], v[60:61], v[104:105]
	v_cndmask_b32_e64 v105, v37, 0, s[6:7]
	v_cndmask_b32_e64 v104, v36, 0, s[6:7]
	v_pk_fma_f32 v[56:57], v[104:105], v[72:73], v[56:57]
	v_cndmask_b32_e64 v103, v51, 0, s[6:7]
	v_pk_add_f32 v[56:57], v[68:69], v[56:57]
	v_cndmask_b32_e64 v102, v50, 0, s[6:7]
	v_mul_f32_e32 v97, 0xbfb8aa3b, v56
	v_exp_f32_e32 v97, v97
	v_mul_f32_e32 v101, 0xbfb8aa3b, v57
	v_pk_fma_f32 v[66:67], v[102:103], v[86:87], v[66:67]
	v_pk_mul_f32 v[102:103], v[42:43], v[78:79]
	v_exp_f32_e32 v101, v101
	v_pk_fma_f32 v[58:59], v[58:59], v[62:63], v[102:103]
	v_cndmask_b32_e64 v103, v39, 0, s[6:7]
	v_cndmask_b32_e64 v102, v38, 0, s[6:7]
	v_pk_fma_f32 v[58:59], v[102:103], v[74:75], v[58:59]
	v_add_f32_e32 v97, 1.0, v97
	v_pk_add_f32 v[58:59], v[70:71], v[58:59]
	v_rcp_f32_e32 v102, v97
	v_add_f32_e32 v97, 1.0, v101
	v_mul_f32_e32 v101, 0xbfb8aa3b, v58
	v_exp_f32_e32 v101, v101
	v_mul_f32_e32 v103, 0xbfb8aa3b, v59
	v_exp_f32_e32 v105, v103
	v_rcp_f32_e32 v103, v97
	v_add_f32_e32 v97, 1.0, v101
	v_rcp_f32_e32 v104, v97
	v_add_f32_e32 v97, 1.0, v105
	v_rcp_f32_e32 v105, v97
	v_pk_add_f32 v[66:67], v[94:95], v[66:67]
	v_pk_add_f32 v[64:65], v[92:93], v[64:65]
	v_pk_mul_f32 v[56:57], v[56:57], v[102:103]
	v_pk_mul_f32 v[58:59], v[58:59], v[104:105]
	v_readlane_b32 s2, v254, 38
	v_pk_mul_f32 v[56:57], v[64:65], v[56:57]
	v_pk_mul_f32 v[58:59], v[66:67], v[58:59]
	v_readlane_b32 s3, v254, 39
	v_cvt_pk_bf16_f32 v56, v56, v57
	v_cvt_pk_bf16_f32 v57, v58, v59
	v_lshl_add_u64 v[58:59], v[192:193], 1, s[2:3]
	v_lshl_add_u64 v[58:59], v[98:99], 1, v[58:59]
	v_add_co_u32_e32 v58, vcc, 0xffffea00, v58
	s_nop 1
	v_addc_co_u32_e32 v59, vcc, -1, v59, vcc
	global_store_dwordx2 v[58:59], v[56:57], off
	s_or_b64 exec, exec, s[30:31]
	s_and_saveexec_b64 s[8:9], s[18:19]
	s_cbranch_execnz .LBB0_145

; __device__ __forceinline__ unsigned cvt_pk_bf16(float lo, float hi) { f32x2 v = {lo, hi}; bf16x2_t b = __builtin_convertvector(v, bf16x2_t); return __builtin_bit_cast(unsigned, b); }
; __device__ __forceinline__ float sigmoidf_(float v) { return __builtin_amdgcn_rcpf(1.0f + __builtin_amdgcn_exp2f(-1.4426950408889634f * v)); }
;     __device__ __forceinline__ void operator()(const f32x4 (&acc)[2][2][4][2], const Unit& u, int wr, int wc, int fr, int fq) const {
;     ...
;                     if (j >= 1 && j < NBGRP && rowL < nrows) {
;                         const f32x4 ca = wa[0] * acc[ai][0][0][n] + wa[1] * acc[ai][0][1][n] + wa[2] * (seqb ? z4 : acc[ai][0][2][n]) + ba;
;                         const f32x4 cg = wg[0] * acc[ai][1][0][n] + wg[1] * acc[ai][1][1][n] + wg[2] * (seqb ? z4 : acc[ai][1][2][n]) + bg;
;                         u32x2 w; w.x = cvt_pk_bf16(cg[0] * sigmoidf_(cg[0]) * ca[0], cg[1] * sigmoidf_(cg[1]) * ca[1]); w.y = cvt_pk_bf16(cg[2] * sigmoidf_(cg[2]) * ca[2], cg[3] * sigmoidf_(cg[3]) * ca[3]);
;                         *(u32x2*)(ACT + (size_t)rowL * 2816 + f0) = w;
;                     }
.LBB0_143:
	s_waitcnt vmcnt(0)
	v_pk_mul_f32 v[32:33], v[22:23], v[90:91]
	v_pk_mul_f32 v[34:35], v[20:21], v[88:89]
	v_pk_fma_f32 v[30:31], v[30:31], v[82:83], v[32:33]
	v_pk_fma_f32 v[28:29], v[28:29], v[80:81], v[34:35]
	v_pk_mul_f32 v[32:33], v[10:11], v[78:79]
	v_pk_mul_f32 v[34:35], v[8:9], v[76:77]
	v_pk_fma_f32 v[26:27], v[26:27], v[62:63], v[32:33]
	v_pk_fma_f32 v[24:25], v[24:25], v[60:61], v[34:35]
	v_pk_fma_f32 v[26:27], v[6:7], v[74:75], v[26:27]
	v_pk_fma_f32 v[24:25], v[4:5], v[72:73], v[24:25]
	v_pk_add_f32 v[26:27], v[70:71], v[26:27]
	v_pk_add_f32 v[24:25], v[68:69], v[24:25]
	v_mul_f32_e32 v34, 0xbfb8aa3b, v26
	v_mul_f32_e32 v32, 0xbfb8aa3b, v24
	v_mul_f32_e32 v33, 0xbfb8aa3b, v25
	v_mul_f32_e32 v35, 0xbfb8aa3b, v27
	v_exp_f32_e32 v32, v32
	v_exp_f32_e32 v33, v33
	v_exp_f32_e32 v34, v34
	v_exp_f32_e32 v35, v35
	v_add_f32_e32 v32, 1.0, v32
	v_add_f32_e32 v33, 1.0, v33
	v_add_f32_e32 v34, 1.0, v34
	v_add_f32_e32 v35, 1.0, v35
	v_rcp_f32_e32 v32, v32
	v_rcp_f32_e32 v33, v33
	v_rcp_f32_e32 v34, v34
	v_rcp_f32_e32 v35, v35
	v_pk_fma_f32 v[30:31], v[18:19], v[86:87], v[30:31]
	v_pk_fma_f32 v[28:29], v[16:17], v[84:85], v[28:29]
	v_pk_add_f32 v[30:31], v[94:95], v[30:31]
	v_pk_add_f32 v[28:29], v[92:93], v[28:29]
	v_pk_mul_f32 v[24:25], v[24:25], v[32:33]
	v_pk_mul_f32 v[26:27], v[26:27], v[34:35]
	v_readlane_b32 s2, v254, 38
	v_pk_mul_f32 v[24:25], v[28:29], v[24:25]
	v_pk_mul_f32 v[26:27], v[30:31], v[26:27]
	v_mov_b32_e32 v97, v193
	v_readlane_b32 s3, v254, 39
	v_cvt_pk_bf16_f32 v24, v24, v25
	v_cvt_pk_bf16_f32 v25, v26, v27
	v_lshl_add_u64 v[26:27], v[96:97], 1, s[2:3]
	v_lshl_add_u64 v[26:27], v[98:99], 1, v[26:27]
	v_add_co_u32_e32 v26, vcc, 0xffffea00, v26
	s_nop 1
	v_addc_co_u32_e32 v27, vcc, -1, v27, vcc
	global_store_dwordx2 v[26:27], v[24:25], off
	s_or_b64 exec, exec, s[6:7]
	s_and_saveexec_b64 s[6:7], s[0:1]
	s_cbranch_execnz .LBB0_147
	s_branch .LBB0_148

; __device__ __forceinline__ unsigned cvt_pk_bf16(float lo, float hi) { f32x2 v = {lo, hi}; bf16x2_t b = __builtin_convertvector(v, bf16x2_t); return __builtin_bit_cast(unsigned, b); }
; __device__ __forceinline__ float sigmoidf_(float v) { return __builtin_amdgcn_rcpf(1.0f + __builtin_amdgcn_exp2f(-1.4426950408889634f * v)); }
;     __device__ __forceinline__ void operator()(const f32x4 (&acc)[2][2][4][2], const Unit& u, int wr, int wc, int fr, int fq) const {
;     ...
;                     if (j < NBGRP && rowR < nrows) {
;                         const f32x4 ca = wa[0] * (seqb ? z4 : acc[ai][0][1][n]) + wa[1] * acc[ai][0][2][n] + wa[2] * acc[ai][0][3][n] + ba;
;                         const f32x4 cg = wg[0] * (seqb ? z4 : acc[ai][1][1][n]) + wg[1] * acc[ai][1][2][n] + wg[2] * acc[ai][1][3][n] + bg;
;                         u32x2 w; w.x = cvt_pk_bf16(cg[0] * sigmoidf_(cg[0]) * ca[0], cg[1] * sigmoidf_(cg[1]) * ca[1]); w.y = cvt_pk_bf16(cg[2] * sigmoidf_(cg[2]) * ca[2], cg[3] * sigmoidf_(cg[3]) * ca[3]);
;                         *(u32x2*)(ACT + (size_t)rowR * 2816 + f0) = w;
;                     }
.LBB0_145:
	v_cndmask_b32_e64 v41, v41, 0, s[6:7]
	v_cndmask_b32_e64 v40, v40, 0, s[6:7]
	v_cndmask_b32_e64 v43, v43, 0, s[6:7]
	v_cndmask_b32_e64 v42, v42, 0, s[6:7]
	s_waitcnt vmcnt(0)
	v_pk_mul_f32 v[38:39], v[38:39], v[78:79]
	v_pk_mul_f32 v[36:37], v[36:37], v[76:77]
	v_pk_fma_f32 v[38:39], v[42:43], v[62:63], v[38:39]
	v_pk_fma_f32 v[36:37], v[40:41], v[60:61], v[36:37]
	v_pk_fma_f32 v[34:35], v[34:35], v[74:75], v[38:39]
	v_pk_fma_f32 v[32:33], v[32:33], v[72:73], v[36:37]
	v_pk_add_f32 v[34:35], v[70:71], v[34:35]
	v_pk_add_f32 v[32:33], v[68:69], v[32:33]
	v_mul_f32_e32 v38, 0xbfb8aa3b, v34
	v_mul_f32_e32 v36, 0xbfb8aa3b, v32
	v_mul_f32_e32 v37, 0xbfb8aa3b, v33
	v_mul_f32_e32 v39, 0xbfb8aa3b, v35
	v_exp_f32_e32 v36, v36
	v_exp_f32_e32 v37, v37
	v_exp_f32_e32 v38, v38
	v_exp_f32_e32 v39, v39
	v_add_f32_e32 v36, 1.0, v36
	v_add_f32_e32 v37, 1.0, v37
	v_add_f32_e32 v38, 1.0, v38
	v_add_f32_e32 v39, 1.0, v39
	v_rcp_f32_e32 v36, v36
	v_rcp_f32_e32 v37, v37
	v_rcp_f32_e32 v38, v38
	v_rcp_f32_e32 v39, v39
	v_cndmask_b32_e64 v53, v53, 0, s[6:7]
	v_cndmask_b32_e64 v52, v52, 0, s[6:7]
	v_cndmask_b32_e64 v55, v55, 0, s[6:7]
	v_cndmask_b32_e64 v54, v54, 0, s[6:7]
	v_pk_mul_f32 v[50:51], v[50:51], v[90:91]
	v_pk_mul_f32 v[48:49], v[48:49], v[88:89]
	v_pk_fma_f32 v[50:51], v[54:55], v[82:83], v[50:51]
	v_pk_fma_f32 v[48:49], v[52:53], v[80:81], v[48:49]
	v_pk_fma_f32 v[46:47], v[46:47], v[86:87], v[50:51]
	v_pk_fma_f32 v[44:45], v[44:45], v[84:85], v[48:49]
	v_pk_add_f32 v[46:47], v[94:95], v[46:47]
	v_pk_add_f32 v[44:45], v[92:93], v[44:45]
	v_pk_mul_f32 v[32:33], v[32:33], v[36:37]
	v_pk_mul_f32 v[34:35], v[34:35], v[38:39]
	v_readlane_b32 s2, v254, 38
	v_pk_mul_f32 v[32:33], v[44:45], v[32:33]
	v_pk_mul_f32 v[34:35], v[46:47], v[34:35]
	v_readlane_b32 s3, v254, 39
	v_cvt_pk_bf16_f32 v32, v32, v33
	v_cvt_pk_bf16_f32 v33, v34, v35
	v_mov_b64_e32 v[34:35], s[2:3]
	s_movk_i32 s2, 0x1600
	v_mad_i64_i32 v[34:35], s[2:3], v174, s2, v[34:35]
	v_lshl_add_u64 v[34:35], v[98:99], 1, v[34:35]
	global_store_dwordx2 v[34:35], v[32:33], off
	s_or_b64 exec, exec, s[8:9]
	s_and_saveexec_b64 s[6:7], s[28:29]
	s_cbranch_execnz .LBB0_143

; __device__ __forceinline__ unsigned cvt_pk_bf16(float lo, float hi) { f32x2 v = {lo, hi}; bf16x2_t b = __builtin_convertvector(v, bf16x2_t); return __builtin_bit_cast(unsigned, b); }
; __device__ __forceinline__ float sigmoidf_(float v) { return __builtin_amdgcn_rcpf(1.0f + __builtin_amdgcn_exp2f(-1.4426950408889634f * v)); }
;     __device__ __forceinline__ void operator()(const f32x4 (&acc)[2][2][4][2], const Unit& u, int wr, int wc, int fr, int fq) const {
;     ...
;                     if (j < NBGRP && rowR < nrows) {
;                         const f32x4 ca = wa[0] * (seqb ? z4 : acc[ai][0][1][n]) + wa[1] * acc[ai][0][2][n] + wa[2] * acc[ai][0][3][n] + ba;
;                         const f32x4 cg = wg[0] * (seqb ? z4 : acc[ai][1][1][n]) + wg[1] * acc[ai][1][2][n] + wg[2] * acc[ai][1][3][n] + bg;
;                         u32x2 w; w.x = cvt_pk_bf16(cg[0] * sigmoidf_(cg[0]) * ca[0], cg[1] * sigmoidf_(cg[1]) * ca[1]); w.y = cvt_pk_bf16(cg[2] * sigmoidf_(cg[2]) * ca[2], cg[3] * sigmoidf_(cg[3]) * ca[3]);
;                         *(u32x2*)(ACT + (size_t)rowR * 2816 + f0) = w;
;                     }
.LBB0_147:
	s_waitcnt vmcnt(0)
	v_pk_mul_f32 v[6:7], v[6:7], v[78:79]
	v_pk_mul_f32 v[4:5], v[4:5], v[76:77]
	v_pk_fma_f32 v[6:7], v[10:11], v[62:63], v[6:7]
	v_pk_fma_f32 v[4:5], v[8:9], v[60:61], v[4:5]
	v_pk_fma_f32 v[2:3], v[2:3], v[74:75], v[6:7]
	v_pk_fma_f32 v[0:1], v[0:1], v[72:73], v[4:5]
	v_pk_add_f32 v[2:3], v[70:71], v[2:3]
	v_pk_add_f32 v[0:1], v[68:69], v[0:1]
	v_mul_f32_e32 v6, 0xbfb8aa3b, v2
	v_mul_f32_e32 v4, 0xbfb8aa3b, v0
	v_mul_f32_e32 v5, 0xbfb8aa3b, v1
	v_mul_f32_e32 v7, 0xbfb8aa3b, v3
	v_exp_f32_e32 v4, v4
	v_exp_f32_e32 v5, v5
	v_exp_f32_e32 v6, v6
	v_exp_f32_e32 v7, v7
	v_add_f32_e32 v4, 1.0, v4
	v_add_f32_e32 v5, 1.0, v5
	v_add_f32_e32 v6, 1.0, v6
	v_add_f32_e32 v7, 1.0, v7
	v_rcp_f32_e32 v4, v4
	v_rcp_f32_e32 v5, v5
	v_rcp_f32_e32 v6, v6
	v_rcp_f32_e32 v7, v7
	v_pk_mul_f32 v[18:19], v[18:19], v[90:91]
	v_pk_mul_f32 v[16:17], v[16:17], v[88:89]
	v_pk_fma_f32 v[18:19], v[22:23], v[82:83], v[18:19]
	v_pk_fma_f32 v[16:17], v[20:21], v[80:81], v[16:17]
	v_pk_fma_f32 v[14:15], v[14:15], v[86:87], v[18:19]
	v_pk_fma_f32 v[12:13], v[12:13], v[84:85], v[16:17]
	v_pk_add_f32 v[14:15], v[94:95], v[14:15]
	v_pk_add_f32 v[12:13], v[92:93], v[12:13]
	v_pk_mul_f32 v[0:1], v[0:1], v[4:5]
	v_pk_mul_f32 v[2:3], v[2:3], v[6:7]
	v_readlane_b32 s0, v254, 38
	v_pk_mul_f32 v[0:1], v[12:13], v[0:1]
	v_pk_mul_f32 v[2:3], v[14:15], v[2:3]
	v_readlane_b32 s1, v254, 39
	v_cvt_pk_bf16_f32 v0, v0, v1
	v_cvt_pk_bf16_f32 v1, v2, v3
	v_mov_b64_e32 v[2:3], s[0:1]
	s_movk_i32 s0, 0x1600
	v_mad_i64_i32 v[2:3], s[0:1], v100, s0, v[2:3]
	v_lshl_add_u64 v[2:3], v[98:99], 1, v[2:3]
	global_store_dwordx2 v[2:3], v[0:1], off

; __device__ __forceinline__ unsigned cvt_pk_bf16(float lo, float hi) { f32x2 v = {lo, hi}; bf16x2_t b = __builtin_convertvector(v, bf16x2_t); return __builtin_bit_cast(unsigned, b); }
; __device__ __forceinline__ void phase_norm(const Frame& F, const Params& P, int l, int which, int nrows, bf16_t* HB) {
;     ...
; #pragma unroll
;         for (int j = 0; j < 4; ++j) ss += (v[j][0] * v[j][0] + v[j][1] * v[j][1]) + (v[j][2] * v[j][2] + v[j][3] * v[j][3]);
;         ss = wave_sum(ss); const float rinv = rsqrtf(ss * (1.0f / 1024.0f) + EPS);
; #pragma unroll
;         for (int j = 0; j < 4; ++j) {
;             const int col = 4 * F.lane + 256 * j;
;             const f32x4 g = *(const f32x4*)(gn + col), s1 = *(const f32x4*)(sc + col), s0 = *(const f32x4*)(sh + col);
;             const f32x4 y = v[j] * rinv * g * (s1 + 1.0f) + s0;
;             u32x2 w; w.x = cvt_pk_bf16(y[0], y[1]); w.y = cvt_pk_bf16(y[2], y[3]);
;             *(u32x2*)(H + (size_t)row * 1024 + col) = w;
;             if (HB && (((row + 2) & 127) < 4)) *(u32x2*)(HB + (size_t)(4 * ((row + 2) >> 7) + ((row + 2) & 127)) * 1024 + col) = w;
;         }
.LBB0_162:
	s_min_i32 s0, s6, 0x8000
	s_ashr_i32 s0, s0, 13
	s_mulk_i32 s0, 0x1800
	s_ashr_i32 s1, s0, 31
	s_lshl_b64 s[0:1], s[0:1], 2
	v_readlane_b32 s12, v253, 63
	s_add_u32 s0, s12, s0
	v_readlane_b32 s12, v254, 1
	s_addc_u32 s1, s12, s1
	s_add_u32 s12, s0, 0x1000
	s_addc_u32 s13, s1, 0
	global_load_dwordx4 v[40:43], v[22:23], off
	s_nop 0
	global_load_dwordx4 v[44:47], v192, s[12:13]
	global_load_dwordx4 v[48:51], v192, s[0:1]
	s_waitcnt vmcnt(0)
	v_mul_f32_e32 v34, v1, v1
	v_mul_f32_e32 v35, v3, v3
	v_fmac_f32_e32 v34, v0, v0
	v_fmac_f32_e32 v35, v2, v2
	v_add_f32_e32 v34, v34, v35
	v_mul_f32_e32 v35, v9, v9
	v_mul_f32_e32 v36, v11, v11
	v_fmac_f32_e32 v35, v8, v8
	v_fmac_f32_e32 v36, v10, v10
	v_add_f32_e32 v35, v35, v36
	v_add_f32_e32 v34, v34, v35
	v_mul_f32_e32 v35, v5, v5
	v_mul_f32_e32 v36, v7, v7
	v_fmac_f32_e32 v35, v4, v4
	v_fmac_f32_e32 v36, v6, v6
	v_add_f32_e32 v35, v35, v36
	v_add_f32_e32 v34, v35, v34
	v_mul_f32_e32 v35, v13, v13
	v_mul_f32_e32 v36, v15, v15
	v_fmac_f32_e32 v35, v12, v12
	v_fmac_f32_e32 v36, v14, v14
	v_add_f32_e32 v35, v35, v36
	v_add_f32_e32 v34, v35, v34
	ds_swizzle_b32 v35, v34 offset:swizzle(SWAP,1)
	s_mov_b32 s14, 0x800000
	s_waitcnt lgkmcnt(0)
	v_add_f32_e32 v34, v34, v35
	ds_swizzle_b32 v35, v34 offset:swizzle(SWAP,2)
	s_waitcnt lgkmcnt(0)
	v_add_f32_e32 v34, v34, v35
	ds_swizzle_b32 v35, v34 offset:swizzle(SWAP,4)
	s_waitcnt lgkmcnt(0)
	v_add_f32_e32 v34, v34, v35
	ds_swizzle_b32 v35, v34 offset:swizzle(SWAP,8)
	s_waitcnt lgkmcnt(0)
	v_add_f32_e32 v34, v34, v35
	ds_swizzle_b32 v35, v34 offset:swizzle(SWAP,16)
	s_waitcnt lgkmcnt(0)
	v_add_f32_e32 v34, v34, v35
	v_mov_b32_e32 v35, v34
	s_nop 1
	v_permlane32_swap_b32_e32 v34, v35
	v_add_f32_e32 v34, v34, v35
	v_fmamk_f32 v34, v34, 0x3a800000, v226
	v_cmp_gt_f32_e32 vcc, s14, v34
	v_mul_f32_e32 v35, 0x4b800000, v34
	s_add_i32 s14, s6, 2
	v_cndmask_b32_e32 v34, v34, v35, vcc
	v_rsq_f32_e32 v34, v34
	s_and_b32 s18, s14, 0x7f
	s_cmp_lt_u32 s18, 4
	s_cselect_b64 s[16:17], -1, 0
	s_ashr_i32 s14, s14, 5
	s_and_b32 s14, s14, -4
	v_mul_f32_e32 v35, 0x45800000, v34
	s_or_b32 s14, s14, s18
	v_cndmask_b32_e32 v34, v34, v35, vcc
	s_ashr_i32 s15, s14, 31
	s_lshl_b64 s[14:15], s[14:15], 11
	v_pk_mul_f32 v[2:3], v[2:3], v[34:35] op_sel_hi:[1,0]
	v_pk_mul_f32 v[0:1], v[0:1], v[34:35] op_sel_hi:[1,0]
	s_add_u32 s14, s2, s14
	s_addc_u32 s15, s3, s15
	v_pk_mul_f32 v[0:1], v[40:41], v[0:1]
	v_pk_mul_f32 v[2:3], v[42:43], v[2:3]
	v_pk_add_f32 v[36:37], v[46:47], 1.0 op_sel_hi:[1,0]
	v_pk_add_f32 v[40:41], v[44:45], 1.0 op_sel_hi:[1,0]
	v_pk_fma_f32 v[36:37], v[36:37], v[2:3], v[50:51]
	v_pk_fma_f32 v[0:1], v[40:41], v[0:1], v[48:49]
	s_cmp_gt_u32 s18, 3
	v_cvt_pk_bf16_f32 v2, v0, v1
	v_cvt_pk_bf16_f32 v3, v36, v37
	v_lshlrev_b32_e32 v0, 1, v16
	global_store_dwordx2 v[32:33], v[2:3], off
	s_cbranch_scc1 .LBB0_164
	v_mov_b32_e32 v1, v193
	v_lshl_add_u64 v[36:37], s[14:15], 0, v[0:1]
	global_store_dwordx2 v[36:37], v[2:3], off
.LBB0_164:
	v_lshl_add_u64 v[2:3], s[0:1], 0, v[192:193]
	global_load_dwordx4 v[40:43], v[24:25], off
	global_load_dwordx4 v[44:47], v17, s[12:13]
	global_load_dwordx4 v[48:51], v[2:3], off offset:1024
	v_mov_b32_e32 v35, v34
	v_mov_b32_e32 v36, v34
	v_mov_b32_e32 v37, v34
	v_pk_mul_f32 v[10:11], v[10:11], v[36:37]
	v_pk_mul_f32 v[8:9], v[8:9], v[34:35]
	v_cndmask_b32_e64 v1, 0, 1, s[16:17]
	v_cmp_ne_u32_e64 s[0:1], 1, v1
	s_andn2_b64 vcc, exec, s[16:17]
	s_waitcnt vmcnt(0)
	v_pk_mul_f32 v[10:11], v[10:11], v[42:43]
	v_pk_mul_f32 v[8:9], v[8:9], v[40:41]
	v_pk_add_f32 v[40:41], v[46:47], 1.0 op_sel_hi:[1,0]
	v_pk_add_f32 v[42:43], v[44:45], 1.0 op_sel_hi:[1,0]
	v_pk_fma_f32 v[10:11], v[10:11], v[40:41], v[50:51]
	v_pk_fma_f32 v[8:9], v[8:9], v[42:43], v[48:49]
	s_nop 0
	v_cvt_pk_bf16_f32 v8, v8, v9
	v_cvt_pk_bf16_f32 v9, v10, v11
	global_store_dwordx2 v[32:33], v[8:9], off offset:512
	s_cbranch_vccnz .LBB0_166
	v_mov_b32_e32 v1, v193
	v_lshl_add_u64 v[10:11], s[14:15], 0, v[0:1]
	global_store_dwordx2 v[10:11], v[8:9], off offset:512
.LBB0_166:
	global_load_dwordx4 v[8:11], v[26:27], off
	s_nop 0
	global_load_dwordx4 v[40:43], v38, s[12:13]
	global_load_dwordx4 v[44:47], v[2:3], off offset:2048
	v_pk_mul_f32 v[6:7], v[6:7], v[36:37]
	v_pk_mul_f32 v[4:5], v[4:5], v[34:35]
	s_and_b64 vcc, exec, s[0:1]
	s_waitcnt vmcnt(0)
	v_pk_mul_f32 v[6:7], v[6:7], v[10:11]
	v_pk_mul_f32 v[4:5], v[4:5], v[8:9]
	v_pk_add_f32 v[8:9], v[42:43], 1.0 op_sel_hi:[1,0]
	v_pk_add_f32 v[10:11], v[40:41], 1.0 op_sel_hi:[1,0]
	v_pk_fma_f32 v[6:7], v[6:7], v[8:9], v[46:47]
	v_pk_fma_f32 v[4:5], v[4:5], v[10:11], v[44:45]
	s_nop 0
	v_cvt_pk_bf16_f32 v4, v4, v5
	v_cvt_pk_bf16_f32 v5, v6, v7
	global_store_dwordx2 v[32:33], v[4:5], off offset:1024
	s_cbranch_vccnz .LBB0_168
	v_mov_b32_e32 v1, v193
	v_lshl_add_u64 v[6:7], s[14:15], 0, v[0:1]
	global_store_dwordx2 v[6:7], v[4:5], off offset:1024
.LBB0_168:
	global_load_dwordx4 v[4:7], v[28:29], off
	s_nop 0
	global_load_dwordx4 v[8:11], v39, s[12:13]
	global_load_dwordx4 v[40:43], v[2:3], off offset:3072
	v_mov_b32_e32 v2, v34
	v_mov_b32_e32 v3, v34
	v_pk_mul_f32 v[12:13], v[12:13], v[34:35]
	v_pk_mul_f32 v[2:3], v[14:15], v[2:3]
	s_and_b64 vcc, exec, s[0:1]
	s_waitcnt vmcnt(0)
	v_pk_mul_f32 v[2:3], v[2:3], v[6:7]
	v_pk_mul_f32 v[4:5], v[12:13], v[4:5]
	v_pk_add_f32 v[6:7], v[10:11], 1.0 op_sel_hi:[1,0]
	v_pk_add_f32 v[8:9], v[8:9], 1.0 op_sel_hi:[1,0]
	v_pk_fma_f32 v[6:7], v[2:3], v[6:7], v[42:43]
	v_pk_fma_f32 v[2:3], v[4:5], v[8:9], v[40:41]
	s_nop 0
	v_cvt_pk_bf16_f32 v2, v2, v3
	v_cvt_pk_bf16_f32 v3, v6, v7
	global_store_dwordx2 v[32:33], v[2:3], off offset:1536
	s_cbranch_vccnz .LBB0_159
	v_mov_b32_e32 v1, v193
	v_lshl_add_u64 v[0:1], s[14:15], 0, v[0:1]
	global_store_dwordx2 v[0:1], v[2:3], off offset:1536
	s_branch .LBB0_159

;     __device__ __forceinline__ void operator()(const f32x4 (&acc)[2][2][4][2], const Unit& u, int wr, int wc, int fr, int fq) const {
;     ...
; #pragma unroll
;             for (int bj = 0; bj < 2; ++bj)
; #pragma unroll
;                 for (int n = 0; n < 2; ++n) *(f32x4*)(op + ro + 128 * bj + 4 * n) = pre[g & 1][bj][n] + mv[bj][n] * acc[ai][bj][m][n];
.LBB0_203:
	s_andn2_b64 vcc, exec, s[16:17]
	s_mov_b64 s[16:17], -1
	global_store_dwordx4 v[148:149], v[144:147], off offset:528
	s_cbranch_vccnz .LBB0_187
	s_branch .LBB0_206

; #define FOR_AI_M _Pragma("unroll") for (int ai = 0; ai < 2; ++ai) _Pragma("unroll") for (int m = 0; m < 4; ++m)
;     __device__ __forceinline__ void operator()(const f32x4 (&acc)[2][2][4][2], const Unit& u, int wr, int wc, int fr, int fq) const {
;     ...
;         if (u.mode > 0) {
;             float* pp = part + (size_t)(u.mode - 1) * NCTX * 1024 + (size_t)(row0 - NLAT) * 1024;
;             FOR_AI_M {
;                 const size_t ro = (size_t)(128 * ai + 64 * wr + 16 * m + fr) * 1024 + cb0;
; #pragma unroll
;                 for (int bj = 0; bj < 2; ++bj)
; #pragma unroll
;                     for (int n = 0; n < 2; ++n) *(f32x4*)(pp + ro + 128 * bj + 4 * n) = mv[bj][n] * acc[ai][bj][m][n];
;             }
;             return;
.LBB0_205:
	v_readlane_b32 s8, v253, 15
	v_readlane_b32 s9, v253, 16
	s_mov_b32 s11, s9
	s_add_i32 s10, s94, -1
	v_writelane_b32 v253, s8, 15
	s_lshl_b64 s[20:21], s[10:11], 22
	v_lshlrev_b64 v[146:147], 12, v[180:181]
	v_writelane_b32 v253, s9, 16
	v_readlane_b32 s8, v254, 57
	s_add_u32 s18, s8, s20
	v_readlane_b32 s8, v254, 58
	s_addc_u32 s26, s8, s21
	s_ashr_i32 s25, s24, 31
	s_lshl_b64 s[20:21], s[24:25], 12
	s_add_u32 s20, s18, s20
	s_addc_u32 s21, s26, s21
	s_brev_b32 s8, 31
	v_lshl_add_u64 v[144:145], v[182:183], 2, s[20:21]
	s_mov_b32 s9, -1
	v_lshl_add_u64 v[144:145], v[144:145], 0, s[8:9]
	v_lshl_add_u64 v[146:147], v[144:145], 0, v[146:147]
	s_waitcnt vmcnt(0) lgkmcnt(0)
	v_pk_mul_f32 v[106:107], v[106:107], v[130:131]
	v_pk_mul_f32 v[104:105], v[104:105], v[128:129]
	v_ashrrev_i32_e32 v179, 31, v178
	v_pk_mul_f32 v[118:119], v[118:119], v[134:135]
	v_pk_mul_f32 v[116:117], v[116:117], v[132:133]
	global_store_dwordx4 v[146:147], v[104:107], off offset:528
	global_store_dwordx4 v[146:147], v[116:119], off offset:512
	v_pk_mul_f32 v[90:91], v[90:91], v[130:131]
	v_lshlrev_b64 v[104:105], 12, v[178:179]
	v_lshl_add_u64 v[116:117], v[144:145], 0, v[104:105]
	v_pk_mul_f32 v[88:89], v[88:89], v[128:129]
	v_ashrrev_i32_e32 v177, 31, v176
	v_pk_mul_f32 v[98:99], v[98:99], v[134:135]
	v_pk_mul_f32 v[96:97], v[96:97], v[132:133]
	global_store_dwordx4 v[116:117], v[88:91], off offset:528
	global_store_dwordx4 v[116:117], v[96:99], off offset:512
	v_pk_mul_f32 v[74:75], v[74:75], v[130:131]
	v_lshlrev_b64 v[88:89], 12, v[176:177]
	v_lshl_add_u64 v[96:97], v[144:145], 0, v[88:89]
	v_pk_mul_f32 v[72:73], v[72:73], v[128:129]
	v_ashrrev_i32_e32 v175, 31, v174
	v_pk_mul_f32 v[82:83], v[82:83], v[134:135]
	v_pk_mul_f32 v[80:81], v[80:81], v[132:133]
	global_store_dwordx4 v[96:97], v[72:75], off offset:528
	global_store_dwordx4 v[96:97], v[80:83], off offset:512
	v_pk_mul_f32 v[66:67], v[66:67], v[130:131]
	v_lshlrev_b64 v[72:73], 12, v[174:175]
	v_lshl_add_u64 v[80:81], v[144:145], 0, v[72:73]
	v_pk_mul_f32 v[64:65], v[64:65], v[128:129]
	v_ashrrev_i32_e32 v173, 31, v172
	global_store_dwordx4 v[80:81], v[64:67], off offset:528
	v_pk_mul_f32 v[42:43], v[42:43], v[130:131]
	v_pk_mul_f32 v[40:41], v[40:41], v[128:129]
	v_lshlrev_b64 v[64:65], 12, v[172:173]
	v_lshl_add_u64 v[64:65], v[144:145], 0, v[64:65]
	v_ashrrev_i32_e32 v171, 31, v170
	v_pk_mul_f32 v[50:51], v[50:51], v[134:135]
	v_pk_mul_f32 v[48:49], v[48:49], v[132:133]
	global_store_dwordx4 v[64:65], v[40:43], off offset:528
	global_store_dwordx4 v[64:65], v[48:51], off offset:512
	v_pk_mul_f32 v[26:27], v[26:27], v[130:131]
	v_lshlrev_b64 v[40:41], 12, v[170:171]
	v_lshl_add_u64 v[48:49], v[144:145], 0, v[40:41]
	v_pk_mul_f32 v[24:25], v[24:25], v[128:129]
	v_ashrrev_i32_e32 v169, 31, v168
	v_pk_mul_f32 v[34:35], v[34:35], v[134:135]
	v_pk_mul_f32 v[32:33], v[32:33], v[132:133]
	global_store_dwordx4 v[48:49], v[24:27], off offset:528
	global_store_dwordx4 v[48:49], v[32:35], off offset:512
	v_pk_mul_f32 v[10:11], v[10:11], v[130:131]
	v_lshlrev_b64 v[24:25], 12, v[168:169]
	v_lshl_add_u64 v[32:33], v[144:145], 0, v[24:25]
	v_pk_mul_f32 v[8:9], v[8:9], v[128:129]
	v_ashrrev_i32_e32 v167, 31, v166
	global_store_dwordx4 v[32:33], v[8:11], off offset:528
	v_pk_mul_f32 v[126:127], v[126:127], v[142:143]
	v_pk_mul_f32 v[124:125], v[124:125], v[140:141]
	v_lshlrev_b64 v[8:9], 12, v[166:167]
	v_pk_mul_f32 v[122:123], v[122:123], v[138:139]
	v_pk_mul_f32 v[120:121], v[120:121], v[136:137]
	v_pk_mul_f32 v[106:107], v[114:115], v[142:143]
	v_pk_mul_f32 v[104:105], v[112:113], v[140:141]
	v_pk_mul_f32 v[90:91], v[102:103], v[142:143]
	v_pk_mul_f32 v[88:89], v[100:101], v[140:141]
	v_pk_mul_f32 v[74:75], v[86:87], v[142:143]
	v_pk_mul_f32 v[72:73], v[84:85], v[140:141]
	v_pk_mul_f32 v[42:43], v[54:55], v[142:143]
	v_pk_mul_f32 v[40:41], v[52:53], v[140:141]
	v_pk_mul_f32 v[26:27], v[38:39], v[142:143]
	v_pk_mul_f32 v[24:25], v[36:37], v[140:141]
	v_lshl_add_u64 v[148:149], v[144:145], 0, v[8:9]
	v_pk_mul_f32 v[10:11], v[22:23], v[142:143]
	v_pk_mul_f32 v[8:9], v[20:21], v[140:141]
	global_store_dwordx4 v[146:147], v[124:127], off
	global_store_dwordx4 v[146:147], v[120:123], off offset:16
	global_store_dwordx4 v[116:117], v[104:107], off
	global_store_dwordx4 v[96:97], v[88:91], off
	global_store_dwordx4 v[80:81], v[72:75], off
	v_pk_mul_f32 v[106:107], v[110:111], v[138:139]
	v_pk_mul_f32 v[104:105], v[108:109], v[136:137]
	v_pk_mul_f32 v[90:91], v[94:95], v[138:139]
	v_pk_mul_f32 v[88:89], v[92:93], v[136:137]
	v_pk_mul_f32 v[74:75], v[78:79], v[138:139]
	v_pk_mul_f32 v[72:73], v[76:77], v[136:137]
	v_pk_mul_f32 v[70:71], v[70:71], v[134:135]
	v_pk_mul_f32 v[68:69], v[68:69], v[132:133]
	v_pk_mul_f32 v[62:63], v[62:63], v[142:143]
	v_pk_mul_f32 v[60:61], v[60:61], v[140:141]
	v_pk_mul_f32 v[58:59], v[58:59], v[138:139]
	v_pk_mul_f32 v[56:57], v[56:57], v[136:137]
	global_store_dwordx4 v[48:49], v[40:43], off
	global_store_dwordx4 v[32:33], v[24:27], off
	v_pk_mul_f32 v[18:19], v[18:19], v[134:135]
	v_pk_mul_f32 v[42:43], v[46:47], v[138:139]
	v_pk_mul_f32 v[40:41], v[44:45], v[136:137]
	v_pk_mul_f32 v[26:27], v[30:31], v[138:139]
	v_pk_mul_f32 v[24:25], v[28:29], v[136:137]
	v_pk_mul_f32 v[16:17], v[16:17], v[132:133]
	global_store_dwordx4 v[148:149], v[8:11], off
	v_pk_mul_f32 v[6:7], v[6:7], v[134:135]
	v_pk_mul_f32 v[4:5], v[4:5], v[132:133]
	v_pk_mul_f32 v[10:11], v[14:15], v[138:139]
	v_pk_mul_f32 v[8:9], v[12:13], v[136:137]
	v_pk_mul_f32 v[146:147], v[2:3], v[130:131]
	v_pk_mul_f32 v[144:145], v[0:1], v[128:129]
	global_store_dwordx4 v[116:117], v[104:107], off offset:16
	global_store_dwordx4 v[96:97], v[88:91], off offset:16
	global_store_dwordx4 v[80:81], v[72:75], off offset:16
	global_store_dwordx4 v[80:81], v[68:71], off offset:512
	global_store_dwordx4 v[64:65], v[60:63], off
	global_store_dwordx4 v[64:65], v[56:59], off offset:16
	global_store_dwordx4 v[48:49], v[40:43], off offset:16
	global_store_dwordx4 v[32:33], v[24:27], off offset:16
	global_store_dwordx4 v[32:33], v[16:19], off offset:512
	global_store_dwordx4 v[148:149], v[8:11], off offset:16
	global_store_dwordx4 v[148:149], v[4:7], off offset:512
	s_andn2_b64 vcc, exec, s[16:17]
	s_mov_b64 s[16:17], -1
	global_store_dwordx4 v[148:149], v[144:147], off offset:528
	s_cbranch_vccnz .LBB0_187

; __device__ __forceinline__ unsigned cvt_pk_bf16(float lo, float hi) { f32x2 v = {lo, hi}; bf16x2_t b = __builtin_convertvector(v, bf16x2_t); return __builtin_bit_cast(unsigned, b); }
; __device__ __forceinline__ float bflo(unsigned w) { return __uint_as_float(w << 16); }
; __device__ __forceinline__ float bfhi(unsigned w) { return __uint_as_float(w & 0xffff0000u); }
;     __device__ __forceinline__ void operator()(const f32x4 (&acc)[2][2][4][2], const Unit& u, int wr, int wc, int fr, int fq) const {
;     ...
;         for (int g = 0; g < 8; ++g) {
;             const int ai = g >> 2, m = g & 3;
;             const size_t row = (size_t)256 * u.pm + 128 * ai + 64 * wr + 16 * m + fr;
;             if (g + 1 < 8) {
;                 const int an = (g + 1) >> 2, mn = (g + 1) & 3;
; #pragma unroll
;                 for (int bj = 0; bj < 2; ++bj) {
;                     const int i0 = (((an * 2 + bj) * 4 + mn) * 2) * 512 + tid, i1 = i0 + 512;
;                     gp[(g + 1) & 1][bj][0] = *(const u32x2*)(stg + (size_t)i0 * 2); gp[(g + 1) & 1][bj][1] = *(const u32x2*)(stg + (size_t)i1 * 2);
;                     if (addm) { mp[(g + 1) & 1][bj][0] = *(const f32x4*)(stm + (size_t)i0 * 4); mp[(g + 1) & 1][bj][1] = *(const f32x4*)(stm + (size_t)i1 * 4); }
;                 }
;             }
;             asm volatile("" ::: "memory");
; #pragma unroll
;             for (int bj = 0; bj < 2; ++bj) {
;                 const int i0 = (((ai * 2 + bj) * 4 + m) * 2) * 512 + tid, i1 = i0 + 512;
;                 const u32x2 g0 = gp[g & 1][bj][0], g1 = gp[g & 1][bj][1];
;                 f32x4 a = acc[ai][bj][m][0], b = acc[ai][bj][m][1];
;                 a = a * (f32x4){bflo(g0.x), bfhi(g0.x), bflo(g0.y), bfhi(g0.y)}; b = b * (f32x4){bflo(g1.x), bfhi(g1.x), bflo(g1.y), bfhi(g1.y)};
;                 if (addm) { a += mp[g & 1][bj][0]; b += mp[g & 1][bj][1]; }
;                 if (sub < 5) { *(f32x4*)(stm + (size_t)i0 * 4) = a; *(f32x4*)(stm + (size_t)i1 * 4) = b; }
;                 else {
;                     u32x4 w; w.x = cvt_pk_bf16(a[0], a[1]); w.y = cvt_pk_bf16(a[2], a[3]); w.z = cvt_pk_bf16(b[0], b[1]); w.w = cvt_pk_bf16(b[2], b[3]);
;                     bf16_t* dst = iso ? MCTX + (size_t)((sub - 8) >> 1) * NCTX * 1024 + (row - NLAT) * 1024 : M + row * 1024;
;                     *(u32x4*)(dst + 256 * u.pn + 128 * bj + 32 * wc + 8 * fq) = w;
;                 }
.LBB0_266:
	v_mov_b32_e32 v166, v247
	v_mov_b32_e32 v162, v197
	v_readlane_b32 s0, v254, 61
	v_lshlrev_b32_e32 v128, 4, v166
	s_bitcmp1_b32 s92, 0
	v_add3_u32 v178, s0, v162, v128
	s_cselect_b64 s[8:9], -1, 0
	v_readlane_b32 s96, v254, 42
	s_mov_b64 s[0:1], -1
	s_and_b64 vcc, exec, s[8:9]
	v_ashrrev_i32_e32 v179, 31, v178
	s_mov_b32 s64, 0x3f22f983
	v_readlane_b32 s97, v254, 43
	s_cbranch_vccz .LBB0_365
	v_add_u32_e32 v128, 0x200, v178
	v_lshl_add_u64 v[130:131], v[178:179], 3, s[28:29]
	v_ashrrev_i32_e32 v129, 31, v128
	v_lshl_add_u64 v[132:133], v[128:129], 3, s[28:29]
	global_load_dwordx2 v[164:165], v[130:131], off
	global_load_dwordx2 v[160:161], v[132:133], off
	s_add_i32 s0, s92, -2
	s_cmp_lt_u32 s0, 6
	s_cselect_b64 s[8:9], -1, 0
	s_cmp_gt_u32 s0, 5
	v_lshl_add_u64 v[206:207], v[178:179], 4, s[26:27]
	v_lshl_add_u64 v[208:209], v[128:129], 4, s[26:27]
	s_cbranch_scc1 .LBB0_269
	global_load_dwordx4 v[156:159], v[206:207], off
	global_load_dwordx4 v[152:155], v[208:209], off
.LBB0_269:
	v_add_u32_e32 v128, 0x1000, v178
	v_add_u32_e32 v130, 0x1200, v178
	v_ashrrev_i32_e32 v129, 31, v128
	v_lshl_add_u64 v[132:133], v[128:129], 3, s[28:29]
	v_ashrrev_i32_e32 v131, 31, v130
	v_lshl_add_u64 v[134:135], v[130:131], 3, s[28:29]
	global_load_dwordx2 v[214:215], v[132:133], off
	global_load_dwordx2 v[210:211], v[134:135], off
	v_cndmask_b32_e64 v132, 0, 1, s[8:9]
	v_cmp_ne_u32_e64 s[14:15], 1, v132
	s_andn2_b64 vcc, exec, s[8:9]
	v_lshl_add_u64 v[198:199], v[128:129], 4, s[26:27]
	v_lshl_add_u64 v[200:201], v[130:131], 4, s[26:27]
	s_cbranch_vccnz .LBB0_271
	global_load_dwordx4 v[148:151], v[198:199], off
	global_load_dwordx4 v[144:147], v[200:201], off
.LBB0_271:
	v_add_u32_e32 v128, 0x400, v178
	v_add_u32_e32 v130, 0x600, v178
	v_ashrrev_i32_e32 v129, 31, v128
	v_lshl_add_u64 v[132:133], v[128:129], 3, s[28:29]
	v_ashrrev_i32_e32 v131, 31, v130
	v_lshl_add_u64 v[134:135], v[130:131], 3, s[28:29]
	global_load_dwordx2 v[216:217], v[132:133], off
	global_load_dwordx2 v[212:213], v[134:135], off
	s_and_b64 vcc, exec, s[14:15]
	v_lshl_add_u64 v[188:189], v[128:129], 4, s[26:27]
	v_lshl_add_u64 v[190:191], v[130:131], 4, s[26:27]
	s_cbranch_vccnz .LBB0_273
	global_load_dwordx4 v[140:143], v[188:189], off
	global_load_dwordx4 v[136:139], v[190:191], off
.LBB0_273:
	v_add_u32_e32 v128, 0x1400, v178
	v_add_u32_e32 v130, 0x1600, v178
	v_ashrrev_i32_e32 v129, 31, v128
	v_lshl_add_u64 v[132:133], v[128:129], 3, s[28:29]
	v_ashrrev_i32_e32 v131, 31, v130
	v_lshl_add_u64 v[134:135], v[130:131], 3, s[28:29]
	global_load_dwordx2 v[204:205], v[132:133], off
	global_load_dwordx2 v[202:203], v[134:135], off
	s_and_b64 vcc, exec, s[14:15]
	v_lshl_add_u64 v[184:185], v[128:129], 4, s[26:27]
	v_lshl_add_u64 v[186:187], v[130:131], 4, s[26:27]
	s_cbranch_vccnz .LBB0_275
	global_load_dwordx4 v[132:135], v[184:185], off
	global_load_dwordx4 v[128:131], v[186:187], off
.LBB0_275:
	s_cmp_lt_i32 s92, 8
	v_readlane_b32 s0, v255, 5
	s_cselect_b64 s[10:11], -1, 0
	v_ashrrev_i32_e32 v163, 31, v162
	v_readlane_b32 s1, v255, 6
	s_cmp_gt_i32 s92, 4
	s_cselect_b64 s[96:97], -1, 0
	v_lshl_add_u64 v[162:163], v[162:163], 0, s[0:1]
	s_ashr_i32 s13, s12, 31
	v_readlane_b32 s0, v253, 15
	s_lshl_b64 s[12:13], s[12:13], 19
	v_lshlrev_b64 v[162:163], 11, v[162:163]
	s_add_i32 s92, s92, -8
	v_readlane_b32 s1, v253, 16
	v_lshl_add_u64 v[182:183], v[162:163], 0, s[12:13]
	s_waitcnt vmcnt(0) lgkmcnt(0)
	v_lshlrev_b32_e32 v162, 16, v164
	v_and_b32_e32 v163, 0xffff0000, v164
	v_lshlrev_b32_e32 v164, 16, v165
	v_and_b32_e32 v165, 0xffff0000, v165
	v_lshlrev_b32_e32 v220, 16, v160
	v_and_b32_e32 v221, 0xffff0000, v160
	v_lshlrev_b32_e32 v160, 16, v161
	v_and_b32_e32 v161, 0xffff0000, v161
	s_mov_b32 s61, s1
	s_lshr_b32 s60, s92, 1
	v_writelane_b32 v253, s0, 15
	v_lshlrev_b32_e32 v180, 3, v166
	v_pk_mul_f32 v[166:167], v[124:125], v[162:163]
	v_pk_mul_f32 v[218:219], v[126:127], v[164:165]
	v_pk_mul_f32 v[222:223], v[120:121], v[220:221]
	v_pk_mul_f32 v[224:225], v[122:123], v[160:161]
	v_pk_fma_f32 v[230:231], v[124:125], v[162:163], v[156:157]
	v_pk_fma_f32 v[162:163], v[126:127], v[164:165], v[158:159]
	v_pk_fma_f32 v[164:165], v[120:121], v[220:221], v[152:153]
	v_pk_fma_f32 v[220:221], v[122:123], v[160:161], v[154:155]
	v_writelane_b32 v253, s1, 16
	s_lshl_b64 s[0:1], s[60:61], 21
	v_ashrrev_i32_e32 v181, 31, v180
	v_cndmask_b32_e64 v163, v219, v163, s[8:9]
	v_cndmask_b32_e64 v162, v218, v162, s[8:9]
	v_cndmask_b32_e64 v161, v167, v231, s[8:9]
	v_cndmask_b32_e64 v160, v166, v230, s[8:9]
	v_cndmask_b32_e64 v167, v225, v221, s[8:9]
	v_cndmask_b32_e64 v166, v224, v220, s[8:9]
	v_cndmask_b32_e64 v165, v223, v165, s[8:9]
	v_cndmask_b32_e64 v164, v222, v164, s[8:9]
	s_mov_b64 s[12:13], -1
	s_and_b64 vcc, exec, s[96:97]
	v_lshl_add_u64 v[218:219], s[24:25], 0, v[182:183]
	s_cbranch_vccz .LBB0_277
	s_add_u32 s12, s23, s0
	s_addc_u32 s13, s6, s1
	v_lshl_add_u64 v[224:225], s[12:13], 0, v[182:183]
	s_brev_b32 s12, 63
	s_mov_b32 s13, -1
	v_lshl_add_u64 v[224:225], v[224:225], 0, s[12:13]
	s_lshl_b32 s12, s3, 8
	v_cndmask_b32_e64 v225, v225, v219, s[10:11]
	v_cndmask_b32_e64 v224, v224, v218, s[10:11]
	s_ashr_i32 s13, s12, 31
	v_lshl_add_u64 v[224:225], s[12:13], 1, v[224:225]
	v_readlane_b32 s12, v253, 15
	v_readlane_b32 s13, v253, 16
	s_mov_b32 s61, s13
	s_lshl_b32 s60, s7, 1
	v_lshl_add_u64 v[224:225], v[224:225], 0, s[60:61]
	v_cvt_pk_bf16_f32 v220, v160, v161
	v_cvt_pk_bf16_f32 v221, v162, v163
	v_cvt_pk_bf16_f32 v222, v164, v165
	v_cvt_pk_bf16_f32 v223, v166, v167
	v_writelane_b32 v253, s12, 15
	v_lshl_add_u64 v[224:225], v[180:181], 1, v[224:225]
	global_store_dwordx4 v[224:225], v[220:223], off
	v_writelane_b32 v253, s13, 16
	s_mov_b64 s[12:13], 0
; __device__ __forceinline__ unsigned cvt_pk_bf16(float lo, float hi) { f32x2 v = {lo, hi}; bf16x2_t b = __builtin_convertvector(v, bf16x2_t); return __builtin_bit_cast(unsigned, b); }
; __device__ __forceinline__ float bflo(unsigned w) { return __uint_as_float(w << 16); }
; __device__ __forceinline__ float bfhi(unsigned w) { return __uint_as_float(w & 0xffff0000u); }
;     __device__ __forceinline__ void operator()(const f32x4 (&acc)[2][2][4][2], const Unit& u, int wr, int wc, int fr, int fq) const {
;     ...
;         for (int g = 0; g < 8; ++g) {
;             const int ai = g >> 2, m = g & 3;
;             const size_t row = (size_t)256 * u.pm + 128 * ai + 64 * wr + 16 * m + fr;
;             if (g + 1 < 8) {
;                 const int an = (g + 1) >> 2, mn = (g + 1) & 3;
; #pragma unroll
;                 for (int bj = 0; bj < 2; ++bj) {
;                     const int i0 = (((an * 2 + bj) * 4 + mn) * 2) * 512 + tid, i1 = i0 + 512;
;                     gp[(g + 1) & 1][bj][0] = *(const u32x2*)(stg + (size_t)i0 * 2); gp[(g + 1) & 1][bj][1] = *(const u32x2*)(stg + (size_t)i1 * 2);
;                     if (addm) { mp[(g + 1) & 1][bj][0] = *(const f32x4*)(stm + (size_t)i0 * 4); mp[(g + 1) & 1][bj][1] = *(const f32x4*)(stm + (size_t)i1 * 4); }
;                 }
;             }
;             asm volatile("" ::: "memory");
; #pragma unroll
;             for (int bj = 0; bj < 2; ++bj) {
;                 const int i0 = (((ai * 2 + bj) * 4 + m) * 2) * 512 + tid, i1 = i0 + 512;
;                 const u32x2 g0 = gp[g & 1][bj][0], g1 = gp[g & 1][bj][1];
;                 f32x4 a = acc[ai][bj][m][0], b = acc[ai][bj][m][1];
;                 a = a * (f32x4){bflo(g0.x), bfhi(g0.x), bflo(g0.y), bfhi(g0.y)}; b = b * (f32x4){bflo(g1.x), bfhi(g1.x), bflo(g1.y), bfhi(g1.y)};
;                 if (addm) { a += mp[g & 1][bj][0]; b += mp[g & 1][bj][1]; }
;                 if (sub < 5) { *(f32x4*)(stm + (size_t)i0 * 4) = a; *(f32x4*)(stm + (size_t)i1 * 4) = b; }
;                 else {
;                     u32x4 w; w.x = cvt_pk_bf16(a[0], a[1]); w.y = cvt_pk_bf16(a[2], a[3]); w.z = cvt_pk_bf16(b[0], b[1]); w.w = cvt_pk_bf16(b[2], b[3]);
;                     bf16_t* dst = iso ? MCTX + (size_t)((sub - 8) >> 1) * NCTX * 1024 + (row - NLAT) * 1024 : M + row * 1024;
;                     *(u32x4*)(dst + 256 * u.pn + 128 * bj + 32 * wc + 8 * fq) = w;
;                 }
.LBB0_277:
	s_andn2_b64 vcc, exec, s[12:13]
	s_cbranch_vccnz .LBB0_279
	global_store_dwordx4 v[206:207], v[160:163], off
	global_store_dwordx4 v[208:209], v[164:167], off
.LBB0_279:
	s_nop 0
	v_lshlrev_b32_e32 v160, 16, v214
	v_and_b32_e32 v161, 0xffff0000, v214
	v_lshlrev_b32_e32 v206, 16, v210
	v_and_b32_e32 v207, 0xffff0000, v210
	v_lshlrev_b32_e32 v162, 16, v215
	v_and_b32_e32 v163, 0xffff0000, v215
	v_pk_mul_f32 v[164:165], v[116:117], v[160:161]
	v_lshlrev_b32_e32 v208, 16, v211
	v_and_b32_e32 v209, 0xffff0000, v211
	v_pk_mul_f32 v[210:211], v[112:113], v[206:207]
	v_pk_fma_f32 v[160:161], v[116:117], v[160:161], v[148:149]
	v_pk_fma_f32 v[206:207], v[112:113], v[206:207], v[144:145]
	v_pk_mul_f32 v[166:167], v[118:119], v[162:163]
	v_pk_mul_f32 v[214:215], v[114:115], v[208:209]
	v_pk_fma_f32 v[162:163], v[118:119], v[162:163], v[150:151]
	v_pk_fma_f32 v[208:209], v[114:115], v[208:209], v[146:147]
	v_cndmask_b32_e64 v160, v164, v160, s[8:9]
	v_cndmask_b32_e64 v164, v210, v206, s[8:9]
	v_cndmask_b32_e64 v206, 0, 1, s[96:97]
	v_cndmask_b32_e64 v163, v167, v163, s[8:9]
	v_cndmask_b32_e64 v162, v166, v162, s[8:9]
	v_cndmask_b32_e64 v161, v165, v161, s[8:9]
	v_cndmask_b32_e64 v167, v215, v209, s[8:9]
	v_cndmask_b32_e64 v166, v214, v208, s[8:9]
	v_cndmask_b32_e64 v165, v211, v207, s[8:9]
	v_cmp_ne_u32_e64 s[12:13], 1, v206
	s_andn2_b64 vcc, exec, s[96:97]
	s_mov_b64 s[96:97], -1
	s_cbranch_vccnz .LBB0_281
	s_add_u32 s60, s23, s0
	s_addc_u32 s61, s6, s1
	v_lshl_add_u64 v[210:211], s[60:61], 0, v[182:183]
	s_brev_b32 s60, 63
	s_mov_b32 s61, -1
	v_lshl_add_u64 v[210:211], v[210:211], 0, s[60:61]
	s_lshl_b32 s60, s3, 8
	v_cndmask_b32_e64 v211, v211, v219, s[10:11]
	v_cndmask_b32_e64 v210, v210, v218, s[10:11]
	s_ashr_i32 s61, s60, 31
	v_lshl_add_u64 v[210:211], s[60:61], 1, v[210:211]
	v_readlane_b32 s60, v253, 15
	v_readlane_b32 s61, v253, 16
	s_lshl_b32 s60, s7, 1
	s_mov_b32 s21, s61
	v_writelane_b32 v253, s20, 15
	v_lshl_add_u64 v[210:211], v[210:211], 0, s[60:61]
	v_cvt_pk_bf16_f32 v206, v160, v161
	v_cvt_pk_bf16_f32 v207, v162, v163
	v_cvt_pk_bf16_f32 v208, v164, v165
	v_cvt_pk_bf16_f32 v209, v166, v167
	v_writelane_b32 v253, s21, 16
	v_lshl_add_u64 v[210:211], v[180:181], 1, v[210:211]
	s_mov_b64 s[96:97], 0
	global_store_dwordx4 v[210:211], v[206:209], off offset:256
.LBB0_281:
	s_andn2_b64 vcc, exec, s[96:97]
	s_cbranch_vccnz .LBB0_283
	global_store_dwordx4 v[198:199], v[160:163], off
	global_store_dwordx4 v[200:201], v[164:167], off
.LBB0_283:
	s_nop 0
	v_add_u32_e32 v160, 0x800, v178
	v_add_u32_e32 v162, 0xa00, v178
	v_ashrrev_i32_e32 v161, 31, v160
	v_lshl_add_u64 v[164:165], v[160:161], 3, s[28:29]
	v_ashrrev_i32_e32 v163, 31, v162
	v_lshl_add_u64 v[166:167], v[162:163], 3, s[28:29]
	global_load_dwordx2 v[222:223], v[164:165], off
	global_load_dwordx2 v[218:219], v[166:167], off
	s_and_b64 vcc, exec, s[14:15]
	v_lshl_add_u64 v[206:207], v[160:161], 4, s[26:27]
	v_lshl_add_u64 v[208:209], v[162:163], 4, s[26:27]
	s_cbranch_vccnz .LBB0_285
	global_load_dwordx4 v[156:159], v[206:207], off
	global_load_dwordx4 v[152:155], v[208:209], off
.LBB0_285:
	v_add_u32_e32 v160, 0x1800, v178
	v_add_u32_e32 v162, 0x1a00, v178
	v_ashrrev_i32_e32 v161, 31, v160
	v_lshl_add_u64 v[164:165], v[160:161], 3, s[28:29]
	v_ashrrev_i32_e32 v163, 31, v162
	v_lshl_add_u64 v[166:167], v[162:163], 3, s[28:29]
	global_load_dwordx2 v[214:215], v[164:165], off
	global_load_dwordx2 v[210:211], v[166:167], off
	s_and_b64 vcc, exec, s[14:15]
	v_lshl_add_u64 v[198:199], v[160:161], 4, s[26:27]
	v_lshl_add_u64 v[200:201], v[162:163], 4, s[26:27]
	s_cbranch_vccnz .LBB0_287
	global_load_dwordx4 v[148:151], v[198:199], off
	global_load_dwordx4 v[144:147], v[200:201], off
.LBB0_287:
	s_mov_b64 s[60:61], 0x8000
	v_lshlrev_b32_e32 v160, 16, v216
	v_and_b32_e32 v161, 0xffff0000, v216
	v_lshlrev_b32_e32 v162, 16, v217
	v_and_b32_e32 v163, 0xffff0000, v217
	v_lshlrev_b32_e32 v216, 16, v212
	v_and_b32_e32 v217, 0xffff0000, v212
	v_lshlrev_b32_e32 v212, 16, v213
	v_and_b32_e32 v213, 0xffff0000, v213
	v_lshl_add_u64 v[220:221], v[182:183], 0, s[60:61]
	v_pk_mul_f32 v[164:165], v[108:109], v[160:161]
	v_pk_mul_f32 v[166:167], v[110:111], v[162:163]
	v_pk_mul_f32 v[224:225], v[104:105], v[216:217]
	v_pk_mul_f32 v[230:231], v[106:107], v[212:213]
	v_pk_fma_f32 v[160:161], v[108:109], v[160:161], v[140:141]
	v_pk_fma_f32 v[162:163], v[110:111], v[162:163], v[142:143]
	v_pk_fma_f32 v[216:217], v[104:105], v[216:217], v[136:137]
	v_pk_fma_f32 v[212:213], v[106:107], v[212:213], v[138:139]
	v_cndmask_b32_e64 v163, v167, v163, s[8:9]
	v_cndmask_b32_e64 v162, v166, v162, s[8:9]
	v_cndmask_b32_e64 v161, v165, v161, s[8:9]
	v_cndmask_b32_e64 v160, v164, v160, s[8:9]
	v_cndmask_b32_e64 v167, v231, v213, s[8:9]
	v_cndmask_b32_e64 v166, v230, v212, s[8:9]
	v_cndmask_b32_e64 v165, v225, v217, s[8:9]
	v_cndmask_b32_e64 v164, v224, v216, s[8:9]
	s_mov_b64 s[96:97], -1
	s_and_b64 vcc, exec, s[12:13]
	v_lshl_add_u64 v[212:213], s[24:25], 0, v[220:221]
	s_cbranch_vccnz .LBB0_289
	s_add_u32 s60, s23, s0
	s_addc_u32 s61, s6, s1
	v_lshl_add_u64 v[216:217], s[60:61], 0, v[220:221]
	s_brev_b32 s60, 63
	s_mov_b32 s61, -1
	v_lshl_add_u64 v[216:217], v[216:217], 0, s[60:61]
	s_lshl_b32 s60, s3, 8
	v_cndmask_b32_e64 v217, v217, v213, s[10:11]
	v_cndmask_b32_e64 v216, v216, v212, s[10:11]
	s_ashr_i32 s61, s60, 31
	v_lshl_add_u64 v[216:217], s[60:61], 1, v[216:217]
	v_readlane_b32 s60, v253, 15
	v_readlane_b32 s61, v253, 16
	s_lshl_b32 s60, s7, 1
	s_mov_b32 s21, s61
	v_writelane_b32 v253, s20, 15
	v_lshl_add_u64 v[216:217], v[216:217], 0, s[60:61]
	v_cvt_pk_bf16_f32 v234, v160, v161
	v_cvt_pk_bf16_f32 v235, v162, v163
	v_cvt_pk_bf16_f32 v236, v164, v165
	v_cvt_pk_bf16_f32 v237, v166, v167
	v_writelane_b32 v253, s21, 16
	v_lshl_add_u64 v[216:217], v[180:181], 1, v[216:217]
	s_mov_b64 s[96:97], 0
	global_store_dwordx4 v[216:217], v[234:237], off
;     __device__ __forceinline__ void operator()(const f32x4 (&acc)[2][2][4][2], const Unit& u, int wr, int wc, int fr, int fq) const {
;     ...
;         const bool iso = sub >= 8, addm = (sub > 1) && !iso;
;         u32x2 gp[2][2][2]; f32x4 mp[2][2][2];
; #pragma unroll
;         for (int bj = 0; bj < 2; ++bj) {
;             const int i0 = ((bj * 4) * 2) * 512 + tid, i1 = i0 + 512;
;             gp[0][bj][0] = *(const u32x2*)(stg + (size_t)i0 * 2); gp[0][bj][1] = *(const u32x2*)(stg + (size_t)i1 * 2);
;             if (addm) { mp[0][bj][0] = *(const f32x4*)(stm + (size_t)i0 * 4); mp[0][bj][1] = *(const f32x4*)(stm + (size_t)i1 * 4); }
;         }
; #pragma unroll
;         for (int g = 0; g < 8; ++g) {
;             const int ai = g >> 2, m = g & 3;
;             const size_t row = (size_t)256 * u.pm + 128 * ai + 64 * wr + 16 * m + fr;
;             if (g + 1 < 8) {
;                 const int an = (g + 1) >> 2, mn = (g + 1) & 3;
; #pragma unroll
;                 for (int bj = 0; bj < 2; ++bj) {
;                     const int i0 = (((an * 2 + bj) * 4 + mn) * 2) * 512 + tid, i1 = i0 + 512;
;                     gp[(g + 1) & 1][bj][0] = *(const u32x2*)(stg + (size_t)i0 * 2); gp[(g + 1) & 1][bj][1] = *(const u32x2*)(stg + (size_t)i1 * 2);
;                     if (addm) { mp[(g + 1) & 1][bj][0] = *(const f32x4*)(stm + (size_t)i0 * 4); mp[(g + 1) & 1][bj][1] = *(const f32x4*)(stm + (size_t)i1 * 4); }
;                 }
;             }
;             asm volatile("" ::: "memory");
; #pragma unroll
;             for (int bj = 0; bj < 2; ++bj) {
;                 const int i0 = (((ai * 2 + bj) * 4 + m) * 2) * 512 + tid, i1 = i0 + 512;
;                 const u32x2 g0 = gp[g & 1][bj][0], g1 = gp[g & 1][bj][1];
;                 f32x4 a = acc[ai][bj][m][0], b = acc[ai][bj][m][1];
;                 a = a * (f32x4){bflo(g0.x), bfhi(g0.x), bflo(g0.y), bfhi(g0.y)}; b = b * (f32x4){bflo(g1.x), bfhi(g1.x), bflo(g1.y), bfhi(g1.y)};
;                 if (addm) { a += mp[g & 1][bj][0]; b += mp[g & 1][bj][1]; }
;                 if (sub < 5) { *(f32x4*)(stm + (size_t)i0 * 4) = a; *(f32x4*)(stm + (size_t)i1 * 4) = b; }
;                 else {
;                     u32x4 w; w.x = cvt_pk_bf16(a[0], a[1]); w.y = cvt_pk_bf16(a[2], a[3]); w.z = cvt_pk_bf16(b[0], b[1]); w.w = cvt_pk_bf16(b[2], b[3]);
.LBB0_289:
	s_andn2_b64 vcc, exec, s[96:97]
	s_cbranch_vccnz .LBB0_291
	global_store_dwordx4 v[188:189], v[160:163], off
	global_store_dwordx4 v[190:191], v[164:167], off
.LBB0_291:
	s_nop 0
	v_lshlrev_b32_e32 v160, 16, v204
	v_and_b32_e32 v161, 0xffff0000, v204
	v_lshlrev_b32_e32 v162, 16, v205
	v_and_b32_e32 v163, 0xffff0000, v205
	v_lshlrev_b32_e32 v188, 16, v202
	v_and_b32_e32 v189, 0xffff0000, v202
	v_lshlrev_b32_e32 v190, 16, v203
	v_and_b32_e32 v191, 0xffff0000, v203
	v_pk_mul_f32 v[164:165], v[100:101], v[160:161]
	v_pk_mul_f32 v[166:167], v[102:103], v[162:163]
	v_pk_mul_f32 v[202:203], v[96:97], v[188:189]
	v_pk_mul_f32 v[204:205], v[98:99], v[190:191]
	v_pk_fma_f32 v[160:161], v[100:101], v[160:161], v[132:133]
	v_pk_fma_f32 v[162:163], v[102:103], v[162:163], v[134:135]
	v_pk_fma_f32 v[188:189], v[96:97], v[188:189], v[128:129]
	v_pk_fma_f32 v[190:191], v[98:99], v[190:191], v[130:131]
	v_cndmask_b32_e64 v163, v167, v163, s[8:9]
	v_cndmask_b32_e64 v162, v166, v162, s[8:9]
	v_cndmask_b32_e64 v161, v165, v161, s[8:9]
	v_cndmask_b32_e64 v160, v164, v160, s[8:9]
	v_cndmask_b32_e64 v167, v205, v191, s[8:9]
	v_cndmask_b32_e64 v166, v204, v190, s[8:9]
	v_cndmask_b32_e64 v165, v203, v189, s[8:9]
	v_cndmask_b32_e64 v164, v202, v188, s[8:9]
	s_and_b64 vcc, exec, s[12:13]
	s_mov_b64 s[96:97], -1
	s_cbranch_vccnz .LBB0_293
	s_add_u32 s60, s23, s0
	s_addc_u32 s61, s6, s1
	v_lshl_add_u64 v[202:203], s[60:61], 0, v[220:221]
	s_brev_b32 s60, 63
	s_mov_b32 s61, -1
	v_lshl_add_u64 v[202:203], v[202:203], 0, s[60:61]
	s_lshl_b32 s60, s3, 8
	v_cndmask_b32_e64 v203, v203, v213, s[10:11]
	v_cndmask_b32_e64 v202, v202, v212, s[10:11]
	s_ashr_i32 s61, s60, 31
	v_lshl_add_u64 v[202:203], s[60:61], 1, v[202:203]
	v_readlane_b32 s60, v253, 15
	v_readlane_b32 s61, v253, 16
	s_lshl_b32 s60, s7, 1
	s_mov_b32 s21, s61
	v_writelane_b32 v253, s20, 15
	v_lshl_add_u64 v[202:203], v[202:203], 0, s[60:61]
	v_cvt_pk_bf16_f32 v188, v160, v161
	v_cvt_pk_bf16_f32 v189, v162, v163
	v_cvt_pk_bf16_f32 v190, v164, v165
	v_cvt_pk_bf16_f32 v191, v166, v167
	v_writelane_b32 v253, s21, 16
	v_lshl_add_u64 v[202:203], v[180:181], 1, v[202:203]
	s_mov_b64 s[96:97], 0
	global_store_dwordx4 v[202:203], v[188:191], off offset:256
.LBB0_293:
	s_andn2_b64 vcc, exec, s[96:97]
	s_cbranch_vccnz .LBB0_295
	global_store_dwordx4 v[184:185], v[160:163], off
	global_store_dwordx4 v[186:187], v[164:167], off
.LBB0_295:
	s_nop 0
	v_add_u32_e32 v160, 0xc00, v178
	v_add_u32_e32 v162, 0xe00, v178
	v_ashrrev_i32_e32 v161, 31, v160
	v_lshl_add_u64 v[164:165], v[160:161], 3, s[28:29]
	v_ashrrev_i32_e32 v163, 31, v162
	v_lshl_add_u64 v[166:167], v[162:163], 3, s[28:29]
	global_load_dwordx2 v[224:225], v[164:165], off
	global_load_dwordx2 v[220:221], v[166:167], off
	s_and_b64 vcc, exec, s[14:15]
	v_lshl_add_u64 v[202:203], v[160:161], 4, s[26:27]
	v_lshl_add_u64 v[204:205], v[162:163], 4, s[26:27]
	s_cbranch_vccnz .LBB0_297
	global_load_dwordx4 v[140:143], v[202:203], off
	global_load_dwordx4 v[136:139], v[204:205], off
.LBB0_297:
	v_add_u32_e32 v160, 0x1c00, v178
	v_add_u32_e32 v162, 0x1e00, v178
	v_ashrrev_i32_e32 v161, 31, v160
	v_lshl_add_u64 v[164:165], v[160:161], 3, s[28:29]
	v_ashrrev_i32_e32 v163, 31, v162
	v_lshl_add_u64 v[166:167], v[162:163], 3, s[28:29]
	global_load_dwordx2 v[216:217], v[164:165], off
	global_load_dwordx2 v[212:213], v[166:167], off
	s_and_b64 vcc, exec, s[14:15]
	v_lshl_add_u64 v[188:189], v[160:161], 4, s[26:27]
	v_lshl_add_u64 v[190:191], v[162:163], 4, s[26:27]
	s_cbranch_vccnz .LBB0_299
	global_load_dwordx4 v[132:135], v[188:189], off
	global_load_dwordx4 v[128:131], v[190:191], off
; __device__ __forceinline__ unsigned cvt_pk_bf16(float lo, float hi) { f32x2 v = {lo, hi}; bf16x2_t b = __builtin_convertvector(v, bf16x2_t); return __builtin_bit_cast(unsigned, b); }
; __device__ __forceinline__ float bflo(unsigned w) { return __uint_as_float(w << 16); }
; __device__ __forceinline__ float bfhi(unsigned w) { return __uint_as_float(w & 0xffff0000u); }
;     __device__ __forceinline__ void operator()(const f32x4 (&acc)[2][2][4][2], const Unit& u, int wr, int wc, int fr, int fq) const {
;     ...
;             if (g + 1 < 8) {
;                 const int an = (g + 1) >> 2, mn = (g + 1) & 3;
; #pragma unroll
;                 for (int bj = 0; bj < 2; ++bj) {
;                     const int i0 = (((an * 2 + bj) * 4 + mn) * 2) * 512 + tid, i1 = i0 + 512;
;                     gp[(g + 1) & 1][bj][0] = *(const u32x2*)(stg + (size_t)i0 * 2); gp[(g + 1) & 1][bj][1] = *(const u32x2*)(stg + (size_t)i1 * 2);
;                     if (addm) { mp[(g + 1) & 1][bj][0] = *(const f32x4*)(stm + (size_t)i0 * 4); mp[(g + 1) & 1][bj][1] = *(const f32x4*)(stm + (size_t)i1 * 4); }
;                 }
;             }
;             asm volatile("" ::: "memory");
; #pragma unroll
;             for (int bj = 0; bj < 2; ++bj) {
;                 const int i0 = (((ai * 2 + bj) * 4 + m) * 2) * 512 + tid, i1 = i0 + 512;
;                 const u32x2 g0 = gp[g & 1][bj][0], g1 = gp[g & 1][bj][1];
;                 f32x4 a = acc[ai][bj][m][0], b = acc[ai][bj][m][1];
;                 a = a * (f32x4){bflo(g0.x), bfhi(g0.x), bflo(g0.y), bfhi(g0.y)}; b = b * (f32x4){bflo(g1.x), bfhi(g1.x), bflo(g1.y), bfhi(g1.y)};
;                 if (addm) { a += mp[g & 1][bj][0]; b += mp[g & 1][bj][1]; }
;                 if (sub < 5) { *(f32x4*)(stm + (size_t)i0 * 4) = a; *(f32x4*)(stm + (size_t)i1 * 4) = b; }
;                 else {
;                     u32x4 w; w.x = cvt_pk_bf16(a[0], a[1]); w.y = cvt_pk_bf16(a[2], a[3]); w.z = cvt_pk_bf16(b[0], b[1]); w.w = cvt_pk_bf16(b[2], b[3]);
;                     bf16_t* dst = iso ? MCTX + (size_t)((sub - 8) >> 1) * NCTX * 1024 + (row - NLAT) * 1024 : M + row * 1024;
;                     *(u32x4*)(dst + 256 * u.pn + 128 * bj + 32 * wc + 8 * fq) = w;
.LBB0_299:
	s_mov_b64 s[60:61], 0x10000
	s_waitcnt vmcnt(0) lgkmcnt(0)
	v_lshlrev_b32_e32 v160, 16, v222
	v_and_b32_e32 v161, 0xffff0000, v222
	v_lshlrev_b32_e32 v162, 16, v223
	v_and_b32_e32 v163, 0xffff0000, v223
	v_lshlrev_b32_e32 v186, 16, v218
	v_and_b32_e32 v187, 0xffff0000, v218
	v_lshlrev_b32_e32 v218, 16, v219
	v_and_b32_e32 v219, 0xffff0000, v219
	v_lshl_add_u64 v[184:185], v[182:183], 0, s[60:61]
	v_pk_mul_f32 v[164:165], v[92:93], v[160:161]
	v_pk_mul_f32 v[166:167], v[94:95], v[162:163]
	v_pk_mul_f32 v[222:223], v[88:89], v[186:187]
	v_pk_mul_f32 v[230:231], v[90:91], v[218:219]
	v_pk_fma_f32 v[160:161], v[92:93], v[160:161], v[156:157]
	v_pk_fma_f32 v[162:163], v[94:95], v[162:163], v[158:159]
	v_pk_fma_f32 v[186:187], v[88:89], v[186:187], v[152:153]
	v_pk_fma_f32 v[218:219], v[90:91], v[218:219], v[154:155]
	v_cndmask_b32_e64 v163, v167, v163, s[8:9]
	v_cndmask_b32_e64 v162, v166, v162, s[8:9]
	v_cndmask_b32_e64 v161, v165, v161, s[8:9]
	v_cndmask_b32_e64 v160, v164, v160, s[8:9]
	v_cndmask_b32_e64 v167, v231, v219, s[8:9]
	v_cndmask_b32_e64 v166, v230, v218, s[8:9]
	v_cndmask_b32_e64 v165, v223, v187, s[8:9]
	v_cndmask_b32_e64 v164, v222, v186, s[8:9]
	s_mov_b64 s[96:97], -1
	s_and_b64 vcc, exec, s[12:13]
	v_lshl_add_u64 v[186:187], s[24:25], 0, v[184:185]
	s_cbranch_vccnz .LBB0_301
	s_add_u32 s60, s23, s0
	s_addc_u32 s61, s6, s1
	v_lshl_add_u64 v[218:219], s[60:61], 0, v[184:185]
	s_brev_b32 s60, 63
	s_mov_b32 s61, -1
	v_lshl_add_u64 v[218:219], v[218:219], 0, s[60:61]
	s_lshl_b32 s60, s3, 8
	v_cndmask_b32_e64 v219, v219, v187, s[10:11]
	v_cndmask_b32_e64 v218, v218, v186, s[10:11]
	s_ashr_i32 s61, s60, 31
	v_lshl_add_u64 v[218:219], s[60:61], 1, v[218:219]
	v_readlane_b32 s60, v253, 15
	v_readlane_b32 s61, v253, 16
	s_lshl_b32 s60, s7, 1
	s_mov_b32 s21, s61
	v_writelane_b32 v253, s20, 15
	v_lshl_add_u64 v[218:219], v[218:219], 0, s[60:61]
	v_cvt_pk_bf16_f32 v234, v160, v161
	v_cvt_pk_bf16_f32 v235, v162, v163
	v_cvt_pk_bf16_f32 v236, v164, v165
	v_cvt_pk_bf16_f32 v237, v166, v167
	v_writelane_b32 v253, s21, 16
	v_lshl_add_u64 v[218:219], v[180:181], 1, v[218:219]
	s_mov_b64 s[96:97], 0
	global_store_dwordx4 v[218:219], v[234:237], off
.LBB0_301:
	s_andn2_b64 vcc, exec, s[96:97]
	s_cbranch_vccnz .LBB0_303
	global_store_dwordx4 v[206:207], v[160:163], off
	global_store_dwordx4 v[208:209], v[164:167], off
.LBB0_303:
	s_nop 0
	v_lshlrev_b32_e32 v160, 16, v214
	v_and_b32_e32 v161, 0xffff0000, v214
	v_lshlrev_b32_e32 v162, 16, v215
	v_and_b32_e32 v163, 0xffff0000, v215
	v_lshlrev_b32_e32 v206, 16, v210
	v_and_b32_e32 v207, 0xffff0000, v210
	v_lshlrev_b32_e32 v208, 16, v211
	v_and_b32_e32 v209, 0xffff0000, v211
	v_pk_mul_f32 v[164:165], v[84:85], v[160:161]
	v_pk_mul_f32 v[166:167], v[86:87], v[162:163]
	v_pk_mul_f32 v[210:211], v[80:81], v[206:207]
	v_pk_mul_f32 v[214:215], v[82:83], v[208:209]
	v_pk_fma_f32 v[160:161], v[84:85], v[160:161], v[148:149]
	v_pk_fma_f32 v[162:163], v[86:87], v[162:163], v[150:151]
	v_pk_fma_f32 v[206:207], v[80:81], v[206:207], v[144:145]
	v_pk_fma_f32 v[208:209], v[82:83], v[208:209], v[146:147]
	v_cndmask_b32_e64 v163, v167, v163, s[8:9]
	v_cndmask_b32_e64 v162, v166, v162, s[8:9]
	v_cndmask_b32_e64 v161, v165, v161, s[8:9]
	v_cndmask_b32_e64 v160, v164, v160, s[8:9]
	v_cndmask_b32_e64 v167, v215, v209, s[8:9]
	v_cndmask_b32_e64 v166, v214, v208, s[8:9]
	v_cndmask_b32_e64 v165, v211, v207, s[8:9]
	v_cndmask_b32_e64 v164, v210, v206, s[8:9]
	s_and_b64 vcc, exec, s[12:13]
	s_mov_b64 s[96:97], -1
	s_cbranch_vccnz .LBB0_305
	s_add_u32 s60, s23, s0
	s_addc_u32 s61, s6, s1
	v_lshl_add_u64 v[184:185], s[60:61], 0, v[184:185]
	s_brev_b32 s60, 63
	s_mov_b32 s61, -1
	v_lshl_add_u64 v[184:185], v[184:185], 0, s[60:61]
	s_lshl_b32 s60, s3, 8
	v_cndmask_b32_e64 v185, v185, v187, s[10:11]
	v_cndmask_b32_e64 v184, v184, v186, s[10:11]
	s_ashr_i32 s61, s60, 31
	v_lshl_add_u64 v[184:185], s[60:61], 1, v[184:185]
	v_readlane_b32 s60, v253, 15
	v_readlane_b32 s61, v253, 16
	s_lshl_b32 s60, s7, 1
	s_mov_b32 s21, s61
	v_writelane_b32 v253, s20, 15
	v_lshl_add_u64 v[184:185], v[184:185], 0, s[60:61]
	v_cvt_pk_bf16_f32 v206, v160, v161
	v_cvt_pk_bf16_f32 v207, v162, v163
	v_cvt_pk_bf16_f32 v208, v164, v165
	v_cvt_pk_bf16_f32 v209, v166, v167
	v_writelane_b32 v253, s21, 16
	v_lshl_add_u64 v[184:185], v[180:181], 1, v[184:185]
	s_mov_b64 s[96:97], 0
	global_store_dwordx4 v[184:185], v[206:209], off offset:256

; __device__ __forceinline__ unsigned cvt_pk_bf16(float lo, float hi) { f32x2 v = {lo, hi}; bf16x2_t b = __builtin_convertvector(v, bf16x2_t); return __builtin_bit_cast(unsigned, b); }
; __device__ __forceinline__ float bflo(unsigned w) { return __uint_as_float(w << 16); }
; __device__ __forceinline__ float bfhi(unsigned w) { return __uint_as_float(w & 0xffff0000u); }
;     __device__ __forceinline__ void operator()(const f32x4 (&acc)[2][2][4][2], const Unit& u, int wr, int wc, int fr, int fq) const {
;     ...
;             if (g + 1 < 8) {
;                 const int an = (g + 1) >> 2, mn = (g + 1) & 3;
; #pragma unroll
;                 for (int bj = 0; bj < 2; ++bj) {
;                     const int i0 = (((an * 2 + bj) * 4 + mn) * 2) * 512 + tid, i1 = i0 + 512;
;                     gp[(g + 1) & 1][bj][0] = *(const u32x2*)(stg + (size_t)i0 * 2); gp[(g + 1) & 1][bj][1] = *(const u32x2*)(stg + (size_t)i1 * 2);
;                     if (addm) { mp[(g + 1) & 1][bj][0] = *(const f32x4*)(stm + (size_t)i0 * 4); mp[(g + 1) & 1][bj][1] = *(const f32x4*)(stm + (size_t)i1 * 4); }
;                 }
;             }
;             asm volatile("" ::: "memory");
; #pragma unroll
;             for (int bj = 0; bj < 2; ++bj) {
;                 const int i0 = (((ai * 2 + bj) * 4 + m) * 2) * 512 + tid, i1 = i0 + 512;
;                 const u32x2 g0 = gp[g & 1][bj][0], g1 = gp[g & 1][bj][1];
;                 f32x4 a = acc[ai][bj][m][0], b = acc[ai][bj][m][1];
;                 a = a * (f32x4){bflo(g0.x), bfhi(g0.x), bflo(g0.y), bfhi(g0.y)}; b = b * (f32x4){bflo(g1.x), bfhi(g1.x), bflo(g1.y), bfhi(g1.y)};
;                 if (addm) { a += mp[g & 1][bj][0]; b += mp[g & 1][bj][1]; }
;                 if (sub < 5) { *(f32x4*)(stm + (size_t)i0 * 4) = a; *(f32x4*)(stm + (size_t)i1 * 4) = b; }
;                 else {
;                     u32x4 w; w.x = cvt_pk_bf16(a[0], a[1]); w.y = cvt_pk_bf16(a[2], a[3]); w.z = cvt_pk_bf16(b[0], b[1]); w.w = cvt_pk_bf16(b[2], b[3]);
;                     bf16_t* dst = iso ? MCTX + (size_t)((sub - 8) >> 1) * NCTX * 1024 + (row - NLAT) * 1024 : M + row * 1024;
;                     *(u32x4*)(dst + 256 * u.pn + 128 * bj + 32 * wc + 8 * fq) = w;
.LBB0_307:
	s_nop 0
	v_add_u32_e32 v160, 0x2000, v178
	v_add_u32_e32 v162, 0x2200, v178
	v_ashrrev_i32_e32 v161, 31, v160
	v_lshl_add_u64 v[164:165], v[160:161], 3, s[28:29]
	v_ashrrev_i32_e32 v163, 31, v162
	v_lshl_add_u64 v[166:167], v[162:163], 3, s[28:29]
	global_load_dwordx2 v[218:219], v[164:165], off
	global_load_dwordx2 v[214:215], v[166:167], off
	s_and_b64 vcc, exec, s[14:15]
	v_lshl_add_u64 v[198:199], v[160:161], 4, s[26:27]
	v_lshl_add_u64 v[200:201], v[162:163], 4, s[26:27]
	s_cbranch_vccnz .LBB0_309
	global_load_dwordx4 v[156:159], v[198:199], off
	global_load_dwordx4 v[152:155], v[200:201], off
.LBB0_309:
	v_add_u32_e32 v160, 0x3000, v178
	v_add_u32_e32 v162, 0x3200, v178
	v_ashrrev_i32_e32 v161, 31, v160
	v_lshl_add_u64 v[164:165], v[160:161], 3, s[28:29]
	v_ashrrev_i32_e32 v163, 31, v162
	v_lshl_add_u64 v[166:167], v[162:163], 3, s[28:29]
	global_load_dwordx2 v[210:211], v[164:165], off
	global_load_dwordx2 v[206:207], v[166:167], off
	s_and_b64 vcc, exec, s[14:15]
	v_lshl_add_u64 v[184:185], v[160:161], 4, s[26:27]
	v_lshl_add_u64 v[186:187], v[162:163], 4, s[26:27]
	s_cbranch_vccnz .LBB0_311
	global_load_dwordx4 v[148:151], v[184:185], off
	global_load_dwordx4 v[144:147], v[186:187], off
.LBB0_311:
	s_mov_b64 s[60:61], 0x18000
	v_lshlrev_b32_e32 v160, 16, v224
	v_and_b32_e32 v161, 0xffff0000, v224
	v_lshlrev_b32_e32 v162, 16, v225
	v_and_b32_e32 v163, 0xffff0000, v225
	v_lshlrev_b32_e32 v222, 16, v220
	v_and_b32_e32 v223, 0xffff0000, v220
	v_lshlrev_b32_e32 v220, 16, v221
	v_and_b32_e32 v221, 0xffff0000, v221
	v_lshl_add_u64 v[208:209], v[182:183], 0, s[60:61]
	v_pk_mul_f32 v[164:165], v[76:77], v[160:161]
	v_pk_mul_f32 v[166:167], v[78:79], v[162:163]
	v_pk_mul_f32 v[224:225], v[72:73], v[222:223]
	v_pk_mul_f32 v[230:231], v[74:75], v[220:221]
	v_pk_fma_f32 v[160:161], v[76:77], v[160:161], v[140:141]
	v_pk_fma_f32 v[162:163], v[78:79], v[162:163], v[142:143]
	v_pk_fma_f32 v[222:223], v[72:73], v[222:223], v[136:137]
	v_pk_fma_f32 v[220:221], v[74:75], v[220:221], v[138:139]
	v_cndmask_b32_e64 v163, v167, v163, s[8:9]
	v_cndmask_b32_e64 v162, v166, v162, s[8:9]
	v_cndmask_b32_e64 v161, v165, v161, s[8:9]
	v_cndmask_b32_e64 v160, v164, v160, s[8:9]
	v_cndmask_b32_e64 v167, v231, v221, s[8:9]
	v_cndmask_b32_e64 v166, v230, v220, s[8:9]
	v_cndmask_b32_e64 v165, v225, v223, s[8:9]
	v_cndmask_b32_e64 v164, v224, v222, s[8:9]
	s_mov_b64 s[96:97], -1
	s_and_b64 vcc, exec, s[12:13]
	v_lshl_add_u64 v[220:221], s[24:25], 0, v[208:209]
	s_cbranch_vccnz .LBB0_313
	s_add_u32 s60, s23, s0
	s_addc_u32 s61, s6, s1
	v_lshl_add_u64 v[230:231], s[60:61], 0, v[208:209]
	s_brev_b32 s60, 63
	s_mov_b32 s61, -1
	v_lshl_add_u64 v[230:231], v[230:231], 0, s[60:61]
	s_lshl_b32 s60, s3, 8
	v_cndmask_b32_e64 v231, v231, v221, s[10:11]
	v_cndmask_b32_e64 v230, v230, v220, s[10:11]
	s_ashr_i32 s61, s60, 31
	v_lshl_add_u64 v[230:231], s[60:61], 1, v[230:231]
	v_readlane_b32 s60, v253, 15
	v_readlane_b32 s61, v253, 16
	s_lshl_b32 s60, s7, 1
	s_mov_b32 s21, s61
	v_writelane_b32 v253, s20, 15
	v_lshl_add_u64 v[230:231], v[230:231], 0, s[60:61]
	v_cvt_pk_bf16_f32 v222, v160, v161
	v_cvt_pk_bf16_f32 v223, v162, v163
	v_cvt_pk_bf16_f32 v224, v164, v165
	v_cvt_pk_bf16_f32 v225, v166, v167
	v_writelane_b32 v253, s21, 16
	v_lshl_add_u64 v[230:231], v[180:181], 1, v[230:231]
	s_mov_b64 s[96:97], 0
	global_store_dwordx4 v[230:231], v[222:225], off
.LBB0_313:
	s_andn2_b64 vcc, exec, s[96:97]
	s_cbranch_vccnz .LBB0_315
	global_store_dwordx4 v[202:203], v[160:163], off
	global_store_dwordx4 v[204:205], v[164:167], off
.LBB0_315:
	s_nop 0
	v_lshlrev_b32_e32 v160, 16, v216
	v_and_b32_e32 v161, 0xffff0000, v216
	v_lshlrev_b32_e32 v162, 16, v217
	v_and_b32_e32 v163, 0xffff0000, v217
	v_lshlrev_b32_e32 v202, 16, v212
	v_and_b32_e32 v203, 0xffff0000, v212
	v_lshlrev_b32_e32 v204, 16, v213
	v_and_b32_e32 v205, 0xffff0000, v213
	v_pk_mul_f32 v[164:165], v[68:69], v[160:161]
	v_pk_mul_f32 v[166:167], v[70:71], v[162:163]
	v_pk_mul_f32 v[212:213], v[64:65], v[202:203]
	v_pk_mul_f32 v[216:217], v[66:67], v[204:205]
	v_pk_fma_f32 v[160:161], v[68:69], v[160:161], v[132:133]
	v_pk_fma_f32 v[162:163], v[70:71], v[162:163], v[134:135]
	v_pk_fma_f32 v[202:203], v[64:65], v[202:203], v[128:129]
	v_pk_fma_f32 v[204:205], v[66:67], v[204:205], v[130:131]
	v_cndmask_b32_e64 v163, v167, v163, s[8:9]
	v_cndmask_b32_e64 v162, v166, v162, s[8:9]
	v_cndmask_b32_e64 v161, v165, v161, s[8:9]
	v_cndmask_b32_e64 v160, v164, v160, s[8:9]
	v_cndmask_b32_e64 v167, v217, v205, s[8:9]
	v_cndmask_b32_e64 v166, v216, v204, s[8:9]
	v_cndmask_b32_e64 v165, v213, v203, s[8:9]
	v_cndmask_b32_e64 v164, v212, v202, s[8:9]
	s_and_b64 vcc, exec, s[12:13]
	s_mov_b64 s[96:97], -1
	s_cbranch_vccnz .LBB0_317
	s_add_u32 s60, s23, s0
	s_addc_u32 s61, s6, s1
	v_lshl_add_u64 v[208:209], s[60:61], 0, v[208:209]
	s_brev_b32 s60, 63
	s_mov_b32 s61, -1
	v_lshl_add_u64 v[208:209], v[208:209], 0, s[60:61]
	s_lshl_b32 s60, s3, 8
	v_cndmask_b32_e64 v209, v209, v221, s[10:11]
	v_cndmask_b32_e64 v208, v208, v220, s[10:11]
	s_ashr_i32 s61, s60, 31
	v_lshl_add_u64 v[208:209], s[60:61], 1, v[208:209]
	v_readlane_b32 s60, v253, 15
	v_readlane_b32 s61, v253, 16
	s_lshl_b32 s60, s7, 1
	s_mov_b32 s21, s61
	v_writelane_b32 v253, s20, 15
	v_lshl_add_u64 v[208:209], v[208:209], 0, s[60:61]
	v_cvt_pk_bf16_f32 v202, v160, v161
	v_cvt_pk_bf16_f32 v203, v162, v163
	v_cvt_pk_bf16_f32 v204, v164, v165
	v_cvt_pk_bf16_f32 v205, v166, v167
	v_writelane_b32 v253, s21, 16
	v_lshl_add_u64 v[208:209], v[180:181], 1, v[208:209]
	s_mov_b64 s[96:97], 0
	global_store_dwordx4 v[208:209], v[202:205], off offset:256

; __device__ __forceinline__ unsigned cvt_pk_bf16(float lo, float hi) { f32x2 v = {lo, hi}; bf16x2_t b = __builtin_convertvector(v, bf16x2_t); return __builtin_bit_cast(unsigned, b); }
; __device__ __forceinline__ float bflo(unsigned w) { return __uint_as_float(w << 16); }
; __device__ __forceinline__ float bfhi(unsigned w) { return __uint_as_float(w & 0xffff0000u); }
;     __device__ __forceinline__ void operator()(const f32x4 (&acc)[2][2][4][2], const Unit& u, int wr, int wc, int fr, int fq) const {
;     ...
;             if (g + 1 < 8) {
;                 const int an = (g + 1) >> 2, mn = (g + 1) & 3;
; #pragma unroll
;                 for (int bj = 0; bj < 2; ++bj) {
;                     const int i0 = (((an * 2 + bj) * 4 + mn) * 2) * 512 + tid, i1 = i0 + 512;
;                     gp[(g + 1) & 1][bj][0] = *(const u32x2*)(stg + (size_t)i0 * 2); gp[(g + 1) & 1][bj][1] = *(const u32x2*)(stg + (size_t)i1 * 2);
;                     if (addm) { mp[(g + 1) & 1][bj][0] = *(const f32x4*)(stm + (size_t)i0 * 4); mp[(g + 1) & 1][bj][1] = *(const f32x4*)(stm + (size_t)i1 * 4); }
;                 }
;             }
;             asm volatile("" ::: "memory");
; #pragma unroll
;             for (int bj = 0; bj < 2; ++bj) {
;                 const int i0 = (((ai * 2 + bj) * 4 + m) * 2) * 512 + tid, i1 = i0 + 512;
;                 const u32x2 g0 = gp[g & 1][bj][0], g1 = gp[g & 1][bj][1];
;                 f32x4 a = acc[ai][bj][m][0], b = acc[ai][bj][m][1];
;                 a = a * (f32x4){bflo(g0.x), bfhi(g0.x), bflo(g0.y), bfhi(g0.y)}; b = b * (f32x4){bflo(g1.x), bfhi(g1.x), bflo(g1.y), bfhi(g1.y)};
;                 if (addm) { a += mp[g & 1][bj][0]; b += mp[g & 1][bj][1]; }
;                 if (sub < 5) { *(f32x4*)(stm + (size_t)i0 * 4) = a; *(f32x4*)(stm + (size_t)i1 * 4) = b; }
;                 else {
;                     u32x4 w; w.x = cvt_pk_bf16(a[0], a[1]); w.y = cvt_pk_bf16(a[2], a[3]); w.z = cvt_pk_bf16(b[0], b[1]); w.w = cvt_pk_bf16(b[2], b[3]);
;                     bf16_t* dst = iso ? MCTX + (size_t)((sub - 8) >> 1) * NCTX * 1024 + (row - NLAT) * 1024 : M + row * 1024;
;                     *(u32x4*)(dst + 256 * u.pn + 128 * bj + 32 * wc + 8 * fq) = w;
.LBB0_319:
	s_nop 0
	v_add_u32_e32 v160, 0x2400, v178
	v_add_u32_e32 v162, 0x2600, v178
	v_ashrrev_i32_e32 v161, 31, v160
	v_lshl_add_u64 v[164:165], v[160:161], 3, s[28:29]
	v_ashrrev_i32_e32 v163, 31, v162
	v_lshl_add_u64 v[166:167], v[162:163], 3, s[28:29]
	global_load_dwordx2 v[220:221], v[164:165], off
	global_load_dwordx2 v[216:217], v[166:167], off
	s_and_b64 vcc, exec, s[14:15]
	v_lshl_add_u64 v[202:203], v[160:161], 4, s[26:27]
	v_lshl_add_u64 v[204:205], v[162:163], 4, s[26:27]
	s_cbranch_vccnz .LBB0_321
	global_load_dwordx4 v[140:143], v[202:203], off
	global_load_dwordx4 v[136:139], v[204:205], off
.LBB0_321:
	v_add_u32_e32 v160, 0x3400, v178
	v_add_u32_e32 v162, 0x3600, v178
	v_ashrrev_i32_e32 v161, 31, v160
	v_lshl_add_u64 v[164:165], v[160:161], 3, s[28:29]
	v_ashrrev_i32_e32 v163, 31, v162
	v_lshl_add_u64 v[166:167], v[162:163], 3, s[28:29]
	global_load_dwordx2 v[212:213], v[164:165], off
	global_load_dwordx2 v[208:209], v[166:167], off
	s_and_b64 vcc, exec, s[14:15]
	v_lshl_add_u64 v[188:189], v[160:161], 4, s[26:27]
	v_lshl_add_u64 v[190:191], v[162:163], 4, s[26:27]
	s_cbranch_vccnz .LBB0_323
	global_load_dwordx4 v[132:135], v[188:189], off
	global_load_dwordx4 v[128:131], v[190:191], off
.LBB0_323:
	s_mov_b64 s[60:61], 0x40000
	s_waitcnt vmcnt(0) lgkmcnt(0)
	v_lshlrev_b32_e32 v160, 16, v218
	v_and_b32_e32 v161, 0xffff0000, v218
	v_lshlrev_b32_e32 v162, 16, v219
	v_and_b32_e32 v163, 0xffff0000, v219
	v_lshlrev_b32_e32 v218, 16, v214
	v_and_b32_e32 v219, 0xffff0000, v214
	v_lshlrev_b32_e32 v214, 16, v215
	v_and_b32_e32 v215, 0xffff0000, v215
	v_lshl_add_u64 v[222:223], v[182:183], 0, s[60:61]
	v_pk_mul_f32 v[164:165], v[60:61], v[160:161]
	v_pk_mul_f32 v[166:167], v[62:63], v[162:163]
	v_pk_mul_f32 v[224:225], v[56:57], v[218:219]
	v_pk_mul_f32 v[230:231], v[58:59], v[214:215]
	v_pk_fma_f32 v[160:161], v[60:61], v[160:161], v[156:157]
	v_pk_fma_f32 v[162:163], v[62:63], v[162:163], v[158:159]
	v_pk_fma_f32 v[218:219], v[56:57], v[218:219], v[152:153]
	v_pk_fma_f32 v[214:215], v[58:59], v[214:215], v[154:155]
	v_cndmask_b32_e64 v163, v167, v163, s[8:9]
	v_cndmask_b32_e64 v162, v166, v162, s[8:9]
	v_cndmask_b32_e64 v161, v165, v161, s[8:9]
	v_cndmask_b32_e64 v160, v164, v160, s[8:9]
	v_cndmask_b32_e64 v167, v231, v215, s[8:9]
	v_cndmask_b32_e64 v166, v230, v214, s[8:9]
	v_cndmask_b32_e64 v165, v225, v219, s[8:9]
	v_cndmask_b32_e64 v164, v224, v218, s[8:9]
	s_mov_b64 s[96:97], -1
	s_and_b64 vcc, exec, s[12:13]
	v_lshl_add_u64 v[214:215], s[24:25], 0, v[222:223]
	s_cbranch_vccnz .LBB0_325
	s_add_u32 s60, s23, s0
	s_addc_u32 s61, s6, s1
	v_lshl_add_u64 v[218:219], s[60:61], 0, v[222:223]
	s_brev_b32 s60, 63
	s_mov_b32 s61, -1
	v_lshl_add_u64 v[218:219], v[218:219], 0, s[60:61]
	s_lshl_b32 s60, s3, 8
	v_cndmask_b32_e64 v219, v219, v215, s[10:11]
	v_cndmask_b32_e64 v218, v218, v214, s[10:11]
	s_ashr_i32 s61, s60, 31
	v_lshl_add_u64 v[218:219], s[60:61], 1, v[218:219]
	v_readlane_b32 s60, v253, 15
	v_readlane_b32 s61, v253, 16
	s_lshl_b32 s60, s7, 1
	s_mov_b32 s21, s61
	v_writelane_b32 v253, s20, 15
	v_lshl_add_u64 v[218:219], v[218:219], 0, s[60:61]
	v_cvt_pk_bf16_f32 v234, v160, v161
	v_cvt_pk_bf16_f32 v235, v162, v163
	v_cvt_pk_bf16_f32 v236, v164, v165
	v_cvt_pk_bf16_f32 v237, v166, v167
	v_writelane_b32 v253, s21, 16
	v_lshl_add_u64 v[218:219], v[180:181], 1, v[218:219]
	s_mov_b64 s[96:97], 0
	global_store_dwordx4 v[218:219], v[234:237], off

; __device__ __forceinline__ unsigned cvt_pk_bf16(float lo, float hi) { f32x2 v = {lo, hi}; bf16x2_t b = __builtin_convertvector(v, bf16x2_t); return __builtin_bit_cast(unsigned, b); }
; __device__ __forceinline__ float bflo(unsigned w) { return __uint_as_float(w << 16); }
; __device__ __forceinline__ float bfhi(unsigned w) { return __uint_as_float(w & 0xffff0000u); }
;     __device__ __forceinline__ void operator()(const f32x4 (&acc)[2][2][4][2], const Unit& u, int wr, int wc, int fr, int fq) const {
;     ...
;             for (int bj = 0; bj < 2; ++bj) {
;                 const int i0 = (((ai * 2 + bj) * 4 + m) * 2) * 512 + tid, i1 = i0 + 512;
;                 const u32x2 g0 = gp[g & 1][bj][0], g1 = gp[g & 1][bj][1];
;                 f32x4 a = acc[ai][bj][m][0], b = acc[ai][bj][m][1];
;                 a = a * (f32x4){bflo(g0.x), bfhi(g0.x), bflo(g0.y), bfhi(g0.y)}; b = b * (f32x4){bflo(g1.x), bfhi(g1.x), bflo(g1.y), bfhi(g1.y)};
;                 if (addm) { a += mp[g & 1][bj][0]; b += mp[g & 1][bj][1]; }
;                 if (sub < 5) { *(f32x4*)(stm + (size_t)i0 * 4) = a; *(f32x4*)(stm + (size_t)i1 * 4) = b; }
;                 else {
;                     u32x4 w; w.x = cvt_pk_bf16(a[0], a[1]); w.y = cvt_pk_bf16(a[2], a[3]); w.z = cvt_pk_bf16(b[0], b[1]); w.w = cvt_pk_bf16(b[2], b[3]);
;                     bf16_t* dst = iso ? MCTX + (size_t)((sub - 8) >> 1) * NCTX * 1024 + (row - NLAT) * 1024 : M + row * 1024;
;                     *(u32x4*)(dst + 256 * u.pn + 128 * bj + 32 * wc + 8 * fq) = w;
.LBB0_327:
	s_nop 0
	v_lshlrev_b32_e32 v160, 16, v210
	v_and_b32_e32 v161, 0xffff0000, v210
	v_lshlrev_b32_e32 v162, 16, v211
	v_and_b32_e32 v163, 0xffff0000, v211
	v_lshlrev_b32_e32 v198, 16, v206
	v_and_b32_e32 v199, 0xffff0000, v206
	v_lshlrev_b32_e32 v200, 16, v207
	v_and_b32_e32 v201, 0xffff0000, v207
	v_pk_mul_f32 v[164:165], v[52:53], v[160:161]
	v_pk_mul_f32 v[166:167], v[54:55], v[162:163]
	v_pk_mul_f32 v[206:207], v[48:49], v[198:199]
	v_pk_mul_f32 v[210:211], v[50:51], v[200:201]
	v_pk_fma_f32 v[160:161], v[52:53], v[160:161], v[148:149]
	v_pk_fma_f32 v[162:163], v[54:55], v[162:163], v[150:151]
	v_pk_fma_f32 v[198:199], v[48:49], v[198:199], v[144:145]
	v_pk_fma_f32 v[200:201], v[50:51], v[200:201], v[146:147]
	v_cndmask_b32_e64 v163, v167, v163, s[8:9]
	v_cndmask_b32_e64 v162, v166, v162, s[8:9]
	v_cndmask_b32_e64 v161, v165, v161, s[8:9]
	v_cndmask_b32_e64 v160, v164, v160, s[8:9]
	v_cndmask_b32_e64 v167, v211, v201, s[8:9]
	v_cndmask_b32_e64 v166, v210, v200, s[8:9]
	v_cndmask_b32_e64 v165, v207, v199, s[8:9]
	v_cndmask_b32_e64 v164, v206, v198, s[8:9]
	s_and_b64 vcc, exec, s[12:13]
	s_mov_b64 s[96:97], -1
	s_cbranch_vccnz .LBB0_329
	s_add_u32 s60, s23, s0
	s_addc_u32 s61, s6, s1
	v_lshl_add_u64 v[206:207], s[60:61], 0, v[222:223]
	s_brev_b32 s60, 63
	s_mov_b32 s61, -1
	v_lshl_add_u64 v[206:207], v[206:207], 0, s[60:61]
	s_lshl_b32 s60, s3, 8
	v_cndmask_b32_e64 v207, v207, v215, s[10:11]
	v_cndmask_b32_e64 v206, v206, v214, s[10:11]
	s_ashr_i32 s61, s60, 31
	v_lshl_add_u64 v[206:207], s[60:61], 1, v[206:207]
	v_readlane_b32 s60, v253, 15
	v_readlane_b32 s61, v253, 16
	s_lshl_b32 s60, s7, 1
	s_mov_b32 s21, s61
	v_writelane_b32 v253, s20, 15
	v_lshl_add_u64 v[206:207], v[206:207], 0, s[60:61]
	v_cvt_pk_bf16_f32 v198, v160, v161
	v_cvt_pk_bf16_f32 v199, v162, v163
	v_cvt_pk_bf16_f32 v200, v164, v165
	v_cvt_pk_bf16_f32 v201, v166, v167
	v_writelane_b32 v253, s21, 16
	v_lshl_add_u64 v[206:207], v[180:181], 1, v[206:207]
	s_mov_b64 s[96:97], 0
	global_store_dwordx4 v[206:207], v[198:201], off offset:256

; __device__ __forceinline__ unsigned cvt_pk_bf16(float lo, float hi) { f32x2 v = {lo, hi}; bf16x2_t b = __builtin_convertvector(v, bf16x2_t); return __builtin_bit_cast(unsigned, b); }
; __device__ __forceinline__ float bflo(unsigned w) { return __uint_as_float(w << 16); }
; __device__ __forceinline__ float bfhi(unsigned w) { return __uint_as_float(w & 0xffff0000u); }
;     __device__ __forceinline__ void operator()(const f32x4 (&acc)[2][2][4][2], const Unit& u, int wr, int wc, int fr, int fq) const {
;     ...
;             if (g + 1 < 8) {
;                 const int an = (g + 1) >> 2, mn = (g + 1) & 3;
; #pragma unroll
;                 for (int bj = 0; bj < 2; ++bj) {
;                     const int i0 = (((an * 2 + bj) * 4 + mn) * 2) * 512 + tid, i1 = i0 + 512;
;                     gp[(g + 1) & 1][bj][0] = *(const u32x2*)(stg + (size_t)i0 * 2); gp[(g + 1) & 1][bj][1] = *(const u32x2*)(stg + (size_t)i1 * 2);
;                     if (addm) { mp[(g + 1) & 1][bj][0] = *(const f32x4*)(stm + (size_t)i0 * 4); mp[(g + 1) & 1][bj][1] = *(const f32x4*)(stm + (size_t)i1 * 4); }
;                 }
;             }
;             asm volatile("" ::: "memory");
; #pragma unroll
;             for (int bj = 0; bj < 2; ++bj) {
;                 const int i0 = (((ai * 2 + bj) * 4 + m) * 2) * 512 + tid, i1 = i0 + 512;
;                 const u32x2 g0 = gp[g & 1][bj][0], g1 = gp[g & 1][bj][1];
;                 f32x4 a = acc[ai][bj][m][0], b = acc[ai][bj][m][1];
;                 a = a * (f32x4){bflo(g0.x), bfhi(g0.x), bflo(g0.y), bfhi(g0.y)}; b = b * (f32x4){bflo(g1.x), bfhi(g1.x), bflo(g1.y), bfhi(g1.y)};
;                 if (addm) { a += mp[g & 1][bj][0]; b += mp[g & 1][bj][1]; }
;                 if (sub < 5) { *(f32x4*)(stm + (size_t)i0 * 4) = a; *(f32x4*)(stm + (size_t)i1 * 4) = b; }
;                 else {
;                     u32x4 w; w.x = cvt_pk_bf16(a[0], a[1]); w.y = cvt_pk_bf16(a[2], a[3]); w.z = cvt_pk_bf16(b[0], b[1]); w.w = cvt_pk_bf16(b[2], b[3]);
;                     bf16_t* dst = iso ? MCTX + (size_t)((sub - 8) >> 1) * NCTX * 1024 + (row - NLAT) * 1024 : M + row * 1024;
;                     *(u32x4*)(dst + 256 * u.pn + 128 * bj + 32 * wc + 8 * fq) = w;
.LBB0_331:
	s_nop 0
	v_add_u32_e32 v160, 0x2800, v178
	v_add_u32_e32 v162, 0x2a00, v178
	v_ashrrev_i32_e32 v161, 31, v160
	v_lshl_add_u64 v[164:165], v[160:161], 3, s[28:29]
	v_ashrrev_i32_e32 v163, 31, v162
	v_lshl_add_u64 v[166:167], v[162:163], 3, s[28:29]
	global_load_dwordx2 v[218:219], v[164:165], off
	global_load_dwordx2 v[214:215], v[166:167], off
	s_and_b64 vcc, exec, s[14:15]
	v_lshl_add_u64 v[198:199], v[160:161], 4, s[26:27]
	v_lshl_add_u64 v[200:201], v[162:163], 4, s[26:27]
	s_cbranch_vccnz .LBB0_333
	global_load_dwordx4 v[156:159], v[198:199], off
	global_load_dwordx4 v[152:155], v[200:201], off
.LBB0_333:
	v_add_u32_e32 v160, 0x3800, v178
	v_add_u32_e32 v162, 0x3a00, v178
	v_ashrrev_i32_e32 v161, 31, v160
	v_lshl_add_u64 v[164:165], v[160:161], 3, s[28:29]
	v_ashrrev_i32_e32 v163, 31, v162
	v_lshl_add_u64 v[166:167], v[162:163], 3, s[28:29]
	global_load_dwordx2 v[210:211], v[164:165], off
	global_load_dwordx2 v[206:207], v[166:167], off
	s_and_b64 vcc, exec, s[14:15]
	v_lshl_add_u64 v[184:185], v[160:161], 4, s[26:27]
	v_lshl_add_u64 v[186:187], v[162:163], 4, s[26:27]
	s_cbranch_vccnz .LBB0_335
	global_load_dwordx4 v[148:151], v[184:185], off
	global_load_dwordx4 v[144:147], v[186:187], off
.LBB0_335:
	s_mov_b64 s[60:61], 0x48000
	v_lshlrev_b32_e32 v160, 16, v220
	v_and_b32_e32 v161, 0xffff0000, v220
	v_lshlrev_b32_e32 v162, 16, v221
	v_and_b32_e32 v163, 0xffff0000, v221
	v_lshlrev_b32_e32 v220, 16, v216
	v_and_b32_e32 v221, 0xffff0000, v216
	v_lshlrev_b32_e32 v216, 16, v217
	v_and_b32_e32 v217, 0xffff0000, v217
	v_lshl_add_u64 v[222:223], v[182:183], 0, s[60:61]
	v_pk_mul_f32 v[164:165], v[44:45], v[160:161]
	v_pk_mul_f32 v[166:167], v[46:47], v[162:163]
	v_pk_mul_f32 v[224:225], v[40:41], v[220:221]
	v_pk_mul_f32 v[230:231], v[42:43], v[216:217]
	v_pk_fma_f32 v[160:161], v[44:45], v[160:161], v[140:141]
	v_pk_fma_f32 v[162:163], v[46:47], v[162:163], v[142:143]
	v_pk_fma_f32 v[220:221], v[40:41], v[220:221], v[136:137]
	v_pk_fma_f32 v[216:217], v[42:43], v[216:217], v[138:139]
	v_cndmask_b32_e64 v163, v167, v163, s[8:9]
	v_cndmask_b32_e64 v162, v166, v162, s[8:9]
	v_cndmask_b32_e64 v161, v165, v161, s[8:9]
	v_cndmask_b32_e64 v160, v164, v160, s[8:9]
	v_cndmask_b32_e64 v167, v231, v217, s[8:9]
	v_cndmask_b32_e64 v166, v230, v216, s[8:9]
	v_cndmask_b32_e64 v165, v225, v221, s[8:9]
	v_cndmask_b32_e64 v164, v224, v220, s[8:9]
	s_mov_b64 s[96:97], -1
	s_and_b64 vcc, exec, s[12:13]
	v_lshl_add_u64 v[216:217], s[24:25], 0, v[222:223]
	s_cbranch_vccnz .LBB0_337
	s_add_u32 s60, s23, s0
	s_addc_u32 s61, s6, s1
	v_lshl_add_u64 v[220:221], s[60:61], 0, v[222:223]
	s_brev_b32 s60, 63
	s_mov_b32 s61, -1
	v_lshl_add_u64 v[220:221], v[220:221], 0, s[60:61]
	s_lshl_b32 s60, s3, 8
	v_cndmask_b32_e64 v221, v221, v217, s[10:11]
	v_cndmask_b32_e64 v220, v220, v216, s[10:11]
	s_ashr_i32 s61, s60, 31
	v_lshl_add_u64 v[220:221], s[60:61], 1, v[220:221]
	v_readlane_b32 s60, v253, 15
	v_readlane_b32 s61, v253, 16
	s_lshl_b32 s60, s7, 1
	s_mov_b32 s21, s61
	v_writelane_b32 v253, s20, 15
	v_lshl_add_u64 v[220:221], v[220:221], 0, s[60:61]
	v_cvt_pk_bf16_f32 v234, v160, v161
	v_cvt_pk_bf16_f32 v235, v162, v163
	v_cvt_pk_bf16_f32 v236, v164, v165
	v_cvt_pk_bf16_f32 v237, v166, v167
	v_writelane_b32 v253, s21, 16
	v_lshl_add_u64 v[220:221], v[180:181], 1, v[220:221]
	s_mov_b64 s[96:97], 0
	global_store_dwordx4 v[220:221], v[234:237], off

; __device__ __forceinline__ unsigned cvt_pk_bf16(float lo, float hi) { f32x2 v = {lo, hi}; bf16x2_t b = __builtin_convertvector(v, bf16x2_t); return __builtin_bit_cast(unsigned, b); }
; __device__ __forceinline__ float bflo(unsigned w) { return __uint_as_float(w << 16); }
; __device__ __forceinline__ float bfhi(unsigned w) { return __uint_as_float(w & 0xffff0000u); }
;     __device__ __forceinline__ void operator()(const f32x4 (&acc)[2][2][4][2], const Unit& u, int wr, int wc, int fr, int fq) const {
;     ...
;             for (int bj = 0; bj < 2; ++bj) {
;                 const int i0 = (((ai * 2 + bj) * 4 + m) * 2) * 512 + tid, i1 = i0 + 512;
;                 const u32x2 g0 = gp[g & 1][bj][0], g1 = gp[g & 1][bj][1];
;                 f32x4 a = acc[ai][bj][m][0], b = acc[ai][bj][m][1];
;                 a = a * (f32x4){bflo(g0.x), bfhi(g0.x), bflo(g0.y), bfhi(g0.y)}; b = b * (f32x4){bflo(g1.x), bfhi(g1.x), bflo(g1.y), bfhi(g1.y)};
;                 if (addm) { a += mp[g & 1][bj][0]; b += mp[g & 1][bj][1]; }
;                 if (sub < 5) { *(f32x4*)(stm + (size_t)i0 * 4) = a; *(f32x4*)(stm + (size_t)i1 * 4) = b; }
;                 else {
;                     u32x4 w; w.x = cvt_pk_bf16(a[0], a[1]); w.y = cvt_pk_bf16(a[2], a[3]); w.z = cvt_pk_bf16(b[0], b[1]); w.w = cvt_pk_bf16(b[2], b[3]);
;                     bf16_t* dst = iso ? MCTX + (size_t)((sub - 8) >> 1) * NCTX * 1024 + (row - NLAT) * 1024 : M + row * 1024;
;                     *(u32x4*)(dst + 256 * u.pn + 128 * bj + 32 * wc + 8 * fq) = w;
.LBB0_339:
	s_nop 0
	v_lshlrev_b32_e32 v160, 16, v212
	v_and_b32_e32 v161, 0xffff0000, v212
	v_lshlrev_b32_e32 v162, 16, v213
	v_and_b32_e32 v163, 0xffff0000, v213
	v_lshlrev_b32_e32 v202, 16, v208
	v_and_b32_e32 v203, 0xffff0000, v208
	v_lshlrev_b32_e32 v204, 16, v209
	v_and_b32_e32 v205, 0xffff0000, v209
	v_pk_mul_f32 v[164:165], v[36:37], v[160:161]
	v_pk_mul_f32 v[166:167], v[38:39], v[162:163]
	v_pk_mul_f32 v[208:209], v[32:33], v[202:203]
	v_pk_mul_f32 v[212:213], v[34:35], v[204:205]
	v_pk_fma_f32 v[160:161], v[36:37], v[160:161], v[132:133]
	v_pk_fma_f32 v[162:163], v[38:39], v[162:163], v[134:135]
	v_pk_fma_f32 v[202:203], v[32:33], v[202:203], v[128:129]
	v_pk_fma_f32 v[204:205], v[34:35], v[204:205], v[130:131]
	v_cndmask_b32_e64 v163, v167, v163, s[8:9]
	v_cndmask_b32_e64 v162, v166, v162, s[8:9]
	v_cndmask_b32_e64 v161, v165, v161, s[8:9]
	v_cndmask_b32_e64 v160, v164, v160, s[8:9]
	v_cndmask_b32_e64 v167, v213, v205, s[8:9]
	v_cndmask_b32_e64 v166, v212, v204, s[8:9]
	v_cndmask_b32_e64 v165, v209, v203, s[8:9]
	v_cndmask_b32_e64 v164, v208, v202, s[8:9]
	s_and_b64 vcc, exec, s[12:13]
	s_mov_b64 s[96:97], -1
	s_cbranch_vccnz .LBB0_341
	s_add_u32 s60, s23, s0
	s_addc_u32 s61, s6, s1
	v_lshl_add_u64 v[208:209], s[60:61], 0, v[222:223]
	s_brev_b32 s60, 63
	s_mov_b32 s61, -1
	v_lshl_add_u64 v[208:209], v[208:209], 0, s[60:61]
	s_lshl_b32 s60, s3, 8
	v_cndmask_b32_e64 v209, v209, v217, s[10:11]
	v_cndmask_b32_e64 v208, v208, v216, s[10:11]
	s_ashr_i32 s61, s60, 31
	v_lshl_add_u64 v[208:209], s[60:61], 1, v[208:209]
	v_readlane_b32 s60, v253, 15
	v_readlane_b32 s61, v253, 16
	s_lshl_b32 s60, s7, 1
	s_mov_b32 s21, s61
	v_writelane_b32 v253, s20, 15
	v_lshl_add_u64 v[208:209], v[208:209], 0, s[60:61]
	v_cvt_pk_bf16_f32 v202, v160, v161
	v_cvt_pk_bf16_f32 v203, v162, v163
	v_cvt_pk_bf16_f32 v204, v164, v165
	v_cvt_pk_bf16_f32 v205, v166, v167
	v_writelane_b32 v253, s21, 16
	v_lshl_add_u64 v[208:209], v[180:181], 1, v[208:209]
	s_mov_b64 s[96:97], 0
	global_store_dwordx4 v[208:209], v[202:205], off offset:256

; __device__ __forceinline__ unsigned cvt_pk_bf16(float lo, float hi) { f32x2 v = {lo, hi}; bf16x2_t b = __builtin_convertvector(v, bf16x2_t); return __builtin_bit_cast(unsigned, b); }
; __device__ __forceinline__ float bflo(unsigned w) { return __uint_as_float(w << 16); }
; __device__ __forceinline__ float bfhi(unsigned w) { return __uint_as_float(w & 0xffff0000u); }
;     __device__ __forceinline__ void operator()(const f32x4 (&acc)[2][2][4][2], const Unit& u, int wr, int wc, int fr, int fq) const {
;     ...
;             if (g + 1 < 8) {
;                 const int an = (g + 1) >> 2, mn = (g + 1) & 3;
; #pragma unroll
;                 for (int bj = 0; bj < 2; ++bj) {
;                     const int i0 = (((an * 2 + bj) * 4 + mn) * 2) * 512 + tid, i1 = i0 + 512;
;                     gp[(g + 1) & 1][bj][0] = *(const u32x2*)(stg + (size_t)i0 * 2); gp[(g + 1) & 1][bj][1] = *(const u32x2*)(stg + (size_t)i1 * 2);
;                     if (addm) { mp[(g + 1) & 1][bj][0] = *(const f32x4*)(stm + (size_t)i0 * 4); mp[(g + 1) & 1][bj][1] = *(const f32x4*)(stm + (size_t)i1 * 4); }
;                 }
;             }
;             asm volatile("" ::: "memory");
; #pragma unroll
;             for (int bj = 0; bj < 2; ++bj) {
;                 const int i0 = (((ai * 2 + bj) * 4 + m) * 2) * 512 + tid, i1 = i0 + 512;
;                 const u32x2 g0 = gp[g & 1][bj][0], g1 = gp[g & 1][bj][1];
;                 f32x4 a = acc[ai][bj][m][0], b = acc[ai][bj][m][1];
;                 a = a * (f32x4){bflo(g0.x), bfhi(g0.x), bflo(g0.y), bfhi(g0.y)}; b = b * (f32x4){bflo(g1.x), bfhi(g1.x), bflo(g1.y), bfhi(g1.y)};
;                 if (addm) { a += mp[g & 1][bj][0]; b += mp[g & 1][bj][1]; }
;                 if (sub < 5) { *(f32x4*)(stm + (size_t)i0 * 4) = a; *(f32x4*)(stm + (size_t)i1 * 4) = b; }
;                 else {
;                     u32x4 w; w.x = cvt_pk_bf16(a[0], a[1]); w.y = cvt_pk_bf16(a[2], a[3]); w.z = cvt_pk_bf16(b[0], b[1]); w.w = cvt_pk_bf16(b[2], b[3]);
;                     bf16_t* dst = iso ? MCTX + (size_t)((sub - 8) >> 1) * NCTX * 1024 + (row - NLAT) * 1024 : M + row * 1024;
;                     *(u32x4*)(dst + 256 * u.pn + 128 * bj + 32 * wc + 8 * fq) = w;
.LBB0_343:
	s_nop 0
	v_add_u32_e32 v160, 0x2c00, v178
	v_add_u32_e32 v162, 0x2e00, v178
	v_ashrrev_i32_e32 v161, 31, v160
	v_lshl_add_u64 v[164:165], v[160:161], 3, s[28:29]
	v_ashrrev_i32_e32 v163, 31, v162
	v_lshl_add_u64 v[166:167], v[162:163], 3, s[28:29]
	global_load_dwordx2 v[204:205], v[164:165], off
	global_load_dwordx2 v[202:203], v[166:167], off
	v_readlane_b32 s96, v254, 42
	s_and_b64 vcc, exec, s[14:15]
	v_lshl_add_u64 v[164:165], v[160:161], 4, s[26:27]
	v_lshl_add_u64 v[166:167], v[162:163], 4, s[26:27]
	v_readlane_b32 s97, v254, 43
	s_cbranch_vccnz .LBB0_345
	global_load_dwordx4 v[140:143], v[164:165], off
	global_load_dwordx4 v[136:139], v[166:167], off
.LBB0_345:
	v_add_u32_e32 v160, 0x3c00, v178
	v_add_u32_e32 v162, 0x3e00, v178
	v_ashrrev_i32_e32 v161, 31, v160
	v_lshl_add_u64 v[188:189], v[160:161], 3, s[28:29]
	v_ashrrev_i32_e32 v163, 31, v162
	v_lshl_add_u64 v[208:209], v[162:163], 3, s[28:29]
	global_load_dwordx2 v[190:191], v[188:189], off
	s_nop 0
	global_load_dwordx2 v[188:189], v[208:209], off
	s_and_b64 vcc, exec, s[14:15]
	v_lshl_add_u64 v[160:161], v[160:161], 4, s[26:27]
	v_lshl_add_u64 v[162:163], v[162:163], 4, s[26:27]
	s_cbranch_vccnz .LBB0_347
	global_load_dwordx4 v[132:135], v[160:161], off
	global_load_dwordx4 v[128:131], v[162:163], off
.LBB0_347:
	s_mov_b64 s[14:15], 0x50000
	s_waitcnt vmcnt(0) lgkmcnt(0)
	v_lshlrev_b32_e32 v212, 16, v218
	v_and_b32_e32 v213, 0xffff0000, v218
	v_lshlrev_b32_e32 v216, 16, v219
	v_and_b32_e32 v217, 0xffff0000, v219
	v_lshlrev_b32_e32 v222, 16, v214
	v_and_b32_e32 v223, 0xffff0000, v214
	v_lshlrev_b32_e32 v214, 16, v215
	v_and_b32_e32 v215, 0xffff0000, v215
	v_lshl_add_u64 v[208:209], v[182:183], 0, s[14:15]
	v_pk_mul_f32 v[218:219], v[28:29], v[212:213]
	v_pk_mul_f32 v[220:221], v[30:31], v[216:217]
	v_pk_mul_f32 v[224:225], v[24:25], v[222:223]
	v_pk_mul_f32 v[230:231], v[26:27], v[214:215]
	v_pk_fma_f32 v[156:157], v[28:29], v[212:213], v[156:157]
	v_pk_fma_f32 v[158:159], v[30:31], v[216:217], v[158:159]
	v_pk_fma_f32 v[212:213], v[24:25], v[222:223], v[152:153]
	v_pk_fma_f32 v[214:215], v[26:27], v[214:215], v[154:155]
	v_cndmask_b32_e64 v155, v221, v159, s[8:9]
	v_cndmask_b32_e64 v154, v220, v158, s[8:9]
	v_cndmask_b32_e64 v153, v219, v157, s[8:9]
	v_cndmask_b32_e64 v152, v218, v156, s[8:9]
	v_cndmask_b32_e64 v159, v231, v215, s[8:9]
	v_cndmask_b32_e64 v158, v230, v214, s[8:9]
	v_cndmask_b32_e64 v157, v225, v213, s[8:9]
	v_cndmask_b32_e64 v156, v224, v212, s[8:9]
	s_mov_b64 s[14:15], -1
	s_and_b64 vcc, exec, s[12:13]
	v_lshl_add_u64 v[212:213], s[24:25], 0, v[208:209]
	s_cbranch_vccnz .LBB0_349
	s_add_u32 s14, s23, s0
	s_addc_u32 s15, s6, s1
	v_lshl_add_u64 v[218:219], s[14:15], 0, v[208:209]
	s_brev_b32 s14, 63
	s_mov_b32 s15, -1
	v_lshl_add_u64 v[218:219], v[218:219], 0, s[14:15]
	s_lshl_b32 s14, s3, 8
	v_cndmask_b32_e64 v219, v219, v213, s[10:11]
	v_cndmask_b32_e64 v218, v218, v212, s[10:11]
	s_ashr_i32 s15, s14, 31
	v_lshl_add_u64 v[218:219], s[14:15], 1, v[218:219]
	v_readlane_b32 s14, v253, 15
	v_readlane_b32 s15, v253, 16
	s_mov_b32 s61, s15
	s_lshl_b32 s60, s7, 1
	v_writelane_b32 v253, s14, 15
	v_lshl_add_u64 v[218:219], v[218:219], 0, s[60:61]
	v_cvt_pk_bf16_f32 v214, v152, v153
	v_cvt_pk_bf16_f32 v215, v154, v155
	v_cvt_pk_bf16_f32 v216, v156, v157
	v_cvt_pk_bf16_f32 v217, v158, v159
	v_writelane_b32 v253, s15, 16
	v_lshl_add_u64 v[218:219], v[180:181], 1, v[218:219]
	s_mov_b64 s[14:15], 0
	global_store_dwordx4 v[218:219], v[214:217], off
.LBB0_349:
	s_andn2_b64 vcc, exec, s[14:15]
	s_cbranch_vccnz .LBB0_351
	global_store_dwordx4 v[198:199], v[152:155], off
	global_store_dwordx4 v[200:201], v[156:159], off
.LBB0_351:
	s_nop 0
	v_lshlrev_b32_e32 v152, 16, v210
	v_and_b32_e32 v153, 0xffff0000, v210
	v_lshlrev_b32_e32 v154, 16, v211
	v_and_b32_e32 v155, 0xffff0000, v211
	v_lshlrev_b32_e32 v198, 16, v206
	v_and_b32_e32 v199, 0xffff0000, v206
	v_lshlrev_b32_e32 v200, 16, v207
	v_and_b32_e32 v201, 0xffff0000, v207
	v_pk_mul_f32 v[156:157], v[20:21], v[152:153]
	v_pk_mul_f32 v[158:159], v[22:23], v[154:155]
	v_pk_mul_f32 v[206:207], v[16:17], v[198:199]
	v_pk_mul_f32 v[210:211], v[18:19], v[200:201]
	v_pk_fma_f32 v[148:149], v[20:21], v[152:153], v[148:149]
	v_pk_fma_f32 v[150:151], v[22:23], v[154:155], v[150:151]
	v_pk_fma_f32 v[152:153], v[16:17], v[198:199], v[144:145]
	v_pk_fma_f32 v[154:155], v[18:19], v[200:201], v[146:147]
	v_cndmask_b32_e64 v147, v159, v151, s[8:9]
	v_cndmask_b32_e64 v146, v158, v150, s[8:9]
	v_cndmask_b32_e64 v145, v157, v149, s[8:9]
	v_cndmask_b32_e64 v144, v156, v148, s[8:9]
	v_cndmask_b32_e64 v151, v211, v155, s[8:9]
	v_cndmask_b32_e64 v150, v210, v154, s[8:9]
	v_cndmask_b32_e64 v149, v207, v153, s[8:9]
	v_cndmask_b32_e64 v148, v206, v152, s[8:9]
	s_and_b64 vcc, exec, s[12:13]
	s_mov_b64 s[14:15], -1
	s_cbranch_vccnz .LBB0_353
	s_add_u32 s14, s23, s0
	s_addc_u32 s15, s6, s1
	v_lshl_add_u64 v[156:157], s[14:15], 0, v[208:209]
	s_brev_b32 s14, 63
	s_mov_b32 s15, -1
	v_lshl_add_u64 v[156:157], v[156:157], 0, s[14:15]
	s_lshl_b32 s14, s3, 8
	v_cndmask_b32_e64 v157, v157, v213, s[10:11]
	v_cndmask_b32_e64 v156, v156, v212, s[10:11]
	s_ashr_i32 s15, s14, 31
	v_lshl_add_u64 v[156:157], s[14:15], 1, v[156:157]
	v_readlane_b32 s14, v253, 15
	v_readlane_b32 s15, v253, 16
	s_mov_b32 s61, s15
	s_lshl_b32 s60, s7, 1
	v_writelane_b32 v253, s14, 15
	v_lshl_add_u64 v[156:157], v[156:157], 0, s[60:61]
	v_cvt_pk_bf16_f32 v152, v144, v145
	v_cvt_pk_bf16_f32 v153, v146, v147
	v_cvt_pk_bf16_f32 v154, v148, v149
	v_cvt_pk_bf16_f32 v155, v150, v151
	v_writelane_b32 v253, s15, 16
	v_lshl_add_u64 v[156:157], v[180:181], 1, v[156:157]
	s_mov_b64 s[14:15], 0
	global_store_dwordx4 v[156:157], v[152:155], off offset:256
; __device__ __forceinline__ unsigned cvt_pk_bf16(float lo, float hi) { f32x2 v = {lo, hi}; bf16x2_t b = __builtin_convertvector(v, bf16x2_t); return __builtin_bit_cast(unsigned, b); }
; __device__ __forceinline__ float bflo(unsigned w) { return __uint_as_float(w << 16); }
; __device__ __forceinline__ float bfhi(unsigned w) { return __uint_as_float(w & 0xffff0000u); }
;     __device__ __forceinline__ void operator()(const f32x4 (&acc)[2][2][4][2], const Unit& u, int wr, int wc, int fr, int fq) const {
;     ...
;             for (int bj = 0; bj < 2; ++bj) {
;                 const int i0 = (((ai * 2 + bj) * 4 + m) * 2) * 512 + tid, i1 = i0 + 512;
;                 const u32x2 g0 = gp[g & 1][bj][0], g1 = gp[g & 1][bj][1];
;                 f32x4 a = acc[ai][bj][m][0], b = acc[ai][bj][m][1];
;                 a = a * (f32x4){bflo(g0.x), bfhi(g0.x), bflo(g0.y), bfhi(g0.y)}; b = b * (f32x4){bflo(g1.x), bfhi(g1.x), bflo(g1.y), bfhi(g1.y)};
;                 if (addm) { a += mp[g & 1][bj][0]; b += mp[g & 1][bj][1]; }
;                 if (sub < 5) { *(f32x4*)(stm + (size_t)i0 * 4) = a; *(f32x4*)(stm + (size_t)i1 * 4) = b; }
;                 else {
;                     u32x4 w; w.x = cvt_pk_bf16(a[0], a[1]); w.y = cvt_pk_bf16(a[2], a[3]); w.z = cvt_pk_bf16(b[0], b[1]); w.w = cvt_pk_bf16(b[2], b[3]);
;                     bf16_t* dst = iso ? MCTX + (size_t)((sub - 8) >> 1) * NCTX * 1024 + (row - NLAT) * 1024 : M + row * 1024;
;                     *(u32x4*)(dst + 256 * u.pn + 128 * bj + 32 * wc + 8 * fq) = w;
.LBB0_353:
	s_andn2_b64 vcc, exec, s[14:15]
	s_cbranch_vccnz .LBB0_355
	global_store_dwordx4 v[184:185], v[144:147], off
	global_store_dwordx4 v[186:187], v[148:151], off
.LBB0_355:
	s_mov_b64 s[14:15], 0x58000
	v_lshlrev_b32_e32 v146, 16, v204
	v_and_b32_e32 v147, 0xffff0000, v204
	v_lshlrev_b32_e32 v148, 16, v205
	v_and_b32_e32 v149, 0xffff0000, v205
	v_lshlrev_b32_e32 v154, 16, v202
	v_and_b32_e32 v155, 0xffff0000, v202
	v_lshlrev_b32_e32 v156, 16, v203
	v_and_b32_e32 v157, 0xffff0000, v203
	v_lshl_add_u64 v[144:145], v[182:183], 0, s[14:15]
	v_pk_mul_f32 v[150:151], v[12:13], v[146:147]
	v_pk_mul_f32 v[152:153], v[14:15], v[148:149]
	v_pk_mul_f32 v[158:159], v[8:9], v[154:155]
	v_pk_mul_f32 v[182:183], v[10:11], v[156:157]
	v_pk_fma_f32 v[140:141], v[12:13], v[146:147], v[140:141]
	v_pk_fma_f32 v[142:143], v[14:15], v[148:149], v[142:143]
	v_pk_fma_f32 v[146:147], v[8:9], v[154:155], v[136:137]
	v_pk_fma_f32 v[148:149], v[10:11], v[156:157], v[138:139]
	v_cndmask_b32_e64 v139, v153, v143, s[8:9]
	v_cndmask_b32_e64 v138, v152, v142, s[8:9]
	v_cndmask_b32_e64 v137, v151, v141, s[8:9]
	v_cndmask_b32_e64 v136, v150, v140, s[8:9]
	v_cndmask_b32_e64 v143, v183, v149, s[8:9]
	v_cndmask_b32_e64 v142, v182, v148, s[8:9]
	v_cndmask_b32_e64 v141, v159, v147, s[8:9]
	v_cndmask_b32_e64 v140, v158, v146, s[8:9]
	s_mov_b64 s[14:15], -1
	s_and_b64 vcc, exec, s[12:13]
	v_lshl_add_u64 v[146:147], s[24:25], 0, v[144:145]
	s_cbranch_vccnz .LBB0_357
	s_add_u32 s14, s23, s0
	s_addc_u32 s15, s6, s1
	v_lshl_add_u64 v[152:153], s[14:15], 0, v[144:145]
	s_brev_b32 s14, 63
	s_mov_b32 s15, -1
	v_lshl_add_u64 v[152:153], v[152:153], 0, s[14:15]
	s_lshl_b32 s14, s3, 8
	v_cndmask_b32_e64 v153, v153, v147, s[10:11]
	v_cndmask_b32_e64 v152, v152, v146, s[10:11]
	s_ashr_i32 s15, s14, 31
	v_lshl_add_u64 v[152:153], s[14:15], 1, v[152:153]
	v_readlane_b32 s14, v253, 15
	v_readlane_b32 s15, v253, 16
	s_mov_b32 s61, s15
	s_lshl_b32 s60, s7, 1
	v_writelane_b32 v253, s14, 15
	v_lshl_add_u64 v[152:153], v[152:153], 0, s[60:61]
	v_cvt_pk_bf16_f32 v148, v136, v137
	v_cvt_pk_bf16_f32 v149, v138, v139
	v_cvt_pk_bf16_f32 v150, v140, v141
	v_cvt_pk_bf16_f32 v151, v142, v143
	v_writelane_b32 v253, s15, 16
	v_lshl_add_u64 v[152:153], v[180:181], 1, v[152:153]
	s_mov_b64 s[14:15], 0
	global_store_dwordx4 v[152:153], v[148:151], off
.LBB0_357:
	s_andn2_b64 vcc, exec, s[14:15]
	s_cbranch_vccnz .LBB0_359
	global_store_dwordx4 v[164:165], v[136:139], off
	global_store_dwordx4 v[166:167], v[140:143], off
.LBB0_359:
	s_nop 0
	v_lshlrev_b32_e32 v136, 16, v190
	v_and_b32_e32 v137, 0xffff0000, v190
	v_lshlrev_b32_e32 v138, 16, v191
	v_and_b32_e32 v139, 0xffff0000, v191
	v_lshlrev_b32_e32 v148, 16, v188
	v_and_b32_e32 v149, 0xffff0000, v188
	v_lshlrev_b32_e32 v150, 16, v189
	v_and_b32_e32 v151, 0xffff0000, v189
	v_pk_mul_f32 v[140:141], v[4:5], v[136:137]
	v_pk_mul_f32 v[142:143], v[6:7], v[138:139]
	v_pk_mul_f32 v[152:153], v[0:1], v[148:149]
	v_pk_mul_f32 v[154:155], v[2:3], v[150:151]
	v_pk_fma_f32 v[132:133], v[4:5], v[136:137], v[132:133]
	v_pk_fma_f32 v[134:135], v[6:7], v[138:139], v[134:135]
	v_pk_fma_f32 v[136:137], v[0:1], v[148:149], v[128:129]
	v_pk_fma_f32 v[138:139], v[2:3], v[150:151], v[130:131]
	v_cndmask_b32_e64 v131, v143, v135, s[8:9]
	v_cndmask_b32_e64 v130, v142, v134, s[8:9]
	v_cndmask_b32_e64 v129, v141, v133, s[8:9]
	v_cndmask_b32_e64 v128, v140, v132, s[8:9]
	v_cndmask_b32_e64 v135, v155, v139, s[8:9]
	v_cndmask_b32_e64 v134, v154, v138, s[8:9]
	v_cndmask_b32_e64 v133, v153, v137, s[8:9]
	v_cndmask_b32_e64 v132, v152, v136, s[8:9]
	s_and_b64 vcc, exec, s[12:13]
	s_mov_b64 s[8:9], -1
	s_cbranch_vccnz .LBB0_361
	s_add_u32 s0, s23, s0
	s_addc_u32 s1, s6, s1
	v_lshl_add_u64 v[140:141], s[0:1], 0, v[144:145]
	s_brev_b32 s0, 63
	s_mov_b32 s1, -1
	v_lshl_add_u64 v[140:141], v[140:141], 0, s[0:1]
	s_lshl_b32 s0, s3, 8
	v_cndmask_b32_e64 v141, v141, v147, s[10:11]
	v_cndmask_b32_e64 v140, v140, v146, s[10:11]
	s_ashr_i32 s1, s0, 31
	v_lshl_add_u64 v[140:141], s[0:1], 1, v[140:141]
	v_readlane_b32 s0, v253, 15
	v_readlane_b32 s1, v253, 16
	s_mov_b32 s9, s1
	s_lshl_b32 s8, s7, 1
	v_writelane_b32 v253, s0, 15
	v_lshl_add_u64 v[140:141], v[140:141], 0, s[8:9]
	v_cvt_pk_bf16_f32 v136, v128, v129
	v_cvt_pk_bf16_f32 v137, v130, v131
	v_cvt_pk_bf16_f32 v138, v132, v133
	v_cvt_pk_bf16_f32 v139, v134, v135
	v_writelane_b32 v253, s1, 16
	v_lshl_add_u64 v[140:141], v[180:181], 1, v[140:141]
	s_mov_b64 s[8:9], 0
	global_store_dwordx4 v[140:141], v[136:139], off offset:256
.LBB0_361:
	s_andn2_b64 vcc, exec, s[8:9]
	s_cbranch_vccnz .LBB0_363
	global_store_dwordx4 v[160:161], v[128:131], off
	global_store_dwordx4 v[162:163], v[132:135], off

; __device__ __forceinline__ unsigned cvt_pk_bf16(float lo, float hi) { f32x2 v = {lo, hi}; bf16x2_t b = __builtin_convertvector(v, bf16x2_t); return __builtin_bit_cast(unsigned, b); }
; __device__ __forceinline__ float sigmoidf_(float v) { return __builtin_amdgcn_rcpf(1.0f + __builtin_amdgcn_exp2f(-1.4426950408889634f * v)); }
; #define FOR_AI_M _Pragma("unroll") for (int ai = 0; ai < 2; ++ai) _Pragma("unroll") for (int m = 0; m < 4; ++m)
;     __device__ __forceinline__ void operator()(const f32x4 (&acc)[2][2][4][2], const Unit& u, int wr, int wc, int fr, int fq) const {
;     ...
;         if ((sub & 1) == 0) {
;             FOR_AI_M {
; #pragma unroll
;                 for (int bj = 0; bj < 2; ++bj) {
;                     const int i0 = (((ai * 2 + bj) * 4 + m) * 2) * 512 + tid, i1 = i0 + 512;
;                     const f32x4 a = acc[ai][bj][m][0], b = acc[ai][bj][m][1];
;                     u32x2 w0, w1; w0.x = cvt_pk_bf16(sigmoidf_(a[0]), sigmoidf_(a[1])); w0.y = cvt_pk_bf16(sigmoidf_(a[2]), sigmoidf_(a[3]));
;                     w1.x = cvt_pk_bf16(sigmoidf_(b[0]), sigmoidf_(b[1])); w1.y = cvt_pk_bf16(sigmoidf_(b[2]), sigmoidf_(b[3]));
;                     *(u32x2*)(stg + (size_t)i0 * 2) = w0; *(u32x2*)(stg + (size_t)i1 * 2) = w1;
;                 }
;                 asm volatile("" ::: "memory");
;             }
;             return;
.LBB0_365:
	s_and_b64 vcc, exec, s[0:1]
	s_movk_i32 s0, 0x1000
	s_cbranch_vccz .LBB0_364
	v_mul_f32_e32 v124, 0xbfb8aa3b, v124
	v_mul_f32_e32 v125, 0xbfb8aa3b, v125
	v_mul_f32_e32 v126, 0xbfb8aa3b, v126
	v_mul_f32_e32 v127, 0xbfb8aa3b, v127
	v_mul_f32_e32 v120, 0xbfb8aa3b, v120
	v_mul_f32_e32 v121, 0xbfb8aa3b, v121
	v_exp_f32_e32 v124, v124
	v_exp_f32_e32 v125, v125
	v_exp_f32_e32 v126, v126
	v_exp_f32_e32 v127, v127
	v_exp_f32_e32 v120, v120
	v_exp_f32_e32 v121, v121
	v_mul_f32_e32 v122, 0xbfb8aa3b, v122
	v_exp_f32_e32 v122, v122
	v_mul_f32_e32 v123, 0xbfb8aa3b, v123
	v_exp_f32_e32 v123, v123
	v_add_f32_e32 v124, 1.0, v124
	v_add_f32_e32 v125, 1.0, v125
	v_add_f32_e32 v126, 1.0, v126
	v_add_f32_e32 v127, 1.0, v127
	v_add_f32_e32 v120, 1.0, v120
	v_add_f32_e32 v121, 1.0, v121
	v_rcp_f32_e32 v124, v124
	v_rcp_f32_e32 v125, v125
	v_rcp_f32_e32 v126, v126
	v_rcp_f32_e32 v127, v127
	v_rcp_f32_e32 v120, v120
	v_rcp_f32_e32 v121, v121
	v_add_f32_e32 v122, 1.0, v122
	v_rcp_f32_e32 v128, v122
	v_add_f32_e32 v122, 1.0, v123
	v_mul_f32_e32 v112, 0xbfb8aa3b, v112
	v_rcp_f32_e32 v129, v122
	v_exp_f32_e32 v112, v112
	v_mul_f32_e32 v113, 0xbfb8aa3b, v113
	v_exp_f32_e32 v113, v113
	v_cvt_pk_bf16_f32 v122, v124, v125
	v_cvt_pk_bf16_f32 v123, v126, v127
	v_cvt_pk_bf16_f32 v124, v120, v121
	v_lshl_add_u64 v[120:121], v[178:179], 3, s[28:29]
	global_store_dwordx2 v[120:121], v[122:123], off
	v_add_co_u32_e32 v122, vcc, s0, v120
	v_mul_f32_e32 v116, 0xbfb8aa3b, v116
	v_mul_f32_e32 v117, 0xbfb8aa3b, v117
	v_cvt_pk_bf16_f32 v125, v128, v129
	v_addc_co_u32_e32 v123, vcc, 0, v121, vcc
	v_exp_f32_e32 v116, v116
	v_exp_f32_e32 v117, v117
	v_mul_f32_e32 v118, 0xbfb8aa3b, v118
	v_mul_f32_e32 v119, 0xbfb8aa3b, v119
	v_add_f32_e32 v112, 1.0, v112
	global_store_dwordx2 v[122:123], v[124:125], off
	v_exp_f32_e32 v118, v118
	v_exp_f32_e32 v119, v119
	v_rcp_f32_e32 v122, v112
	v_add_f32_e32 v112, 1.0, v113
	v_mul_f32_e32 v113, 0xbfb8aa3b, v114
	v_exp_f32_e32 v113, v113
	v_mul_f32_e32 v114, 0xbfb8aa3b, v115
	v_exp_f32_e32 v114, v114
	v_add_f32_e32 v116, 1.0, v116
	v_add_f32_e32 v117, 1.0, v117
	v_rcp_f32_e32 v116, v116
	v_rcp_f32_e32 v117, v117
	v_add_f32_e32 v118, 1.0, v118
	v_add_f32_e32 v119, 1.0, v119
	v_rcp_f32_e32 v118, v118
	v_rcp_f32_e32 v119, v119
	v_rcp_f32_e32 v115, v112
	v_add_f32_e32 v112, 1.0, v113
	v_rcp_f32_e32 v123, v112
	v_add_f32_e32 v112, 1.0, v114
	v_mul_f32_e32 v104, 0xbfb8aa3b, v104
	v_rcp_f32_e32 v124, v112
	s_mov_b32 s0, 0x8000
	v_exp_f32_e32 v104, v104
	v_mul_f32_e32 v105, 0xbfb8aa3b, v105
	v_cvt_pk_bf16_f32 v112, v116, v117
	v_add_co_u32_e32 v116, vcc, s0, v120
	v_exp_f32_e32 v105, v105
	v_cvt_pk_bf16_f32 v113, v118, v119
	v_addc_co_u32_e32 v117, vcc, 0, v121, vcc
	s_mov_b32 s0, 0x9000
	global_store_dwordx2 v[116:117], v[112:113], off
	v_add_co_u32_e32 v112, vcc, s0, v120
	v_mul_f32_e32 v108, 0xbfb8aa3b, v108
	v_mul_f32_e32 v109, 0xbfb8aa3b, v109
	v_cvt_pk_bf16_f32 v114, v122, v115
	v_cvt_pk_bf16_f32 v115, v123, v124
	v_addc_co_u32_e32 v113, vcc, 0, v121, vcc
	v_exp_f32_e32 v108, v108
	v_exp_f32_e32 v109, v109
	v_mul_f32_e32 v110, 0xbfb8aa3b, v110
	v_mul_f32_e32 v111, 0xbfb8aa3b, v111
	v_add_f32_e32 v104, 1.0, v104
	global_store_dwordx2 v[112:113], v[114:115], off
	v_exp_f32_e32 v110, v110
	v_exp_f32_e32 v111, v111
	v_rcp_f32_e32 v112, v104
	v_add_f32_e32 v104, 1.0, v105
	v_mul_f32_e32 v105, 0xbfb8aa3b, v106
	v_exp_f32_e32 v105, v105
	v_mul_f32_e32 v106, 0xbfb8aa3b, v107
	v_exp_f32_e32 v106, v106
	v_add_f32_e32 v108, 1.0, v108
	v_add_f32_e32 v109, 1.0, v109
	v_rcp_f32_e32 v108, v108
	v_rcp_f32_e32 v109, v109
	v_add_f32_e32 v110, 1.0, v110
	v_add_f32_e32 v111, 1.0, v111
	v_rcp_f32_e32 v110, v110
	v_rcp_f32_e32 v111, v111
	v_rcp_f32_e32 v107, v104
	v_add_f32_e32 v104, 1.0, v105
	v_rcp_f32_e32 v113, v104
	v_add_f32_e32 v104, 1.0, v106
	v_mul_f32_e32 v96, 0xbfb8aa3b, v96
	v_rcp_f32_e32 v114, v104
	s_movk_i32 s0, 0x2000
	v_exp_f32_e32 v96, v96
	v_mul_f32_e32 v97, 0xbfb8aa3b, v97
	v_cvt_pk_bf16_f32 v104, v108, v109
	v_add_co_u32_e32 v108, vcc, s0, v120
	v_exp_f32_e32 v97, v97
	v_cvt_pk_bf16_f32 v105, v110, v111
	v_addc_co_u32_e32 v109, vcc, 0, v121, vcc
	s_movk_i32 s0, 0x3000
	global_store_dwordx2 v[108:109], v[104:105], off
	v_add_co_u32_e32 v104, vcc, s0, v120
	v_mul_f32_e32 v100, 0xbfb8aa3b, v100
	v_mul_f32_e32 v101, 0xbfb8aa3b, v101
	v_cvt_pk_bf16_f32 v106, v112, v107
	v_cvt_pk_bf16_f32 v107, v113, v114
	v_addc_co_u32_e32 v105, vcc, 0, v121, vcc
	v_exp_f32_e32 v100, v100
	v_exp_f32_e32 v101, v101
	v_mul_f32_e32 v102, 0xbfb8aa3b, v102
	v_mul_f32_e32 v103, 0xbfb8aa3b, v103
	v_add_f32_e32 v96, 1.0, v96
	global_store_dwordx2 v[104:105], v[106:107], off
	v_exp_f32_e32 v102, v102
	v_exp_f32_e32 v103, v103
	v_rcp_f32_e32 v104, v96
	v_add_f32_e32 v96, 1.0, v97
	v_mul_f32_e32 v97, 0xbfb8aa3b, v98
	v_exp_f32_e32 v97, v97
	v_mul_f32_e32 v98, 0xbfb8aa3b, v99
	v_exp_f32_e32 v98, v98
	v_add_f32_e32 v100, 1.0, v100
	v_add_f32_e32 v101, 1.0, v101
	v_rcp_f32_e32 v100, v100
	v_rcp_f32_e32 v101, v101
	v_add_f32_e32 v102, 1.0, v102
	v_add_f32_e32 v103, 1.0, v103
	v_rcp_f32_e32 v102, v102
	v_rcp_f32_e32 v103, v103
	v_rcp_f32_e32 v99, v96
	v_add_f32_e32 v96, 1.0, v97
	v_rcp_f32_e32 v105, v96
	v_add_f32_e32 v96, 1.0, v98
	v_mul_f32_e32 v88, 0xbfb8aa3b, v88
	v_rcp_f32_e32 v106, v96
	s_mov_b32 s0, 0xa000
	v_exp_f32_e32 v88, v88
	v_mul_f32_e32 v89, 0xbfb8aa3b, v89
	v_cvt_pk_bf16_f32 v96, v100, v101
	v_add_co_u32_e32 v100, vcc, s0, v120
	v_exp_f32_e32 v89, v89
	v_cvt_pk_bf16_f32 v97, v102, v103
	v_addc_co_u32_e32 v101, vcc, 0, v121, vcc
	s_mov_b32 s0, 0xb000
	global_store_dwordx2 v[100:101], v[96:97], off
	v_add_co_u32_e32 v96, vcc, s0, v120
	v_mul_f32_e32 v92, 0xbfb8aa3b, v92
; __device__ __forceinline__ unsigned cvt_pk_bf16(float lo, float hi) { f32x2 v = {lo, hi}; bf16x2_t b = __builtin_convertvector(v, bf16x2_t); return __builtin_bit_cast(unsigned, b); }
; __device__ __forceinline__ float sigmoidf_(float v) { return __builtin_amdgcn_rcpf(1.0f + __builtin_amdgcn_exp2f(-1.4426950408889634f * v)); }
; #define FOR_AI_M _Pragma("unroll") for (int ai = 0; ai < 2; ++ai) _Pragma("unroll") for (int m = 0; m < 4; ++m)
;     __device__ __forceinline__ void operator()(const f32x4 (&acc)[2][2][4][2], const Unit& u, int wr, int wc, int fr, int fq) const {
;     ...
;         if ((sub & 1) == 0) {
;             FOR_AI_M {
; #pragma unroll
;                 for (int bj = 0; bj < 2; ++bj) {
;                     const int i0 = (((ai * 2 + bj) * 4 + m) * 2) * 512 + tid, i1 = i0 + 512;
;                     const f32x4 a = acc[ai][bj][m][0], b = acc[ai][bj][m][1];
;                     u32x2 w0, w1; w0.x = cvt_pk_bf16(sigmoidf_(a[0]), sigmoidf_(a[1])); w0.y = cvt_pk_bf16(sigmoidf_(a[2]), sigmoidf_(a[3]));
;                     w1.x = cvt_pk_bf16(sigmoidf_(b[0]), sigmoidf_(b[1])); w1.y = cvt_pk_bf16(sigmoidf_(b[2]), sigmoidf_(b[3]));
;                     *(u32x2*)(stg + (size_t)i0 * 2) = w0; *(u32x2*)(stg + (size_t)i1 * 2) = w1;
;                 }
;                 asm volatile("" ::: "memory");
;             }
;             return;
	v_mul_f32_e32 v93, 0xbfb8aa3b, v93
	v_cvt_pk_bf16_f32 v98, v104, v99
	v_cvt_pk_bf16_f32 v99, v105, v106
	v_addc_co_u32_e32 v97, vcc, 0, v121, vcc
	v_exp_f32_e32 v92, v92
	v_exp_f32_e32 v93, v93
	v_mul_f32_e32 v94, 0xbfb8aa3b, v94
	v_mul_f32_e32 v95, 0xbfb8aa3b, v95
	v_add_f32_e32 v88, 1.0, v88
	global_store_dwordx2 v[96:97], v[98:99], off
	v_exp_f32_e32 v94, v94
	v_exp_f32_e32 v95, v95
	v_rcp_f32_e32 v96, v88
	v_add_f32_e32 v88, 1.0, v89
	v_mul_f32_e32 v89, 0xbfb8aa3b, v90
	v_exp_f32_e32 v89, v89
	v_mul_f32_e32 v90, 0xbfb8aa3b, v91
	v_exp_f32_e32 v90, v90
	v_add_f32_e32 v92, 1.0, v92
	v_add_f32_e32 v93, 1.0, v93
	v_rcp_f32_e32 v92, v92
	v_rcp_f32_e32 v93, v93
	v_add_f32_e32 v94, 1.0, v94
	v_add_f32_e32 v95, 1.0, v95
	v_rcp_f32_e32 v94, v94
	v_rcp_f32_e32 v95, v95
	v_rcp_f32_e32 v91, v88
	v_add_f32_e32 v88, 1.0, v89
	v_rcp_f32_e32 v97, v88
	v_add_f32_e32 v88, 1.0, v90
	v_mul_f32_e32 v80, 0xbfb8aa3b, v80
	v_rcp_f32_e32 v98, v88
	s_movk_i32 s0, 0x4000
	v_exp_f32_e32 v80, v80
	v_mul_f32_e32 v81, 0xbfb8aa3b, v81
	v_cvt_pk_bf16_f32 v88, v92, v93
	v_add_co_u32_e32 v92, vcc, s0, v120
	v_exp_f32_e32 v81, v81
	v_cvt_pk_bf16_f32 v89, v94, v95
	v_addc_co_u32_e32 v93, vcc, 0, v121, vcc
	s_movk_i32 s0, 0x5000
	global_store_dwordx2 v[92:93], v[88:89], off
	v_add_co_u32_e32 v88, vcc, s0, v120
	v_mul_f32_e32 v84, 0xbfb8aa3b, v84
	v_mul_f32_e32 v85, 0xbfb8aa3b, v85
	v_cvt_pk_bf16_f32 v90, v96, v91
	v_cvt_pk_bf16_f32 v91, v97, v98
	v_addc_co_u32_e32 v89, vcc, 0, v121, vcc
	v_exp_f32_e32 v84, v84
	v_exp_f32_e32 v85, v85
	v_mul_f32_e32 v86, 0xbfb8aa3b, v86
	v_mul_f32_e32 v87, 0xbfb8aa3b, v87
	v_add_f32_e32 v80, 1.0, v80
	global_store_dwordx2 v[88:89], v[90:91], off
	v_exp_f32_e32 v86, v86
	v_exp_f32_e32 v87, v87
	v_rcp_f32_e32 v88, v80
	v_add_f32_e32 v80, 1.0, v81
	v_mul_f32_e32 v81, 0xbfb8aa3b, v82
	v_exp_f32_e32 v81, v81
	v_mul_f32_e32 v82, 0xbfb8aa3b, v83
	v_exp_f32_e32 v82, v82
	v_add_f32_e32 v84, 1.0, v84
	v_add_f32_e32 v85, 1.0, v85
	v_rcp_f32_e32 v84, v84
	v_rcp_f32_e32 v85, v85
	v_add_f32_e32 v86, 1.0, v86
	v_add_f32_e32 v87, 1.0, v87
	v_rcp_f32_e32 v86, v86
	v_rcp_f32_e32 v87, v87
	v_rcp_f32_e32 v83, v80
	v_add_f32_e32 v80, 1.0, v81
	v_rcp_f32_e32 v89, v80
	v_add_f32_e32 v80, 1.0, v82
	v_mul_f32_e32 v72, 0xbfb8aa3b, v72
	v_rcp_f32_e32 v90, v80
	s_mov_b32 s0, 0xc000
	v_exp_f32_e32 v72, v72
	v_mul_f32_e32 v73, 0xbfb8aa3b, v73
	v_cvt_pk_bf16_f32 v80, v84, v85
	v_add_co_u32_e32 v84, vcc, s0, v120
	v_exp_f32_e32 v73, v73
	v_cvt_pk_bf16_f32 v81, v86, v87
	v_addc_co_u32_e32 v85, vcc, 0, v121, vcc
	s_mov_b32 s0, 0xd000
	global_store_dwordx2 v[84:85], v[80:81], off
	v_add_co_u32_e32 v80, vcc, s0, v120
	v_mul_f32_e32 v76, 0xbfb8aa3b, v76
	v_mul_f32_e32 v77, 0xbfb8aa3b, v77
	v_cvt_pk_bf16_f32 v82, v88, v83
	v_cvt_pk_bf16_f32 v83, v89, v90
	v_addc_co_u32_e32 v81, vcc, 0, v121, vcc
	v_exp_f32_e32 v76, v76
	v_exp_f32_e32 v77, v77
	v_mul_f32_e32 v78, 0xbfb8aa3b, v78
	v_mul_f32_e32 v79, 0xbfb8aa3b, v79
	v_add_f32_e32 v72, 1.0, v72
	global_store_dwordx2 v[80:81], v[82:83], off
	v_exp_f32_e32 v78, v78
	v_exp_f32_e32 v79, v79
	v_rcp_f32_e32 v80, v72
	v_add_f32_e32 v72, 1.0, v73
	v_mul_f32_e32 v73, 0xbfb8aa3b, v74
	v_exp_f32_e32 v73, v73
	v_mul_f32_e32 v74, 0xbfb8aa3b, v75
	v_exp_f32_e32 v74, v74
	v_add_f32_e32 v76, 1.0, v76
	v_add_f32_e32 v77, 1.0, v77
	v_rcp_f32_e32 v76, v76
	v_rcp_f32_e32 v77, v77
	v_add_f32_e32 v78, 1.0, v78
	v_add_f32_e32 v79, 1.0, v79
	v_rcp_f32_e32 v78, v78
	v_rcp_f32_e32 v79, v79
	v_rcp_f32_e32 v75, v72
	v_add_f32_e32 v72, 1.0, v73
	v_rcp_f32_e32 v81, v72
	v_add_f32_e32 v72, 1.0, v74
	v_mul_f32_e32 v64, 0xbfb8aa3b, v64
	v_rcp_f32_e32 v82, v72
	v_exp_f32_e32 v64, v64
	v_mul_f32_e32 v65, 0xbfb8aa3b, v65
	v_cvt_pk_bf16_f32 v72, v76, v77
	v_add_co_u32_e32 v76, vcc, s93, v120
	v_exp_f32_e32 v65, v65
	v_cvt_pk_bf16_f32 v73, v78, v79
	v_addc_co_u32_e32 v77, vcc, 0, v121, vcc
	s_movk_i32 s0, 0x7000
	global_store_dwordx2 v[76:77], v[72:73], off
	v_add_co_u32_e32 v72, vcc, s0, v120
	v_mul_f32_e32 v68, 0xbfb8aa3b, v68
	v_mul_f32_e32 v69, 0xbfb8aa3b, v69
	v_cvt_pk_bf16_f32 v74, v80, v75
	v_cvt_pk_bf16_f32 v75, v81, v82
	v_addc_co_u32_e32 v73, vcc, 0, v121, vcc
	v_exp_f32_e32 v68, v68
	v_exp_f32_e32 v69, v69
	v_mul_f32_e32 v70, 0xbfb8aa3b, v70
	v_mul_f32_e32 v71, 0xbfb8aa3b, v71
	v_add_f32_e32 v64, 1.0, v64
	global_store_dwordx2 v[72:73], v[74:75], off
	v_exp_f32_e32 v70, v70
	v_exp_f32_e32 v71, v71
	v_rcp_f32_e32 v72, v64
	v_add_f32_e32 v64, 1.0, v65
	v_mul_f32_e32 v65, 0xbfb8aa3b, v66
	v_exp_f32_e32 v65, v65
	v_mul_f32_e32 v66, 0xbfb8aa3b, v67
	v_exp_f32_e32 v66, v66
	v_add_f32_e32 v68, 1.0, v68
	v_add_f32_e32 v69, 1.0, v69
	v_rcp_f32_e32 v68, v68
	v_rcp_f32_e32 v69, v69
	v_add_f32_e32 v70, 1.0, v70
	v_add_f32_e32 v71, 1.0, v71
	v_rcp_f32_e32 v70, v70
	v_rcp_f32_e32 v71, v71
	v_rcp_f32_e32 v67, v64
	v_add_f32_e32 v64, 1.0, v65
	v_rcp_f32_e32 v73, v64
	v_add_f32_e32 v64, 1.0, v66
	v_mul_f32_e32 v56, 0xbfb8aa3b, v56
	v_rcp_f32_e32 v74, v64
	s_mov_b32 s0, 0xe000
	v_exp_f32_e32 v56, v56
	v_mul_f32_e32 v57, 0xbfb8aa3b, v57
	v_cvt_pk_bf16_f32 v64, v68, v69
	v_add_co_u32_e32 v68, vcc, s0, v120
	v_exp_f32_e32 v57, v57
	v_cvt_pk_bf16_f32 v65, v70, v71
	v_addc_co_u32_e32 v69, vcc, 0, v121, vcc
	s_mov_b32 s0, 0xf000
	global_store_dwordx2 v[68:69], v[64:65], off
	v_add_co_u32_e32 v64, vcc, s0, v120
	v_mul_f32_e32 v60, 0xbfb8aa3b, v60
	v_mul_f32_e32 v61, 0xbfb8aa3b, v61
	v_cvt_pk_bf16_f32 v66, v72, v67
	v_cvt_pk_bf16_f32 v67, v73, v74
	v_addc_co_u32_e32 v65, vcc, 0, v121, vcc
	v_exp_f32_e32 v60, v60
	v_exp_f32_e32 v61, v61
	v_mul_f32_e32 v62, 0xbfb8aa3b, v62
	v_mul_f32_e32 v63, 0xbfb8aa3b, v63
	v_add_f32_e32 v56, 1.0, v56
	global_store_dwordx2 v[64:65], v[66:67], off
; __device__ __forceinline__ unsigned cvt_pk_bf16(float lo, float hi) { f32x2 v = {lo, hi}; bf16x2_t b = __builtin_convertvector(v, bf16x2_t); return __builtin_bit_cast(unsigned, b); }
; __device__ __forceinline__ float sigmoidf_(float v) { return __builtin_amdgcn_rcpf(1.0f + __builtin_amdgcn_exp2f(-1.4426950408889634f * v)); }
; #define FOR_AI_M _Pragma("unroll") for (int ai = 0; ai < 2; ++ai) _Pragma("unroll") for (int m = 0; m < 4; ++m)
;     __device__ __forceinline__ void operator()(const f32x4 (&acc)[2][2][4][2], const Unit& u, int wr, int wc, int fr, int fq) const {
;     ...
;         if ((sub & 1) == 0) {
;             FOR_AI_M {
; #pragma unroll
;                 for (int bj = 0; bj < 2; ++bj) {
;                     const int i0 = (((ai * 2 + bj) * 4 + m) * 2) * 512 + tid, i1 = i0 + 512;
;                     const f32x4 a = acc[ai][bj][m][0], b = acc[ai][bj][m][1];
;                     u32x2 w0, w1; w0.x = cvt_pk_bf16(sigmoidf_(a[0]), sigmoidf_(a[1])); w0.y = cvt_pk_bf16(sigmoidf_(a[2]), sigmoidf_(a[3]));
;                     w1.x = cvt_pk_bf16(sigmoidf_(b[0]), sigmoidf_(b[1])); w1.y = cvt_pk_bf16(sigmoidf_(b[2]), sigmoidf_(b[3]));
;                     *(u32x2*)(stg + (size_t)i0 * 2) = w0; *(u32x2*)(stg + (size_t)i1 * 2) = w1;
;                 }
;                 asm volatile("" ::: "memory");
;             }
;             return;
	v_exp_f32_e32 v62, v62
	v_exp_f32_e32 v63, v63
	v_rcp_f32_e32 v64, v56
	v_add_f32_e32 v56, 1.0, v57
	v_mul_f32_e32 v57, 0xbfb8aa3b, v58
	v_exp_f32_e32 v57, v57
	v_mul_f32_e32 v58, 0xbfb8aa3b, v59
	v_exp_f32_e32 v58, v58
	v_add_f32_e32 v60, 1.0, v60
	v_add_f32_e32 v61, 1.0, v61
	v_rcp_f32_e32 v60, v60
	v_rcp_f32_e32 v61, v61
	v_add_f32_e32 v62, 1.0, v62
	v_add_f32_e32 v63, 1.0, v63
	v_rcp_f32_e32 v62, v62
	v_rcp_f32_e32 v63, v63
	v_rcp_f32_e32 v59, v56
	v_add_f32_e32 v56, 1.0, v57
	v_rcp_f32_e32 v65, v56
	v_add_f32_e32 v56, 1.0, v58
	v_mul_f32_e32 v48, 0xbfb8aa3b, v48
	v_rcp_f32_e32 v66, v56
	s_mov_b32 s0, 0x10000
	v_exp_f32_e32 v48, v48
	v_mul_f32_e32 v49, 0xbfb8aa3b, v49
	v_cvt_pk_bf16_f32 v56, v60, v61
	v_add_co_u32_e32 v60, vcc, s0, v120
	v_exp_f32_e32 v49, v49
	v_cvt_pk_bf16_f32 v57, v62, v63
	v_addc_co_u32_e32 v61, vcc, 0, v121, vcc
	s_mov_b32 s0, 0x11000
	global_store_dwordx2 v[60:61], v[56:57], off
	v_add_co_u32_e32 v56, vcc, s0, v120
	v_mul_f32_e32 v52, 0xbfb8aa3b, v52
	v_mul_f32_e32 v53, 0xbfb8aa3b, v53
	v_cvt_pk_bf16_f32 v58, v64, v59
	v_cvt_pk_bf16_f32 v59, v65, v66
	v_addc_co_u32_e32 v57, vcc, 0, v121, vcc
	v_exp_f32_e32 v52, v52
	v_exp_f32_e32 v53, v53
	v_mul_f32_e32 v54, 0xbfb8aa3b, v54
	v_mul_f32_e32 v55, 0xbfb8aa3b, v55
	v_add_f32_e32 v48, 1.0, v48
	global_store_dwordx2 v[56:57], v[58:59], off
	v_exp_f32_e32 v54, v54
	v_exp_f32_e32 v55, v55
	v_rcp_f32_e32 v56, v48
	v_add_f32_e32 v48, 1.0, v49
	v_mul_f32_e32 v49, 0xbfb8aa3b, v50
	v_exp_f32_e32 v49, v49
	v_mul_f32_e32 v50, 0xbfb8aa3b, v51
	v_exp_f32_e32 v50, v50
	v_add_f32_e32 v52, 1.0, v52
	v_add_f32_e32 v53, 1.0, v53
	v_rcp_f32_e32 v52, v52
	v_rcp_f32_e32 v53, v53
	v_add_f32_e32 v54, 1.0, v54
	v_add_f32_e32 v55, 1.0, v55
	v_rcp_f32_e32 v54, v54
	v_rcp_f32_e32 v55, v55
	v_rcp_f32_e32 v51, v48
	v_add_f32_e32 v48, 1.0, v49
	v_rcp_f32_e32 v57, v48
	v_add_f32_e32 v48, 1.0, v50
	v_mul_f32_e32 v40, 0xbfb8aa3b, v40
	v_rcp_f32_e32 v58, v48
	s_mov_b32 s0, 0x18000
	v_exp_f32_e32 v40, v40
	v_mul_f32_e32 v41, 0xbfb8aa3b, v41
	v_cvt_pk_bf16_f32 v48, v52, v53
	v_add_co_u32_e32 v52, vcc, s0, v120
	v_exp_f32_e32 v41, v41
	v_cvt_pk_bf16_f32 v49, v54, v55
	v_addc_co_u32_e32 v53, vcc, 0, v121, vcc
	s_mov_b32 s0, 0x19000
	global_store_dwordx2 v[52:53], v[48:49], off
	v_add_co_u32_e32 v48, vcc, s0, v120
	v_mul_f32_e32 v44, 0xbfb8aa3b, v44
	v_mul_f32_e32 v45, 0xbfb8aa3b, v45
	v_cvt_pk_bf16_f32 v50, v56, v51
	v_cvt_pk_bf16_f32 v51, v57, v58
	v_addc_co_u32_e32 v49, vcc, 0, v121, vcc
	v_exp_f32_e32 v44, v44
	v_exp_f32_e32 v45, v45
	v_mul_f32_e32 v46, 0xbfb8aa3b, v46
	v_mul_f32_e32 v47, 0xbfb8aa3b, v47
	v_add_f32_e32 v40, 1.0, v40
	global_store_dwordx2 v[48:49], v[50:51], off
	v_exp_f32_e32 v46, v46
	v_exp_f32_e32 v47, v47
	v_rcp_f32_e32 v48, v40
	v_add_f32_e32 v40, 1.0, v41
	v_mul_f32_e32 v41, 0xbfb8aa3b, v42
	v_exp_f32_e32 v41, v41
	v_mul_f32_e32 v42, 0xbfb8aa3b, v43
	v_exp_f32_e32 v42, v42
	v_add_f32_e32 v44, 1.0, v44
	v_add_f32_e32 v45, 1.0, v45
	v_rcp_f32_e32 v44, v44
	v_rcp_f32_e32 v45, v45
	v_add_f32_e32 v46, 1.0, v46
	v_add_f32_e32 v47, 1.0, v47
	v_rcp_f32_e32 v46, v46
	v_rcp_f32_e32 v47, v47
	v_rcp_f32_e32 v43, v40
	v_add_f32_e32 v40, 1.0, v41
	v_rcp_f32_e32 v49, v40
	v_add_f32_e32 v40, 1.0, v42
	v_mul_f32_e32 v32, 0xbfb8aa3b, v32
	v_rcp_f32_e32 v50, v40
	s_mov_b32 s0, 0x12000
	v_exp_f32_e32 v32, v32
	v_mul_f32_e32 v33, 0xbfb8aa3b, v33
	v_cvt_pk_bf16_f32 v40, v44, v45
	v_add_co_u32_e32 v44, vcc, s0, v120
	v_exp_f32_e32 v33, v33
	v_cvt_pk_bf16_f32 v41, v46, v47
	v_addc_co_u32_e32 v45, vcc, 0, v121, vcc
	s_mov_b32 s0, 0x13000
	global_store_dwordx2 v[44:45], v[40:41], off
	v_add_co_u32_e32 v40, vcc, s0, v120
	v_mul_f32_e32 v36, 0xbfb8aa3b, v36
	v_mul_f32_e32 v37, 0xbfb8aa3b, v37
	v_cvt_pk_bf16_f32 v42, v48, v43
	v_cvt_pk_bf16_f32 v43, v49, v50
	v_addc_co_u32_e32 v41, vcc, 0, v121, vcc
	v_exp_f32_e32 v36, v36
	v_exp_f32_e32 v37, v37
	v_mul_f32_e32 v38, 0xbfb8aa3b, v38
	v_mul_f32_e32 v39, 0xbfb8aa3b, v39
	v_add_f32_e32 v32, 1.0, v32
	global_store_dwordx2 v[40:41], v[42:43], off
	v_exp_f32_e32 v38, v38
	v_exp_f32_e32 v39, v39
	v_rcp_f32_e32 v40, v32
	v_add_f32_e32 v32, 1.0, v33
	v_mul_f32_e32 v33, 0xbfb8aa3b, v34
	v_exp_f32_e32 v33, v33
	v_mul_f32_e32 v34, 0xbfb8aa3b, v35
	v_exp_f32_e32 v34, v34
	v_add_f32_e32 v36, 1.0, v36
	v_add_f32_e32 v37, 1.0, v37
	v_rcp_f32_e32 v36, v36
	v_rcp_f32_e32 v37, v37
	v_add_f32_e32 v38, 1.0, v38
	v_add_f32_e32 v39, 1.0, v39
	v_rcp_f32_e32 v38, v38
	v_rcp_f32_e32 v39, v39
	v_rcp_f32_e32 v35, v32
	v_add_f32_e32 v32, 1.0, v33
	v_rcp_f32_e32 v41, v32
	v_add_f32_e32 v32, 1.0, v34
	v_mul_f32_e32 v24, 0xbfb8aa3b, v24
	v_rcp_f32_e32 v42, v32
	s_mov_b32 s0, 0x1a000
	v_exp_f32_e32 v24, v24
	v_mul_f32_e32 v25, 0xbfb8aa3b, v25
	v_cvt_pk_bf16_f32 v32, v36, v37
	v_add_co_u32_e32 v36, vcc, s0, v120
	v_exp_f32_e32 v25, v25
	v_cvt_pk_bf16_f32 v33, v38, v39
	v_addc_co_u32_e32 v37, vcc, 0, v121, vcc
	s_mov_b32 s0, 0x1b000
	global_store_dwordx2 v[36:37], v[32:33], off
	v_add_co_u32_e32 v32, vcc, s0, v120
	v_mul_f32_e32 v28, 0xbfb8aa3b, v28
	v_mul_f32_e32 v29, 0xbfb8aa3b, v29
	v_cvt_pk_bf16_f32 v34, v40, v35
	v_cvt_pk_bf16_f32 v35, v41, v42
	v_addc_co_u32_e32 v33, vcc, 0, v121, vcc
; __device__ __forceinline__ unsigned cvt_pk_bf16(float lo, float hi) { f32x2 v = {lo, hi}; bf16x2_t b = __builtin_convertvector(v, bf16x2_t); return __builtin_bit_cast(unsigned, b); }
; __device__ __forceinline__ float sigmoidf_(float v) { return __builtin_amdgcn_rcpf(1.0f + __builtin_amdgcn_exp2f(-1.4426950408889634f * v)); }
; #define FOR_AI_M _Pragma("unroll") for (int ai = 0; ai < 2; ++ai) _Pragma("unroll") for (int m = 0; m < 4; ++m)
;     __device__ __forceinline__ void operator()(const f32x4 (&acc)[2][2][4][2], const Unit& u, int wr, int wc, int fr, int fq) const {
;     ...
;         if ((sub & 1) == 0) {
;             FOR_AI_M {
; #pragma unroll
;                 for (int bj = 0; bj < 2; ++bj) {
;                     const int i0 = (((ai * 2 + bj) * 4 + m) * 2) * 512 + tid, i1 = i0 + 512;
;                     const f32x4 a = acc[ai][bj][m][0], b = acc[ai][bj][m][1];
;                     u32x2 w0, w1; w0.x = cvt_pk_bf16(sigmoidf_(a[0]), sigmoidf_(a[1])); w0.y = cvt_pk_bf16(sigmoidf_(a[2]), sigmoidf_(a[3]));
;                     w1.x = cvt_pk_bf16(sigmoidf_(b[0]), sigmoidf_(b[1])); w1.y = cvt_pk_bf16(sigmoidf_(b[2]), sigmoidf_(b[3]));
;                     *(u32x2*)(stg + (size_t)i0 * 2) = w0; *(u32x2*)(stg + (size_t)i1 * 2) = w1;
;                 }
;                 asm volatile("" ::: "memory");
;             }
;             return;
	v_exp_f32_e32 v28, v28
	v_exp_f32_e32 v29, v29
	v_mul_f32_e32 v30, 0xbfb8aa3b, v30
	v_mul_f32_e32 v31, 0xbfb8aa3b, v31
	v_add_f32_e32 v24, 1.0, v24
	global_store_dwordx2 v[32:33], v[34:35], off
	v_exp_f32_e32 v30, v30
	v_exp_f32_e32 v31, v31
	v_rcp_f32_e32 v32, v24
	v_add_f32_e32 v24, 1.0, v25
	v_mul_f32_e32 v25, 0xbfb8aa3b, v26
	v_exp_f32_e32 v25, v25
	v_mul_f32_e32 v26, 0xbfb8aa3b, v27
	v_exp_f32_e32 v26, v26
	v_add_f32_e32 v28, 1.0, v28
	v_add_f32_e32 v29, 1.0, v29
	v_rcp_f32_e32 v28, v28
	v_rcp_f32_e32 v29, v29
	v_add_f32_e32 v30, 1.0, v30
	v_add_f32_e32 v31, 1.0, v31
	v_rcp_f32_e32 v30, v30
	v_rcp_f32_e32 v31, v31
	v_rcp_f32_e32 v27, v24
	v_add_f32_e32 v24, 1.0, v25
	v_rcp_f32_e32 v33, v24
	v_add_f32_e32 v24, 1.0, v26
	v_mul_f32_e32 v16, 0xbfb8aa3b, v16
	v_rcp_f32_e32 v34, v24
	s_mov_b32 s0, 0x14000
	v_exp_f32_e32 v16, v16
	v_mul_f32_e32 v17, 0xbfb8aa3b, v17
	v_cvt_pk_bf16_f32 v24, v28, v29
	v_add_co_u32_e32 v28, vcc, s0, v120
	v_exp_f32_e32 v17, v17
	v_cvt_pk_bf16_f32 v25, v30, v31
	v_addc_co_u32_e32 v29, vcc, 0, v121, vcc
	s_mov_b32 s0, 0x15000
	global_store_dwordx2 v[28:29], v[24:25], off
	v_add_co_u32_e32 v24, vcc, s0, v120
	v_mul_f32_e32 v20, 0xbfb8aa3b, v20
	v_mul_f32_e32 v21, 0xbfb8aa3b, v21
	v_cvt_pk_bf16_f32 v26, v32, v27
	v_cvt_pk_bf16_f32 v27, v33, v34
	v_addc_co_u32_e32 v25, vcc, 0, v121, vcc
	v_exp_f32_e32 v20, v20
	v_exp_f32_e32 v21, v21
	v_mul_f32_e32 v22, 0xbfb8aa3b, v22
	v_mul_f32_e32 v23, 0xbfb8aa3b, v23
	v_add_f32_e32 v16, 1.0, v16
	global_store_dwordx2 v[24:25], v[26:27], off
	v_exp_f32_e32 v22, v22
	v_exp_f32_e32 v23, v23
	v_rcp_f32_e32 v24, v16
	v_add_f32_e32 v16, 1.0, v17
	v_mul_f32_e32 v17, 0xbfb8aa3b, v18
	v_exp_f32_e32 v17, v17
	v_mul_f32_e32 v18, 0xbfb8aa3b, v19
	v_exp_f32_e32 v18, v18
	v_add_f32_e32 v20, 1.0, v20
	v_add_f32_e32 v21, 1.0, v21
	v_rcp_f32_e32 v20, v20
	v_rcp_f32_e32 v21, v21
	v_add_f32_e32 v22, 1.0, v22
	v_add_f32_e32 v23, 1.0, v23
	v_rcp_f32_e32 v22, v22
	v_rcp_f32_e32 v23, v23
	v_rcp_f32_e32 v19, v16
	v_add_f32_e32 v16, 1.0, v17
	v_rcp_f32_e32 v25, v16
	v_add_f32_e32 v16, 1.0, v18
	v_mul_f32_e32 v8, 0xbfb8aa3b, v8
	v_rcp_f32_e32 v26, v16
	s_mov_b32 s0, 0x1c000
	v_exp_f32_e32 v8, v8
	v_mul_f32_e32 v9, 0xbfb8aa3b, v9
	v_cvt_pk_bf16_f32 v16, v20, v21
	v_add_co_u32_e32 v20, vcc, s0, v120
	v_exp_f32_e32 v9, v9
	v_cvt_pk_bf16_f32 v17, v22, v23
	v_addc_co_u32_e32 v21, vcc, 0, v121, vcc
	s_mov_b32 s0, 0x1d000
	global_store_dwordx2 v[20:21], v[16:17], off
	v_add_co_u32_e32 v16, vcc, s0, v120
	v_mul_f32_e32 v12, 0xbfb8aa3b, v12
	v_mul_f32_e32 v13, 0xbfb8aa3b, v13
	v_cvt_pk_bf16_f32 v18, v24, v19
	v_cvt_pk_bf16_f32 v19, v25, v26
	v_addc_co_u32_e32 v17, vcc, 0, v121, vcc
	v_exp_f32_e32 v12, v12
	v_exp_f32_e32 v13, v13
	v_mul_f32_e32 v14, 0xbfb8aa3b, v14
	v_mul_f32_e32 v15, 0xbfb8aa3b, v15
	v_add_f32_e32 v8, 1.0, v8
	global_store_dwordx2 v[16:17], v[18:19], off
	v_exp_f32_e32 v14, v14
	v_exp_f32_e32 v15, v15
	v_rcp_f32_e32 v16, v8
	v_add_f32_e32 v8, 1.0, v9
	v_mul_f32_e32 v9, 0xbfb8aa3b, v10
	v_exp_f32_e32 v9, v9
	v_mul_f32_e32 v10, 0xbfb8aa3b, v11
	v_exp_f32_e32 v10, v10
	v_add_f32_e32 v12, 1.0, v12
	v_add_f32_e32 v13, 1.0, v13
	v_rcp_f32_e32 v12, v12
	v_rcp_f32_e32 v13, v13
	v_add_f32_e32 v14, 1.0, v14
	v_add_f32_e32 v15, 1.0, v15
	v_rcp_f32_e32 v14, v14
	v_rcp_f32_e32 v15, v15
	v_rcp_f32_e32 v11, v8
	v_add_f32_e32 v8, 1.0, v9
	v_rcp_f32_e32 v17, v8
	v_add_f32_e32 v8, 1.0, v10
	v_mul_f32_e32 v0, 0xbfb8aa3b, v0
	v_rcp_f32_e32 v18, v8
	s_mov_b32 s0, 0x16000
	v_exp_f32_e32 v0, v0
	v_mul_f32_e32 v1, 0xbfb8aa3b, v1
	v_cvt_pk_bf16_f32 v8, v12, v13
	v_add_co_u32_e32 v12, vcc, s0, v120
	v_exp_f32_e32 v1, v1
	v_cvt_pk_bf16_f32 v9, v14, v15
	v_addc_co_u32_e32 v13, vcc, 0, v121, vcc
	s_mov_b32 s0, 0x17000
	global_store_dwordx2 v[12:13], v[8:9], off
	v_add_co_u32_e32 v8, vcc, s0, v120
	v_mul_f32_e32 v4, 0xbfb8aa3b, v4
	v_mul_f32_e32 v5, 0xbfb8aa3b, v5
	v_cvt_pk_bf16_f32 v10, v16, v11
	v_cvt_pk_bf16_f32 v11, v17, v18
	v_addc_co_u32_e32 v9, vcc, 0, v121, vcc
	v_exp_f32_e32 v4, v4
	v_exp_f32_e32 v5, v5
	v_mul_f32_e32 v6, 0xbfb8aa3b, v6
	v_mul_f32_e32 v7, 0xbfb8aa3b, v7
	v_add_f32_e32 v0, 1.0, v0
	global_store_dwordx2 v[8:9], v[10:11], off
	v_exp_f32_e32 v6, v6
	v_exp_f32_e32 v7, v7
	v_rcp_f32_e32 v8, v0
	v_add_f32_e32 v0, 1.0, v1
	v_mul_f32_e32 v1, 0xbfb8aa3b, v2
	v_exp_f32_e32 v1, v1
	v_mul_f32_e32 v2, 0xbfb8aa3b, v3
	v_exp_f32_e32 v2, v2
	v_add_f32_e32 v4, 1.0, v4
	v_add_f32_e32 v5, 1.0, v5
	v_rcp_f32_e32 v4, v4
	v_rcp_f32_e32 v5, v5
	v_add_f32_e32 v6, 1.0, v6
	v_add_f32_e32 v7, 1.0, v7
	v_rcp_f32_e32 v6, v6
	v_rcp_f32_e32 v7, v7
	v_rcp_f32_e32 v3, v0
	v_add_f32_e32 v0, 1.0, v1
	v_rcp_f32_e32 v9, v0
	v_add_f32_e32 v0, 1.0, v2
	v_rcp_f32_e32 v10, v0
	v_cvt_pk_bf16_f32 v0, v4, v5
	v_add_co_u32_e32 v4, vcc, 0x1e000, v120
	v_cvt_pk_bf16_f32 v1, v6, v7
	s_nop 0
	v_addc_co_u32_e32 v5, vcc, 0, v121, vcc
	global_store_dwordx2 v[4:5], v[0:1], off
	v_add_co_u32_e32 v0, vcc, 0x1f000, v120
	v_cvt_pk_bf16_f32 v2, v8, v3
	v_cvt_pk_bf16_f32 v3, v9, v10
	v_addc_co_u32_e32 v1, vcc, 0, v121, vcc
	global_store_dwordx2 v[0:1], v[2:3], off
	s_andn2_b64 vcc, exec, s[18:19]
	s_mov_b64 s[0:1], -1
	s_cbranch_vccnz .LBB0_232

; __device__ __forceinline__ unsigned cvt_pk_bf16(float lo, float hi) { f32x2 v = {lo, hi}; bf16x2_t b = __builtin_convertvector(v, bf16x2_t); return __builtin_bit_cast(unsigned, b); }
; __device__ __forceinline__ float bflo(unsigned w) { return __uint_as_float(w << 16); }
; __device__ __forceinline__ float bfhi(unsigned w) { return __uint_as_float(w & 0xffff0000u); }
; __device__ __forceinline__ float sigmoidf_(float v) { return __builtin_amdgcn_rcpf(1.0f + __builtin_amdgcn_exp2f(-1.4426950408889634f * v)); }
;     __device__ __forceinline__ void operator()(const f32x4 (&acc)[2][2][4][2], const Unit& u, int wr, int wc, int fr, int fq) const {
;         f32x4 bv[2][2];
; #pragma unroll
;         for (int bj = 0; bj < 2; ++bj)
; #pragma unroll
;             for (int n = 0; n < 2; ++n) bv[bj][n] = *(const f32x4*)(bglu + 256 * u.pn + 128 * bj + 32 * wc + 8 * fq + 4 * n);
;         const size_t col0 = (size_t)256 * u.pn + 32 * wc + 8 * fq;
;         u32x4 gpre[2][2];
; #pragma unroll
;         for (int bj = 0; bj < 2; ++bj) gpre[0][bj] = *(const u32x4*)(GACT + ((size_t)256 * u.pm + 64 * wr + fr) * 1024 + col0 + 128 * bj);
; #pragma unroll
;         for (int g = 0; g < 8; ++g) {
;             const int ai = g >> 2, m = g & 3;
;             const size_t row = (size_t)256 * u.pm + 128 * ai + 64 * wr + 16 * m + fr;
;             if (g + 1 < 8) {
;                 const size_t rn = (size_t)256 * u.pm + 128 * ((g + 1) >> 2) + 64 * wr + 16 * ((g + 1) & 3) + fr;
; #pragma unroll
;                 for (int bj = 0; bj < 2; ++bj) gpre[(g + 1) & 1][bj] = *(const u32x4*)(GACT + rn * 1024 + col0 + 128 * bj);
;             }
;             asm volatile("" ::: "memory");
; #pragma unroll
;             for (int bj = 0; bj < 2; ++bj) {
;                 const u32x4 gv = gpre[g & 1][bj];
;                 const f32x4 a = acc[ai][bj][m][0] + bv[bj][0], b = acc[ai][bj][m][1] + bv[bj][1];
;                 u32x4 w;
;                 w.x = cvt_pk_bf16(bflo(gv.x) * sigmoidf_(a[0]), bfhi(gv.x) * sigmoidf_(a[1])); w.y = cvt_pk_bf16(bflo(gv.y) * sigmoidf_(a[2]), bfhi(gv.y) * sigmoidf_(a[3]));
;                 w.z = cvt_pk_bf16(bflo(gv.z) * sigmoidf_(b[0]), bfhi(gv.z) * sigmoidf_(b[1])); w.w = cvt_pk_bf16(bflo(gv.w) * sigmoidf_(b[2]), bfhi(gv.w) * sigmoidf_(b[3]));
;                 *(u32x4*)(YB + row * 1024 + col0 + 128 * bj) = w;
;             }
;         }
;     }
.LBB0_387:
	s_lshl_b32 s2, s18, 8
	s_ashr_i32 s3, s2, 31
	v_mov_b32_e32 v40, v173
	v_mov_b32_e32 v136, v172
	s_lshl_b64 s[2:3], s[2:3], 2
	s_add_u32 s2, s11, s2
	v_lshlrev_b32_e32 v138, 3, v40
	s_addc_u32 s3, s10, s3
	v_ashrrev_i32_e32 v139, 31, v138
	s_ashr_i32 s19, s18, 31
	v_lshl_add_u64 v[44:45], v[138:139], 2, s[2:3]
	s_lshl_b64 s[2:3], s[18:19], 8
	v_readlane_b32 s18, v253, 15
	global_load_dwordx4 v[56:59], v[44:45], off offset:16
	global_load_dwordx4 v[60:63], v[44:45], off
	global_load_dwordx4 v[40:43], v[44:45], off offset:528
	s_nop 0
	global_load_dwordx4 v[44:47], v[44:45], off offset:512
	v_readlane_b32 s19, v253, 16
	s_or_b64 s[2:3], s[2:3], s[18:19]
	s_ashr_i32 s17, s16, 31
	v_lshl_add_u64 v[138:139], s[2:3], 0, v[138:139]
	s_lshl_b64 s[2:3], s[16:17], 8
	s_add_u32 s2, s2, s7
	s_addc_u32 s3, s3, s23
	v_ashrrev_i32_e32 v137, 31, v136
	v_lshl_add_u64 v[136:137], s[2:3], 0, v[136:137]
	v_lshlrev_b64 v[168:169], 11, v[136:137]
	v_lshl_add_u64 v[136:137], s[0:1], 0, v[168:169]
	v_lshlrev_b64 v[170:171], 1, v[138:139]
	v_lshl_add_u64 v[166:167], v[136:137], 0, v[170:171]
	global_load_dwordx4 v[176:179], v[166:167], off
	global_load_dwordx4 v[152:155], v[166:167], off offset:256
	s_mov_b32 s13, 0x8000
	s_mov_b64 s[2:3], 0x8000
	v_add_co_u32_e32 v138, vcc, s13, v166
	v_lshl_add_u64 v[136:137], v[166:167], 0, s[2:3]
	s_nop 0
	v_addc_co_u32_e32 v139, vcc, 0, v167, vcc
	global_load_dwordx4 v[140:143], v[138:139], off
	s_nop 0
	global_load_dwordx4 v[136:139], v[136:137], off offset:256
	s_mov_b32 s18, 0x10000
	s_mov_b64 s[16:17], 0x10000
	s_waitcnt vmcnt(0)
	v_pk_add_f32 v[180:181], v[146:147], v[58:59]
	v_pk_add_f32 v[148:149], v[148:149], v[60:61]
	v_pk_add_f32 v[146:147], v[144:145], v[56:57]
	v_mul_f32_e32 v144, 0xbfb8aa3b, v148
	v_mul_f32_e32 v145, 0xbfb8aa3b, v149
	v_exp_f32_e32 v144, v144
	v_exp_f32_e32 v145, v145
	v_pk_add_f32 v[150:151], v[150:151], v[62:63]
	v_mul_f32_e32 v146, 0xbfb8aa3b, v146
	v_add_f32_e32 v144, 1.0, v144
	v_add_f32_e32 v145, 1.0, v145
	v_rcp_f32_e32 v144, v144
	v_rcp_f32_e32 v145, v145
	v_mul_f32_e32 v147, 0xbfb8aa3b, v147
	v_exp_f32_e32 v146, v146
	v_exp_f32_e32 v147, v147
	s_waitcnt lgkmcnt(0)
	v_lshlrev_b32_e32 v148, 16, v176
	v_and_b32_e32 v149, 0xffff0000, v176
	v_pk_mul_f32 v[144:145], v[144:145], v[148:149]
	v_add_f32_e32 v146, 1.0, v146
	v_cvt_pk_bf16_f32 v144, v144, v145
	v_mul_f32_e32 v145, 0xbfb8aa3b, v150
	v_exp_f32_e32 v145, v145
	v_add_f32_e32 v147, 1.0, v147
	v_rcp_f32_e32 v146, v146
	v_rcp_f32_e32 v147, v147
	v_add_f32_e32 v145, 1.0, v145
	v_rcp_f32_e32 v148, v145
	v_mul_f32_e32 v145, 0xbfb8aa3b, v151
	v_exp_f32_e32 v145, v145
	v_lshlrev_b32_e32 v150, 16, v177
	v_and_b32_e32 v151, 0xffff0000, v177
	v_pk_add_f32 v[132:133], v[132:133], v[44:45]
	v_add_f32_e32 v145, 1.0, v145
	v_rcp_f32_e32 v149, v145
	v_mul_f32_e32 v132, 0xbfb8aa3b, v132
	v_mul_f32_e32 v133, 0xbfb8aa3b, v133
	v_exp_f32_e32 v132, v132
	v_pk_mul_f32 v[148:149], v[148:149], v[150:151]
	v_exp_f32_e32 v133, v133
	v_cvt_pk_bf16_f32 v145, v148, v149
	v_lshlrev_b32_e32 v148, 16, v178
	v_and_b32_e32 v149, 0xffff0000, v178
	v_pk_mul_f32 v[146:147], v[146:147], v[148:149]
	v_lshlrev_b32_e32 v150, 16, v179
	v_cvt_pk_bf16_f32 v146, v146, v147
	v_mul_f32_e32 v147, 0xbfb8aa3b, v180
	v_exp_f32_e32 v147, v147
	v_and_b32_e32 v151, 0xffff0000, v179
	v_add_f32_e32 v132, 1.0, v132
	v_add_f32_e32 v133, 1.0, v133
	v_add_f32_e32 v147, 1.0, v147
	v_rcp_f32_e32 v148, v147
	v_mul_f32_e32 v147, 0xbfb8aa3b, v181
	v_exp_f32_e32 v147, v147
	v_rcp_f32_e32 v132, v132
	v_rcp_f32_e32 v133, v133
	v_pk_add_f32 v[134:135], v[134:135], v[46:47]
	v_add_f32_e32 v147, 1.0, v147
	v_rcp_f32_e32 v149, v147
	v_pk_add_f32 v[128:129], v[128:129], v[40:41]
	v_pk_add_f32 v[124:125], v[124:125], v[60:61]
	v_mul_f32_e32 v128, 0xbfb8aa3b, v128
	v_pk_mul_f32 v[148:149], v[148:149], v[150:151]
	v_mul_f32_e32 v129, 0xbfb8aa3b, v129
	v_cvt_pk_bf16_f32 v147, v148, v149
	v_lshl_add_u64 v[148:149], s[8:9], 0, v[168:169]
	v_lshl_add_u64 v[148:149], v[148:149], 0, v[170:171]
	global_store_dwordx4 v[148:149], v[144:147], off
	v_exp_f32_e32 v128, v128
	v_exp_f32_e32 v129, v129
	v_lshlrev_b32_e32 v144, 16, v152
	v_and_b32_e32 v145, 0xffff0000, v152
	v_pk_mul_f32 v[132:133], v[132:133], v[144:145]
	v_add_f32_e32 v128, 1.0, v128
	v_cvt_pk_bf16_f32 v132, v132, v133
	v_mul_f32_e32 v133, 0xbfb8aa3b, v134
	v_exp_f32_e32 v133, v133
	v_add_f32_e32 v129, 1.0, v129
	v_rcp_f32_e32 v128, v128
	v_rcp_f32_e32 v129, v129
	v_add_f32_e32 v133, 1.0, v133
	v_rcp_f32_e32 v134, v133
	v_mul_f32_e32 v133, 0xbfb8aa3b, v135
	v_exp_f32_e32 v133, v133
	v_lshlrev_b32_e32 v144, 16, v153
	v_and_b32_e32 v145, 0xffff0000, v153
	v_pk_add_f32 v[130:131], v[130:131], v[42:43]
	v_add_f32_e32 v133, 1.0, v133
	v_rcp_f32_e32 v135, v133
	v_pk_add_f32 v[126:127], v[126:127], v[62:63]
	v_pk_add_f32 v[116:117], v[116:117], v[44:45]
	v_pk_add_f32 v[118:119], v[118:119], v[46:47]
	v_pk_mul_f32 v[134:135], v[134:135], v[144:145]
	v_pk_add_f32 v[144:145], v[122:123], v[58:59]
	v_cvt_pk_bf16_f32 v133, v134, v135
	v_lshlrev_b32_e32 v134, 16, v154
	v_and_b32_e32 v135, 0xffff0000, v154
	v_pk_mul_f32 v[128:129], v[128:129], v[134:135]
	v_pk_add_f32 v[122:123], v[120:121], v[56:57]
	v_mul_f32_e32 v120, 0xbfb8aa3b, v124
	v_mul_f32_e32 v121, 0xbfb8aa3b, v125
	v_cvt_pk_bf16_f32 v134, v128, v129
	v_mul_f32_e32 v128, 0xbfb8aa3b, v130
	v_mul_f32_e32 v129, 0xbfb8aa3b, v131
	v_exp_f32_e32 v120, v120
	v_exp_f32_e32 v121, v121
	v_exp_f32_e32 v128, v128
	v_exp_f32_e32 v129, v129
	v_add_f32_e32 v120, 1.0, v120
	v_add_f32_e32 v121, 1.0, v121
	v_add_f32_e32 v128, 1.0, v128
	v_add_f32_e32 v129, 1.0, v129
	v_rcp_f32_e32 v120, v120
	v_rcp_f32_e32 v121, v121
; __device__ __forceinline__ unsigned cvt_pk_bf16(float lo, float hi) { f32x2 v = {lo, hi}; bf16x2_t b = __builtin_convertvector(v, bf16x2_t); return __builtin_bit_cast(unsigned, b); }
; __device__ __forceinline__ float bflo(unsigned w) { return __uint_as_float(w << 16); }
; __device__ __forceinline__ float bfhi(unsigned w) { return __uint_as_float(w & 0xffff0000u); }
; __device__ __forceinline__ float sigmoidf_(float v) { return __builtin_amdgcn_rcpf(1.0f + __builtin_amdgcn_exp2f(-1.4426950408889634f * v)); }
;     __device__ __forceinline__ void operator()(const f32x4 (&acc)[2][2][4][2], const Unit& u, int wr, int wc, int fr, int fq) const {
;     ...
;         for (int bj = 0; bj < 2; ++bj) gpre[0][bj] = *(const u32x4*)(GACT + ((size_t)256 * u.pm + 64 * wr + fr) * 1024 + col0 + 128 * bj);
; #pragma unroll
;         for (int g = 0; g < 8; ++g) {
;             const int ai = g >> 2, m = g & 3;
;             const size_t row = (size_t)256 * u.pm + 128 * ai + 64 * wr + 16 * m + fr;
;             if (g + 1 < 8) {
;                 const size_t rn = (size_t)256 * u.pm + 128 * ((g + 1) >> 2) + 64 * wr + 16 * ((g + 1) & 3) + fr;
; #pragma unroll
;                 for (int bj = 0; bj < 2; ++bj) gpre[(g + 1) & 1][bj] = *(const u32x4*)(GACT + rn * 1024 + col0 + 128 * bj);
;             }
;             asm volatile("" ::: "memory");
; #pragma unroll
;             for (int bj = 0; bj < 2; ++bj) {
;                 const u32x4 gv = gpre[g & 1][bj];
;                 const f32x4 a = acc[ai][bj][m][0] + bv[bj][0], b = acc[ai][bj][m][1] + bv[bj][1];
;                 u32x4 w;
;                 w.x = cvt_pk_bf16(bflo(gv.x) * sigmoidf_(a[0]), bfhi(gv.x) * sigmoidf_(a[1])); w.y = cvt_pk_bf16(bflo(gv.y) * sigmoidf_(a[2]), bfhi(gv.y) * sigmoidf_(a[3]));
;                 w.z = cvt_pk_bf16(bflo(gv.z) * sigmoidf_(b[0]), bfhi(gv.z) * sigmoidf_(b[1])); w.w = cvt_pk_bf16(bflo(gv.w) * sigmoidf_(b[2]), bfhi(gv.w) * sigmoidf_(b[3]));
;                 *(u32x4*)(YB + row * 1024 + col0 + 128 * bj) = w;
;             }
	v_rcp_f32_e32 v128, v128
	v_rcp_f32_e32 v129, v129
	v_lshlrev_b32_e32 v124, 16, v140
	v_and_b32_e32 v125, 0xffff0000, v140
	v_lshlrev_b32_e32 v130, 16, v155
	v_and_b32_e32 v131, 0xffff0000, v155
	v_pk_mul_f32 v[120:121], v[120:121], v[124:125]
	v_pk_mul_f32 v[128:129], v[128:129], v[130:131]
	v_cvt_pk_bf16_f32 v120, v120, v121
	v_mul_f32_e32 v121, 0xbfb8aa3b, v126
	v_cvt_pk_bf16_f32 v135, v128, v129
	v_add_co_u32_e32 v130, vcc, s18, v166
	v_exp_f32_e32 v121, v121
	global_store_dwordx4 v[148:149], v[132:135], off offset:256
	v_lshl_add_u64 v[128:129], v[166:167], 0, s[16:17]
	v_addc_co_u32_e32 v131, vcc, 0, v167, vcc
	global_load_dwordx4 v[132:135], v[130:131], off
	s_nop 0
	global_load_dwordx4 v[128:131], v[128:129], off offset:256
	v_add_f32_e32 v121, 1.0, v121
	v_rcp_f32_e32 v124, v121
	v_mul_f32_e32 v121, 0xbfb8aa3b, v127
	v_exp_f32_e32 v121, v121
	v_mul_f32_e32 v122, 0xbfb8aa3b, v122
	v_mul_f32_e32 v123, 0xbfb8aa3b, v123
	v_exp_f32_e32 v122, v122
	v_exp_f32_e32 v123, v123
	v_add_f32_e32 v121, 1.0, v121
	v_rcp_f32_e32 v125, v121
	v_add_f32_e32 v122, 1.0, v122
	v_add_f32_e32 v123, 1.0, v123
	v_rcp_f32_e32 v122, v122
	v_rcp_f32_e32 v123, v123
	v_lshlrev_b32_e32 v126, 16, v141
	v_and_b32_e32 v127, 0xffff0000, v141
	v_pk_mul_f32 v[124:125], v[124:125], v[126:127]
	v_lshlrev_b32_e32 v126, 16, v143
	v_cvt_pk_bf16_f32 v121, v124, v125
	v_lshlrev_b32_e32 v124, 16, v142
	v_and_b32_e32 v125, 0xffff0000, v142
	v_pk_mul_f32 v[122:123], v[122:123], v[124:125]
	v_and_b32_e32 v127, 0xffff0000, v143
	v_cvt_pk_bf16_f32 v122, v122, v123
	v_mul_f32_e32 v123, 0xbfb8aa3b, v144
	v_exp_f32_e32 v123, v123
	v_pk_add_f32 v[108:109], v[108:109], v[60:61]
	v_pk_add_f32 v[110:111], v[110:111], v[62:63]
	v_add_f32_e32 v123, 1.0, v123
	v_rcp_f32_e32 v124, v123
	v_mul_f32_e32 v123, 0xbfb8aa3b, v145
	v_exp_f32_e32 v123, v123
	v_pk_add_f32 v[100:101], v[100:101], v[44:45]
	v_pk_add_f32 v[102:103], v[102:103], v[46:47]
	v_pk_add_f32 v[92:93], v[92:93], v[60:61]
	v_add_f32_e32 v123, 1.0, v123
	v_rcp_f32_e32 v125, v123
	v_pk_add_f32 v[94:95], v[94:95], v[62:63]
	v_pk_add_f32 v[84:85], v[84:85], v[44:45]
	v_pk_add_f32 v[86:87], v[86:87], v[46:47]
	v_pk_mul_f32 v[124:125], v[124:125], v[126:127]
	v_add_co_u32_e32 v126, vcc, s13, v148
	v_cvt_pk_bf16_f32 v123, v124, v125
	s_nop 0
	v_addc_co_u32_e32 v127, vcc, 0, v149, vcc
	global_store_dwordx4 v[126:127], v[120:123], off
	v_lshl_add_u64 v[124:125], v[148:149], 0, s[2:3]
	s_mov_b32 s13, 0x18000
	v_pk_add_f32 v[120:121], v[114:115], v[42:43]
	v_pk_add_f32 v[114:115], v[112:113], v[40:41]
	v_mul_f32_e32 v112, 0xbfb8aa3b, v116
	v_mul_f32_e32 v113, 0xbfb8aa3b, v117
	v_exp_f32_e32 v112, v112
	v_exp_f32_e32 v113, v113
	v_lshlrev_b32_e32 v116, 16, v136
	v_and_b32_e32 v117, 0xffff0000, v136
	v_add_f32_e32 v112, 1.0, v112
	v_add_f32_e32 v113, 1.0, v113
	v_rcp_f32_e32 v112, v112
	v_rcp_f32_e32 v113, v113
	v_mul_f32_e32 v114, 0xbfb8aa3b, v114
	v_mul_f32_e32 v115, 0xbfb8aa3b, v115
	v_exp_f32_e32 v114, v114
	v_pk_mul_f32 v[112:113], v[112:113], v[116:117]
	v_exp_f32_e32 v115, v115
	v_cvt_pk_bf16_f32 v112, v112, v113
	v_mul_f32_e32 v113, 0xbfb8aa3b, v118
	v_exp_f32_e32 v113, v113
	v_add_f32_e32 v114, 1.0, v114
	v_add_f32_e32 v115, 1.0, v115
	v_rcp_f32_e32 v114, v114
	v_add_f32_e32 v113, 1.0, v113
	v_rcp_f32_e32 v116, v113
	v_mul_f32_e32 v113, 0xbfb8aa3b, v119
	v_exp_f32_e32 v113, v113
	v_rcp_f32_e32 v115, v115
	v_lshlrev_b32_e32 v118, 16, v137
	v_and_b32_e32 v119, 0xffff0000, v137
	v_add_f32_e32 v113, 1.0, v113
	v_rcp_f32_e32 v117, v113
	s_mov_b64 s[2:3], 0x18000
	v_pk_add_f32 v[76:77], v[76:77], v[60:61]
	v_pk_add_f32 v[78:79], v[78:79], v[62:63]
	v_pk_mul_f32 v[116:117], v[116:117], v[118:119]
	v_lshlrev_b32_e32 v118, 16, v139
	v_cvt_pk_bf16_f32 v113, v116, v117
	v_lshlrev_b32_e32 v116, 16, v138
	v_and_b32_e32 v117, 0xffff0000, v138
	v_pk_mul_f32 v[114:115], v[114:115], v[116:117]
	v_and_b32_e32 v119, 0xffff0000, v139
	v_cvt_pk_bf16_f32 v114, v114, v115
	v_mul_f32_e32 v115, 0xbfb8aa3b, v120
	v_exp_f32_e32 v115, v115
	v_pk_add_f32 v[68:69], v[68:69], v[44:45]
	v_pk_add_f32 v[70:71], v[70:71], v[46:47]
	v_pk_add_f32 v[52:53], v[52:53], v[60:61]
	v_add_f32_e32 v115, 1.0, v115
	v_rcp_f32_e32 v116, v115
	v_mul_f32_e32 v115, 0xbfb8aa3b, v121
	v_pk_add_f32 v[120:121], v[106:107], v[58:59]
	v_pk_add_f32 v[106:107], v[104:105], v[56:57]
	v_mul_f32_e32 v104, 0xbfb8aa3b, v108
	v_mul_f32_e32 v105, 0xbfb8aa3b, v109
	v_exp_f32_e32 v115, v115
	v_exp_f32_e32 v104, v104
	v_exp_f32_e32 v105, v105
	s_waitcnt vmcnt(0) lgkmcnt(0)
; __device__ __forceinline__ unsigned cvt_pk_bf16(float lo, float hi) { f32x2 v = {lo, hi}; bf16x2_t b = __builtin_convertvector(v, bf16x2_t); return __builtin_bit_cast(unsigned, b); }
; __device__ __forceinline__ float bflo(unsigned w) { return __uint_as_float(w << 16); }
; __device__ __forceinline__ float bfhi(unsigned w) { return __uint_as_float(w & 0xffff0000u); }
; __device__ __forceinline__ float sigmoidf_(float v) { return __builtin_amdgcn_rcpf(1.0f + __builtin_amdgcn_exp2f(-1.4426950408889634f * v)); }
;     __device__ __forceinline__ void operator()(const f32x4 (&acc)[2][2][4][2], const Unit& u, int wr, int wc, int fr, int fq) const {
;     ...
;         for (int bj = 0; bj < 2; ++bj) gpre[0][bj] = *(const u32x4*)(GACT + ((size_t)256 * u.pm + 64 * wr + fr) * 1024 + col0 + 128 * bj);
; #pragma unroll
;         for (int g = 0; g < 8; ++g) {
;             const int ai = g >> 2, m = g & 3;
;             const size_t row = (size_t)256 * u.pm + 128 * ai + 64 * wr + 16 * m + fr;
;             if (g + 1 < 8) {
;                 const size_t rn = (size_t)256 * u.pm + 128 * ((g + 1) >> 2) + 64 * wr + 16 * ((g + 1) & 3) + fr;
; #pragma unroll
;                 for (int bj = 0; bj < 2; ++bj) gpre[(g + 1) & 1][bj] = *(const u32x4*)(GACT + rn * 1024 + col0 + 128 * bj);
;             }
;             asm volatile("" ::: "memory");
; #pragma unroll
;             for (int bj = 0; bj < 2; ++bj) {
;                 const u32x4 gv = gpre[g & 1][bj];
;                 const f32x4 a = acc[ai][bj][m][0] + bv[bj][0], b = acc[ai][bj][m][1] + bv[bj][1];
;                 u32x4 w;
;                 w.x = cvt_pk_bf16(bflo(gv.x) * sigmoidf_(a[0]), bfhi(gv.x) * sigmoidf_(a[1])); w.y = cvt_pk_bf16(bflo(gv.y) * sigmoidf_(a[2]), bfhi(gv.y) * sigmoidf_(a[3]));
;                 w.z = cvt_pk_bf16(bflo(gv.z) * sigmoidf_(b[0]), bfhi(gv.z) * sigmoidf_(b[1])); w.w = cvt_pk_bf16(bflo(gv.w) * sigmoidf_(b[2]), bfhi(gv.w) * sigmoidf_(b[3]));
;                 *(u32x4*)(YB + row * 1024 + col0 + 128 * bj) = w;
;             }
	v_lshlrev_b32_e32 v108, 16, v132
	v_add_f32_e32 v115, 1.0, v115
	v_add_f32_e32 v104, 1.0, v104
	v_add_f32_e32 v105, 1.0, v105
	v_rcp_f32_e32 v117, v115
	v_rcp_f32_e32 v104, v104
	v_rcp_f32_e32 v105, v105
	v_and_b32_e32 v109, 0xffff0000, v132
	v_pk_mul_f32 v[116:117], v[116:117], v[118:119]
	v_mul_f32_e32 v106, 0xbfb8aa3b, v106
	v_pk_mul_f32 v[104:105], v[104:105], v[108:109]
	v_cvt_pk_bf16_f32 v115, v116, v117
	v_cvt_pk_bf16_f32 v104, v104, v105
	v_mul_f32_e32 v105, 0xbfb8aa3b, v110
	global_store_dwordx4 v[124:125], v[112:115], off offset:256
	v_exp_f32_e32 v105, v105
	v_mul_f32_e32 v107, 0xbfb8aa3b, v107
	v_add_co_u32_e32 v114, vcc, s13, v166
	v_lshl_add_u64 v[112:113], v[166:167], 0, s[2:3]
	s_nop 0
	v_addc_co_u32_e32 v115, vcc, 0, v167, vcc
	global_load_dwordx4 v[116:119], v[114:115], off
	s_nop 0
	global_load_dwordx4 v[112:115], v[112:113], off offset:256
	v_add_f32_e32 v105, 1.0, v105
	v_rcp_f32_e32 v108, v105
	v_mul_f32_e32 v105, 0xbfb8aa3b, v111
	v_exp_f32_e32 v105, v105
	v_exp_f32_e32 v106, v106
	v_exp_f32_e32 v107, v107
	v_lshlrev_b32_e32 v110, 16, v133
	v_add_f32_e32 v105, 1.0, v105
	v_rcp_f32_e32 v109, v105
	v_add_f32_e32 v106, 1.0, v106
	v_add_f32_e32 v107, 1.0, v107
	v_rcp_f32_e32 v106, v106
	v_rcp_f32_e32 v107, v107
	v_and_b32_e32 v111, 0xffff0000, v133
	v_pk_mul_f32 v[108:109], v[108:109], v[110:111]
	v_lshlrev_b32_e32 v110, 16, v135
	v_cvt_pk_bf16_f32 v105, v108, v109
	v_lshlrev_b32_e32 v108, 16, v134
	v_and_b32_e32 v109, 0xffff0000, v134
	v_pk_mul_f32 v[106:107], v[106:107], v[108:109]
	v_and_b32_e32 v111, 0xffff0000, v135
	v_cvt_pk_bf16_f32 v106, v106, v107
	v_mul_f32_e32 v107, 0xbfb8aa3b, v120
	v_exp_f32_e32 v107, v107
	v_pk_add_f32 v[54:55], v[54:55], v[62:63]
	v_pk_add_f32 v[36:37], v[36:37], v[44:45]
	v_add_f32_e32 v107, 1.0, v107
	v_rcp_f32_e32 v108, v107
	v_mul_f32_e32 v107, 0xbfb8aa3b, v121
	v_exp_f32_e32 v107, v107
	v_pk_add_f32 v[38:39], v[38:39], v[46:47]
	v_pk_add_f32 v[28:29], v[28:29], v[60:61]
	v_pk_add_f32 v[30:31], v[30:31], v[62:63]
	v_add_f32_e32 v107, 1.0, v107
	v_rcp_f32_e32 v109, v107
	v_pk_add_f32 v[20:21], v[20:21], v[44:45]
	v_pk_add_f32 v[22:23], v[22:23], v[46:47]
	v_pk_add_f32 v[12:13], v[12:13], v[60:61]
	v_pk_mul_f32 v[108:109], v[108:109], v[110:111]
	v_add_co_u32_e32 v110, vcc, s18, v148
	v_cvt_pk_bf16_f32 v107, v108, v109
	s_nop 0
	v_addc_co_u32_e32 v111, vcc, 0, v149, vcc
	global_store_dwordx4 v[110:111], v[104:107], off
	v_lshl_add_u64 v[108:109], v[148:149], 0, s[16:17]
	s_mov_b64 s[16:17], 0x40000
	v_pk_add_f32 v[104:105], v[98:99], v[42:43]
	v_pk_add_f32 v[98:99], v[96:97], v[40:41]
	v_mul_f32_e32 v96, 0xbfb8aa3b, v100
	v_mul_f32_e32 v97, 0xbfb8aa3b, v101
	v_exp_f32_e32 v96, v96
	v_exp_f32_e32 v97, v97
	v_lshlrev_b32_e32 v100, 16, v128
	v_and_b32_e32 v101, 0xffff0000, v128
	v_add_f32_e32 v96, 1.0, v96
	v_add_f32_e32 v97, 1.0, v97
	v_rcp_f32_e32 v96, v96
	v_rcp_f32_e32 v97, v97
	v_mul_f32_e32 v98, 0xbfb8aa3b, v98
	v_mul_f32_e32 v99, 0xbfb8aa3b, v99
	v_exp_f32_e32 v98, v98
	v_pk_mul_f32 v[96:97], v[96:97], v[100:101]
	v_exp_f32_e32 v99, v99
	v_cvt_pk_bf16_f32 v96, v96, v97
	v_mul_f32_e32 v97, 0xbfb8aa3b, v102
	v_exp_f32_e32 v97, v97
	v_add_f32_e32 v98, 1.0, v98
	v_add_f32_e32 v99, 1.0, v99
	v_rcp_f32_e32 v98, v98
	v_add_f32_e32 v97, 1.0, v97
	v_rcp_f32_e32 v100, v97
	v_mul_f32_e32 v97, 0xbfb8aa3b, v103
	v_exp_f32_e32 v97, v97
	v_rcp_f32_e32 v99, v99
	v_lshlrev_b32_e32 v102, 16, v129
	v_and_b32_e32 v103, 0xffff0000, v129
	v_add_f32_e32 v97, 1.0, v97
	v_rcp_f32_e32 v101, v97
	s_mov_b64 s[18:19], 0x48000
	v_pk_add_f32 v[14:15], v[14:15], v[62:63]
	v_pk_add_f32 v[4:5], v[4:5], v[44:45]
	v_pk_mul_f32 v[100:101], v[100:101], v[102:103]
	v_lshlrev_b32_e32 v102, 16, v131
	v_cvt_pk_bf16_f32 v97, v100, v101
	v_lshlrev_b32_e32 v100, 16, v130
	v_and_b32_e32 v101, 0xffff0000, v130
	v_pk_mul_f32 v[98:99], v[98:99], v[100:101]
	v_and_b32_e32 v103, 0xffff0000, v131
	v_cvt_pk_bf16_f32 v98, v98, v99
	v_mul_f32_e32 v99, 0xbfb8aa3b, v104
	v_exp_f32_e32 v99, v99
	v_pk_add_f32 v[6:7], v[6:7], v[46:47]
	v_add_f32_e32 v99, 1.0, v99
	v_rcp_f32_e32 v100, v99
	v_mul_f32_e32 v99, 0xbfb8aa3b, v105
	v_pk_add_f32 v[104:105], v[90:91], v[58:59]
	v_pk_add_f32 v[90:91], v[88:89], v[56:57]
	v_mul_f32_e32 v88, 0xbfb8aa3b, v92
	v_mul_f32_e32 v89, 0xbfb8aa3b, v93
	v_exp_f32_e32 v99, v99
	v_exp_f32_e32 v88, v88
	v_exp_f32_e32 v89, v89
	s_waitcnt vmcnt(0) lgkmcnt(0)
; __device__ __forceinline__ unsigned cvt_pk_bf16(float lo, float hi) { f32x2 v = {lo, hi}; bf16x2_t b = __builtin_convertvector(v, bf16x2_t); return __builtin_bit_cast(unsigned, b); }
; __device__ __forceinline__ float bflo(unsigned w) { return __uint_as_float(w << 16); }
; __device__ __forceinline__ float bfhi(unsigned w) { return __uint_as_float(w & 0xffff0000u); }
; __device__ __forceinline__ float sigmoidf_(float v) { return __builtin_amdgcn_rcpf(1.0f + __builtin_amdgcn_exp2f(-1.4426950408889634f * v)); }
;     __device__ __forceinline__ void operator()(const f32x4 (&acc)[2][2][4][2], const Unit& u, int wr, int wc, int fr, int fq) const {
;     ...
;         for (int bj = 0; bj < 2; ++bj) gpre[0][bj] = *(const u32x4*)(GACT + ((size_t)256 * u.pm + 64 * wr + fr) * 1024 + col0 + 128 * bj);
; #pragma unroll
;         for (int g = 0; g < 8; ++g) {
;             const int ai = g >> 2, m = g & 3;
;             const size_t row = (size_t)256 * u.pm + 128 * ai + 64 * wr + 16 * m + fr;
;             if (g + 1 < 8) {
;                 const size_t rn = (size_t)256 * u.pm + 128 * ((g + 1) >> 2) + 64 * wr + 16 * ((g + 1) & 3) + fr;
; #pragma unroll
;                 for (int bj = 0; bj < 2; ++bj) gpre[(g + 1) & 1][bj] = *(const u32x4*)(GACT + rn * 1024 + col0 + 128 * bj);
;             }
;             asm volatile("" ::: "memory");
; #pragma unroll
;             for (int bj = 0; bj < 2; ++bj) {
;                 const u32x4 gv = gpre[g & 1][bj];
;                 const f32x4 a = acc[ai][bj][m][0] + bv[bj][0], b = acc[ai][bj][m][1] + bv[bj][1];
;                 u32x4 w;
;                 w.x = cvt_pk_bf16(bflo(gv.x) * sigmoidf_(a[0]), bfhi(gv.x) * sigmoidf_(a[1])); w.y = cvt_pk_bf16(bflo(gv.y) * sigmoidf_(a[2]), bfhi(gv.y) * sigmoidf_(a[3]));
;                 w.z = cvt_pk_bf16(bflo(gv.z) * sigmoidf_(b[0]), bfhi(gv.z) * sigmoidf_(b[1])); w.w = cvt_pk_bf16(bflo(gv.w) * sigmoidf_(b[2]), bfhi(gv.w) * sigmoidf_(b[3]));
;                 *(u32x4*)(YB + row * 1024 + col0 + 128 * bj) = w;
;             }
	v_lshlrev_b32_e32 v92, 16, v116
	v_add_f32_e32 v99, 1.0, v99
	v_add_f32_e32 v88, 1.0, v88
	v_add_f32_e32 v89, 1.0, v89
	v_rcp_f32_e32 v101, v99
	v_rcp_f32_e32 v88, v88
	v_rcp_f32_e32 v89, v89
	v_and_b32_e32 v93, 0xffff0000, v116
	v_pk_mul_f32 v[100:101], v[100:101], v[102:103]
	v_mul_f32_e32 v90, 0xbfb8aa3b, v90
	v_pk_mul_f32 v[88:89], v[88:89], v[92:93]
	v_cvt_pk_bf16_f32 v99, v100, v101
	v_cvt_pk_bf16_f32 v88, v88, v89
	v_mul_f32_e32 v89, 0xbfb8aa3b, v94
	global_store_dwordx4 v[108:109], v[96:99], off offset:256
	v_exp_f32_e32 v89, v89
	v_mul_f32_e32 v91, 0xbfb8aa3b, v91
	v_add_co_u32_e32 v98, vcc, s33, v166
	v_lshl_add_u64 v[96:97], v[166:167], 0, s[16:17]
	s_nop 0
	v_addc_co_u32_e32 v99, vcc, 0, v167, vcc
	global_load_dwordx4 v[100:103], v[98:99], off
	s_nop 0
	global_load_dwordx4 v[96:99], v[96:97], off offset:256
	v_add_f32_e32 v89, 1.0, v89
	v_rcp_f32_e32 v92, v89
	v_mul_f32_e32 v89, 0xbfb8aa3b, v95
	v_exp_f32_e32 v89, v89
	v_exp_f32_e32 v90, v90
	v_exp_f32_e32 v91, v91
	v_lshlrev_b32_e32 v94, 16, v117
	v_add_f32_e32 v89, 1.0, v89
	v_rcp_f32_e32 v93, v89
	v_add_f32_e32 v90, 1.0, v90
	v_add_f32_e32 v91, 1.0, v91
	v_rcp_f32_e32 v90, v90
	v_rcp_f32_e32 v91, v91
	v_and_b32_e32 v95, 0xffff0000, v117
	v_pk_mul_f32 v[92:93], v[92:93], v[94:95]
	v_lshlrev_b32_e32 v94, 16, v119
	v_cvt_pk_bf16_f32 v89, v92, v93
	v_lshlrev_b32_e32 v92, 16, v118
	v_and_b32_e32 v93, 0xffff0000, v118
	v_pk_mul_f32 v[90:91], v[90:91], v[92:93]
	v_and_b32_e32 v95, 0xffff0000, v119
	v_cvt_pk_bf16_f32 v90, v90, v91
	v_mul_f32_e32 v91, 0xbfb8aa3b, v104
	v_exp_f32_e32 v91, v91
	s_nop 0
	v_add_f32_e32 v91, 1.0, v91
	v_rcp_f32_e32 v92, v91
	v_mul_f32_e32 v91, 0xbfb8aa3b, v105
	v_exp_f32_e32 v91, v91
	s_nop 0
	v_add_f32_e32 v91, 1.0, v91
	v_rcp_f32_e32 v93, v91
	s_nop 0
	v_pk_mul_f32 v[92:93], v[92:93], v[94:95]
	v_add_co_u32_e32 v94, vcc, s13, v148
	v_cvt_pk_bf16_f32 v91, v92, v93
	s_nop 0
	v_addc_co_u32_e32 v95, vcc, 0, v149, vcc
	global_store_dwordx4 v[94:95], v[88:91], off
	v_lshl_add_u64 v[92:93], v[148:149], 0, s[2:3]
	s_mov_b32 s2, 0x48000
	v_pk_add_f32 v[88:89], v[82:83], v[42:43]
	v_pk_add_f32 v[82:83], v[80:81], v[40:41]
	v_mul_f32_e32 v80, 0xbfb8aa3b, v84
	v_mul_f32_e32 v81, 0xbfb8aa3b, v85
	v_exp_f32_e32 v80, v80
	v_exp_f32_e32 v81, v81
	v_lshlrev_b32_e32 v84, 16, v112
	v_and_b32_e32 v85, 0xffff0000, v112
	v_add_f32_e32 v80, 1.0, v80
	v_add_f32_e32 v81, 1.0, v81
	v_rcp_f32_e32 v80, v80
	v_rcp_f32_e32 v81, v81
	v_mul_f32_e32 v82, 0xbfb8aa3b, v82
	v_mul_f32_e32 v83, 0xbfb8aa3b, v83
	v_exp_f32_e32 v82, v82
	v_pk_mul_f32 v[80:81], v[80:81], v[84:85]
	v_exp_f32_e32 v83, v83
	v_cvt_pk_bf16_f32 v80, v80, v81
	v_mul_f32_e32 v81, 0xbfb8aa3b, v86
	v_exp_f32_e32 v81, v81
	v_add_f32_e32 v82, 1.0, v82
	v_add_f32_e32 v83, 1.0, v83
	v_rcp_f32_e32 v82, v82
	v_add_f32_e32 v81, 1.0, v81
	v_rcp_f32_e32 v84, v81
	v_mul_f32_e32 v81, 0xbfb8aa3b, v87
	v_exp_f32_e32 v81, v81
	v_rcp_f32_e32 v83, v83
	v_lshlrev_b32_e32 v86, 16, v113
	v_and_b32_e32 v87, 0xffff0000, v113
	v_add_f32_e32 v81, 1.0, v81
	v_rcp_f32_e32 v85, v81
	s_mov_b32 s3, 0x50000
	v_pk_mul_f32 v[84:85], v[84:85], v[86:87]
	s_nop 0
	v_cvt_pk_bf16_f32 v81, v84, v85
	v_lshlrev_b32_e32 v84, 16, v114
	v_and_b32_e32 v85, 0xffff0000, v114
	v_pk_mul_f32 v[82:83], v[82:83], v[84:85]
	v_lshlrev_b32_e32 v86, 16, v115
	v_cvt_pk_bf16_f32 v82, v82, v83
	v_mul_f32_e32 v83, 0xbfb8aa3b, v88
	v_exp_f32_e32 v83, v83
	v_and_b32_e32 v87, 0xffff0000, v115
	v_add_f32_e32 v83, 1.0, v83
	v_rcp_f32_e32 v84, v83
	v_mul_f32_e32 v83, 0xbfb8aa3b, v89
	v_pk_add_f32 v[88:89], v[74:75], v[58:59]
	v_pk_add_f32 v[74:75], v[72:73], v[56:57]
	v_mul_f32_e32 v72, 0xbfb8aa3b, v76
	v_mul_f32_e32 v73, 0xbfb8aa3b, v77
	v_exp_f32_e32 v83, v83
	v_exp_f32_e32 v72, v72
	v_exp_f32_e32 v73, v73
	s_waitcnt vmcnt(0) lgkmcnt(0)
	v_lshlrev_b32_e32 v76, 16, v100
	v_add_f32_e32 v83, 1.0, v83
	v_add_f32_e32 v72, 1.0, v72
	v_add_f32_e32 v73, 1.0, v73
	v_rcp_f32_e32 v85, v83
	v_rcp_f32_e32 v72, v72
	v_rcp_f32_e32 v73, v73
	v_and_b32_e32 v77, 0xffff0000, v100
	v_pk_mul_f32 v[84:85], v[84:85], v[86:87]
	v_mul_f32_e32 v74, 0xbfb8aa3b, v74
	v_pk_mul_f32 v[72:73], v[72:73], v[76:77]
	v_cvt_pk_bf16_f32 v83, v84, v85
	v_cvt_pk_bf16_f32 v72, v72, v73
	v_mul_f32_e32 v73, 0xbfb8aa3b, v78
	global_store_dwordx4 v[92:93], v[80:83], off offset:256
	v_exp_f32_e32 v73, v73
	v_mul_f32_e32 v75, 0xbfb8aa3b, v75
	v_add_co_u32_e32 v82, vcc, s2, v166
	v_lshl_add_u64 v[80:81], v[166:167], 0, s[18:19]
	s_nop 0
	v_addc_co_u32_e32 v83, vcc, 0, v167, vcc
	global_load_dwordx4 v[84:87], v[82:83], off
	s_nop 0
	global_load_dwordx4 v[80:83], v[80:81], off offset:256
	v_add_f32_e32 v73, 1.0, v73
	v_rcp_f32_e32 v76, v73
	v_mul_f32_e32 v73, 0xbfb8aa3b, v79
	v_exp_f32_e32 v73, v73
	v_exp_f32_e32 v74, v74
	v_exp_f32_e32 v75, v75
	v_lshlrev_b32_e32 v78, 16, v101
	v_add_f32_e32 v73, 1.0, v73
	v_rcp_f32_e32 v77, v73
	v_add_f32_e32 v74, 1.0, v74
	v_add_f32_e32 v75, 1.0, v75
	v_rcp_f32_e32 v74, v74
	v_rcp_f32_e32 v75, v75
	v_and_b32_e32 v79, 0xffff0000, v101
	v_pk_mul_f32 v[76:77], v[76:77], v[78:79]
	v_lshlrev_b32_e32 v78, 16, v103
	v_cvt_pk_bf16_f32 v73, v76, v77
	v_lshlrev_b32_e32 v76, 16, v102
	v_and_b32_e32 v77, 0xffff0000, v102
	v_pk_mul_f32 v[74:75], v[74:75], v[76:77]
	v_and_b32_e32 v79, 0xffff0000, v103
	v_cvt_pk_bf16_f32 v74, v74, v75
	v_mul_f32_e32 v75, 0xbfb8aa3b, v88
	v_exp_f32_e32 v75, v75
	s_nop 0
	v_add_f32_e32 v75, 1.0, v75
	v_rcp_f32_e32 v76, v75
	v_mul_f32_e32 v75, 0xbfb8aa3b, v89
	v_exp_f32_e32 v75, v75
	s_nop 0
	v_add_f32_e32 v75, 1.0, v75
	v_rcp_f32_e32 v77, v75
	s_nop 0
	v_pk_mul_f32 v[76:77], v[76:77], v[78:79]
	v_add_co_u32_e32 v78, vcc, s33, v148
	v_cvt_pk_bf16_f32 v75, v76, v77
	s_nop 0
; __device__ __forceinline__ unsigned cvt_pk_bf16(float lo, float hi) { f32x2 v = {lo, hi}; bf16x2_t b = __builtin_convertvector(v, bf16x2_t); return __builtin_bit_cast(unsigned, b); }
; __device__ __forceinline__ float bflo(unsigned w) { return __uint_as_float(w << 16); }
; __device__ __forceinline__ float bfhi(unsigned w) { return __uint_as_float(w & 0xffff0000u); }
; __device__ __forceinline__ float sigmoidf_(float v) { return __builtin_amdgcn_rcpf(1.0f + __builtin_amdgcn_exp2f(-1.4426950408889634f * v)); }
;     __device__ __forceinline__ void operator()(const f32x4 (&acc)[2][2][4][2], const Unit& u, int wr, int wc, int fr, int fq) const {
;     ...
;         for (int bj = 0; bj < 2; ++bj) gpre[0][bj] = *(const u32x4*)(GACT + ((size_t)256 * u.pm + 64 * wr + fr) * 1024 + col0 + 128 * bj);
; #pragma unroll
;         for (int g = 0; g < 8; ++g) {
;             const int ai = g >> 2, m = g & 3;
;             const size_t row = (size_t)256 * u.pm + 128 * ai + 64 * wr + 16 * m + fr;
;             if (g + 1 < 8) {
;                 const size_t rn = (size_t)256 * u.pm + 128 * ((g + 1) >> 2) + 64 * wr + 16 * ((g + 1) & 3) + fr;
; #pragma unroll
;                 for (int bj = 0; bj < 2; ++bj) gpre[(g + 1) & 1][bj] = *(const u32x4*)(GACT + rn * 1024 + col0 + 128 * bj);
;             }
;             asm volatile("" ::: "memory");
; #pragma unroll
;             for (int bj = 0; bj < 2; ++bj) {
;                 const u32x4 gv = gpre[g & 1][bj];
;                 const f32x4 a = acc[ai][bj][m][0] + bv[bj][0], b = acc[ai][bj][m][1] + bv[bj][1];
;                 u32x4 w;
;                 w.x = cvt_pk_bf16(bflo(gv.x) * sigmoidf_(a[0]), bfhi(gv.x) * sigmoidf_(a[1])); w.y = cvt_pk_bf16(bflo(gv.y) * sigmoidf_(a[2]), bfhi(gv.y) * sigmoidf_(a[3]));
;                 w.z = cvt_pk_bf16(bflo(gv.z) * sigmoidf_(b[0]), bfhi(gv.z) * sigmoidf_(b[1])); w.w = cvt_pk_bf16(bflo(gv.w) * sigmoidf_(b[2]), bfhi(gv.w) * sigmoidf_(b[3]));
;                 *(u32x4*)(YB + row * 1024 + col0 + 128 * bj) = w;
;             }
	v_addc_co_u32_e32 v79, vcc, 0, v149, vcc
	global_store_dwordx4 v[78:79], v[72:75], off
	v_lshl_add_u64 v[76:77], v[148:149], 0, s[16:17]
	s_mov_b64 s[16:17], 0x50000
	v_pk_add_f32 v[72:73], v[66:67], v[42:43]
	v_pk_add_f32 v[66:67], v[64:65], v[40:41]
	v_mul_f32_e32 v64, 0xbfb8aa3b, v68
	v_mul_f32_e32 v65, 0xbfb8aa3b, v69
	v_exp_f32_e32 v64, v64
	v_exp_f32_e32 v65, v65
	v_lshlrev_b32_e32 v68, 16, v96
	v_and_b32_e32 v69, 0xffff0000, v96
	v_add_f32_e32 v64, 1.0, v64
	v_add_f32_e32 v65, 1.0, v65
	v_rcp_f32_e32 v64, v64
	v_rcp_f32_e32 v65, v65
	v_mul_f32_e32 v66, 0xbfb8aa3b, v66
	v_mul_f32_e32 v67, 0xbfb8aa3b, v67
	v_exp_f32_e32 v66, v66
	v_pk_mul_f32 v[64:65], v[64:65], v[68:69]
	v_exp_f32_e32 v67, v67
	v_cvt_pk_bf16_f32 v64, v64, v65
	v_mul_f32_e32 v65, 0xbfb8aa3b, v70
	v_exp_f32_e32 v65, v65
	v_add_f32_e32 v66, 1.0, v66
	v_add_f32_e32 v67, 1.0, v67
	v_rcp_f32_e32 v66, v66
	v_add_f32_e32 v65, 1.0, v65
	v_rcp_f32_e32 v68, v65
	v_mul_f32_e32 v65, 0xbfb8aa3b, v71
	v_exp_f32_e32 v65, v65
	v_rcp_f32_e32 v67, v67
	v_lshlrev_b32_e32 v70, 16, v97
	v_and_b32_e32 v71, 0xffff0000, v97
	v_add_f32_e32 v65, 1.0, v65
	v_rcp_f32_e32 v69, v65
	s_nop 0
	v_pk_mul_f32 v[68:69], v[68:69], v[70:71]
	s_nop 0
	v_cvt_pk_bf16_f32 v65, v68, v69
	v_lshlrev_b32_e32 v68, 16, v98
	v_and_b32_e32 v69, 0xffff0000, v98
	v_pk_mul_f32 v[66:67], v[66:67], v[68:69]
	v_lshlrev_b32_e32 v70, 16, v99
	v_cvt_pk_bf16_f32 v66, v66, v67
	v_mul_f32_e32 v67, 0xbfb8aa3b, v72
	v_exp_f32_e32 v67, v67
	v_and_b32_e32 v71, 0xffff0000, v99
	v_add_f32_e32 v67, 1.0, v67
	v_rcp_f32_e32 v68, v67
	v_mul_f32_e32 v67, 0xbfb8aa3b, v73
	v_pk_add_f32 v[72:73], v[50:51], v[58:59]
	v_pk_add_f32 v[50:51], v[48:49], v[56:57]
	v_mul_f32_e32 v48, 0xbfb8aa3b, v52
	v_mul_f32_e32 v49, 0xbfb8aa3b, v53
	v_exp_f32_e32 v67, v67
	v_exp_f32_e32 v48, v48
	v_exp_f32_e32 v49, v49
	s_waitcnt vmcnt(0) lgkmcnt(0)
	v_lshlrev_b32_e32 v52, 16, v84
	v_add_f32_e32 v67, 1.0, v67
	v_add_f32_e32 v48, 1.0, v48
	v_add_f32_e32 v49, 1.0, v49
	v_rcp_f32_e32 v69, v67
	v_rcp_f32_e32 v48, v48
	v_rcp_f32_e32 v49, v49
	v_and_b32_e32 v53, 0xffff0000, v84
	v_pk_mul_f32 v[68:69], v[68:69], v[70:71]
	v_mul_f32_e32 v50, 0xbfb8aa3b, v50
	v_pk_mul_f32 v[48:49], v[48:49], v[52:53]
	v_cvt_pk_bf16_f32 v67, v68, v69
	v_cvt_pk_bf16_f32 v48, v48, v49
	v_mul_f32_e32 v49, 0xbfb8aa3b, v54
	global_store_dwordx4 v[76:77], v[64:67], off offset:256
	v_exp_f32_e32 v49, v49
	v_mul_f32_e32 v51, 0xbfb8aa3b, v51
	v_add_co_u32_e32 v66, vcc, s3, v166
	v_lshl_add_u64 v[64:65], v[166:167], 0, s[16:17]
	s_nop 0
	v_addc_co_u32_e32 v67, vcc, 0, v167, vcc
	global_load_dwordx4 v[68:71], v[66:67], off
	s_nop 0
	global_load_dwordx4 v[64:67], v[64:65], off offset:256
	v_add_f32_e32 v49, 1.0, v49
	v_rcp_f32_e32 v52, v49
	v_mul_f32_e32 v49, 0xbfb8aa3b, v55
	v_exp_f32_e32 v49, v49
	v_exp_f32_e32 v50, v50
	v_exp_f32_e32 v51, v51
	v_lshlrev_b32_e32 v54, 16, v85
	v_add_f32_e32 v49, 1.0, v49
	v_rcp_f32_e32 v53, v49
	v_add_f32_e32 v50, 1.0, v50
	v_add_f32_e32 v51, 1.0, v51
	v_rcp_f32_e32 v50, v50
	v_rcp_f32_e32 v51, v51
	v_and_b32_e32 v55, 0xffff0000, v85
	v_pk_mul_f32 v[52:53], v[52:53], v[54:55]
	v_lshlrev_b32_e32 v54, 16, v87
	v_cvt_pk_bf16_f32 v49, v52, v53
	v_lshlrev_b32_e32 v52, 16, v86
	v_and_b32_e32 v53, 0xffff0000, v86
	v_pk_mul_f32 v[50:51], v[50:51], v[52:53]
	v_and_b32_e32 v55, 0xffff0000, v87
	v_cvt_pk_bf16_f32 v50, v50, v51
	v_mul_f32_e32 v51, 0xbfb8aa3b, v72
	v_exp_f32_e32 v51, v51
	s_nop 0
	v_add_f32_e32 v51, 1.0, v51
	v_rcp_f32_e32 v52, v51
	v_mul_f32_e32 v51, 0xbfb8aa3b, v73
	v_exp_f32_e32 v51, v51
	s_nop 0
	v_add_f32_e32 v51, 1.0, v51
	v_rcp_f32_e32 v53, v51
	s_nop 0
	v_pk_mul_f32 v[52:53], v[52:53], v[54:55]
	v_add_co_u32_e32 v54, vcc, s2, v148
	v_cvt_pk_bf16_f32 v51, v52, v53
	s_nop 0
	v_addc_co_u32_e32 v55, vcc, 0, v149, vcc
	global_store_dwordx4 v[54:55], v[48:51], off
	v_lshl_add_u64 v[52:53], v[148:149], 0, s[18:19]
	s_mov_b32 s2, 0x58000
	v_pk_add_f32 v[48:49], v[34:35], v[42:43]
	v_pk_add_f32 v[34:35], v[32:33], v[40:41]
	v_mul_f32_e32 v32, 0xbfb8aa3b, v36
	v_mul_f32_e32 v33, 0xbfb8aa3b, v37
	v_exp_f32_e32 v32, v32
	v_exp_f32_e32 v33, v33
	v_lshlrev_b32_e32 v36, 16, v80
	v_and_b32_e32 v37, 0xffff0000, v80
	v_add_f32_e32 v32, 1.0, v32
	v_add_f32_e32 v33, 1.0, v33
	v_rcp_f32_e32 v32, v32
	v_rcp_f32_e32 v33, v33
	v_mul_f32_e32 v34, 0xbfb8aa3b, v34
	v_mul_f32_e32 v35, 0xbfb8aa3b, v35
	v_exp_f32_e32 v34, v34
	v_pk_mul_f32 v[32:33], v[32:33], v[36:37]
	v_exp_f32_e32 v35, v35
	v_cvt_pk_bf16_f32 v32, v32, v33
	v_mul_f32_e32 v33, 0xbfb8aa3b, v38
	v_exp_f32_e32 v33, v33
	v_add_f32_e32 v34, 1.0, v34
	v_add_f32_e32 v35, 1.0, v35
	v_rcp_f32_e32 v34, v34
	v_add_f32_e32 v33, 1.0, v33
	v_rcp_f32_e32 v36, v33
	v_mul_f32_e32 v33, 0xbfb8aa3b, v39
	v_exp_f32_e32 v33, v33
	v_rcp_f32_e32 v35, v35
	v_lshlrev_b32_e32 v38, 16, v81
	v_and_b32_e32 v39, 0xffff0000, v81
	v_add_f32_e32 v33, 1.0, v33
	v_rcp_f32_e32 v37, v33
	s_mov_b64 s[18:19], 0x58000
	v_pk_mul_f32 v[36:37], v[36:37], v[38:39]
	s_nop 0
	v_cvt_pk_bf16_f32 v33, v36, v37
	v_lshlrev_b32_e32 v36, 16, v82
	v_and_b32_e32 v37, 0xffff0000, v82
	v_pk_mul_f32 v[34:35], v[34:35], v[36:37]
	v_lshlrev_b32_e32 v38, 16, v83
	v_cvt_pk_bf16_f32 v34, v34, v35
	v_mul_f32_e32 v35, 0xbfb8aa3b, v48
	v_exp_f32_e32 v35, v35
	v_and_b32_e32 v39, 0xffff0000, v83
	v_add_f32_e32 v35, 1.0, v35
	v_rcp_f32_e32 v36, v35
	v_mul_f32_e32 v35, 0xbfb8aa3b, v49
	v_pk_add_f32 v[48:49], v[26:27], v[58:59]
	v_pk_add_f32 v[26:27], v[24:25], v[56:57]
	v_mul_f32_e32 v24, 0xbfb8aa3b, v28
	v_mul_f32_e32 v25, 0xbfb8aa3b, v29
	v_exp_f32_e32 v24, v24
	v_exp_f32_e32 v25, v25
	s_waitcnt vmcnt(0) lgkmcnt(0)
; __device__ __forceinline__ unsigned cvt_pk_bf16(float lo, float hi) { f32x2 v = {lo, hi}; bf16x2_t b = __builtin_convertvector(v, bf16x2_t); return __builtin_bit_cast(unsigned, b); }
; __device__ __forceinline__ float bflo(unsigned w) { return __uint_as_float(w << 16); }
; __device__ __forceinline__ float bfhi(unsigned w) { return __uint_as_float(w & 0xffff0000u); }
; __device__ __forceinline__ float sigmoidf_(float v) { return __builtin_amdgcn_rcpf(1.0f + __builtin_amdgcn_exp2f(-1.4426950408889634f * v)); }
;     __device__ __forceinline__ void operator()(const f32x4 (&acc)[2][2][4][2], const Unit& u, int wr, int wc, int fr, int fq) const {
;     ...
;         for (int bj = 0; bj < 2; ++bj) gpre[0][bj] = *(const u32x4*)(GACT + ((size_t)256 * u.pm + 64 * wr + fr) * 1024 + col0 + 128 * bj);
; #pragma unroll
;         for (int g = 0; g < 8; ++g) {
;             const int ai = g >> 2, m = g & 3;
;             const size_t row = (size_t)256 * u.pm + 128 * ai + 64 * wr + 16 * m + fr;
;             if (g + 1 < 8) {
;                 const size_t rn = (size_t)256 * u.pm + 128 * ((g + 1) >> 2) + 64 * wr + 16 * ((g + 1) & 3) + fr;
; #pragma unroll
;                 for (int bj = 0; bj < 2; ++bj) gpre[(g + 1) & 1][bj] = *(const u32x4*)(GACT + rn * 1024 + col0 + 128 * bj);
;             }
;             asm volatile("" ::: "memory");
; #pragma unroll
;             for (int bj = 0; bj < 2; ++bj) {
;                 const u32x4 gv = gpre[g & 1][bj];
;                 const f32x4 a = acc[ai][bj][m][0] + bv[bj][0], b = acc[ai][bj][m][1] + bv[bj][1];
;                 u32x4 w;
;                 w.x = cvt_pk_bf16(bflo(gv.x) * sigmoidf_(a[0]), bfhi(gv.x) * sigmoidf_(a[1])); w.y = cvt_pk_bf16(bflo(gv.y) * sigmoidf_(a[2]), bfhi(gv.y) * sigmoidf_(a[3]));
;                 w.z = cvt_pk_bf16(bflo(gv.z) * sigmoidf_(b[0]), bfhi(gv.z) * sigmoidf_(b[1])); w.w = cvt_pk_bf16(bflo(gv.w) * sigmoidf_(b[2]), bfhi(gv.w) * sigmoidf_(b[3]));
;                 *(u32x4*)(YB + row * 1024 + col0 + 128 * bj) = w;
;             }
	v_lshlrev_b32_e32 v28, 16, v68
	v_and_b32_e32 v29, 0xffff0000, v68
	v_add_f32_e32 v24, 1.0, v24
	v_add_f32_e32 v25, 1.0, v25
	v_rcp_f32_e32 v24, v24
	v_rcp_f32_e32 v25, v25
	v_exp_f32_e32 v35, v35
	v_mul_f32_e32 v26, 0xbfb8aa3b, v26
	v_mul_f32_e32 v27, 0xbfb8aa3b, v27
	v_pk_mul_f32 v[24:25], v[24:25], v[28:29]
	v_add_f32_e32 v35, 1.0, v35
	v_cvt_pk_bf16_f32 v24, v24, v25
	v_mul_f32_e32 v25, 0xbfb8aa3b, v30
	v_exp_f32_e32 v25, v25
	v_rcp_f32_e32 v37, v35
	v_exp_f32_e32 v26, v26
	v_exp_f32_e32 v27, v27
	v_add_f32_e32 v25, 1.0, v25
	v_rcp_f32_e32 v28, v25
	v_mul_f32_e32 v25, 0xbfb8aa3b, v31
	v_exp_f32_e32 v25, v25
	v_pk_mul_f32 v[36:37], v[36:37], v[38:39]
	v_add_f32_e32 v26, 1.0, v26
	v_cvt_pk_bf16_f32 v35, v36, v37
	v_add_f32_e32 v25, 1.0, v25
	v_rcp_f32_e32 v29, v25
	global_store_dwordx4 v[52:53], v[32:35], off offset:256
	v_add_f32_e32 v27, 1.0, v27
	v_rcp_f32_e32 v26, v26
	v_add_co_u32_e32 v34, vcc, s2, v166
	v_lshl_add_u64 v[32:33], v[166:167], 0, s[18:19]
	s_nop 0
	v_addc_co_u32_e32 v35, vcc, 0, v167, vcc
	v_rcp_f32_e32 v27, v27
	global_load_dwordx4 v[36:39], v[34:35], off
	s_nop 0
	global_load_dwordx4 v[32:35], v[32:33], off offset:256
	v_lshlrev_b32_e32 v30, 16, v69
	v_and_b32_e32 v31, 0xffff0000, v69
	v_pk_mul_f32 v[28:29], v[28:29], v[30:31]
	v_lshlrev_b32_e32 v30, 16, v71
	v_cvt_pk_bf16_f32 v25, v28, v29
	v_lshlrev_b32_e32 v28, 16, v70
	v_and_b32_e32 v29, 0xffff0000, v70
	v_pk_mul_f32 v[26:27], v[26:27], v[28:29]
	v_and_b32_e32 v31, 0xffff0000, v71
	v_cvt_pk_bf16_f32 v26, v26, v27
	v_mul_f32_e32 v27, 0xbfb8aa3b, v48
	v_exp_f32_e32 v27, v27
	s_nop 0
	v_add_f32_e32 v27, 1.0, v27
	v_rcp_f32_e32 v28, v27
	v_mul_f32_e32 v27, 0xbfb8aa3b, v49
	v_exp_f32_e32 v27, v27
	s_nop 0
	v_add_f32_e32 v27, 1.0, v27
	v_rcp_f32_e32 v29, v27
	s_nop 0
	v_pk_mul_f32 v[28:29], v[28:29], v[30:31]
	v_add_co_u32_e32 v30, vcc, s3, v148
	v_cvt_pk_bf16_f32 v27, v28, v29
	s_nop 0
	v_addc_co_u32_e32 v31, vcc, 0, v149, vcc
	global_store_dwordx4 v[30:31], v[24:27], off
	v_lshl_add_u64 v[28:29], v[148:149], 0, s[16:17]
	s_mov_b64 s[16:17], -1
	v_pk_add_f32 v[24:25], v[18:19], v[42:43]
	v_pk_add_f32 v[18:19], v[16:17], v[40:41]
	v_mul_f32_e32 v16, 0xbfb8aa3b, v20
	v_mul_f32_e32 v17, 0xbfb8aa3b, v21
	v_exp_f32_e32 v16, v16
	v_exp_f32_e32 v17, v17
	v_lshlrev_b32_e32 v20, 16, v64
	v_and_b32_e32 v21, 0xffff0000, v64
	v_add_f32_e32 v16, 1.0, v16
	v_add_f32_e32 v17, 1.0, v17
	v_rcp_f32_e32 v16, v16
	v_rcp_f32_e32 v17, v17
	v_mul_f32_e32 v18, 0xbfb8aa3b, v18
	v_mul_f32_e32 v19, 0xbfb8aa3b, v19
	v_exp_f32_e32 v18, v18
	v_pk_mul_f32 v[16:17], v[16:17], v[20:21]
	v_exp_f32_e32 v19, v19
	v_cvt_pk_bf16_f32 v16, v16, v17
	v_mul_f32_e32 v17, 0xbfb8aa3b, v22
	v_exp_f32_e32 v17, v17
	v_add_f32_e32 v18, 1.0, v18
	v_add_f32_e32 v19, 1.0, v19
	v_rcp_f32_e32 v18, v18
	v_add_f32_e32 v17, 1.0, v17
	v_rcp_f32_e32 v20, v17
	v_mul_f32_e32 v17, 0xbfb8aa3b, v23
	v_exp_f32_e32 v17, v17
	v_rcp_f32_e32 v19, v19
	v_lshlrev_b32_e32 v22, 16, v65
	v_and_b32_e32 v23, 0xffff0000, v65
	v_add_f32_e32 v17, 1.0, v17
	v_rcp_f32_e32 v21, v17
	s_nop 0
	v_pk_mul_f32 v[20:21], v[20:21], v[22:23]
	s_nop 0
	v_cvt_pk_bf16_f32 v17, v20, v21
	v_lshlrev_b32_e32 v20, 16, v66
	v_and_b32_e32 v21, 0xffff0000, v66
	v_pk_mul_f32 v[18:19], v[18:19], v[20:21]
	v_lshlrev_b32_e32 v22, 16, v67
	v_cvt_pk_bf16_f32 v18, v18, v19
	v_mul_f32_e32 v19, 0xbfb8aa3b, v24
	v_exp_f32_e32 v19, v19
	v_and_b32_e32 v23, 0xffff0000, v67
	v_add_f32_e32 v19, 1.0, v19
	v_rcp_f32_e32 v20, v19
	v_mul_f32_e32 v19, 0xbfb8aa3b, v25
	v_exp_f32_e32 v19, v19
	s_nop 0
	v_add_f32_e32 v19, 1.0, v19
	v_rcp_f32_e32 v21, v19
	s_nop 0
	v_pk_mul_f32 v[20:21], v[20:21], v[22:23]
	s_nop 0
	v_cvt_pk_bf16_f32 v19, v20, v21
	global_store_dwordx4 v[28:29], v[16:19], off offset:256
	s_nop 1
	v_pk_add_f32 v[16:17], v[10:11], v[58:59]
	v_pk_add_f32 v[10:11], v[8:9], v[56:57]
	v_mul_f32_e32 v8, 0xbfb8aa3b, v12
	v_mul_f32_e32 v9, 0xbfb8aa3b, v13
	v_exp_f32_e32 v8, v8
	v_exp_f32_e32 v9, v9
	s_waitcnt vmcnt(0) lgkmcnt(0)
; __device__ __forceinline__ unsigned cvt_pk_bf16(float lo, float hi) { f32x2 v = {lo, hi}; bf16x2_t b = __builtin_convertvector(v, bf16x2_t); return __builtin_bit_cast(unsigned, b); }
; __device__ __forceinline__ float bflo(unsigned w) { return __uint_as_float(w << 16); }
; __device__ __forceinline__ float bfhi(unsigned w) { return __uint_as_float(w & 0xffff0000u); }
; __device__ __forceinline__ float sigmoidf_(float v) { return __builtin_amdgcn_rcpf(1.0f + __builtin_amdgcn_exp2f(-1.4426950408889634f * v)); }
;     __device__ __forceinline__ void operator()(const f32x4 (&acc)[2][2][4][2], const Unit& u, int wr, int wc, int fr, int fq) const {
;     ...
;             for (int bj = 0; bj < 2; ++bj) {
;                 const u32x4 gv = gpre[g & 1][bj];
;                 const f32x4 a = acc[ai][bj][m][0] + bv[bj][0], b = acc[ai][bj][m][1] + bv[bj][1];
;                 u32x4 w;
;                 w.x = cvt_pk_bf16(bflo(gv.x) * sigmoidf_(a[0]), bfhi(gv.x) * sigmoidf_(a[1])); w.y = cvt_pk_bf16(bflo(gv.y) * sigmoidf_(a[2]), bfhi(gv.y) * sigmoidf_(a[3]));
;                 w.z = cvt_pk_bf16(bflo(gv.z) * sigmoidf_(b[0]), bfhi(gv.z) * sigmoidf_(b[1])); w.w = cvt_pk_bf16(bflo(gv.w) * sigmoidf_(b[2]), bfhi(gv.w) * sigmoidf_(b[3]));
;                 *(u32x4*)(YB + row * 1024 + col0 + 128 * bj) = w;
	v_lshlrev_b32_e32 v12, 16, v36
	v_and_b32_e32 v13, 0xffff0000, v36
	v_add_f32_e32 v8, 1.0, v8
	v_add_f32_e32 v9, 1.0, v9
	v_rcp_f32_e32 v8, v8
	v_rcp_f32_e32 v9, v9
	v_mul_f32_e32 v10, 0xbfb8aa3b, v10
	v_mul_f32_e32 v11, 0xbfb8aa3b, v11
	v_exp_f32_e32 v10, v10
	v_pk_mul_f32 v[8:9], v[8:9], v[12:13]
	v_exp_f32_e32 v11, v11
	v_cvt_pk_bf16_f32 v8, v8, v9
	v_mul_f32_e32 v9, 0xbfb8aa3b, v14
	v_exp_f32_e32 v9, v9
	v_add_f32_e32 v10, 1.0, v10
	v_add_f32_e32 v11, 1.0, v11
	v_rcp_f32_e32 v10, v10
	v_add_f32_e32 v9, 1.0, v9
	v_rcp_f32_e32 v12, v9
	v_mul_f32_e32 v9, 0xbfb8aa3b, v15
	v_exp_f32_e32 v9, v9
	v_rcp_f32_e32 v11, v11
	v_lshlrev_b32_e32 v14, 16, v37
	v_and_b32_e32 v15, 0xffff0000, v37
	v_add_f32_e32 v9, 1.0, v9
	v_rcp_f32_e32 v13, v9
	s_nop 0
	v_pk_mul_f32 v[12:13], v[12:13], v[14:15]
	s_nop 0
	v_cvt_pk_bf16_f32 v9, v12, v13
	v_lshlrev_b32_e32 v12, 16, v38
	v_and_b32_e32 v13, 0xffff0000, v38
	v_pk_mul_f32 v[10:11], v[10:11], v[12:13]
	v_lshlrev_b32_e32 v14, 16, v39
	v_cvt_pk_bf16_f32 v10, v10, v11
	v_mul_f32_e32 v11, 0xbfb8aa3b, v16
	v_exp_f32_e32 v11, v11
	v_and_b32_e32 v15, 0xffff0000, v39
	v_add_f32_e32 v11, 1.0, v11
	v_rcp_f32_e32 v12, v11
	v_mul_f32_e32 v11, 0xbfb8aa3b, v17
	v_exp_f32_e32 v11, v11
	s_nop 0
	v_add_f32_e32 v11, 1.0, v11
	v_rcp_f32_e32 v13, v11
	s_nop 0
	v_pk_mul_f32 v[12:13], v[12:13], v[14:15]
	v_add_co_u32_e32 v14, vcc, s2, v148
	v_cvt_pk_bf16_f32 v11, v12, v13
	s_nop 0
	v_addc_co_u32_e32 v15, vcc, 0, v149, vcc
	global_store_dwordx4 v[14:15], v[8:11], off
	v_lshl_add_u64 v[12:13], v[148:149], 0, s[18:19]
	s_andn2_b64 vcc, exec, s[14:15]
	v_pk_add_f32 v[8:9], v[2:3], v[42:43]
	v_pk_add_f32 v[2:3], v[0:1], v[40:41]
	v_mul_f32_e32 v0, 0xbfb8aa3b, v4
	v_mul_f32_e32 v1, 0xbfb8aa3b, v5
	v_exp_f32_e32 v0, v0
	v_exp_f32_e32 v1, v1
	v_lshlrev_b32_e32 v4, 16, v32
	v_and_b32_e32 v5, 0xffff0000, v32
	v_add_f32_e32 v0, 1.0, v0
	v_add_f32_e32 v1, 1.0, v1
	v_rcp_f32_e32 v0, v0
	v_rcp_f32_e32 v1, v1
	v_mul_f32_e32 v2, 0xbfb8aa3b, v2
	v_mul_f32_e32 v3, 0xbfb8aa3b, v3
	v_exp_f32_e32 v2, v2
	v_pk_mul_f32 v[0:1], v[0:1], v[4:5]
	v_exp_f32_e32 v3, v3
	v_cvt_pk_bf16_f32 v0, v0, v1
	v_mul_f32_e32 v1, 0xbfb8aa3b, v6
	v_exp_f32_e32 v1, v1
	v_add_f32_e32 v2, 1.0, v2
	v_add_f32_e32 v3, 1.0, v3
	v_rcp_f32_e32 v2, v2
	v_add_f32_e32 v1, 1.0, v1
	v_rcp_f32_e32 v4, v1
	v_mul_f32_e32 v1, 0xbfb8aa3b, v7
	v_exp_f32_e32 v1, v1
	v_rcp_f32_e32 v3, v3
	v_lshlrev_b32_e32 v6, 16, v33
	v_and_b32_e32 v7, 0xffff0000, v33
	v_add_f32_e32 v1, 1.0, v1
	v_rcp_f32_e32 v5, v1
	s_nop 0
	v_pk_mul_f32 v[4:5], v[4:5], v[6:7]
	s_nop 0
	v_cvt_pk_bf16_f32 v1, v4, v5
	v_lshlrev_b32_e32 v4, 16, v34
	v_and_b32_e32 v5, 0xffff0000, v34
	v_pk_mul_f32 v[2:3], v[2:3], v[4:5]
	v_lshlrev_b32_e32 v6, 16, v35
	v_cvt_pk_bf16_f32 v2, v2, v3
	v_mul_f32_e32 v3, 0xbfb8aa3b, v8
	v_exp_f32_e32 v3, v3
	v_and_b32_e32 v7, 0xffff0000, v35
	v_add_f32_e32 v3, 1.0, v3
	v_rcp_f32_e32 v4, v3
	v_mul_f32_e32 v3, 0xbfb8aa3b, v9
	v_exp_f32_e32 v3, v3
	s_nop 0
	v_add_f32_e32 v3, 1.0, v3
	v_rcp_f32_e32 v5, v3
	s_nop 0
	v_pk_mul_f32 v[4:5], v[4:5], v[6:7]
	s_nop 0
	v_cvt_pk_bf16_f32 v3, v4, v5
	global_store_dwordx4 v[12:13], v[0:3], off offset:256
	s_cbranch_vccnz .LBB0_380
	v_readlane_b32 s2, v254, 47
	v_readlane_b32 s3, v254, 48
	s_andn2_b64 vcc, exec, s[2:3]
	s_cbranch_vccnz .LBB0_379
	s_barrier
	s_branch .LBB0_379

; __device__ __forceinline__ unsigned cvt_pk_bf16(float lo, float hi) { f32x2 v = {lo, hi}; bf16x2_t b = __builtin_convertvector(v, bf16x2_t); return __builtin_bit_cast(unsigned, b); }
; __device__ __forceinline__ float gelu_tanh(float y) { const float u = 1.5957691216057308f * (y + 0.044715f * y * y * y); return y * sigmoidf_(u); }
; #define FOR_AI_M _Pragma("unroll") for (int ai = 0; ai < 2; ++ai) _Pragma("unroll") for (int m = 0; m < 4; ++m)
; __device__ __forceinline__ float sigmoidf_(float v) { return __builtin_amdgcn_rcpf(1.0f + __builtin_amdgcn_exp2f(-1.4426950408889634f * v)); }
;     __device__ __forceinline__ void operator()(const f32x4 (&acc)[2][2][4][2], const Unit& u, int wr, int wc, int fr, int fq) const {
;         FOR_AI_M {
;             const int chunk = 256 * u.pm + 128 * ai + 64 * wr + 16 * m + fr;
;             if (chunk < NCHUNK) {
; #pragma unroll
;                 for (int bj = 0; bj < 2; ++bj)
; #pragma unroll
;                     for (int n = 0; n < 2; ++n) {
;                         const int tl = 16 * u.pn + 8 * bj + 2 * wc + n; const size_t row = (size_t)chunk * 32 + tl;
;                         const f32x4 v = acc[ai][bj][m][n];
;                         u32x2 w; w.x = cvt_pk_bf16(gelu_tanh(v[0]), gelu_tanh(v[1])); w.y = cvt_pk_bf16(gelu_tanh(v[2]), gelu_tanh(v[3]));
;                         *(u32x2*)(GACT + row * 1024 + 16 * u.mode + 4 * fq) = w;
;                     }
.LBB0_444:
	v_mov_b32_e32 v136, v138
	v_mov_b32_e32 v134, v139
	s_lshl_b32 s2, s2, 8
	v_lshlrev_b32_e32 v134, 2, v134
	s_add_i32 s2, s2, s51
	v_ashrrev_i32_e32 v135, 31, v134
	v_add_u32_e32 v136, s2, v136
	s_movk_i32 s22, 0x420
	v_cmp_gt_i32_e32 vcc, s22, v136
	v_lshlrev_b64 v[134:135], 1, v[134:135]
	s_and_saveexec_b64 s[16:17], vcc
	s_cbranch_execz .LBB0_446
	v_ashrrev_i32_e32 v137, 31, v136
	v_lshlrev_b64 v[142:143], 16, v[136:137]
	v_mul_f32_e32 v137, 0x3d372713, v124
	v_mul_f32_e32 v137, v124, v137
	v_fma_f32 v137, v124, v137, v124
	v_mul_f32_e32 v137, 0x3fcc422a, v137
	v_mul_f32_e32 v137, 0xbfb8aa3b, v137
	v_exp_f32_e32 v137, v137
	s_lshl_b32 s2, s97, 4
	s_or_b32 s18, s2, s95
	s_ashr_i32 s19, s18, 31
	v_add_f32_e32 v137, 1.0, v137
	v_rcp_f32_e32 v144, v137
	v_mul_f32_e32 v137, 0x3d372713, v125
	v_mul_f32_e32 v137, v125, v137
	v_fma_f32 v137, v125, v137, v125
	v_mul_f32_e32 v137, 0x3fcc422a, v137
	v_mul_f32_e32 v137, 0xbfb8aa3b, v137
	v_exp_f32_e32 v137, v137
	s_lshl_b64 s[2:3], s[18:19], 11
	s_or_b32 s24, s18, 1
	s_ashr_i32 s25, s24, 31
	v_add_f32_e32 v137, 1.0, v137
	v_rcp_f32_e32 v145, v137
	s_nop 0
	v_pk_mul_f32 v[124:125], v[124:125], v[144:145]
	s_nop 0
	v_cvt_pk_bf16_f32 v144, v124, v125
	v_mul_f32_e32 v124, 0x3d372713, v126
	v_mul_f32_e32 v125, 0x3d372713, v127
	v_mul_f32_e32 v124, v126, v124
	v_mul_f32_e32 v125, v127, v125
	v_fma_f32 v124, v126, v124, v126
	v_fma_f32 v125, v127, v125, v127
	v_mul_f32_e32 v124, 0x3fcc422a, v124
	v_mul_f32_e32 v125, 0x3fcc422a, v125
	v_mul_f32_e32 v124, 0xbfb8aa3b, v124
	v_mul_f32_e32 v125, 0xbfb8aa3b, v125
	v_exp_f32_e32 v124, v124
	v_exp_f32_e32 v125, v125
	v_add_f32_e32 v124, 1.0, v124
	v_add_f32_e32 v125, 1.0, v125
	v_rcp_f32_e32 v124, v124
	v_rcp_f32_e32 v125, v125
	s_nop 0
	v_pk_mul_f32 v[124:125], v[126:127], v[124:125]
	s_nop 0
	v_cvt_pk_bf16_f32 v145, v124, v125
	v_lshl_add_u64 v[124:125], s[6:7], 0, v[142:143]
	v_lshl_add_u64 v[126:127], v[124:125], 0, s[2:3]
	s_lshl_b32 s2, s1, 4
	s_ashr_i32 s3, s2, 31
	s_lshl_b64 s[20:21], s[2:3], 1
	v_lshl_add_u64 v[126:127], v[126:127], 0, s[20:21]
	v_lshl_add_u64 v[126:127], v[126:127], 0, v[134:135]
	global_store_dwordx2 v[126:127], v[144:145], off
	v_mul_f32_e32 v126, 0x3d372713, v120
	v_mul_f32_e32 v127, 0x3d372713, v121
	v_mul_f32_e32 v126, v120, v126
	v_mul_f32_e32 v127, v121, v127
	v_fma_f32 v126, v120, v126, v120
	v_fma_f32 v127, v121, v127, v121
	v_mul_f32_e32 v126, 0x3fcc422a, v126
	v_mul_f32_e32 v127, 0x3fcc422a, v127
	v_mul_f32_e32 v126, 0xbfb8aa3b, v126
	v_mul_f32_e32 v127, 0xbfb8aa3b, v127
	v_exp_f32_e32 v126, v126
	v_exp_f32_e32 v127, v127
	s_lshl_b64 s[2:3], s[24:25], 11
	s_or_b32 s24, s18, 8
	v_add_f32_e32 v126, 1.0, v126
	v_add_f32_e32 v127, 1.0, v127
	v_rcp_f32_e32 v126, v126
	v_rcp_f32_e32 v127, v127
	s_ashr_i32 s25, s24, 31
	s_or_b32 s18, s18, 9
	s_ashr_i32 s19, s18, 31
	v_pk_mul_f32 v[120:121], v[120:121], v[126:127]
	s_nop 0
	v_cvt_pk_bf16_f32 v120, v120, v121
	v_mul_f32_e32 v121, 0x3d372713, v122
	v_mul_f32_e32 v121, v122, v121
	v_fma_f32 v121, v122, v121, v122
	v_mul_f32_e32 v121, 0x3fcc422a, v121
	v_mul_f32_e32 v121, 0xbfb8aa3b, v121
	v_exp_f32_e32 v121, v121
	s_nop 0
	v_add_f32_e32 v121, 1.0, v121
	v_rcp_f32_e32 v126, v121
	v_mul_f32_e32 v121, 0x3d372713, v123
	v_mul_f32_e32 v121, v123, v121
	v_fma_f32 v121, v123, v121, v123
	v_mul_f32_e32 v121, 0x3fcc422a, v121
	v_mul_f32_e32 v121, 0xbfb8aa3b, v121
	v_exp_f32_e32 v121, v121
	s_nop 0
	v_add_f32_e32 v121, 1.0, v121
	v_rcp_f32_e32 v127, v121
	s_nop 0
	v_pk_mul_f32 v[122:123], v[122:123], v[126:127]
	s_nop 0
	v_cvt_pk_bf16_f32 v121, v122, v123
	v_lshl_add_u64 v[122:123], v[124:125], 0, s[2:3]
	v_lshl_add_u64 v[122:123], v[122:123], 0, s[20:21]
	v_lshl_add_u64 v[122:123], v[122:123], 0, v[134:135]
	global_store_dwordx2 v[122:123], v[120:121], off
	v_mul_f32_e32 v120, 0x3d372713, v116
	v_mul_f32_e32 v121, 0x3d372713, v117
	v_mul_f32_e32 v120, v116, v120
	v_mul_f32_e32 v121, v117, v121
	v_fma_f32 v120, v116, v120, v116
	v_fma_f32 v121, v117, v121, v117
	v_mul_f32_e32 v120, 0x3fcc422a, v120
	v_mul_f32_e32 v121, 0x3fcc422a, v121
	v_mul_f32_e32 v120, 0xbfb8aa3b, v120
	v_mul_f32_e32 v121, 0xbfb8aa3b, v121
	v_exp_f32_e32 v120, v120
	v_exp_f32_e32 v121, v121
	s_lshl_b64 s[2:3], s[24:25], 11
	v_add_f32_e32 v120, 1.0, v120
	v_add_f32_e32 v121, 1.0, v121
	v_rcp_f32_e32 v120, v120
	v_rcp_f32_e32 v121, v121
	s_nop 0
	v_pk_mul_f32 v[116:117], v[116:117], v[120:121]
	s_nop 0
	v_cvt_pk_bf16_f32 v116, v116, v117
	v_mul_f32_e32 v117, 0x3d372713, v118
	v_mul_f32_e32 v117, v118, v117
	v_fma_f32 v117, v118, v117, v118
	v_mul_f32_e32 v117, 0x3fcc422a, v117
	v_mul_f32_e32 v117, 0xbfb8aa3b, v117
	v_exp_f32_e32 v117, v117
	s_nop 0
	v_add_f32_e32 v117, 1.0, v117
	v_rcp_f32_e32 v120, v117
	v_mul_f32_e32 v117, 0x3d372713, v119
	v_mul_f32_e32 v117, v119, v117
	v_fma_f32 v117, v119, v117, v119
	v_mul_f32_e32 v117, 0x3fcc422a, v117
	v_mul_f32_e32 v117, 0xbfb8aa3b, v117
	v_exp_f32_e32 v117, v117
	s_nop 0
	v_add_f32_e32 v117, 1.0, v117
	v_rcp_f32_e32 v121, v117
	s_nop 0
	v_pk_mul_f32 v[118:119], v[118:119], v[120:121]
	s_nop 0
	v_cvt_pk_bf16_f32 v117, v118, v119
	v_lshl_add_u64 v[118:119], v[124:125], 0, s[2:3]
	v_lshl_add_u64 v[118:119], v[118:119], 0, s[20:21]
	v_lshl_add_u64 v[118:119], v[118:119], 0, v[134:135]
	global_store_dwordx2 v[118:119], v[116:117], off
	v_mul_f32_e32 v116, 0x3d372713, v112
	v_mul_f32_e32 v117, 0x3d372713, v113
	v_mul_f32_e32 v116, v112, v116
	v_mul_f32_e32 v117, v113, v117
	v_fma_f32 v116, v112, v116, v112
	v_fma_f32 v117, v113, v117, v113
	v_mul_f32_e32 v116, 0x3fcc422a, v116
	v_mul_f32_e32 v117, 0x3fcc422a, v117
	v_mul_f32_e32 v116, 0xbfb8aa3b, v116
	v_mul_f32_e32 v117, 0xbfb8aa3b, v117
	v_exp_f32_e32 v116, v116
	v_exp_f32_e32 v117, v117
	s_lshl_b64 s[2:3], s[18:19], 11
	v_add_f32_e32 v116, 1.0, v116
	v_add_f32_e32 v117, 1.0, v117
	v_rcp_f32_e32 v116, v116
	v_rcp_f32_e32 v117, v117
	s_nop 0
	v_pk_mul_f32 v[112:113], v[112:113], v[116:117]
	s_nop 0
	v_cvt_pk_bf16_f32 v112, v112, v113
	v_mul_f32_e32 v113, 0x3d372713, v114
	v_mul_f32_e32 v113, v114, v113
	v_fma_f32 v113, v114, v113, v114
	v_mul_f32_e32 v113, 0x3fcc422a, v113
	v_mul_f32_e32 v113, 0xbfb8aa3b, v113
	v_exp_f32_e32 v113, v113
	s_nop 0
	v_add_f32_e32 v113, 1.0, v113
	v_rcp_f32_e32 v116, v113
	v_mul_f32_e32 v113, 0x3d372713, v115
	v_mul_f32_e32 v113, v115, v113
	v_fma_f32 v113, v115, v113, v115
	v_mul_f32_e32 v113, 0x3fcc422a, v113
	v_mul_f32_e32 v113, 0xbfb8aa3b, v113
	v_exp_f32_e32 v113, v113
	s_nop 0
	v_add_f32_e32 v113, 1.0, v113
	v_rcp_f32_e32 v117, v113
	s_nop 0
	v_pk_mul_f32 v[114:115], v[114:115], v[116:117]
	s_nop 0
	v_cvt_pk_bf16_f32 v113, v114, v115
	v_lshl_add_u64 v[114:115], v[124:125], 0, s[2:3]
	v_lshl_add_u64 v[114:115], v[114:115], 0, s[20:21]
	v_lshl_add_u64 v[114:115], v[114:115], 0, v[134:135]
	global_store_dwordx2 v[114:115], v[112:113], off
; __device__ __forceinline__ unsigned cvt_pk_bf16(float lo, float hi) { f32x2 v = {lo, hi}; bf16x2_t b = __builtin_convertvector(v, bf16x2_t); return __builtin_bit_cast(unsigned, b); }
; __device__ __forceinline__ float gelu_tanh(float y) { const float u = 1.5957691216057308f * (y + 0.044715f * y * y * y); return y * sigmoidf_(u); }
; __device__ __forceinline__ float sigmoidf_(float v) { return __builtin_amdgcn_rcpf(1.0f + __builtin_amdgcn_exp2f(-1.4426950408889634f * v)); }
;     __device__ __forceinline__ void operator()(const f32x4 (&acc)[2][2][4][2], const Unit& u, int wr, int wc, int fr, int fq) const {
;     ...
;             const int chunk = 256 * u.pm + 128 * ai + 64 * wr + 16 * m + fr;
;             if (chunk < NCHUNK) {
; #pragma unroll
;                 for (int bj = 0; bj < 2; ++bj)
; #pragma unroll
;                     for (int n = 0; n < 2; ++n) {
;                         const int tl = 16 * u.pn + 8 * bj + 2 * wc + n; const size_t row = (size_t)chunk * 32 + tl;
;                         const f32x4 v = acc[ai][bj][m][n];
;                         u32x2 w; w.x = cvt_pk_bf16(gelu_tanh(v[0]), gelu_tanh(v[1])); w.y = cvt_pk_bf16(gelu_tanh(v[2]), gelu_tanh(v[3]));
;                         *(u32x2*)(GACT + row * 1024 + 16 * u.mode + 4 * fq) = w;
;                     }
.LBB0_446:
	s_or_b64 exec, exec, s[16:17]
	v_add_u32_e32 v112, 16, v136
	v_cmp_gt_i32_e32 vcc, s22, v112
	s_and_saveexec_b64 s[16:17], vcc
	s_cbranch_execz .LBB0_448
	v_mul_f32_e32 v114, 0x3d372713, v108
	v_mul_f32_e32 v115, 0x3d372713, v109
	v_mul_f32_e32 v114, v108, v114
	v_mul_f32_e32 v115, v109, v115
	v_fma_f32 v114, v108, v114, v108
	v_fma_f32 v115, v109, v115, v109
	v_mul_f32_e32 v114, 0x3fcc422a, v114
	v_mul_f32_e32 v115, 0x3fcc422a, v115
	v_mul_f32_e32 v114, 0xbfb8aa3b, v114
	v_mul_f32_e32 v115, 0xbfb8aa3b, v115
	v_exp_f32_e32 v114, v114
	v_exp_f32_e32 v115, v115
	s_lshl_b32 s2, s97, 4
	v_ashrrev_i32_e32 v113, 31, v112
	v_add_f32_e32 v114, 1.0, v114
	v_add_f32_e32 v115, 1.0, v115
	v_rcp_f32_e32 v114, v114
	v_rcp_f32_e32 v115, v115
	s_or_b32 s18, s2, s95
	v_lshlrev_b64 v[112:113], 16, v[112:113]
	s_ashr_i32 s19, s18, 31
	v_pk_mul_f32 v[108:109], v[108:109], v[114:115]
	s_lshl_b64 s[2:3], s[18:19], 11
	v_cvt_pk_bf16_f32 v114, v108, v109
	v_mul_f32_e32 v108, 0x3d372713, v110
	v_mul_f32_e32 v109, 0x3d372713, v111
	v_mul_f32_e32 v108, v110, v108
	v_mul_f32_e32 v109, v111, v109
	v_fma_f32 v108, v110, v108, v110
	v_fma_f32 v109, v111, v109, v111
	v_mul_f32_e32 v108, 0x3fcc422a, v108
	v_mul_f32_e32 v109, 0x3fcc422a, v109
	v_mul_f32_e32 v108, 0xbfb8aa3b, v108
	v_mul_f32_e32 v109, 0xbfb8aa3b, v109
	v_exp_f32_e32 v108, v108
	v_exp_f32_e32 v109, v109
	s_or_b32 s24, s18, 1
	s_ashr_i32 s25, s24, 31
	v_add_f32_e32 v108, 1.0, v108
	v_add_f32_e32 v109, 1.0, v109
	v_rcp_f32_e32 v108, v108
	v_rcp_f32_e32 v109, v109
	s_nop 0
	v_pk_mul_f32 v[108:109], v[110:111], v[108:109]
	s_nop 0
	v_cvt_pk_bf16_f32 v115, v108, v109
	v_lshl_add_u64 v[108:109], s[6:7], 0, v[112:113]
	v_lshl_add_u64 v[110:111], v[108:109], 0, s[2:3]
	s_lshl_b32 s2, s1, 4
	s_ashr_i32 s3, s2, 31
	s_lshl_b64 s[20:21], s[2:3], 1
	v_lshl_add_u64 v[110:111], v[110:111], 0, s[20:21]
	v_lshl_add_u64 v[110:111], v[110:111], 0, v[134:135]
	global_store_dwordx2 v[110:111], v[114:115], off
	v_mul_f32_e32 v110, 0x3d372713, v104
	v_mul_f32_e32 v111, 0x3d372713, v105
	v_mul_f32_e32 v110, v104, v110
	v_mul_f32_e32 v111, v105, v111
	v_fma_f32 v110, v104, v110, v104
	v_fma_f32 v111, v105, v111, v105
	v_mul_f32_e32 v110, 0x3fcc422a, v110
	v_mul_f32_e32 v111, 0x3fcc422a, v111
	v_mul_f32_e32 v110, 0xbfb8aa3b, v110
	v_mul_f32_e32 v111, 0xbfb8aa3b, v111
	v_exp_f32_e32 v110, v110
	v_exp_f32_e32 v111, v111
	s_lshl_b64 s[2:3], s[24:25], 11
	s_or_b32 s24, s18, 8
	v_add_f32_e32 v110, 1.0, v110
	v_add_f32_e32 v111, 1.0, v111
	v_rcp_f32_e32 v110, v110
	v_rcp_f32_e32 v111, v111
	s_ashr_i32 s25, s24, 31
	s_or_b32 s18, s18, 9
	s_ashr_i32 s19, s18, 31
	v_pk_mul_f32 v[104:105], v[104:105], v[110:111]
	s_nop 0
	v_cvt_pk_bf16_f32 v104, v104, v105
	v_mul_f32_e32 v105, 0x3d372713, v106
	v_mul_f32_e32 v105, v106, v105
	v_fma_f32 v105, v106, v105, v106
	v_mul_f32_e32 v105, 0x3fcc422a, v105
	v_mul_f32_e32 v105, 0xbfb8aa3b, v105
	v_exp_f32_e32 v105, v105
	s_nop 0
	v_add_f32_e32 v105, 1.0, v105
	v_rcp_f32_e32 v110, v105
	v_mul_f32_e32 v105, 0x3d372713, v107
	v_mul_f32_e32 v105, v107, v105
	v_fma_f32 v105, v107, v105, v107
	v_mul_f32_e32 v105, 0x3fcc422a, v105
	v_mul_f32_e32 v105, 0xbfb8aa3b, v105
	v_exp_f32_e32 v105, v105
	s_nop 0
	v_add_f32_e32 v105, 1.0, v105
	v_rcp_f32_e32 v111, v105
	s_nop 0
	v_pk_mul_f32 v[106:107], v[106:107], v[110:111]
	s_nop 0
	v_cvt_pk_bf16_f32 v105, v106, v107
	v_lshl_add_u64 v[106:107], v[108:109], 0, s[2:3]
	v_lshl_add_u64 v[106:107], v[106:107], 0, s[20:21]
	v_lshl_add_u64 v[106:107], v[106:107], 0, v[134:135]
	global_store_dwordx2 v[106:107], v[104:105], off
	v_mul_f32_e32 v104, 0x3d372713, v100
	v_mul_f32_e32 v105, 0x3d372713, v101
	v_mul_f32_e32 v104, v100, v104
	v_mul_f32_e32 v105, v101, v105
	v_fma_f32 v104, v100, v104, v100
	v_fma_f32 v105, v101, v105, v101
	v_mul_f32_e32 v104, 0x3fcc422a, v104
	v_mul_f32_e32 v105, 0x3fcc422a, v105
	v_mul_f32_e32 v104, 0xbfb8aa3b, v104
	v_mul_f32_e32 v105, 0xbfb8aa3b, v105
	v_exp_f32_e32 v104, v104
	v_exp_f32_e32 v105, v105
	s_lshl_b64 s[2:3], s[24:25], 11
	v_add_f32_e32 v104, 1.0, v104
	v_add_f32_e32 v105, 1.0, v105
	v_rcp_f32_e32 v104, v104
	v_rcp_f32_e32 v105, v105
	s_nop 0
	v_pk_mul_f32 v[100:101], v[100:101], v[104:105]
	s_nop 0
	v_cvt_pk_bf16_f32 v100, v100, v101
	v_mul_f32_e32 v101, 0x3d372713, v102
	v_mul_f32_e32 v101, v102, v101
	v_fma_f32 v101, v102, v101, v102
	v_mul_f32_e32 v101, 0x3fcc422a, v101
	v_mul_f32_e32 v101, 0xbfb8aa3b, v101
	v_exp_f32_e32 v101, v101
	s_nop 0
	v_add_f32_e32 v101, 1.0, v101
	v_rcp_f32_e32 v104, v101
	v_mul_f32_e32 v101, 0x3d372713, v103
	v_mul_f32_e32 v101, v103, v101
	v_fma_f32 v101, v103, v101, v103
	v_mul_f32_e32 v101, 0x3fcc422a, v101
	v_mul_f32_e32 v101, 0xbfb8aa3b, v101
	v_exp_f32_e32 v101, v101
	s_nop 0
	v_add_f32_e32 v101, 1.0, v101
	v_rcp_f32_e32 v105, v101
	s_nop 0
	v_pk_mul_f32 v[102:103], v[102:103], v[104:105]
	s_nop 0
	v_cvt_pk_bf16_f32 v101, v102, v103
	v_lshl_add_u64 v[102:103], v[108:109], 0, s[2:3]
	v_lshl_add_u64 v[102:103], v[102:103], 0, s[20:21]
	v_lshl_add_u64 v[102:103], v[102:103], 0, v[134:135]
	global_store_dwordx2 v[102:103], v[100:101], off
	v_mul_f32_e32 v100, 0x3d372713, v96
	v_mul_f32_e32 v101, 0x3d372713, v97
	v_mul_f32_e32 v100, v96, v100
	v_mul_f32_e32 v101, v97, v101
	v_fma_f32 v100, v96, v100, v96
	v_fma_f32 v101, v97, v101, v97
	v_mul_f32_e32 v100, 0x3fcc422a, v100
	v_mul_f32_e32 v101, 0x3fcc422a, v101
	v_mul_f32_e32 v100, 0xbfb8aa3b, v100
	v_mul_f32_e32 v101, 0xbfb8aa3b, v101
	v_exp_f32_e32 v100, v100
	v_exp_f32_e32 v101, v101
	s_lshl_b64 s[2:3], s[18:19], 11
	v_add_f32_e32 v100, 1.0, v100
	v_add_f32_e32 v101, 1.0, v101
	v_rcp_f32_e32 v100, v100
	v_rcp_f32_e32 v101, v101
	s_nop 0
	v_pk_mul_f32 v[96:97], v[96:97], v[100:101]
	s_nop 0
	v_cvt_pk_bf16_f32 v96, v96, v97
	v_mul_f32_e32 v97, 0x3d372713, v98
	v_mul_f32_e32 v97, v98, v97
	v_fma_f32 v97, v98, v97, v98
	v_mul_f32_e32 v97, 0x3fcc422a, v97
	v_mul_f32_e32 v97, 0xbfb8aa3b, v97
	v_exp_f32_e32 v97, v97
	s_nop 0
	v_add_f32_e32 v97, 1.0, v97
	v_rcp_f32_e32 v100, v97
	v_mul_f32_e32 v97, 0x3d372713, v99
	v_mul_f32_e32 v97, v99, v97
	v_fma_f32 v97, v99, v97, v99
	v_mul_f32_e32 v97, 0x3fcc422a, v97
	v_mul_f32_e32 v97, 0xbfb8aa3b, v97
	v_exp_f32_e32 v97, v97
	s_nop 0
	v_add_f32_e32 v97, 1.0, v97
	v_rcp_f32_e32 v101, v97
	s_nop 0
	v_pk_mul_f32 v[98:99], v[98:99], v[100:101]
	s_nop 0
	v_cvt_pk_bf16_f32 v97, v98, v99
	v_lshl_add_u64 v[98:99], v[108:109], 0, s[2:3]
	v_lshl_add_u64 v[98:99], v[98:99], 0, s[20:21]
	v_lshl_add_u64 v[98:99], v[98:99], 0, v[134:135]
	global_store_dwordx2 v[98:99], v[96:97], off
; __device__ __forceinline__ unsigned cvt_pk_bf16(float lo, float hi) { f32x2 v = {lo, hi}; bf16x2_t b = __builtin_convertvector(v, bf16x2_t); return __builtin_bit_cast(unsigned, b); }
; __device__ __forceinline__ float gelu_tanh(float y) { const float u = 1.5957691216057308f * (y + 0.044715f * y * y * y); return y * sigmoidf_(u); }
; __device__ __forceinline__ float sigmoidf_(float v) { return __builtin_amdgcn_rcpf(1.0f + __builtin_amdgcn_exp2f(-1.4426950408889634f * v)); }
;     __device__ __forceinline__ void operator()(const f32x4 (&acc)[2][2][4][2], const Unit& u, int wr, int wc, int fr, int fq) const {
;     ...
;             const int chunk = 256 * u.pm + 128 * ai + 64 * wr + 16 * m + fr;
;             if (chunk < NCHUNK) {
; #pragma unroll
;                 for (int bj = 0; bj < 2; ++bj)
; #pragma unroll
;                     for (int n = 0; n < 2; ++n) {
;                         const int tl = 16 * u.pn + 8 * bj + 2 * wc + n; const size_t row = (size_t)chunk * 32 + tl;
;                         const f32x4 v = acc[ai][bj][m][n];
;                         u32x2 w; w.x = cvt_pk_bf16(gelu_tanh(v[0]), gelu_tanh(v[1])); w.y = cvt_pk_bf16(gelu_tanh(v[2]), gelu_tanh(v[3]));
;                         *(u32x2*)(GACT + row * 1024 + 16 * u.mode + 4 * fq) = w;
;                     }
.LBB0_448:
	s_or_b64 exec, exec, s[16:17]
	v_add_u32_e32 v96, 32, v136
	v_cmp_gt_i32_e32 vcc, s22, v96
	s_and_saveexec_b64 s[16:17], vcc
	s_cbranch_execz .LBB0_450
	v_mul_f32_e32 v98, 0x3d372713, v92
	v_mul_f32_e32 v99, 0x3d372713, v93
	v_mul_f32_e32 v98, v92, v98
	v_mul_f32_e32 v99, v93, v99
	v_fma_f32 v98, v92, v98, v92
	v_fma_f32 v99, v93, v99, v93
	v_mul_f32_e32 v98, 0x3fcc422a, v98
	v_mul_f32_e32 v99, 0x3fcc422a, v99
	v_mul_f32_e32 v98, 0xbfb8aa3b, v98
	v_mul_f32_e32 v99, 0xbfb8aa3b, v99
	v_exp_f32_e32 v98, v98
	v_exp_f32_e32 v99, v99
	s_lshl_b32 s2, s97, 4
	v_ashrrev_i32_e32 v97, 31, v96
	v_add_f32_e32 v98, 1.0, v98
	v_add_f32_e32 v99, 1.0, v99
	v_rcp_f32_e32 v98, v98
	v_rcp_f32_e32 v99, v99
	s_or_b32 s18, s2, s95
	v_lshlrev_b64 v[96:97], 16, v[96:97]
	s_ashr_i32 s19, s18, 31
	v_pk_mul_f32 v[92:93], v[92:93], v[98:99]
	s_lshl_b64 s[2:3], s[18:19], 11
	v_cvt_pk_bf16_f32 v98, v92, v93
	v_mul_f32_e32 v92, 0x3d372713, v94
	v_mul_f32_e32 v93, 0x3d372713, v95
	v_mul_f32_e32 v92, v94, v92
	v_mul_f32_e32 v93, v95, v93
	v_fma_f32 v92, v94, v92, v94
	v_fma_f32 v93, v95, v93, v95
	v_mul_f32_e32 v92, 0x3fcc422a, v92
	v_mul_f32_e32 v93, 0x3fcc422a, v93
	v_mul_f32_e32 v92, 0xbfb8aa3b, v92
	v_mul_f32_e32 v93, 0xbfb8aa3b, v93
	v_exp_f32_e32 v92, v92
	v_exp_f32_e32 v93, v93
	s_or_b32 s24, s18, 1
	s_ashr_i32 s25, s24, 31
	v_add_f32_e32 v92, 1.0, v92
	v_add_f32_e32 v93, 1.0, v93
	v_rcp_f32_e32 v92, v92
	v_rcp_f32_e32 v93, v93
	s_nop 0
	v_pk_mul_f32 v[92:93], v[94:95], v[92:93]
	s_nop 0
	v_cvt_pk_bf16_f32 v99, v92, v93
	v_lshl_add_u64 v[92:93], s[6:7], 0, v[96:97]
	v_lshl_add_u64 v[94:95], v[92:93], 0, s[2:3]
	s_lshl_b32 s2, s1, 4
	s_ashr_i32 s3, s2, 31
	s_lshl_b64 s[20:21], s[2:3], 1
	v_lshl_add_u64 v[94:95], v[94:95], 0, s[20:21]
	v_lshl_add_u64 v[94:95], v[94:95], 0, v[134:135]
	global_store_dwordx2 v[94:95], v[98:99], off
	v_mul_f32_e32 v94, 0x3d372713, v88
	v_mul_f32_e32 v95, 0x3d372713, v89
	v_mul_f32_e32 v94, v88, v94
	v_mul_f32_e32 v95, v89, v95
	v_fma_f32 v94, v88, v94, v88
	v_fma_f32 v95, v89, v95, v89
	v_mul_f32_e32 v94, 0x3fcc422a, v94
	v_mul_f32_e32 v95, 0x3fcc422a, v95
	v_mul_f32_e32 v94, 0xbfb8aa3b, v94
	v_mul_f32_e32 v95, 0xbfb8aa3b, v95
	v_exp_f32_e32 v94, v94
	v_exp_f32_e32 v95, v95
	s_lshl_b64 s[2:3], s[24:25], 11
	s_or_b32 s24, s18, 8
	v_add_f32_e32 v94, 1.0, v94
	v_add_f32_e32 v95, 1.0, v95
	v_rcp_f32_e32 v94, v94
	v_rcp_f32_e32 v95, v95
	s_ashr_i32 s25, s24, 31
	s_or_b32 s18, s18, 9
	s_ashr_i32 s19, s18, 31
	v_pk_mul_f32 v[88:89], v[88:89], v[94:95]
	s_nop 0
	v_cvt_pk_bf16_f32 v88, v88, v89
	v_mul_f32_e32 v89, 0x3d372713, v90
	v_mul_f32_e32 v89, v90, v89
	v_fma_f32 v89, v90, v89, v90
	v_mul_f32_e32 v89, 0x3fcc422a, v89
	v_mul_f32_e32 v89, 0xbfb8aa3b, v89
	v_exp_f32_e32 v89, v89
	s_nop 0
	v_add_f32_e32 v89, 1.0, v89
	v_rcp_f32_e32 v94, v89
	v_mul_f32_e32 v89, 0x3d372713, v91
	v_mul_f32_e32 v89, v91, v89
	v_fma_f32 v89, v91, v89, v91
	v_mul_f32_e32 v89, 0x3fcc422a, v89
	v_mul_f32_e32 v89, 0xbfb8aa3b, v89
	v_exp_f32_e32 v89, v89
	s_nop 0
	v_add_f32_e32 v89, 1.0, v89
	v_rcp_f32_e32 v95, v89
	s_nop 0
	v_pk_mul_f32 v[90:91], v[90:91], v[94:95]
	s_nop 0
	v_cvt_pk_bf16_f32 v89, v90, v91
	v_lshl_add_u64 v[90:91], v[92:93], 0, s[2:3]
	v_lshl_add_u64 v[90:91], v[90:91], 0, s[20:21]
	v_lshl_add_u64 v[90:91], v[90:91], 0, v[134:135]
	global_store_dwordx2 v[90:91], v[88:89], off
	v_mul_f32_e32 v88, 0x3d372713, v84
	v_mul_f32_e32 v89, 0x3d372713, v85
	v_mul_f32_e32 v88, v84, v88
	v_mul_f32_e32 v89, v85, v89
	v_fma_f32 v88, v84, v88, v84
	v_fma_f32 v89, v85, v89, v85
	v_mul_f32_e32 v88, 0x3fcc422a, v88
	v_mul_f32_e32 v89, 0x3fcc422a, v89
	v_mul_f32_e32 v88, 0xbfb8aa3b, v88
	v_mul_f32_e32 v89, 0xbfb8aa3b, v89
	v_exp_f32_e32 v88, v88
	v_exp_f32_e32 v89, v89
	s_lshl_b64 s[2:3], s[24:25], 11
	v_add_f32_e32 v88, 1.0, v88
	v_add_f32_e32 v89, 1.0, v89
	v_rcp_f32_e32 v88, v88
	v_rcp_f32_e32 v89, v89
	s_nop 0
	v_pk_mul_f32 v[84:85], v[84:85], v[88:89]
	s_nop 0
	v_cvt_pk_bf16_f32 v84, v84, v85
	v_mul_f32_e32 v85, 0x3d372713, v86
	v_mul_f32_e32 v85, v86, v85
	v_fma_f32 v85, v86, v85, v86
	v_mul_f32_e32 v85, 0x3fcc422a, v85
	v_mul_f32_e32 v85, 0xbfb8aa3b, v85
	v_exp_f32_e32 v85, v85
	s_nop 0
	v_add_f32_e32 v85, 1.0, v85
	v_rcp_f32_e32 v88, v85
	v_mul_f32_e32 v85, 0x3d372713, v87
	v_mul_f32_e32 v85, v87, v85
	v_fma_f32 v85, v87, v85, v87
	v_mul_f32_e32 v85, 0x3fcc422a, v85
	v_mul_f32_e32 v85, 0xbfb8aa3b, v85
	v_exp_f32_e32 v85, v85
	s_nop 0
	v_add_f32_e32 v85, 1.0, v85
	v_rcp_f32_e32 v89, v85
	s_nop 0
	v_pk_mul_f32 v[86:87], v[86:87], v[88:89]
	s_nop 0
	v_cvt_pk_bf16_f32 v85, v86, v87
	v_lshl_add_u64 v[86:87], v[92:93], 0, s[2:3]
	v_lshl_add_u64 v[86:87], v[86:87], 0, s[20:21]
	v_lshl_add_u64 v[86:87], v[86:87], 0, v[134:135]
	global_store_dwordx2 v[86:87], v[84:85], off
	v_mul_f32_e32 v84, 0x3d372713, v80
	v_mul_f32_e32 v85, 0x3d372713, v81
	v_mul_f32_e32 v84, v80, v84
	v_mul_f32_e32 v85, v81, v85
	v_fma_f32 v84, v80, v84, v80
	v_fma_f32 v85, v81, v85, v81
	v_mul_f32_e32 v84, 0x3fcc422a, v84
	v_mul_f32_e32 v85, 0x3fcc422a, v85
	v_mul_f32_e32 v84, 0xbfb8aa3b, v84
	v_mul_f32_e32 v85, 0xbfb8aa3b, v85
	v_exp_f32_e32 v84, v84
	v_exp_f32_e32 v85, v85
	s_lshl_b64 s[2:3], s[18:19], 11
	v_add_f32_e32 v84, 1.0, v84
	v_add_f32_e32 v85, 1.0, v85
	v_rcp_f32_e32 v84, v84
	v_rcp_f32_e32 v85, v85
	s_nop 0
	v_pk_mul_f32 v[80:81], v[80:81], v[84:85]
	s_nop 0
	v_cvt_pk_bf16_f32 v80, v80, v81
	v_mul_f32_e32 v81, 0x3d372713, v82
	v_mul_f32_e32 v81, v82, v81
	v_fma_f32 v81, v82, v81, v82
	v_mul_f32_e32 v81, 0x3fcc422a, v81
	v_mul_f32_e32 v81, 0xbfb8aa3b, v81
	v_exp_f32_e32 v81, v81
	s_nop 0
	v_add_f32_e32 v81, 1.0, v81
	v_rcp_f32_e32 v84, v81
	v_mul_f32_e32 v81, 0x3d372713, v83
	v_mul_f32_e32 v81, v83, v81
	v_fma_f32 v81, v83, v81, v83
	v_mul_f32_e32 v81, 0x3fcc422a, v81
	v_mul_f32_e32 v81, 0xbfb8aa3b, v81
	v_exp_f32_e32 v81, v81
	s_nop 0
	v_add_f32_e32 v81, 1.0, v81
	v_rcp_f32_e32 v85, v81
	s_nop 0
	v_pk_mul_f32 v[82:83], v[82:83], v[84:85]
	s_nop 0
	v_cvt_pk_bf16_f32 v81, v82, v83
	v_lshl_add_u64 v[82:83], v[92:93], 0, s[2:3]
	v_lshl_add_u64 v[82:83], v[82:83], 0, s[20:21]
	v_lshl_add_u64 v[82:83], v[82:83], 0, v[134:135]
	global_store_dwordx2 v[82:83], v[80:81], off
; __device__ __forceinline__ unsigned cvt_pk_bf16(float lo, float hi) { f32x2 v = {lo, hi}; bf16x2_t b = __builtin_convertvector(v, bf16x2_t); return __builtin_bit_cast(unsigned, b); }
; __device__ __forceinline__ float gelu_tanh(float y) { const float u = 1.5957691216057308f * (y + 0.044715f * y * y * y); return y * sigmoidf_(u); }
; __device__ __forceinline__ float sigmoidf_(float v) { return __builtin_amdgcn_rcpf(1.0f + __builtin_amdgcn_exp2f(-1.4426950408889634f * v)); }
;     __device__ __forceinline__ void operator()(const f32x4 (&acc)[2][2][4][2], const Unit& u, int wr, int wc, int fr, int fq) const {
;     ...
;             const int chunk = 256 * u.pm + 128 * ai + 64 * wr + 16 * m + fr;
;             if (chunk < NCHUNK) {
; #pragma unroll
;                 for (int bj = 0; bj < 2; ++bj)
; #pragma unroll
;                     for (int n = 0; n < 2; ++n) {
;                         const int tl = 16 * u.pn + 8 * bj + 2 * wc + n; const size_t row = (size_t)chunk * 32 + tl;
;                         const f32x4 v = acc[ai][bj][m][n];
;                         u32x2 w; w.x = cvt_pk_bf16(gelu_tanh(v[0]), gelu_tanh(v[1])); w.y = cvt_pk_bf16(gelu_tanh(v[2]), gelu_tanh(v[3]));
;                         *(u32x2*)(GACT + row * 1024 + 16 * u.mode + 4 * fq) = w;
;                     }
.LBB0_450:
	s_or_b64 exec, exec, s[16:17]
	v_add_u32_e32 v80, 48, v136
	v_cmp_gt_i32_e32 vcc, s22, v80
	s_and_saveexec_b64 s[16:17], vcc
	s_cbranch_execz .LBB0_452
	v_mul_f32_e32 v82, 0x3d372713, v76
	v_mul_f32_e32 v83, 0x3d372713, v77
	v_mul_f32_e32 v82, v76, v82
	v_mul_f32_e32 v83, v77, v83
	v_fma_f32 v82, v76, v82, v76
	v_fma_f32 v83, v77, v83, v77
	v_mul_f32_e32 v82, 0x3fcc422a, v82
	v_mul_f32_e32 v83, 0x3fcc422a, v83
	v_mul_f32_e32 v82, 0xbfb8aa3b, v82
	v_mul_f32_e32 v83, 0xbfb8aa3b, v83
	v_exp_f32_e32 v82, v82
	v_exp_f32_e32 v83, v83
	s_lshl_b32 s2, s97, 4
	v_ashrrev_i32_e32 v81, 31, v80
	v_add_f32_e32 v82, 1.0, v82
	v_add_f32_e32 v83, 1.0, v83
	v_rcp_f32_e32 v82, v82
	v_rcp_f32_e32 v83, v83
	s_or_b32 s18, s2, s95
	v_lshlrev_b64 v[80:81], 16, v[80:81]
	s_ashr_i32 s19, s18, 31
	v_pk_mul_f32 v[76:77], v[76:77], v[82:83]
	s_lshl_b64 s[2:3], s[18:19], 11
	v_cvt_pk_bf16_f32 v82, v76, v77
	v_mul_f32_e32 v76, 0x3d372713, v78
	v_mul_f32_e32 v77, 0x3d372713, v79
	v_mul_f32_e32 v76, v78, v76
	v_mul_f32_e32 v77, v79, v77
	v_fma_f32 v76, v78, v76, v78
	v_fma_f32 v77, v79, v77, v79
	v_mul_f32_e32 v76, 0x3fcc422a, v76
	v_mul_f32_e32 v77, 0x3fcc422a, v77
	v_mul_f32_e32 v76, 0xbfb8aa3b, v76
	v_mul_f32_e32 v77, 0xbfb8aa3b, v77
	v_exp_f32_e32 v76, v76
	v_exp_f32_e32 v77, v77
	s_or_b32 s24, s18, 1
	s_ashr_i32 s25, s24, 31
	v_add_f32_e32 v76, 1.0, v76
	v_add_f32_e32 v77, 1.0, v77
	v_rcp_f32_e32 v76, v76
	v_rcp_f32_e32 v77, v77
	s_nop 0
	v_pk_mul_f32 v[76:77], v[78:79], v[76:77]
	s_nop 0
	v_cvt_pk_bf16_f32 v83, v76, v77
	v_lshl_add_u64 v[76:77], s[6:7], 0, v[80:81]
	v_lshl_add_u64 v[78:79], v[76:77], 0, s[2:3]
	s_lshl_b32 s2, s1, 4
	s_ashr_i32 s3, s2, 31
	s_lshl_b64 s[20:21], s[2:3], 1
	v_lshl_add_u64 v[78:79], v[78:79], 0, s[20:21]
	v_lshl_add_u64 v[78:79], v[78:79], 0, v[134:135]
	global_store_dwordx2 v[78:79], v[82:83], off
	v_mul_f32_e32 v78, 0x3d372713, v72
	v_mul_f32_e32 v79, 0x3d372713, v73
	v_mul_f32_e32 v78, v72, v78
	v_mul_f32_e32 v79, v73, v79
	v_fma_f32 v78, v72, v78, v72
	v_fma_f32 v79, v73, v79, v73
	v_mul_f32_e32 v78, 0x3fcc422a, v78
	v_mul_f32_e32 v79, 0x3fcc422a, v79
	v_mul_f32_e32 v78, 0xbfb8aa3b, v78
	v_mul_f32_e32 v79, 0xbfb8aa3b, v79
	v_exp_f32_e32 v78, v78
	v_exp_f32_e32 v79, v79
	s_lshl_b64 s[2:3], s[24:25], 11
	s_or_b32 s24, s18, 8
	v_add_f32_e32 v78, 1.0, v78
	v_add_f32_e32 v79, 1.0, v79
	v_rcp_f32_e32 v78, v78
	v_rcp_f32_e32 v79, v79
	s_ashr_i32 s25, s24, 31
	s_or_b32 s18, s18, 9
	s_ashr_i32 s19, s18, 31
	v_pk_mul_f32 v[72:73], v[72:73], v[78:79]
	s_nop 0
	v_cvt_pk_bf16_f32 v72, v72, v73
	v_mul_f32_e32 v73, 0x3d372713, v74
	v_mul_f32_e32 v73, v74, v73
	v_fma_f32 v73, v74, v73, v74
	v_mul_f32_e32 v73, 0x3fcc422a, v73
	v_mul_f32_e32 v73, 0xbfb8aa3b, v73
	v_exp_f32_e32 v73, v73
	s_nop 0
	v_add_f32_e32 v73, 1.0, v73
	v_rcp_f32_e32 v78, v73
	v_mul_f32_e32 v73, 0x3d372713, v75
	v_mul_f32_e32 v73, v75, v73
	v_fma_f32 v73, v75, v73, v75
	v_mul_f32_e32 v73, 0x3fcc422a, v73
	v_mul_f32_e32 v73, 0xbfb8aa3b, v73
	v_exp_f32_e32 v73, v73
	s_nop 0
	v_add_f32_e32 v73, 1.0, v73
	v_rcp_f32_e32 v79, v73
	s_nop 0
	v_pk_mul_f32 v[74:75], v[74:75], v[78:79]
	s_nop 0
	v_cvt_pk_bf16_f32 v73, v74, v75
	v_lshl_add_u64 v[74:75], v[76:77], 0, s[2:3]
	v_lshl_add_u64 v[74:75], v[74:75], 0, s[20:21]
	v_lshl_add_u64 v[74:75], v[74:75], 0, v[134:135]
	global_store_dwordx2 v[74:75], v[72:73], off
	v_mul_f32_e32 v72, 0x3d372713, v68
	v_mul_f32_e32 v73, 0x3d372713, v69
	v_mul_f32_e32 v72, v68, v72
	v_mul_f32_e32 v73, v69, v73
	v_fma_f32 v72, v68, v72, v68
	v_fma_f32 v73, v69, v73, v69
	v_mul_f32_e32 v72, 0x3fcc422a, v72
	v_mul_f32_e32 v73, 0x3fcc422a, v73
	v_mul_f32_e32 v72, 0xbfb8aa3b, v72
	v_mul_f32_e32 v73, 0xbfb8aa3b, v73
	v_exp_f32_e32 v72, v72
	v_exp_f32_e32 v73, v73
	s_lshl_b64 s[2:3], s[24:25], 11
	v_add_f32_e32 v72, 1.0, v72
	v_add_f32_e32 v73, 1.0, v73
	v_rcp_f32_e32 v72, v72
	v_rcp_f32_e32 v73, v73
	s_nop 0
	v_pk_mul_f32 v[68:69], v[68:69], v[72:73]
	s_nop 0
	v_cvt_pk_bf16_f32 v68, v68, v69
	v_mul_f32_e32 v69, 0x3d372713, v70
	v_mul_f32_e32 v69, v70, v69
	v_fma_f32 v69, v70, v69, v70
	v_mul_f32_e32 v69, 0x3fcc422a, v69
	v_mul_f32_e32 v69, 0xbfb8aa3b, v69
	v_exp_f32_e32 v69, v69
	s_nop 0
	v_add_f32_e32 v69, 1.0, v69
	v_rcp_f32_e32 v72, v69
	v_mul_f32_e32 v69, 0x3d372713, v71
	v_mul_f32_e32 v69, v71, v69
	v_fma_f32 v69, v71, v69, v71
	v_mul_f32_e32 v69, 0x3fcc422a, v69
	v_mul_f32_e32 v69, 0xbfb8aa3b, v69
	v_exp_f32_e32 v69, v69
	s_nop 0
	v_add_f32_e32 v69, 1.0, v69
	v_rcp_f32_e32 v73, v69
	s_nop 0
	v_pk_mul_f32 v[70:71], v[70:71], v[72:73]
	s_nop 0
	v_cvt_pk_bf16_f32 v69, v70, v71
	v_lshl_add_u64 v[70:71], v[76:77], 0, s[2:3]
	v_lshl_add_u64 v[70:71], v[70:71], 0, s[20:21]
	v_lshl_add_u64 v[70:71], v[70:71], 0, v[134:135]
	global_store_dwordx2 v[70:71], v[68:69], off
	v_mul_f32_e32 v68, 0x3d372713, v64
	v_mul_f32_e32 v69, 0x3d372713, v65
	v_mul_f32_e32 v68, v64, v68
	v_mul_f32_e32 v69, v65, v69
	v_fma_f32 v68, v64, v68, v64
	v_fma_f32 v69, v65, v69, v65
	v_mul_f32_e32 v68, 0x3fcc422a, v68
	v_mul_f32_e32 v69, 0x3fcc422a, v69
	v_mul_f32_e32 v68, 0xbfb8aa3b, v68
	v_mul_f32_e32 v69, 0xbfb8aa3b, v69
	v_exp_f32_e32 v68, v68
	v_exp_f32_e32 v69, v69
	s_lshl_b64 s[2:3], s[18:19], 11
	v_add_f32_e32 v68, 1.0, v68
	v_add_f32_e32 v69, 1.0, v69
	v_rcp_f32_e32 v68, v68
	v_rcp_f32_e32 v69, v69
	s_nop 0
	v_pk_mul_f32 v[64:65], v[64:65], v[68:69]
	s_nop 0
	v_cvt_pk_bf16_f32 v64, v64, v65
	v_mul_f32_e32 v65, 0x3d372713, v66
	v_mul_f32_e32 v65, v66, v65
	v_fma_f32 v65, v66, v65, v66
	v_mul_f32_e32 v65, 0x3fcc422a, v65
	v_mul_f32_e32 v65, 0xbfb8aa3b, v65
	v_exp_f32_e32 v65, v65
	s_nop 0
	v_add_f32_e32 v65, 1.0, v65
	v_rcp_f32_e32 v68, v65
	v_mul_f32_e32 v65, 0x3d372713, v67
	v_mul_f32_e32 v65, v67, v65
	v_fma_f32 v65, v67, v65, v67
	v_mul_f32_e32 v65, 0x3fcc422a, v65
	v_mul_f32_e32 v65, 0xbfb8aa3b, v65
	v_exp_f32_e32 v65, v65
	s_nop 0
	v_add_f32_e32 v65, 1.0, v65
	v_rcp_f32_e32 v69, v65
	s_nop 0
	v_pk_mul_f32 v[66:67], v[66:67], v[68:69]
	s_nop 0
	v_cvt_pk_bf16_f32 v65, v66, v67
	v_lshl_add_u64 v[66:67], v[76:77], 0, s[2:3]
	v_lshl_add_u64 v[66:67], v[66:67], 0, s[20:21]
	v_lshl_add_u64 v[66:67], v[66:67], 0, v[134:135]
	global_store_dwordx2 v[66:67], v[64:65], off
; __device__ __forceinline__ unsigned cvt_pk_bf16(float lo, float hi) { f32x2 v = {lo, hi}; bf16x2_t b = __builtin_convertvector(v, bf16x2_t); return __builtin_bit_cast(unsigned, b); }
; __device__ __forceinline__ float gelu_tanh(float y) { const float u = 1.5957691216057308f * (y + 0.044715f * y * y * y); return y * sigmoidf_(u); }
; #define FOR_AI_M _Pragma("unroll") for (int ai = 0; ai < 2; ++ai) _Pragma("unroll") for (int m = 0; m < 4; ++m)
;     __device__ __forceinline__ void operator()(const f32x4 (&acc)[2][2][4][2], const Unit& u, int wr, int wc, int fr, int fq) const {
;         FOR_AI_M {
;             const int chunk = 256 * u.pm + 128 * ai + 64 * wr + 16 * m + fr;
;             if (chunk < NCHUNK) {
; #pragma unroll
;                 for (int bj = 0; bj < 2; ++bj)
; #pragma unroll
;                     for (int n = 0; n < 2; ++n) {
;                         const int tl = 16 * u.pn + 8 * bj + 2 * wc + n; const size_t row = (size_t)chunk * 32 + tl;
;                         const f32x4 v = acc[ai][bj][m][n];
;                         u32x2 w; w.x = cvt_pk_bf16(gelu_tanh(v[0]), gelu_tanh(v[1])); w.y = cvt_pk_bf16(gelu_tanh(v[2]), gelu_tanh(v[3]));
;                         *(u32x2*)(GACT + row * 1024 + 16 * u.mode + 4 * fq) = w;
;                     }
;             }
.LBB0_452:
	s_or_b64 exec, exec, s[16:17]
	v_add_u32_e32 v64, 0x80, v136
	v_cmp_gt_i32_e32 vcc, s22, v64
	s_and_saveexec_b64 s[16:17], vcc
	s_cbranch_execz .LBB0_454
	v_mul_f32_e32 v66, 0x3d372713, v60
	v_mul_f32_e32 v67, 0x3d372713, v61
	v_mul_f32_e32 v66, v60, v66
	v_mul_f32_e32 v67, v61, v67
	v_fma_f32 v66, v60, v66, v60
	v_fma_f32 v67, v61, v67, v61
	v_mul_f32_e32 v66, 0x3fcc422a, v66
	v_mul_f32_e32 v67, 0x3fcc422a, v67
	v_mul_f32_e32 v66, 0xbfb8aa3b, v66
	v_mul_f32_e32 v67, 0xbfb8aa3b, v67
	v_exp_f32_e32 v66, v66
	v_exp_f32_e32 v67, v67
	s_lshl_b32 s2, s97, 4
	v_ashrrev_i32_e32 v65, 31, v64
	v_add_f32_e32 v66, 1.0, v66
	v_add_f32_e32 v67, 1.0, v67
	v_rcp_f32_e32 v66, v66
	v_rcp_f32_e32 v67, v67
	s_or_b32 s18, s2, s95
	v_lshlrev_b64 v[64:65], 16, v[64:65]
	s_ashr_i32 s19, s18, 31
	v_pk_mul_f32 v[60:61], v[60:61], v[66:67]
	s_lshl_b64 s[2:3], s[18:19], 11
	v_cvt_pk_bf16_f32 v66, v60, v61
	v_mul_f32_e32 v60, 0x3d372713, v62
	v_mul_f32_e32 v61, 0x3d372713, v63
	v_mul_f32_e32 v60, v62, v60
	v_mul_f32_e32 v61, v63, v61
	v_fma_f32 v60, v62, v60, v62
	v_fma_f32 v61, v63, v61, v63
	v_mul_f32_e32 v60, 0x3fcc422a, v60
	v_mul_f32_e32 v61, 0x3fcc422a, v61
	v_mul_f32_e32 v60, 0xbfb8aa3b, v60
	v_mul_f32_e32 v61, 0xbfb8aa3b, v61
	v_exp_f32_e32 v60, v60
	v_exp_f32_e32 v61, v61
	s_or_b32 s24, s18, 1
	s_ashr_i32 s25, s24, 31
	v_add_f32_e32 v60, 1.0, v60
	v_add_f32_e32 v61, 1.0, v61
	v_rcp_f32_e32 v60, v60
	v_rcp_f32_e32 v61, v61
	s_nop 0
	v_pk_mul_f32 v[60:61], v[62:63], v[60:61]
	s_nop 0
	v_cvt_pk_bf16_f32 v67, v60, v61
	v_lshl_add_u64 v[60:61], s[6:7], 0, v[64:65]
	v_lshl_add_u64 v[62:63], v[60:61], 0, s[2:3]
	s_lshl_b32 s2, s1, 4
	s_ashr_i32 s3, s2, 31
	s_lshl_b64 s[20:21], s[2:3], 1
	v_lshl_add_u64 v[62:63], v[62:63], 0, s[20:21]
	v_lshl_add_u64 v[62:63], v[62:63], 0, v[134:135]
	global_store_dwordx2 v[62:63], v[66:67], off
	v_mul_f32_e32 v62, 0x3d372713, v56
	v_mul_f32_e32 v63, 0x3d372713, v57
	v_mul_f32_e32 v62, v56, v62
	v_mul_f32_e32 v63, v57, v63
	v_fma_f32 v62, v56, v62, v56
	v_fma_f32 v63, v57, v63, v57
	v_mul_f32_e32 v62, 0x3fcc422a, v62
	v_mul_f32_e32 v63, 0x3fcc422a, v63
	v_mul_f32_e32 v62, 0xbfb8aa3b, v62
	v_mul_f32_e32 v63, 0xbfb8aa3b, v63
	v_exp_f32_e32 v62, v62
	v_exp_f32_e32 v63, v63
	s_lshl_b64 s[2:3], s[24:25], 11
	s_or_b32 s24, s18, 8
	v_add_f32_e32 v62, 1.0, v62
	v_add_f32_e32 v63, 1.0, v63
	v_rcp_f32_e32 v62, v62
	v_rcp_f32_e32 v63, v63
	s_ashr_i32 s25, s24, 31
	s_or_b32 s18, s18, 9
	s_ashr_i32 s19, s18, 31
	v_pk_mul_f32 v[56:57], v[56:57], v[62:63]
	s_nop 0
	v_cvt_pk_bf16_f32 v56, v56, v57
	v_mul_f32_e32 v57, 0x3d372713, v58
	v_mul_f32_e32 v57, v58, v57
	v_fma_f32 v57, v58, v57, v58
	v_mul_f32_e32 v57, 0x3fcc422a, v57
	v_mul_f32_e32 v57, 0xbfb8aa3b, v57
	v_exp_f32_e32 v57, v57
	s_nop 0
	v_add_f32_e32 v57, 1.0, v57
	v_rcp_f32_e32 v62, v57
	v_mul_f32_e32 v57, 0x3d372713, v59
	v_mul_f32_e32 v57, v59, v57
	v_fma_f32 v57, v59, v57, v59
	v_mul_f32_e32 v57, 0x3fcc422a, v57
	v_mul_f32_e32 v57, 0xbfb8aa3b, v57
	v_exp_f32_e32 v57, v57
	s_nop 0
	v_add_f32_e32 v57, 1.0, v57
	v_rcp_f32_e32 v63, v57
	s_nop 0
	v_pk_mul_f32 v[58:59], v[58:59], v[62:63]
	s_nop 0
	v_cvt_pk_bf16_f32 v57, v58, v59
	v_lshl_add_u64 v[58:59], v[60:61], 0, s[2:3]
	v_lshl_add_u64 v[58:59], v[58:59], 0, s[20:21]
	v_lshl_add_u64 v[58:59], v[58:59], 0, v[134:135]
	global_store_dwordx2 v[58:59], v[56:57], off
	v_mul_f32_e32 v56, 0x3d372713, v52
	v_mul_f32_e32 v57, 0x3d372713, v53
	v_mul_f32_e32 v56, v52, v56
	v_mul_f32_e32 v57, v53, v57
	v_fma_f32 v56, v52, v56, v52
	v_fma_f32 v57, v53, v57, v53
	v_mul_f32_e32 v56, 0x3fcc422a, v56
	v_mul_f32_e32 v57, 0x3fcc422a, v57
	v_mul_f32_e32 v56, 0xbfb8aa3b, v56
	v_mul_f32_e32 v57, 0xbfb8aa3b, v57
	v_exp_f32_e32 v56, v56
	v_exp_f32_e32 v57, v57
	s_lshl_b64 s[2:3], s[24:25], 11
	v_add_f32_e32 v56, 1.0, v56
	v_add_f32_e32 v57, 1.0, v57
	v_rcp_f32_e32 v56, v56
	v_rcp_f32_e32 v57, v57
	s_nop 0
	v_pk_mul_f32 v[52:53], v[52:53], v[56:57]
	s_nop 0
	v_cvt_pk_bf16_f32 v52, v52, v53
	v_mul_f32_e32 v53, 0x3d372713, v54
	v_mul_f32_e32 v53, v54, v53
	v_fma_f32 v53, v54, v53, v54
	v_mul_f32_e32 v53, 0x3fcc422a, v53
	v_mul_f32_e32 v53, 0xbfb8aa3b, v53
	v_exp_f32_e32 v53, v53
	s_nop 0
	v_add_f32_e32 v53, 1.0, v53
	v_rcp_f32_e32 v56, v53
	v_mul_f32_e32 v53, 0x3d372713, v55
	v_mul_f32_e32 v53, v55, v53
	v_fma_f32 v53, v55, v53, v55
	v_mul_f32_e32 v53, 0x3fcc422a, v53
	v_mul_f32_e32 v53, 0xbfb8aa3b, v53
	v_exp_f32_e32 v53, v53
	s_nop 0
	v_add_f32_e32 v53, 1.0, v53
	v_rcp_f32_e32 v57, v53
	s_nop 0
	v_pk_mul_f32 v[54:55], v[54:55], v[56:57]
	s_nop 0
	v_cvt_pk_bf16_f32 v53, v54, v55
	v_lshl_add_u64 v[54:55], v[60:61], 0, s[2:3]
	v_lshl_add_u64 v[54:55], v[54:55], 0, s[20:21]
	v_lshl_add_u64 v[54:55], v[54:55], 0, v[134:135]
	global_store_dwordx2 v[54:55], v[52:53], off
	v_mul_f32_e32 v52, 0x3d372713, v48
	v_mul_f32_e32 v53, 0x3d372713, v49
	v_mul_f32_e32 v52, v48, v52
	v_mul_f32_e32 v53, v49, v53
	v_fma_f32 v52, v48, v52, v48
	v_fma_f32 v53, v49, v53, v49
	v_mul_f32_e32 v52, 0x3fcc422a, v52
	v_mul_f32_e32 v53, 0x3fcc422a, v53
	v_mul_f32_e32 v52, 0xbfb8aa3b, v52
	v_mul_f32_e32 v53, 0xbfb8aa3b, v53
	v_exp_f32_e32 v52, v52
	v_exp_f32_e32 v53, v53
	s_lshl_b64 s[2:3], s[18:19], 11
	v_add_f32_e32 v52, 1.0, v52
	v_add_f32_e32 v53, 1.0, v53
	v_rcp_f32_e32 v52, v52
	v_rcp_f32_e32 v53, v53
	s_nop 0
	v_pk_mul_f32 v[48:49], v[48:49], v[52:53]
	s_nop 0
	v_cvt_pk_bf16_f32 v48, v48, v49
	v_mul_f32_e32 v49, 0x3d372713, v50
	v_mul_f32_e32 v49, v50, v49
	v_fma_f32 v49, v50, v49, v50
	v_mul_f32_e32 v49, 0x3fcc422a, v49
	v_mul_f32_e32 v49, 0xbfb8aa3b, v49
	v_exp_f32_e32 v49, v49
	s_nop 0
	v_add_f32_e32 v49, 1.0, v49
	v_rcp_f32_e32 v52, v49
	v_mul_f32_e32 v49, 0x3d372713, v51
	v_mul_f32_e32 v49, v51, v49
	v_fma_f32 v49, v51, v49, v51
	v_mul_f32_e32 v49, 0x3fcc422a, v49
	v_mul_f32_e32 v49, 0xbfb8aa3b, v49
	v_exp_f32_e32 v49, v49
	s_nop 0
	v_add_f32_e32 v49, 1.0, v49
	v_rcp_f32_e32 v53, v49
	s_nop 0
	v_pk_mul_f32 v[50:51], v[50:51], v[52:53]
	s_nop 0
	v_cvt_pk_bf16_f32 v49, v50, v51
	v_lshl_add_u64 v[50:51], v[60:61], 0, s[2:3]
	v_lshl_add_u64 v[50:51], v[50:51], 0, s[20:21]
	v_lshl_add_u64 v[50:51], v[50:51], 0, v[134:135]
	global_store_dwordx2 v[50:51], v[48:49], off
; __device__ __forceinline__ unsigned cvt_pk_bf16(float lo, float hi) { f32x2 v = {lo, hi}; bf16x2_t b = __builtin_convertvector(v, bf16x2_t); return __builtin_bit_cast(unsigned, b); }
; __device__ __forceinline__ float gelu_tanh(float y) { const float u = 1.5957691216057308f * (y + 0.044715f * y * y * y); return y * sigmoidf_(u); }
; #define FOR_AI_M _Pragma("unroll") for (int ai = 0; ai < 2; ++ai) _Pragma("unroll") for (int m = 0; m < 4; ++m)
;     __device__ __forceinline__ void operator()(const f32x4 (&acc)[2][2][4][2], const Unit& u, int wr, int wc, int fr, int fq) const {
;         FOR_AI_M {
;             const int chunk = 256 * u.pm + 128 * ai + 64 * wr + 16 * m + fr;
;             if (chunk < NCHUNK) {
; #pragma unroll
;                 for (int bj = 0; bj < 2; ++bj)
; #pragma unroll
;                     for (int n = 0; n < 2; ++n) {
;                         const int tl = 16 * u.pn + 8 * bj + 2 * wc + n; const size_t row = (size_t)chunk * 32 + tl;
;                         const f32x4 v = acc[ai][bj][m][n];
;                         u32x2 w; w.x = cvt_pk_bf16(gelu_tanh(v[0]), gelu_tanh(v[1])); w.y = cvt_pk_bf16(gelu_tanh(v[2]), gelu_tanh(v[3]));
;                         *(u32x2*)(GACT + row * 1024 + 16 * u.mode + 4 * fq) = w;
;                     }
;             }
.LBB0_454:
	s_or_b64 exec, exec, s[16:17]
	v_add_u32_e32 v48, 0x90, v136
	v_cmp_gt_i32_e32 vcc, s22, v48
	s_and_saveexec_b64 s[16:17], vcc
	s_cbranch_execz .LBB0_456
	v_mul_f32_e32 v50, 0x3d372713, v44
	v_mul_f32_e32 v51, 0x3d372713, v45
	v_mul_f32_e32 v50, v44, v50
	v_mul_f32_e32 v51, v45, v51
	v_fma_f32 v50, v44, v50, v44
	v_fma_f32 v51, v45, v51, v45
	v_mul_f32_e32 v50, 0x3fcc422a, v50
	v_mul_f32_e32 v51, 0x3fcc422a, v51
	v_mul_f32_e32 v50, 0xbfb8aa3b, v50
	v_mul_f32_e32 v51, 0xbfb8aa3b, v51
	v_exp_f32_e32 v50, v50
	v_exp_f32_e32 v51, v51
	s_lshl_b32 s2, s97, 4
	v_ashrrev_i32_e32 v49, 31, v48
	v_add_f32_e32 v50, 1.0, v50
	v_add_f32_e32 v51, 1.0, v51
	v_rcp_f32_e32 v50, v50
	v_rcp_f32_e32 v51, v51
	s_or_b32 s18, s2, s95
	v_lshlrev_b64 v[48:49], 16, v[48:49]
	s_ashr_i32 s19, s18, 31
	v_pk_mul_f32 v[44:45], v[44:45], v[50:51]
	s_lshl_b64 s[2:3], s[18:19], 11
	v_cvt_pk_bf16_f32 v50, v44, v45
	v_mul_f32_e32 v44, 0x3d372713, v46
	v_mul_f32_e32 v45, 0x3d372713, v47
	v_mul_f32_e32 v44, v46, v44
	v_mul_f32_e32 v45, v47, v45
	v_fma_f32 v44, v46, v44, v46
	v_fma_f32 v45, v47, v45, v47
	v_mul_f32_e32 v44, 0x3fcc422a, v44
	v_mul_f32_e32 v45, 0x3fcc422a, v45
	v_mul_f32_e32 v44, 0xbfb8aa3b, v44
	v_mul_f32_e32 v45, 0xbfb8aa3b, v45
	v_exp_f32_e32 v44, v44
	v_exp_f32_e32 v45, v45
	s_or_b32 s24, s18, 1
	s_ashr_i32 s25, s24, 31
	v_add_f32_e32 v44, 1.0, v44
	v_add_f32_e32 v45, 1.0, v45
	v_rcp_f32_e32 v44, v44
	v_rcp_f32_e32 v45, v45
	s_nop 0
	v_pk_mul_f32 v[44:45], v[46:47], v[44:45]
	s_nop 0
	v_cvt_pk_bf16_f32 v51, v44, v45
	v_lshl_add_u64 v[44:45], s[6:7], 0, v[48:49]
	v_lshl_add_u64 v[46:47], v[44:45], 0, s[2:3]
	s_lshl_b32 s2, s1, 4
	s_ashr_i32 s3, s2, 31
	s_lshl_b64 s[20:21], s[2:3], 1
	v_lshl_add_u64 v[46:47], v[46:47], 0, s[20:21]
	v_lshl_add_u64 v[46:47], v[46:47], 0, v[134:135]
	global_store_dwordx2 v[46:47], v[50:51], off
	v_mul_f32_e32 v46, 0x3d372713, v40
	v_mul_f32_e32 v47, 0x3d372713, v41
	v_mul_f32_e32 v46, v40, v46
	v_mul_f32_e32 v47, v41, v47
	v_fma_f32 v46, v40, v46, v40
	v_fma_f32 v47, v41, v47, v41
	v_mul_f32_e32 v46, 0x3fcc422a, v46
	v_mul_f32_e32 v47, 0x3fcc422a, v47
	v_mul_f32_e32 v46, 0xbfb8aa3b, v46
	v_mul_f32_e32 v47, 0xbfb8aa3b, v47
	v_exp_f32_e32 v46, v46
	v_exp_f32_e32 v47, v47
	s_lshl_b64 s[2:3], s[24:25], 11
	s_or_b32 s24, s18, 8
	v_add_f32_e32 v46, 1.0, v46
	v_add_f32_e32 v47, 1.0, v47
	v_rcp_f32_e32 v46, v46
	v_rcp_f32_e32 v47, v47
	s_ashr_i32 s25, s24, 31
	s_or_b32 s18, s18, 9
	s_ashr_i32 s19, s18, 31
	v_pk_mul_f32 v[40:41], v[40:41], v[46:47]
	s_nop 0
	v_cvt_pk_bf16_f32 v40, v40, v41
	v_mul_f32_e32 v41, 0x3d372713, v42
	v_mul_f32_e32 v41, v42, v41
	v_fma_f32 v41, v42, v41, v42
	v_mul_f32_e32 v41, 0x3fcc422a, v41
	v_mul_f32_e32 v41, 0xbfb8aa3b, v41
	v_exp_f32_e32 v41, v41
	s_nop 0
	v_add_f32_e32 v41, 1.0, v41
	v_rcp_f32_e32 v46, v41
	v_mul_f32_e32 v41, 0x3d372713, v43
	v_mul_f32_e32 v41, v43, v41
	v_fma_f32 v41, v43, v41, v43
	v_mul_f32_e32 v41, 0x3fcc422a, v41
	v_mul_f32_e32 v41, 0xbfb8aa3b, v41
	v_exp_f32_e32 v41, v41
	s_nop 0
	v_add_f32_e32 v41, 1.0, v41
	v_rcp_f32_e32 v47, v41
	s_nop 0
	v_pk_mul_f32 v[42:43], v[42:43], v[46:47]
	s_nop 0
	v_cvt_pk_bf16_f32 v41, v42, v43
	v_lshl_add_u64 v[42:43], v[44:45], 0, s[2:3]
	v_lshl_add_u64 v[42:43], v[42:43], 0, s[20:21]
	v_lshl_add_u64 v[42:43], v[42:43], 0, v[134:135]
	global_store_dwordx2 v[42:43], v[40:41], off
	v_mul_f32_e32 v40, 0x3d372713, v36
	v_mul_f32_e32 v41, 0x3d372713, v37
	v_mul_f32_e32 v40, v36, v40
	v_mul_f32_e32 v41, v37, v41
	v_fma_f32 v40, v36, v40, v36
	v_fma_f32 v41, v37, v41, v37
	v_mul_f32_e32 v40, 0x3fcc422a, v40
	v_mul_f32_e32 v41, 0x3fcc422a, v41
	v_mul_f32_e32 v40, 0xbfb8aa3b, v40
	v_mul_f32_e32 v41, 0xbfb8aa3b, v41
	v_exp_f32_e32 v40, v40
	v_exp_f32_e32 v41, v41
	s_lshl_b64 s[2:3], s[24:25], 11
	v_add_f32_e32 v40, 1.0, v40
	v_add_f32_e32 v41, 1.0, v41
	v_rcp_f32_e32 v40, v40
	v_rcp_f32_e32 v41, v41
	s_nop 0
	v_pk_mul_f32 v[36:37], v[36:37], v[40:41]
	s_nop 0
	v_cvt_pk_bf16_f32 v36, v36, v37
	v_mul_f32_e32 v37, 0x3d372713, v38
	v_mul_f32_e32 v37, v38, v37
	v_fma_f32 v37, v38, v37, v38
	v_mul_f32_e32 v37, 0x3fcc422a, v37
	v_mul_f32_e32 v37, 0xbfb8aa3b, v37
	v_exp_f32_e32 v37, v37
	s_nop 0
	v_add_f32_e32 v37, 1.0, v37
	v_rcp_f32_e32 v40, v37
	v_mul_f32_e32 v37, 0x3d372713, v39
	v_mul_f32_e32 v37, v39, v37
	v_fma_f32 v37, v39, v37, v39
	v_mul_f32_e32 v37, 0x3fcc422a, v37
	v_mul_f32_e32 v37, 0xbfb8aa3b, v37
	v_exp_f32_e32 v37, v37
	s_nop 0
	v_add_f32_e32 v37, 1.0, v37
	v_rcp_f32_e32 v41, v37
	s_nop 0
	v_pk_mul_f32 v[38:39], v[38:39], v[40:41]
	s_nop 0
	v_cvt_pk_bf16_f32 v37, v38, v39
	v_lshl_add_u64 v[38:39], v[44:45], 0, s[2:3]
	v_lshl_add_u64 v[38:39], v[38:39], 0, s[20:21]
	v_lshl_add_u64 v[38:39], v[38:39], 0, v[134:135]
	global_store_dwordx2 v[38:39], v[36:37], off
	v_mul_f32_e32 v36, 0x3d372713, v32
	v_mul_f32_e32 v37, 0x3d372713, v33
	v_mul_f32_e32 v36, v32, v36
	v_mul_f32_e32 v37, v33, v37
	v_fma_f32 v36, v32, v36, v32
	v_fma_f32 v37, v33, v37, v33
	v_mul_f32_e32 v36, 0x3fcc422a, v36
	v_mul_f32_e32 v37, 0x3fcc422a, v37
	v_mul_f32_e32 v36, 0xbfb8aa3b, v36
	v_mul_f32_e32 v37, 0xbfb8aa3b, v37
	v_exp_f32_e32 v36, v36
	v_exp_f32_e32 v37, v37
	s_lshl_b64 s[2:3], s[18:19], 11
	v_add_f32_e32 v36, 1.0, v36
	v_add_f32_e32 v37, 1.0, v37
	v_rcp_f32_e32 v36, v36
	v_rcp_f32_e32 v37, v37
	s_nop 0
	v_pk_mul_f32 v[32:33], v[32:33], v[36:37]
	s_nop 0
	v_cvt_pk_bf16_f32 v32, v32, v33
	v_mul_f32_e32 v33, 0x3d372713, v34
	v_mul_f32_e32 v33, v34, v33
	v_fma_f32 v33, v34, v33, v34
	v_mul_f32_e32 v33, 0x3fcc422a, v33
	v_mul_f32_e32 v33, 0xbfb8aa3b, v33
	v_exp_f32_e32 v33, v33
	s_nop 0
	v_add_f32_e32 v33, 1.0, v33
	v_rcp_f32_e32 v36, v33
	v_mul_f32_e32 v33, 0x3d372713, v35
	v_mul_f32_e32 v33, v35, v33
	v_fma_f32 v33, v35, v33, v35
	v_mul_f32_e32 v33, 0x3fcc422a, v33
	v_mul_f32_e32 v33, 0xbfb8aa3b, v33
	v_exp_f32_e32 v33, v33
	s_nop 0
	v_add_f32_e32 v33, 1.0, v33
	v_rcp_f32_e32 v37, v33
	s_nop 0
	v_pk_mul_f32 v[34:35], v[34:35], v[36:37]
	s_nop 0
	v_cvt_pk_bf16_f32 v33, v34, v35
	v_lshl_add_u64 v[34:35], v[44:45], 0, s[2:3]
	v_lshl_add_u64 v[34:35], v[34:35], 0, s[20:21]
	v_lshl_add_u64 v[34:35], v[34:35], 0, v[134:135]
	global_store_dwordx2 v[34:35], v[32:33], off
; __device__ __forceinline__ unsigned cvt_pk_bf16(float lo, float hi) { f32x2 v = {lo, hi}; bf16x2_t b = __builtin_convertvector(v, bf16x2_t); return __builtin_bit_cast(unsigned, b); }
; __device__ __forceinline__ float gelu_tanh(float y) { const float u = 1.5957691216057308f * (y + 0.044715f * y * y * y); return y * sigmoidf_(u); }
; #define FOR_AI_M _Pragma("unroll") for (int ai = 0; ai < 2; ++ai) _Pragma("unroll") for (int m = 0; m < 4; ++m)
;     __device__ __forceinline__ void operator()(const f32x4 (&acc)[2][2][4][2], const Unit& u, int wr, int wc, int fr, int fq) const {
;         FOR_AI_M {
;             const int chunk = 256 * u.pm + 128 * ai + 64 * wr + 16 * m + fr;
;             if (chunk < NCHUNK) {
; #pragma unroll
;                 for (int bj = 0; bj < 2; ++bj)
; #pragma unroll
;                     for (int n = 0; n < 2; ++n) {
;                         const int tl = 16 * u.pn + 8 * bj + 2 * wc + n; const size_t row = (size_t)chunk * 32 + tl;
;                         const f32x4 v = acc[ai][bj][m][n];
;                         u32x2 w; w.x = cvt_pk_bf16(gelu_tanh(v[0]), gelu_tanh(v[1])); w.y = cvt_pk_bf16(gelu_tanh(v[2]), gelu_tanh(v[3]));
;                         *(u32x2*)(GACT + row * 1024 + 16 * u.mode + 4 * fq) = w;
;                     }
;             }
.LBB0_456:
	s_or_b64 exec, exec, s[16:17]
	v_add_u32_e32 v32, 0xa0, v136
	v_cmp_gt_i32_e32 vcc, s22, v32
	s_and_saveexec_b64 s[16:17], vcc
	s_cbranch_execz .LBB0_458
	v_mul_f32_e32 v34, 0x3d372713, v28
	v_mul_f32_e32 v35, 0x3d372713, v29
	v_mul_f32_e32 v34, v28, v34
	v_mul_f32_e32 v35, v29, v35
	v_fma_f32 v34, v28, v34, v28
	v_fma_f32 v35, v29, v35, v29
	v_mul_f32_e32 v34, 0x3fcc422a, v34
	v_mul_f32_e32 v35, 0x3fcc422a, v35
	v_mul_f32_e32 v34, 0xbfb8aa3b, v34
	v_mul_f32_e32 v35, 0xbfb8aa3b, v35
	v_exp_f32_e32 v34, v34
	v_exp_f32_e32 v35, v35
	s_lshl_b32 s2, s97, 4
	v_ashrrev_i32_e32 v33, 31, v32
	v_add_f32_e32 v34, 1.0, v34
	v_add_f32_e32 v35, 1.0, v35
	v_rcp_f32_e32 v34, v34
	v_rcp_f32_e32 v35, v35
	s_or_b32 s18, s2, s95
	v_lshlrev_b64 v[32:33], 16, v[32:33]
	s_ashr_i32 s19, s18, 31
	v_pk_mul_f32 v[28:29], v[28:29], v[34:35]
	s_lshl_b64 s[2:3], s[18:19], 11
	v_cvt_pk_bf16_f32 v34, v28, v29
	v_mul_f32_e32 v28, 0x3d372713, v30
	v_mul_f32_e32 v29, 0x3d372713, v31
	v_mul_f32_e32 v28, v30, v28
	v_mul_f32_e32 v29, v31, v29
	v_fma_f32 v28, v30, v28, v30
	v_fma_f32 v29, v31, v29, v31
	v_mul_f32_e32 v28, 0x3fcc422a, v28
	v_mul_f32_e32 v29, 0x3fcc422a, v29
	v_mul_f32_e32 v28, 0xbfb8aa3b, v28
	v_mul_f32_e32 v29, 0xbfb8aa3b, v29
	v_exp_f32_e32 v28, v28
	v_exp_f32_e32 v29, v29
	s_or_b32 s24, s18, 1
	s_ashr_i32 s25, s24, 31
	v_add_f32_e32 v28, 1.0, v28
	v_add_f32_e32 v29, 1.0, v29
	v_rcp_f32_e32 v28, v28
	v_rcp_f32_e32 v29, v29
	s_nop 0
	v_pk_mul_f32 v[28:29], v[30:31], v[28:29]
	s_nop 0
	v_cvt_pk_bf16_f32 v35, v28, v29
	v_lshl_add_u64 v[28:29], s[6:7], 0, v[32:33]
	v_lshl_add_u64 v[30:31], v[28:29], 0, s[2:3]
	s_lshl_b32 s2, s1, 4
	s_ashr_i32 s3, s2, 31
	s_lshl_b64 s[20:21], s[2:3], 1
	v_lshl_add_u64 v[30:31], v[30:31], 0, s[20:21]
	v_lshl_add_u64 v[30:31], v[30:31], 0, v[134:135]
	global_store_dwordx2 v[30:31], v[34:35], off
	v_mul_f32_e32 v30, 0x3d372713, v24
	v_mul_f32_e32 v31, 0x3d372713, v25
	v_mul_f32_e32 v30, v24, v30
	v_mul_f32_e32 v31, v25, v31
	v_fma_f32 v30, v24, v30, v24
	v_fma_f32 v31, v25, v31, v25
	v_mul_f32_e32 v30, 0x3fcc422a, v30
	v_mul_f32_e32 v31, 0x3fcc422a, v31
	v_mul_f32_e32 v30, 0xbfb8aa3b, v30
	v_mul_f32_e32 v31, 0xbfb8aa3b, v31
	v_exp_f32_e32 v30, v30
	v_exp_f32_e32 v31, v31
	s_lshl_b64 s[2:3], s[24:25], 11
	s_or_b32 s24, s18, 8
	v_add_f32_e32 v30, 1.0, v30
	v_add_f32_e32 v31, 1.0, v31
	v_rcp_f32_e32 v30, v30
	v_rcp_f32_e32 v31, v31
	s_ashr_i32 s25, s24, 31
	s_or_b32 s18, s18, 9
	s_ashr_i32 s19, s18, 31
	v_pk_mul_f32 v[24:25], v[24:25], v[30:31]
	s_nop 0
	v_cvt_pk_bf16_f32 v24, v24, v25
	v_mul_f32_e32 v25, 0x3d372713, v26
	v_mul_f32_e32 v25, v26, v25
	v_fma_f32 v25, v26, v25, v26
	v_mul_f32_e32 v25, 0x3fcc422a, v25
	v_mul_f32_e32 v25, 0xbfb8aa3b, v25
	v_exp_f32_e32 v25, v25
	s_nop 0
	v_add_f32_e32 v25, 1.0, v25
	v_rcp_f32_e32 v30, v25
	v_mul_f32_e32 v25, 0x3d372713, v27
	v_mul_f32_e32 v25, v27, v25
	v_fma_f32 v25, v27, v25, v27
	v_mul_f32_e32 v25, 0x3fcc422a, v25
	v_mul_f32_e32 v25, 0xbfb8aa3b, v25
	v_exp_f32_e32 v25, v25
	s_nop 0
	v_add_f32_e32 v25, 1.0, v25
	v_rcp_f32_e32 v31, v25
	s_nop 0
	v_pk_mul_f32 v[26:27], v[26:27], v[30:31]
	s_nop 0
	v_cvt_pk_bf16_f32 v25, v26, v27
	v_lshl_add_u64 v[26:27], v[28:29], 0, s[2:3]
	v_lshl_add_u64 v[26:27], v[26:27], 0, s[20:21]
	v_lshl_add_u64 v[26:27], v[26:27], 0, v[134:135]
	global_store_dwordx2 v[26:27], v[24:25], off
	v_mul_f32_e32 v24, 0x3d372713, v20
	v_mul_f32_e32 v25, 0x3d372713, v21
	v_mul_f32_e32 v24, v20, v24
	v_mul_f32_e32 v25, v21, v25
	v_fma_f32 v24, v20, v24, v20
	v_fma_f32 v25, v21, v25, v21
	v_mul_f32_e32 v24, 0x3fcc422a, v24
	v_mul_f32_e32 v25, 0x3fcc422a, v25
	v_mul_f32_e32 v24, 0xbfb8aa3b, v24
	v_mul_f32_e32 v25, 0xbfb8aa3b, v25
	v_exp_f32_e32 v24, v24
	v_exp_f32_e32 v25, v25
	s_lshl_b64 s[2:3], s[24:25], 11
	v_add_f32_e32 v24, 1.0, v24
	v_add_f32_e32 v25, 1.0, v25
	v_rcp_f32_e32 v24, v24
	v_rcp_f32_e32 v25, v25
	s_nop 0
	v_pk_mul_f32 v[20:21], v[20:21], v[24:25]
	s_nop 0
	v_cvt_pk_bf16_f32 v20, v20, v21
	v_mul_f32_e32 v21, 0x3d372713, v22
	v_mul_f32_e32 v21, v22, v21
	v_fma_f32 v21, v22, v21, v22
	v_mul_f32_e32 v21, 0x3fcc422a, v21
	v_mul_f32_e32 v21, 0xbfb8aa3b, v21
	v_exp_f32_e32 v21, v21
	s_nop 0
	v_add_f32_e32 v21, 1.0, v21
	v_rcp_f32_e32 v24, v21
	v_mul_f32_e32 v21, 0x3d372713, v23
	v_mul_f32_e32 v21, v23, v21
	v_fma_f32 v21, v23, v21, v23
	v_mul_f32_e32 v21, 0x3fcc422a, v21
	v_mul_f32_e32 v21, 0xbfb8aa3b, v21
	v_exp_f32_e32 v21, v21
	s_nop 0
	v_add_f32_e32 v21, 1.0, v21
	v_rcp_f32_e32 v25, v21
	s_nop 0
	v_pk_mul_f32 v[22:23], v[22:23], v[24:25]
	s_nop 0
	v_cvt_pk_bf16_f32 v21, v22, v23
	v_lshl_add_u64 v[22:23], v[28:29], 0, s[2:3]
	v_lshl_add_u64 v[22:23], v[22:23], 0, s[20:21]
	v_lshl_add_u64 v[22:23], v[22:23], 0, v[134:135]
	global_store_dwordx2 v[22:23], v[20:21], off
	v_mul_f32_e32 v20, 0x3d372713, v16
	v_mul_f32_e32 v21, 0x3d372713, v17
	v_mul_f32_e32 v20, v16, v20
	v_mul_f32_e32 v21, v17, v21
	v_fma_f32 v20, v16, v20, v16
	v_fma_f32 v21, v17, v21, v17
	v_mul_f32_e32 v20, 0x3fcc422a, v20
	v_mul_f32_e32 v21, 0x3fcc422a, v21
	v_mul_f32_e32 v20, 0xbfb8aa3b, v20
	v_mul_f32_e32 v21, 0xbfb8aa3b, v21
	v_exp_f32_e32 v20, v20
	v_exp_f32_e32 v21, v21
	s_lshl_b64 s[2:3], s[18:19], 11
	v_add_f32_e32 v20, 1.0, v20
	v_add_f32_e32 v21, 1.0, v21
	v_rcp_f32_e32 v20, v20
	v_rcp_f32_e32 v21, v21
	s_nop 0
	v_pk_mul_f32 v[16:17], v[16:17], v[20:21]
	s_nop 0
	v_cvt_pk_bf16_f32 v16, v16, v17
	v_mul_f32_e32 v17, 0x3d372713, v18
	v_mul_f32_e32 v17, v18, v17
	v_fma_f32 v17, v18, v17, v18
	v_mul_f32_e32 v17, 0x3fcc422a, v17
	v_mul_f32_e32 v17, 0xbfb8aa3b, v17
	v_exp_f32_e32 v17, v17
	s_nop 0
	v_add_f32_e32 v17, 1.0, v17
	v_rcp_f32_e32 v20, v17
	v_mul_f32_e32 v17, 0x3d372713, v19
	v_mul_f32_e32 v17, v19, v17
	v_fma_f32 v17, v19, v17, v19
	v_mul_f32_e32 v17, 0x3fcc422a, v17
	v_mul_f32_e32 v17, 0xbfb8aa3b, v17
	v_exp_f32_e32 v17, v17
	s_nop 0
	v_add_f32_e32 v17, 1.0, v17
	v_rcp_f32_e32 v21, v17
	s_nop 0
	v_pk_mul_f32 v[18:19], v[18:19], v[20:21]
	s_nop 0
	v_cvt_pk_bf16_f32 v17, v18, v19
	v_lshl_add_u64 v[18:19], v[28:29], 0, s[2:3]
	v_lshl_add_u64 v[18:19], v[18:19], 0, s[20:21]
	v_lshl_add_u64 v[18:19], v[18:19], 0, v[134:135]
	global_store_dwordx2 v[18:19], v[16:17], off
; __device__ __forceinline__ unsigned cvt_pk_bf16(float lo, float hi) { f32x2 v = {lo, hi}; bf16x2_t b = __builtin_convertvector(v, bf16x2_t); return __builtin_bit_cast(unsigned, b); }
; __device__ __forceinline__ float gelu_tanh(float y) { const float u = 1.5957691216057308f * (y + 0.044715f * y * y * y); return y * sigmoidf_(u); }
; #define FOR_AI_M _Pragma("unroll") for (int ai = 0; ai < 2; ++ai) _Pragma("unroll") for (int m = 0; m < 4; ++m)
;     __device__ __forceinline__ void operator()(const f32x4 (&acc)[2][2][4][2], const Unit& u, int wr, int wc, int fr, int fq) const {
;         FOR_AI_M {
;             const int chunk = 256 * u.pm + 128 * ai + 64 * wr + 16 * m + fr;
;             if (chunk < NCHUNK) {
; #pragma unroll
;                 for (int bj = 0; bj < 2; ++bj)
; #pragma unroll
;                     for (int n = 0; n < 2; ++n) {
;                         const int tl = 16 * u.pn + 8 * bj + 2 * wc + n; const size_t row = (size_t)chunk * 32 + tl;
;                         const f32x4 v = acc[ai][bj][m][n];
;                         u32x2 w; w.x = cvt_pk_bf16(gelu_tanh(v[0]), gelu_tanh(v[1])); w.y = cvt_pk_bf16(gelu_tanh(v[2]), gelu_tanh(v[3]));
;                         *(u32x2*)(GACT + row * 1024 + 16 * u.mode + 4 * fq) = w;
;                     }
;             }
.LBB0_458:
	s_or_b64 exec, exec, s[16:17]
	v_add_u32_e32 v16, 0xb0, v136
	v_cmp_gt_i32_e32 vcc, s22, v16
	s_and_saveexec_b64 s[16:17], vcc
	s_cbranch_execz .LBB0_460
	v_mul_f32_e32 v18, 0x3d372713, v12
	v_mul_f32_e32 v19, 0x3d372713, v13
	v_mul_f32_e32 v18, v12, v18
	v_mul_f32_e32 v19, v13, v19
	v_fma_f32 v18, v12, v18, v12
	v_fma_f32 v19, v13, v19, v13
	v_mul_f32_e32 v18, 0x3fcc422a, v18
	v_mul_f32_e32 v19, 0x3fcc422a, v19
	v_mul_f32_e32 v18, 0xbfb8aa3b, v18
	v_mul_f32_e32 v19, 0xbfb8aa3b, v19
	v_exp_f32_e32 v18, v18
	v_exp_f32_e32 v19, v19
	s_lshl_b32 s2, s97, 4
	v_ashrrev_i32_e32 v17, 31, v16
	v_add_f32_e32 v18, 1.0, v18
	v_add_f32_e32 v19, 1.0, v19
	v_rcp_f32_e32 v18, v18
	v_rcp_f32_e32 v19, v19
	s_or_b32 s18, s2, s95
	v_lshlrev_b64 v[16:17], 16, v[16:17]
	s_ashr_i32 s19, s18, 31
	v_pk_mul_f32 v[12:13], v[12:13], v[18:19]
	s_lshl_b64 s[2:3], s[18:19], 11
	v_cvt_pk_bf16_f32 v18, v12, v13
	v_mul_f32_e32 v12, 0x3d372713, v14
	v_mul_f32_e32 v13, 0x3d372713, v15
	v_mul_f32_e32 v12, v14, v12
	v_mul_f32_e32 v13, v15, v13
	v_fma_f32 v12, v14, v12, v14
	v_fma_f32 v13, v15, v13, v15
	v_mul_f32_e32 v12, 0x3fcc422a, v12
	v_mul_f32_e32 v13, 0x3fcc422a, v13
	v_mul_f32_e32 v12, 0xbfb8aa3b, v12
	v_mul_f32_e32 v13, 0xbfb8aa3b, v13
	v_exp_f32_e32 v12, v12
	v_exp_f32_e32 v13, v13
	s_or_b32 s24, s18, 1
	s_ashr_i32 s25, s24, 31
	v_add_f32_e32 v12, 1.0, v12
	v_add_f32_e32 v13, 1.0, v13
	v_rcp_f32_e32 v12, v12
	v_rcp_f32_e32 v13, v13
	s_nop 0
	v_pk_mul_f32 v[12:13], v[14:15], v[12:13]
	s_nop 0
	v_cvt_pk_bf16_f32 v19, v12, v13
	v_lshl_add_u64 v[12:13], s[6:7], 0, v[16:17]
	v_lshl_add_u64 v[14:15], v[12:13], 0, s[2:3]
	s_lshl_b32 s2, s1, 4
	s_ashr_i32 s3, s2, 31
	s_lshl_b64 s[20:21], s[2:3], 1
	v_lshl_add_u64 v[14:15], v[14:15], 0, s[20:21]
	v_lshl_add_u64 v[14:15], v[14:15], 0, v[134:135]
	global_store_dwordx2 v[14:15], v[18:19], off
	v_mul_f32_e32 v14, 0x3d372713, v8
	v_mul_f32_e32 v15, 0x3d372713, v9
	v_mul_f32_e32 v14, v8, v14
	v_mul_f32_e32 v15, v9, v15
	v_fma_f32 v14, v8, v14, v8
	v_fma_f32 v15, v9, v15, v9
	v_mul_f32_e32 v14, 0x3fcc422a, v14
	v_mul_f32_e32 v15, 0x3fcc422a, v15
	v_mul_f32_e32 v14, 0xbfb8aa3b, v14
	v_mul_f32_e32 v15, 0xbfb8aa3b, v15
	v_exp_f32_e32 v14, v14
	v_exp_f32_e32 v15, v15
	s_lshl_b64 s[2:3], s[24:25], 11
	s_or_b32 s24, s18, 8
	v_add_f32_e32 v14, 1.0, v14
	v_add_f32_e32 v15, 1.0, v15
	v_rcp_f32_e32 v14, v14
	v_rcp_f32_e32 v15, v15
	s_ashr_i32 s25, s24, 31
	s_or_b32 s18, s18, 9
	s_ashr_i32 s19, s18, 31
	v_pk_mul_f32 v[8:9], v[8:9], v[14:15]
	s_nop 0
	v_cvt_pk_bf16_f32 v8, v8, v9
	v_mul_f32_e32 v9, 0x3d372713, v10
	v_mul_f32_e32 v9, v10, v9
	v_fma_f32 v9, v10, v9, v10
	v_mul_f32_e32 v9, 0x3fcc422a, v9
	v_mul_f32_e32 v9, 0xbfb8aa3b, v9
	v_exp_f32_e32 v9, v9
	s_nop 0
	v_add_f32_e32 v9, 1.0, v9
	v_rcp_f32_e32 v14, v9
	v_mul_f32_e32 v9, 0x3d372713, v11
	v_mul_f32_e32 v9, v11, v9
	v_fma_f32 v9, v11, v9, v11
	v_mul_f32_e32 v9, 0x3fcc422a, v9
	v_mul_f32_e32 v9, 0xbfb8aa3b, v9
	v_exp_f32_e32 v9, v9
	s_nop 0
	v_add_f32_e32 v9, 1.0, v9
	v_rcp_f32_e32 v15, v9
	s_nop 0
	v_pk_mul_f32 v[10:11], v[10:11], v[14:15]
	s_nop 0
	v_cvt_pk_bf16_f32 v9, v10, v11
	v_lshl_add_u64 v[10:11], v[12:13], 0, s[2:3]
	v_lshl_add_u64 v[10:11], v[10:11], 0, s[20:21]
	v_lshl_add_u64 v[10:11], v[10:11], 0, v[134:135]
	global_store_dwordx2 v[10:11], v[8:9], off
	v_mul_f32_e32 v8, 0x3d372713, v4
	v_mul_f32_e32 v9, 0x3d372713, v5
	v_mul_f32_e32 v8, v4, v8
	v_mul_f32_e32 v9, v5, v9
	v_fma_f32 v8, v4, v8, v4
	v_fma_f32 v9, v5, v9, v5
	v_mul_f32_e32 v8, 0x3fcc422a, v8
	v_mul_f32_e32 v9, 0x3fcc422a, v9
	v_mul_f32_e32 v8, 0xbfb8aa3b, v8
	v_mul_f32_e32 v9, 0xbfb8aa3b, v9
	v_exp_f32_e32 v8, v8
	v_exp_f32_e32 v9, v9
	s_lshl_b64 s[2:3], s[24:25], 11
	v_add_f32_e32 v8, 1.0, v8
	v_add_f32_e32 v9, 1.0, v9
	v_rcp_f32_e32 v8, v8
	v_rcp_f32_e32 v9, v9
	s_nop 0
	v_pk_mul_f32 v[4:5], v[4:5], v[8:9]
	s_nop 0
	v_cvt_pk_bf16_f32 v4, v4, v5
	v_mul_f32_e32 v5, 0x3d372713, v6
	v_mul_f32_e32 v5, v6, v5
	v_fma_f32 v5, v6, v5, v6
	v_mul_f32_e32 v5, 0x3fcc422a, v5
	v_mul_f32_e32 v5, 0xbfb8aa3b, v5
	v_exp_f32_e32 v5, v5
	s_nop 0
	v_add_f32_e32 v5, 1.0, v5
	v_rcp_f32_e32 v8, v5
	v_mul_f32_e32 v5, 0x3d372713, v7
	v_mul_f32_e32 v5, v7, v5
	v_fma_f32 v5, v7, v5, v7
	v_mul_f32_e32 v5, 0x3fcc422a, v5
	v_mul_f32_e32 v5, 0xbfb8aa3b, v5
	v_exp_f32_e32 v5, v5
	s_nop 0
	v_add_f32_e32 v5, 1.0, v5
	v_rcp_f32_e32 v9, v5
	s_nop 0
	v_pk_mul_f32 v[6:7], v[6:7], v[8:9]
	s_nop 0
	v_cvt_pk_bf16_f32 v5, v6, v7
	v_lshl_add_u64 v[6:7], v[12:13], 0, s[2:3]
	v_lshl_add_u64 v[6:7], v[6:7], 0, s[20:21]
	v_lshl_add_u64 v[6:7], v[6:7], 0, v[134:135]
	global_store_dwordx2 v[6:7], v[4:5], off
	v_mul_f32_e32 v4, 0x3d372713, v0
	v_mul_f32_e32 v5, 0x3d372713, v1
	v_mul_f32_e32 v4, v0, v4
	v_mul_f32_e32 v5, v1, v5
	v_fma_f32 v4, v0, v4, v0
	v_fma_f32 v5, v1, v5, v1
	v_mul_f32_e32 v4, 0x3fcc422a, v4
	v_mul_f32_e32 v5, 0x3fcc422a, v5
	v_mul_f32_e32 v4, 0xbfb8aa3b, v4
	v_mul_f32_e32 v5, 0xbfb8aa3b, v5
	v_exp_f32_e32 v4, v4
	v_exp_f32_e32 v5, v5
	s_lshl_b64 s[2:3], s[18:19], 11
	v_add_f32_e32 v4, 1.0, v4
	v_add_f32_e32 v5, 1.0, v5
	v_rcp_f32_e32 v4, v4
	v_rcp_f32_e32 v5, v5
	s_nop 0
	v_pk_mul_f32 v[0:1], v[0:1], v[4:5]
	s_nop 0
	v_cvt_pk_bf16_f32 v0, v0, v1
	v_mul_f32_e32 v1, 0x3d372713, v2
	v_mul_f32_e32 v1, v2, v1
	v_fma_f32 v1, v2, v1, v2
	v_mul_f32_e32 v1, 0x3fcc422a, v1
	v_mul_f32_e32 v1, 0xbfb8aa3b, v1
	v_exp_f32_e32 v1, v1
	s_nop 0
	v_add_f32_e32 v1, 1.0, v1
	v_rcp_f32_e32 v4, v1
	v_mul_f32_e32 v1, 0x3d372713, v3
	v_mul_f32_e32 v1, v3, v1
	v_fma_f32 v1, v3, v1, v3
	v_mul_f32_e32 v1, 0x3fcc422a, v1
	v_mul_f32_e32 v1, 0xbfb8aa3b, v1
	v_exp_f32_e32 v1, v1
	s_nop 0
	v_add_f32_e32 v1, 1.0, v1
	v_rcp_f32_e32 v5, v1
	s_nop 0
	v_pk_mul_f32 v[2:3], v[2:3], v[4:5]
	s_nop 0
	v_cvt_pk_bf16_f32 v1, v2, v3
	v_lshl_add_u64 v[2:3], v[12:13], 0, s[2:3]
	v_lshl_add_u64 v[2:3], v[2:3], 0, s[20:21]
	v_lshl_add_u64 v[2:3], v[2:3], 0, v[134:135]
	global_store_dwordx2 v[2:3], v[0:1], off

; #define FOR_AI_M _Pragma("unroll") for (int ai = 0; ai < 2; ++ai) _Pragma("unroll") for (int m = 0; m < 4; ++m)
;     __device__ __forceinline__ void operator()(const f32x4 (&acc)[2][2][4][2], const Unit& u, int wr, int wc, int fr, int fq) const {
;         FOR_AI_M {
;             const int chunk = 256 * u.pm + 128 * ai + 64 * wr + 16 * m + fr;
;             float* rp = S + ((size_t)u.mode * CHPAD + chunk) * 256 + 32 * wc + 4 * fq;
; #pragma unroll
;             for (int bj = 0; bj < 2; ++bj)
; #pragma unroll
;                 for (int n = 0; n < 2; ++n) *(f32x4*)(rp + 128 * bj + 16 * n) = acc[ai][bj][m][n];
;         }
.LBB0_494:
	v_mov_b32_e32 v143, v139
	v_mov_b32_e32 v142, v138
	s_lshl_b32 s1, s51, 8
	s_add_i32 s1, s1, s50
	v_add_u32_e32 v142, s1, v142
	v_lshlrev_b32_e32 v144, 2, v143
	v_ashrrev_i32_e32 v143, 31, v142
	v_mad_i64_i32 v[146:147], s[20:21], s0, v242, v[142:143]
	v_ashrrev_i32_e32 v145, 31, v144
	v_lshlrev_b64 v[146:147], 10, v[146:147]
	v_lshl_add_u64 v[146:147], s[10:11], 0, v[146:147]
	v_lshlrev_b64 v[144:145], 2, v[144:145]
	v_lshl_add_u64 v[146:147], v[146:147], 0, v[144:145]
	global_store_dwordx4 v[146:147], v[124:127], off
	global_store_dwordx4 v[146:147], v[120:123], off offset:64
	global_store_dwordx4 v[146:147], v[108:111], off offset:512
	global_store_dwordx4 v[146:147], v[104:107], off offset:576
	s_andn2_b64 vcc, exec, s[18:19]
	s_nop 0
	v_add_u32_e32 v104, 16, v142
	v_ashrrev_i32_e32 v105, 31, v104
	v_mad_i64_i32 v[104:105], s[20:21], s0, v242, v[104:105]
	v_lshlrev_b64 v[104:105], 10, v[104:105]
	v_lshl_add_u64 v[104:105], s[10:11], 0, v[104:105]
	v_lshl_add_u64 v[104:105], v[104:105], 0, v[144:145]
	global_store_dwordx4 v[104:105], v[116:119], off
	global_store_dwordx4 v[104:105], v[112:115], off offset:64
	global_store_dwordx4 v[104:105], v[92:95], off offset:512
	global_store_dwordx4 v[104:105], v[88:91], off offset:576
	s_nop 1
	v_add_u32_e32 v88, 32, v142
	v_ashrrev_i32_e32 v89, 31, v88
	v_mad_i64_i32 v[88:89], s[20:21], s0, v242, v[88:89]
	v_lshlrev_b64 v[88:89], 10, v[88:89]
	v_lshl_add_u64 v[88:89], s[10:11], 0, v[88:89]
	v_lshl_add_u64 v[88:89], v[88:89], 0, v[144:145]
	global_store_dwordx4 v[88:89], v[100:103], off
	global_store_dwordx4 v[88:89], v[96:99], off offset:64
	global_store_dwordx4 v[88:89], v[76:79], off offset:512
	global_store_dwordx4 v[88:89], v[72:75], off offset:576
	s_nop 1
	v_add_u32_e32 v72, 48, v142
	v_ashrrev_i32_e32 v73, 31, v72
	v_mad_i64_i32 v[72:73], s[20:21], s0, v242, v[72:73]
	v_lshlrev_b64 v[72:73], 10, v[72:73]
	v_lshl_add_u64 v[72:73], s[10:11], 0, v[72:73]
	v_lshl_add_u64 v[72:73], v[72:73], 0, v[144:145]
	global_store_dwordx4 v[72:73], v[84:87], off
	global_store_dwordx4 v[72:73], v[80:83], off offset:64
	global_store_dwordx4 v[72:73], v[68:71], off offset:512
	global_store_dwordx4 v[72:73], v[64:67], off offset:576
	s_nop 1
	v_add_u32_e32 v64, 0x80, v142
	v_ashrrev_i32_e32 v65, 31, v64
	v_mad_i64_i32 v[64:65], s[20:21], s0, v242, v[64:65]
	v_lshlrev_b64 v[64:65], 10, v[64:65]
	v_lshl_add_u64 v[64:65], s[10:11], 0, v[64:65]
	v_lshl_add_u64 v[64:65], v[64:65], 0, v[144:145]
	global_store_dwordx4 v[64:65], v[60:63], off
	global_store_dwordx4 v[64:65], v[56:59], off offset:64
	global_store_dwordx4 v[64:65], v[44:47], off offset:512
	global_store_dwordx4 v[64:65], v[40:43], off offset:576
	s_nop 1
	v_add_u32_e32 v40, 0x90, v142
	v_ashrrev_i32_e32 v41, 31, v40
	v_mad_i64_i32 v[40:41], s[20:21], s0, v242, v[40:41]
	v_lshlrev_b64 v[40:41], 10, v[40:41]
	v_lshl_add_u64 v[40:41], s[10:11], 0, v[40:41]
	v_lshl_add_u64 v[40:41], v[40:41], 0, v[144:145]
	global_store_dwordx4 v[40:41], v[52:55], off
	global_store_dwordx4 v[40:41], v[48:51], off offset:64
	global_store_dwordx4 v[40:41], v[28:31], off offset:512
	global_store_dwordx4 v[40:41], v[24:27], off offset:576
	s_nop 1
	v_add_u32_e32 v24, 0xa0, v142
	v_ashrrev_i32_e32 v25, 31, v24
	v_mad_i64_i32 v[24:25], s[20:21], s0, v242, v[24:25]
	v_lshlrev_b64 v[24:25], 10, v[24:25]
	v_lshl_add_u64 v[24:25], s[10:11], 0, v[24:25]
	v_lshl_add_u64 v[24:25], v[24:25], 0, v[144:145]
	global_store_dwordx4 v[24:25], v[36:39], off
	global_store_dwordx4 v[24:25], v[32:35], off offset:64
	global_store_dwordx4 v[24:25], v[12:15], off offset:512
	global_store_dwordx4 v[24:25], v[8:11], off offset:576
	s_nop 1
	v_add_u32_e32 v8, 0xb0, v142
	v_ashrrev_i32_e32 v9, 31, v8
	v_mad_i64_i32 v[8:9], s[0:1], s0, v242, v[8:9]
	v_lshlrev_b64 v[8:9], 10, v[8:9]
	v_lshl_add_u64 v[8:9], s[10:11], 0, v[8:9]
	v_lshl_add_u64 v[8:9], v[8:9], 0, v[144:145]
	s_mov_b64 s[0:1], -1
	global_store_dwordx4 v[8:9], v[20:23], off
	global_store_dwordx4 v[8:9], v[16:19], off offset:64
	global_store_dwordx4 v[8:9], v[4:7], off offset:512
	global_store_dwordx4 v[8:9], v[0:3], off offset:576
	s_cbranch_vccnz .LBB0_487
	s_andn2_b64 vcc, exec, s[6:7]
	s_cbranch_vccnz .LBB0_486
	s_barrier
	s_branch .LBB0_486

; __device__ __forceinline__ float sum_x32(float v) { auto rr = __builtin_amdgcn_permlane32_swap(__float_as_uint(v), __float_as_uint(v), false, false); return __uint_as_float(rr[0]) + __uint_as_float(rr[1]); }
; #define FOR_AI_M _Pragma("unroll") for (int ai = 0; ai < 2; ++ai) _Pragma("unroll") for (int m = 0; m < 4; ++m)
;     __device__ __forceinline__ void operator()(const f32x4 (&acc)[2][2][4][2], const Unit& u, int wr, int wc, int fr, int fq) const {
;     ...
;         if (kind <= 1) {
;             f32x4 g[2][2];
; #pragma unroll
;             for (int bj = 0; bj < 2; ++bj)
; #pragma unroll
;                 for (int n = 0; n < 2; ++n) g[bj][n] = *(const f32x4*)(gain + 32 * bj + 8 * fq + 4 * n);
;             const float qs = (kind == 0) ? QSCALE : 1.0f;
;             FOR_AI_M {
;                 const int row = 256 * u.pm + 128 * ai + 64 * wr + 16 * m + fr;
;                 f32x4 x[2][2]; float ss = 0.f;
; #pragma unroll
;                 for (int bj = 0; bj < 2; ++bj)
; #pragma unroll
;                     for (int n = 0; n < 2; ++n) { x[bj][n] = acc[ai][bj][m][n]; ss += (x[bj][n][0] * x[bj][n][0] + x[bj][n][1] * x[bj][n][1]) + (x[bj][n][2] * x[bj][n][2] + x[bj][n][3] * x[bj][n][3]); }
;                 ss += shx<16>(ss); ss = sum_x32(ss);
;                 const float rinv = rsqrtf(ss * (1.0f / 64.0f) + EPS);
; #pragma unroll
;                 for (int bj = 0; bj < 2; ++bj)
; #pragma unroll
;                     for (int n = 0; n < 2; ++n) x[bj][n] = x[bj][n] * rinv * g[bj][n];
;                 if (!isctx) {
;                     const int t = row & (SEQ - 1); const int p = (fq < 2) ? (t >> 6) : (t & 63);
;                     const float* tp = tab + (p * 16 + 8 * (fq & 1)) * 2;
; #pragma unroll
;                     for (int n = 0; n < 2; ++n) {
;                         const f32x4 cs0 = *(const f32x4*)(tp + 8 * n), cs1 = *(const f32x4*)(tp + 8 * n + 4);
;                         const float c[4] = {cs0[0], cs0[2], cs1[0], cs1[2]}, s[4] = {cs0[1], cs0[3], cs1[1], cs1[3]};
; #pragma unroll
;                         for (int e = 0; e < 4; ++e) { const float lo = x[0][n][e], hi = x[1][n][e]; x[0][n][e] = lo * c[e] - hi * s[e]; x[1][n][e] = hi * c[e] + lo * s[e]; }
;                     }
;                 }
.LBB0_535:
	v_lshlrev_b32_e32 v144, 3, v210
	v_ashrrev_i32_e32 v145, 31, v144
	v_lshl_add_u64 v[56:57], v[144:145], 2, s[26:27]
	global_load_dwordx4 v[52:55], v[56:57], off offset:16
	global_load_dwordx4 v[60:63], v[56:57], off
	global_load_dwordx4 v[48:51], v[56:57], off offset:144
	s_nop 0
	global_load_dwordx4 v[56:59], v[56:57], off offset:128
	v_lshlrev_b32_e32 v146, 4, v210
	v_and_b32_e32 v151, 16, v146
	v_pk_mul_f32 v[146:147], v[142:143], v[142:143]
	v_pk_mul_f32 v[148:149], v[140:141], v[140:141]
	s_cmpk_lt_i32 s6, 0x80
	v_pk_mov_b32 v[154:155], v[148:149], v[146:147] op_sel:[1,0]
	v_mov_b32_e32 v149, v147
	v_pk_add_f32 v[146:147], v[154:155], v[148:149]
	v_pk_mul_f32 v[148:149], v[138:139], v[138:139]
	v_pk_add_f32 v[146:147], v[146:147], v[146:147] op_sel_hi:[0,1]
	v_pk_mul_f32 v[154:155], v[136:137], v[136:137]
	v_mul_f32_e32 v146, v132, v132
	v_pk_mov_b32 v[156:157], v[154:155], v[148:149] op_sel:[1,0]
	v_mov_b32_e32 v155, v149
	v_pk_add_f32 v[148:149], v[156:157], v[154:155]
	v_pk_fma_f32 v[154:155], v[132:133], v[132:133], v[146:147] op_sel_hi:[1,1,0]
	v_mul_f32_e32 v146, v134, v134
	v_pk_add_f32 v[148:149], v[148:149], v[148:149] op_sel_hi:[0,1]
	v_pk_fma_f32 v[156:157], v[134:135], v[134:135], v[146:147] op_sel_hi:[1,1,0]
	v_mul_f32_e32 v154, v128, v128
	v_mul_f32_e32 v156, v129, v129
	v_mul_f32_e32 v148, v130, v130
	v_mul_f32_e32 v146, v131, v131
	v_pk_add_f32 v[154:155], v[154:155], v[156:157]
	v_pk_add_f32 v[146:147], v[148:149], v[146:147]
	s_cselect_b64 s[18:19], -1, 0
	v_pk_add_f32 v[146:147], v[154:155], v[146:147]
	s_lshl_b32 s2, s6, 8
	v_add_f32_e32 v146, v146, v147
	ds_swizzle_b32 v147, v146 offset:swizzle(SWAP,16)
	s_add_i32 s2, s2, s61
	v_add_u32_e32 v150, s2, v209
	s_mov_b32 s2, 0x800000
	s_cmpk_gt_i32 s6, 0x7f
	s_waitcnt lgkmcnt(0)
	v_add_f32_e32 v146, v146, v147
	v_mov_b32_e32 v147, v146
	s_nop 1
	v_permlane32_swap_b32_e32 v146, v147
	v_add_f32_e32 v146, v146, v147
	v_fmamk_f32 v146, v146, 0x3c800000, v226
	v_cmp_gt_f32_e32 vcc, s2, v146
	v_mul_f32_e32 v147, 0x4b800000, v146
	v_cmp_gt_i32_e64 s[6:7], 2, v210
	v_cndmask_b32_e32 v146, v146, v147, vcc
	v_rsq_f32_e32 v146, v146
	v_and_b32_e32 v152, 63, v209
	v_lshlrev_b32_e32 v151, 2, v151
	v_mul_f32_e32 v147, 0x45800000, v146
	v_cndmask_b32_e32 v154, v146, v147, vcc
	v_pk_mul_f32 v[140:141], v[140:141], v[154:155] op_sel_hi:[1,0]
	v_pk_mul_f32 v[142:143], v[142:143], v[154:155] op_sel_hi:[1,0]
	v_pk_mul_f32 v[136:137], v[136:137], v[154:155] op_sel_hi:[1,0]
	v_pk_mul_f32 v[138:139], v[138:139], v[154:155] op_sel_hi:[1,0]
	v_pk_mul_f32 v[128:129], v[128:129], v[154:155] op_sel_hi:[1,0]
	v_pk_mul_f32 v[130:131], v[130:131], v[154:155] op_sel_hi:[1,0]
	s_waitcnt vmcnt(0)
	v_pk_mul_f32 v[138:139], v[54:55], v[138:139]
	v_pk_mul_f32 v[146:147], v[60:61], v[140:141]
	v_pk_mul_f32 v[140:141], v[132:133], v[154:155] op_sel_hi:[1,0]
	v_pk_mul_f32 v[132:133], v[134:135], v[154:155] op_sel_hi:[1,0]
	v_pk_mul_f32 v[148:149], v[62:63], v[142:143]
	v_pk_mul_f32 v[136:137], v[52:53], v[136:137]
	v_pk_mul_f32 v[132:133], v[58:59], v[132:133]
	v_pk_mul_f32 v[134:135], v[56:57], v[140:141]
	v_pk_mul_f32 v[130:131], v[50:51], v[130:131]
	v_pk_mul_f32 v[140:141], v[48:49], v[128:129]
	s_cbranch_scc1 .LBB0_537
	v_bfe_u32 v128, v150, 6, 7
	v_cndmask_b32_e64 v128, v152, v128, s[6:7]
	v_lshl_or_b32 v192, v128, 7, v151
	v_lshl_add_u64 v[162:163], s[10:11], 0, v[192:193]
	global_load_dwordx4 v[154:157], v[162:163], off
	global_load_dwordx4 v[158:161], v[162:163], off offset:16
	s_waitcnt vmcnt(0) lgkmcnt(0)
	v_mov_b32_e32 v128, v154
	v_mul_f32_e32 v154, v148, v158
	v_mul_f32_e32 v164, v132, v159
	v_mul_f32_e32 v158, v132, v158
	v_mov_b32_e32 v132, v149
	v_mov_b32_e32 v129, v156
	v_mov_b32_e32 v156, v155
	v_pk_mul_f32 v[168:169], v[132:133], v[160:161]
	v_pk_mul_f32 v[142:143], v[134:135], v[156:157]
	v_pk_mul_f32 v[134:135], v[134:135], v[128:129]
	v_mul_f32_e32 v166, v148, v159
	v_mov_b32_e32 v155, v168
	v_mov_b32_e32 v165, v169
	v_mov_b32_e32 v148, v133
	v_pk_fma_f32 v[142:143], v[146:147], v[128:129], v[142:143] neg_lo:[0,0,1] neg_hi:[0,0,1]
	v_pk_add_f32 v[128:129], v[154:155], v[164:165] neg_lo:[0,1] neg_hi:[0,1]
	v_pk_mul_f32 v[132:133], v[148:149], v[160:161]
	v_pk_fma_f32 v[134:135], v[146:147], v[156:157], v[134:135]
	global_load_dwordx4 v[146:149], v[162:163], off offset:32
	global_load_dwordx4 v[154:157], v[162:163], off offset:48
	v_mov_b32_e32 v167, v133
	v_mov_b32_e32 v159, v132
	v_pk_add_f32 v[132:133], v[166:167], v[158:159]
	s_waitcnt vmcnt(0) lgkmcnt(0)
	v_mov_b32_e32 v159, v148
	v_mul_f32_e32 v160, v138, v154
	v_mul_f32_e32 v162, v130, v155
	v_mul_f32_e32 v154, v130, v154
	v_mov_b32_e32 v130, v139
	v_mov_b32_e32 v148, v147
	v_mul_f32_e32 v164, v138, v155
	v_pk_mul_f32 v[166:167], v[130:131], v[156:157]
	v_mov_b32_e32 v138, v131
	v_mov_b32_e32 v158, v146
	v_pk_mul_f32 v[146:147], v[140:141], v[148:149]
	v_mov_b32_e32 v161, v166
	v_mov_b32_e32 v163, v167
	v_pk_mul_f32 v[130:131], v[138:139], v[156:157]
	v_pk_mul_f32 v[140:141], v[140:141], v[158:159]
	v_pk_fma_f32 v[146:147], v[136:137], v[158:159], v[146:147] neg_lo:[0,0,1] neg_hi:[0,0,1]
	v_pk_add_f32 v[158:159], v[160:161], v[162:163] neg_lo:[0,1] neg_hi:[0,1]
	v_mov_b32_e32 v165, v131
	v_mov_b32_e32 v155, v130
	v_pk_fma_f32 v[140:141], v[136:137], v[148:149], v[140:141]
	v_pk_add_f32 v[130:131], v[164:165], v[154:155]
	v_mov_b32_e32 v136, v146
	v_mov_b32_e32 v137, v147
	v_mov_b32_e32 v138, v158
	v_mov_b32_e32 v139, v159
	v_mov_b32_e32 v146, v142
	v_mov_b32_e32 v147, v143
	v_mov_b32_e32 v148, v128
	v_mov_b32_e32 v149, v129
; __device__ __forceinline__ unsigned cvt_pk_bf16(float lo, float hi) { f32x2 v = {lo, hi}; bf16x2_t b = __builtin_convertvector(v, bf16x2_t); return __builtin_bit_cast(unsigned, b); }
; #define FOR_AI_M _Pragma("unroll") for (int ai = 0; ai < 2; ++ai) _Pragma("unroll") for (int m = 0; m < 4; ++m)
;     __device__ __forceinline__ void operator()(const f32x4 (&acc)[2][2][4][2], const Unit& u, int wr, int wc, int fr, int fq) const {
;     ...
;             FOR_AI_M {
;                 const int row = 256 * u.pm + 128 * ai + 64 * wr + 16 * m + fr;
;                 f32x4 x[2][2]; float ss = 0.f;
; #pragma unroll
;                 for (int bj = 0; bj < 2; ++bj)
; #pragma unroll
;                     for (int n = 0; n < 2; ++n) { x[bj][n] = acc[ai][bj][m][n]; ss += (x[bj][n][0] * x[bj][n][0] + x[bj][n][1] * x[bj][n][1]) + (x[bj][n][2] * x[bj][n][2] + x[bj][n][3] * x[bj][n][3]); }
;                 ss += shx<16>(ss); ss = sum_x32(ss);
;                 const float rinv = rsqrtf(ss * (1.0f / 64.0f) + EPS);
; #pragma unroll
;                 for (int bj = 0; bj < 2; ++bj)
; #pragma unroll
;                     for (int n = 0; n < 2; ++n) x[bj][n] = x[bj][n] * rinv * g[bj][n];
;                 if (!isctx) {
;                     const int t = row & (SEQ - 1); const int p = (fq < 2) ? (t >> 6) : (t & 63);
;                     const float* tp = tab + (p * 16 + 8 * (fq & 1)) * 2;
; #pragma unroll
;                     for (int n = 0; n < 2; ++n) {
;                         const f32x4 cs0 = *(const f32x4*)(tp + 8 * n), cs1 = *(const f32x4*)(tp + 8 * n + 4);
;                         const float c[4] = {cs0[0], cs0[2], cs1[0], cs1[2]}, s[4] = {cs0[1], cs0[3], cs1[1], cs1[3]};
; #pragma unroll
;                         for (int e = 0; e < 4; ++e) { const float lo = x[0][n][e], hi = x[1][n][e]; x[0][n][e] = lo * c[e] - hi * s[e]; x[1][n][e] = hi * c[e] + lo * s[e]; }
;                     }
;                 }
; #pragma unroll
;                 for (int bj = 0; bj < 2; ++bj) {
;                     u32x4 w; w.x = cvt_pk_bf16(x[bj][0][0] * qs, x[bj][0][1] * qs); w.y = cvt_pk_bf16(x[bj][0][2] * qs, x[bj][0][3] * qs);
;                     w.z = cvt_pk_bf16(x[bj][1][0] * qs, x[bj][1][1] * qs); w.w = cvt_pk_bf16(x[bj][1][2] * qs, x[bj][1][3] * qs);
;                     *(u32x4*)(dst + (size_t)row * pitch + colbase + 32 * bj + 8 * fq) = w;
;                 }
.LBB0_537:
	s_ashr_i32 s9, s8, 31
	s_lshl_b64 s[2:3], s[8:9], 1
	s_add_u32 s2, s16, s2
	s_addc_u32 s3, s17, s3
	v_ashrrev_i32_e32 v143, 31, v150
	v_lshl_add_u64 v[128:129], v[144:145], 1, s[2:3]
	v_mul_lo_u32 v153, s25, v150
	v_mul_lo_u32 v143, s24, v143
	v_mad_u64_u32 v[144:145], s[2:3], s24, v150, 0
	v_add3_u32 v145, v145, v143, v153
	v_lshl_add_u64 v[154:155], v[144:145], 1, v[128:129]
	v_pk_mul_f32 v[144:145], s[96:97], v[146:147] op_sel_hi:[0,1]
	v_pk_mul_f32 v[146:147], s[96:97], v[148:149] op_sel_hi:[0,1]
	v_pk_mul_f32 v[136:137], s[96:97], v[136:137] op_sel_hi:[0,1]
	v_cvt_pk_bf16_f32 v144, v144, v145
	v_cvt_pk_bf16_f32 v145, v146, v147
	v_cvt_pk_bf16_f32 v146, v136, v137
	v_pk_mul_f32 v[136:137], s[96:97], v[138:139] op_sel_hi:[0,1]
	v_cvt_pk_bf16_f32 v147, v136, v137
	v_pk_mul_f32 v[136:137], v[126:127], v[126:127]
	v_pk_mul_f32 v[138:139], v[124:125], v[124:125]
	global_store_dwordx4 v[154:155], v[144:147], off
	v_pk_mul_f32 v[134:135], s[96:97], v[134:135] op_sel_hi:[0,1]
	v_pk_mul_f32 v[132:133], s[96:97], v[132:133] op_sel_hi:[0,1]
	v_pk_mov_b32 v[144:145], v[138:139], v[136:137] op_sel:[1,0]
	v_mov_b32_e32 v139, v137
	v_pk_add_f32 v[136:137], v[144:145], v[138:139]
	v_pk_mul_f32 v[138:139], v[122:123], v[122:123]
	v_pk_add_f32 v[136:137], v[136:137], v[136:137] op_sel_hi:[0,1]
	v_pk_mul_f32 v[144:145], v[120:121], v[120:121]
	v_mul_f32_e32 v136, v116, v116
	v_pk_mov_b32 v[146:147], v[144:145], v[138:139] op_sel:[1,0]
	v_mov_b32_e32 v145, v139
	v_pk_add_f32 v[138:139], v[146:147], v[144:145]
	v_pk_fma_f32 v[144:145], v[116:117], v[116:117], v[136:137] op_sel_hi:[1,1,0]
	v_mul_f32_e32 v136, v118, v118
	v_pk_add_f32 v[138:139], v[138:139], v[138:139] op_sel_hi:[0,1]
	v_pk_fma_f32 v[146:147], v[118:119], v[118:119], v[136:137] op_sel_hi:[1,1,0]
	v_mul_f32_e32 v144, v112, v112
	v_mul_f32_e32 v146, v113, v113
	v_mul_f32_e32 v138, v114, v114
	v_mul_f32_e32 v136, v115, v115
	v_pk_add_f32 v[144:145], v[144:145], v[146:147]
	v_pk_add_f32 v[136:137], v[138:139], v[136:137]
	v_cvt_pk_bf16_f32 v134, v134, v135
	v_pk_add_f32 v[136:137], v[144:145], v[136:137]
	v_cvt_pk_bf16_f32 v135, v132, v133
	v_add_f32_e32 v137, v136, v137
	ds_swizzle_b32 v138, v137 offset:swizzle(SWAP,16)
	v_pk_mul_f32 v[132:133], s[96:97], v[140:141] op_sel_hi:[0,1]
	v_cvt_pk_bf16_f32 v136, v132, v133
	s_mov_b32 s2, 0x800000
	v_pk_mul_f32 v[130:131], s[96:97], v[130:131] op_sel_hi:[0,1]
	s_waitcnt lgkmcnt(0)
	v_add_f32_e32 v132, v137, v138
	v_mov_b32_e32 v133, v132
	s_nop 1
	v_permlane32_swap_b32_e32 v132, v133
	v_add_f32_e32 v132, v132, v133
	v_fmamk_f32 v132, v132, 0x3c800000, v226
	v_mul_f32_e32 v133, 0x4b800000, v132
	v_cmp_gt_f32_e32 vcc, s2, v132
	v_cvt_pk_bf16_f32 v137, v130, v131
	global_store_dwordx4 v[154:155], v[134:137], off offset:64
	v_cndmask_b32_e32 v132, v132, v133, vcc
	v_rsq_f32_e32 v132, v132
	v_add_u32_e32 v142, 16, v209
	v_and_b32_e32 v142, 63, v142
	v_mul_f32_e32 v130, 0x45800000, v132
	v_cndmask_b32_e32 v134, v132, v130, vcc
	v_pk_mul_f32 v[124:125], v[124:125], v[134:135] op_sel_hi:[1,0]
	v_pk_mul_f32 v[126:127], v[126:127], v[134:135] op_sel_hi:[1,0]
	v_pk_mul_f32 v[130:131], v[60:61], v[124:125]
	v_pk_mul_f32 v[124:125], v[116:117], v[134:135] op_sel_hi:[1,0]
	v_pk_mul_f32 v[116:117], v[118:119], v[134:135] op_sel_hi:[1,0]
	v_pk_mul_f32 v[118:119], v[56:57], v[124:125]
	v_pk_mul_f32 v[124:125], v[112:113], v[134:135] op_sel_hi:[1,0]
	v_pk_mul_f32 v[120:121], v[120:121], v[134:135] op_sel_hi:[1,0]
	v_pk_mul_f32 v[122:123], v[122:123], v[134:135] op_sel_hi:[1,0]
	v_pk_mul_f32 v[112:113], v[114:115], v[134:135] op_sel_hi:[1,0]
	v_pk_mul_f32 v[114:115], v[48:49], v[124:125]
	v_cndmask_b32_e64 v124, 0, 1, s[18:19]
	v_pk_mul_f32 v[132:133], v[62:63], v[126:127]
	v_pk_mul_f32 v[122:123], v[54:55], v[122:123]
	v_pk_mul_f32 v[120:121], v[52:53], v[120:121]
	v_pk_mul_f32 v[116:117], v[58:59], v[116:117]
	v_pk_mul_f32 v[112:113], v[50:51], v[112:113]
	v_cmp_ne_u32_e64 s[8:9], 1, v124
	s_andn2_b64 vcc, exec, s[18:19]
	v_add_u32_e32 v134, 16, v150
	s_cbranch_vccnz .LBB0_539
	v_bfe_u32 v124, v134, 6, 7
	v_cndmask_b32_e64 v124, v142, v124, s[6:7]
	v_lshl_or_b32 v192, v124, 7, v151
	v_lshl_add_u64 v[140:141], s[10:11], 0, v[192:193]
	global_load_dwordx4 v[136:139], v[140:141], off
	global_load_dwordx4 v[144:147], v[140:141], off offset:16
	s_waitcnt vmcnt(0) lgkmcnt(0)
	v_mov_b32_e32 v124, v136
	v_mul_f32_e32 v136, v132, v144
	v_mul_f32_e32 v148, v116, v145
	v_mul_f32_e32 v144, v116, v144
	v_mov_b32_e32 v116, v133
	v_mov_b32_e32 v125, v138
	v_mov_b32_e32 v138, v137
	v_pk_mul_f32 v[156:157], v[116:117], v[146:147]
	v_pk_mul_f32 v[126:127], v[118:119], v[138:139]
	v_pk_mul_f32 v[118:119], v[118:119], v[124:125]
	v_mul_f32_e32 v154, v132, v145
	v_mov_b32_e32 v137, v156
	v_mov_b32_e32 v149, v157
	v_mov_b32_e32 v132, v117
	v_pk_fma_f32 v[126:127], v[130:131], v[124:125], v[126:127] neg_lo:[0,0,1] neg_hi:[0,0,1]
	v_pk_add_f32 v[124:125], v[136:137], v[148:149] neg_lo:[0,1] neg_hi:[0,1]
	v_pk_mul_f32 v[116:117], v[132:133], v[146:147]
	v_pk_fma_f32 v[118:119], v[130:131], v[138:139], v[118:119]
	global_load_dwordx4 v[130:133], v[140:141], off offset:32
	global_load_dwordx4 v[136:139], v[140:141], off offset:48
	v_mov_b32_e32 v155, v117
	v_mov_b32_e32 v145, v116
	v_pk_add_f32 v[116:117], v[154:155], v[144:145]
	s_waitcnt vmcnt(0) lgkmcnt(0)
	v_mov_b32_e32 v141, v132
	v_mul_f32_e32 v144, v122, v136
	v_mul_f32_e32 v146, v112, v137
	v_mul_f32_e32 v136, v112, v136
	v_mov_b32_e32 v112, v123
	v_mov_b32_e32 v132, v131
	v_mul_f32_e32 v148, v122, v137
	v_pk_mul_f32 v[154:155], v[112:113], v[138:139]
	v_mov_b32_e32 v122, v113
	v_mov_b32_e32 v140, v130
	v_pk_mul_f32 v[130:131], v[114:115], v[132:133]
	v_mov_b32_e32 v145, v154
	v_mov_b32_e32 v147, v155
	v_pk_mul_f32 v[112:113], v[122:123], v[138:139]
	v_pk_mul_f32 v[114:115], v[114:115], v[140:141]
	v_pk_fma_f32 v[130:131], v[120:121], v[140:141], v[130:131] neg_lo:[0,0,1] neg_hi:[0,0,1]
	v_pk_add_f32 v[140:141], v[144:145], v[146:147] neg_lo:[0,1] neg_hi:[0,1]
	v_mov_b32_e32 v149, v113
	v_mov_b32_e32 v137, v112
	v_pk_fma_f32 v[114:115], v[120:121], v[132:133], v[114:115]
	v_pk_add_f32 v[112:113], v[148:149], v[136:137]
	v_mov_b32_e32 v120, v130
	v_mov_b32_e32 v121, v131
	v_mov_b32_e32 v122, v140
	v_mov_b32_e32 v123, v141
	v_mov_b32_e32 v130, v126
	v_mov_b32_e32 v131, v127
	v_mov_b32_e32 v132, v124
	v_mov_b32_e32 v133, v125
; __device__ __forceinline__ unsigned cvt_pk_bf16(float lo, float hi) { f32x2 v = {lo, hi}; bf16x2_t b = __builtin_convertvector(v, bf16x2_t); return __builtin_bit_cast(unsigned, b); }
; #define FOR_AI_M _Pragma("unroll") for (int ai = 0; ai < 2; ++ai) _Pragma("unroll") for (int m = 0; m < 4; ++m)
;     __device__ __forceinline__ void operator()(const f32x4 (&acc)[2][2][4][2], const Unit& u, int wr, int wc, int fr, int fq) const {
;     ...
;             FOR_AI_M {
;                 const int row = 256 * u.pm + 128 * ai + 64 * wr + 16 * m + fr;
;                 f32x4 x[2][2]; float ss = 0.f;
; #pragma unroll
;                 for (int bj = 0; bj < 2; ++bj)
; #pragma unroll
;                     for (int n = 0; n < 2; ++n) { x[bj][n] = acc[ai][bj][m][n]; ss += (x[bj][n][0] * x[bj][n][0] + x[bj][n][1] * x[bj][n][1]) + (x[bj][n][2] * x[bj][n][2] + x[bj][n][3] * x[bj][n][3]); }
;                 ss += shx<16>(ss); ss = sum_x32(ss);
;                 const float rinv = rsqrtf(ss * (1.0f / 64.0f) + EPS);
; #pragma unroll
;                 for (int bj = 0; bj < 2; ++bj)
; #pragma unroll
;                     for (int n = 0; n < 2; ++n) x[bj][n] = x[bj][n] * rinv * g[bj][n];
;                 if (!isctx) {
;                     const int t = row & (SEQ - 1); const int p = (fq < 2) ? (t >> 6) : (t & 63);
;                     const float* tp = tab + (p * 16 + 8 * (fq & 1)) * 2;
; #pragma unroll
;                     for (int n = 0; n < 2; ++n) {
;                         const f32x4 cs0 = *(const f32x4*)(tp + 8 * n), cs1 = *(const f32x4*)(tp + 8 * n + 4);
;                         const float c[4] = {cs0[0], cs0[2], cs1[0], cs1[2]}, s[4] = {cs0[1], cs0[3], cs1[1], cs1[3]};
; #pragma unroll
;                         for (int e = 0; e < 4; ++e) { const float lo = x[0][n][e], hi = x[1][n][e]; x[0][n][e] = lo * c[e] - hi * s[e]; x[1][n][e] = hi * c[e] + lo * s[e]; }
;                     }
;                 }
; #pragma unroll
;                 for (int bj = 0; bj < 2; ++bj) {
;                     u32x4 w; w.x = cvt_pk_bf16(x[bj][0][0] * qs, x[bj][0][1] * qs); w.y = cvt_pk_bf16(x[bj][0][2] * qs, x[bj][0][3] * qs);
;                     w.z = cvt_pk_bf16(x[bj][1][0] * qs, x[bj][1][1] * qs); w.w = cvt_pk_bf16(x[bj][1][2] * qs, x[bj][1][3] * qs);
;                     *(u32x4*)(dst + (size_t)row * pitch + colbase + 32 * bj + 8 * fq) = w;
;                 }
.LBB0_539:
	s_mov_b32 s97, s96
	v_ashrrev_i32_e32 v125, 31, v134
	v_mul_lo_u32 v135, s25, v134
	v_mul_lo_u32 v125, s24, v125
	v_mad_u64_u32 v[126:127], s[2:3], s24, v134, 0
	v_pk_mul_f32 v[130:131], s[96:97], v[130:131]
	v_pk_mul_f32 v[132:133], s[96:97], v[132:133]
	v_pk_mul_f32 v[120:121], s[96:97], v[120:121]
	v_add3_u32 v127, v127, v125, v135
	v_cvt_pk_bf16_f32 v130, v130, v131
	v_cvt_pk_bf16_f32 v131, v132, v133
	v_cvt_pk_bf16_f32 v132, v120, v121
	v_pk_mul_f32 v[120:121], s[96:97], v[122:123]
	v_lshl_add_u64 v[126:127], v[126:127], 1, v[128:129]
	v_cvt_pk_bf16_f32 v133, v120, v121
	v_pk_mul_f32 v[120:121], v[110:111], v[110:111]
	v_pk_mul_f32 v[122:123], v[108:109], v[108:109]
	global_store_dwordx4 v[126:127], v[130:133], off
	v_pk_mul_f32 v[114:115], s[96:97], v[114:115]
	s_mov_b32 s2, 0x800000
	v_pk_mov_b32 v[130:131], v[122:123], v[120:121] op_sel:[1,0]
	v_mov_b32_e32 v123, v121
	v_pk_add_f32 v[120:121], v[130:131], v[122:123]
	v_pk_mul_f32 v[122:123], v[106:107], v[106:107]
	v_pk_add_f32 v[120:121], v[120:121], v[120:121] op_sel_hi:[0,1]
	v_pk_mul_f32 v[130:131], v[104:105], v[104:105]
	v_mul_f32_e32 v120, v100, v100
	v_pk_mov_b32 v[132:133], v[130:131], v[122:123] op_sel:[1,0]
	v_mov_b32_e32 v131, v123
	v_pk_add_f32 v[122:123], v[132:133], v[130:131]
	v_pk_fma_f32 v[130:131], v[100:101], v[100:101], v[120:121] op_sel_hi:[1,1,0]
	v_mul_f32_e32 v120, v102, v102
	v_pk_add_f32 v[122:123], v[122:123], v[122:123] op_sel_hi:[0,1]
	v_pk_fma_f32 v[132:133], v[102:103], v[102:103], v[120:121] op_sel_hi:[1,1,0]
	v_mul_f32_e32 v130, v96, v96
	v_mul_f32_e32 v132, v97, v97
	v_mul_f32_e32 v122, v98, v98
	v_mul_f32_e32 v120, v99, v99
	v_pk_add_f32 v[130:131], v[130:131], v[132:133]
	v_pk_add_f32 v[120:121], v[122:123], v[120:121]
	v_pk_mul_f32 v[112:113], s[96:97], v[112:113]
	v_pk_add_f32 v[120:121], v[130:131], v[120:121]
	v_pk_mul_f32 v[118:119], s[96:97], v[118:119]
	v_add_f32_e32 v121, v120, v121
	ds_swizzle_b32 v122, v121 offset:swizzle(SWAP,16)
	v_cvt_pk_bf16_f32 v120, v114, v115
	v_pk_mul_f32 v[116:117], s[96:97], v[116:117]
	v_cvt_pk_bf16_f32 v118, v118, v119
	v_cvt_pk_bf16_f32 v119, v116, v117
	s_waitcnt lgkmcnt(0)
	v_add_f32_e32 v114, v121, v122
	v_mov_b32_e32 v115, v114
	s_nop 1
	v_permlane32_swap_b32_e32 v114, v115
	v_add_f32_e32 v114, v114, v115
	v_fmamk_f32 v114, v114, 0x3c800000, v226
	v_mul_f32_e32 v115, 0x4b800000, v114
	v_cmp_gt_f32_e32 vcc, s2, v114
	v_cvt_pk_bf16_f32 v121, v112, v113
	v_xor_b32_e32 v124, 32, v152
	v_cndmask_b32_e32 v114, v114, v115, vcc
	v_rsq_f32_e32 v114, v114
	global_store_dwordx4 v[126:127], v[118:121], off offset:64
	v_mul_f32_e32 v112, 0x45800000, v114
	v_cndmask_b32_e32 v116, v114, v112, vcc
	v_pk_mul_f32 v[108:109], v[108:109], v[116:117] op_sel_hi:[1,0]
	v_pk_mul_f32 v[110:111], v[110:111], v[116:117] op_sel_hi:[1,0]
	v_pk_mul_f32 v[112:113], v[60:61], v[108:109]
	v_pk_mul_f32 v[108:109], v[100:101], v[116:117] op_sel_hi:[1,0]
	v_pk_mul_f32 v[104:105], v[104:105], v[116:117] op_sel_hi:[1,0]
	v_pk_mul_f32 v[106:107], v[106:107], v[116:117] op_sel_hi:[1,0]
	v_pk_mul_f32 v[100:101], v[102:103], v[116:117] op_sel_hi:[1,0]
	v_pk_mul_f32 v[102:103], v[56:57], v[108:109]
	v_pk_mul_f32 v[108:109], v[96:97], v[116:117] op_sel_hi:[1,0]
	v_pk_mul_f32 v[96:97], v[98:99], v[116:117] op_sel_hi:[1,0]
	v_pk_mul_f32 v[114:115], v[62:63], v[110:111]
	v_pk_mul_f32 v[106:107], v[54:55], v[106:107]
	v_pk_mul_f32 v[104:105], v[52:53], v[104:105]
	v_pk_mul_f32 v[100:101], v[58:59], v[100:101]
	v_pk_mul_f32 v[96:97], v[50:51], v[96:97]
	v_pk_mul_f32 v[98:99], v[48:49], v[108:109]
	s_and_b64 vcc, exec, s[8:9]
	v_add_u32_e32 v116, 32, v150
	s_cbranch_vccnz .LBB0_541
	v_bfe_u32 v108, v116, 6, 7
	v_cndmask_b32_e64 v108, v124, v108, s[6:7]
	v_lshl_or_b32 v192, v108, 7, v151
	v_lshl_add_u64 v[122:123], s[10:11], 0, v[192:193]
	global_load_dwordx4 v[118:121], v[122:123], off
	global_load_dwordx4 v[130:133], v[122:123], off offset:16
	s_waitcnt vmcnt(0) lgkmcnt(0)
	v_mov_b32_e32 v108, v118
	v_mul_f32_e32 v118, v114, v130
	v_mul_f32_e32 v126, v100, v131
	v_mul_f32_e32 v130, v100, v130
	v_mov_b32_e32 v100, v115
	v_mov_b32_e32 v109, v120
	v_mov_b32_e32 v120, v119
	v_pk_mul_f32 v[136:137], v[100:101], v[132:133]
	v_pk_mul_f32 v[110:111], v[102:103], v[120:121]
	v_pk_mul_f32 v[102:103], v[102:103], v[108:109]
	v_mul_f32_e32 v134, v114, v131
	v_mov_b32_e32 v119, v136
	v_mov_b32_e32 v127, v137
	v_mov_b32_e32 v114, v101
	v_pk_fma_f32 v[110:111], v[112:113], v[108:109], v[110:111] neg_lo:[0,0,1] neg_hi:[0,0,1]
	v_pk_add_f32 v[108:109], v[118:119], v[126:127] neg_lo:[0,1] neg_hi:[0,1]
	v_pk_mul_f32 v[100:101], v[114:115], v[132:133]
	v_pk_fma_f32 v[102:103], v[112:113], v[120:121], v[102:103]
	global_load_dwordx4 v[112:115], v[122:123], off offset:32
	global_load_dwordx4 v[118:121], v[122:123], off offset:48
	v_mov_b32_e32 v135, v101
	v_mov_b32_e32 v131, v100
	v_pk_add_f32 v[100:101], v[134:135], v[130:131]
	s_waitcnt vmcnt(0) lgkmcnt(0)
	v_mov_b32_e32 v123, v114
	v_mul_f32_e32 v126, v106, v118
	v_mul_f32_e32 v130, v96, v119
	v_mul_f32_e32 v118, v96, v118
	v_mov_b32_e32 v96, v107
	v_mov_b32_e32 v114, v113
	v_mul_f32_e32 v132, v106, v119
	v_pk_mul_f32 v[134:135], v[96:97], v[120:121]
	v_mov_b32_e32 v106, v97
	v_mov_b32_e32 v122, v112
	v_pk_mul_f32 v[112:113], v[98:99], v[114:115]
	v_mov_b32_e32 v127, v134
	v_mov_b32_e32 v131, v135
	v_pk_mul_f32 v[96:97], v[106:107], v[120:121]
	v_pk_mul_f32 v[98:99], v[98:99], v[122:123]
	v_pk_fma_f32 v[112:113], v[104:105], v[122:123], v[112:113] neg_lo:[0,0,1] neg_hi:[0,0,1]
	v_pk_add_f32 v[122:123], v[126:127], v[130:131] neg_lo:[0,1] neg_hi:[0,1]
	v_mov_b32_e32 v133, v97
	v_mov_b32_e32 v119, v96
	v_pk_fma_f32 v[98:99], v[104:105], v[114:115], v[98:99]
	v_pk_add_f32 v[96:97], v[132:133], v[118:119]
	v_mov_b32_e32 v104, v112
	v_mov_b32_e32 v105, v113
	v_mov_b32_e32 v106, v122
	v_mov_b32_e32 v107, v123
	v_mov_b32_e32 v112, v110
	v_mov_b32_e32 v113, v111
	v_mov_b32_e32 v114, v108
	v_mov_b32_e32 v115, v109
; __device__ __forceinline__ unsigned cvt_pk_bf16(float lo, float hi) { f32x2 v = {lo, hi}; bf16x2_t b = __builtin_convertvector(v, bf16x2_t); return __builtin_bit_cast(unsigned, b); }
; #define FOR_AI_M _Pragma("unroll") for (int ai = 0; ai < 2; ++ai) _Pragma("unroll") for (int m = 0; m < 4; ++m)
;     __device__ __forceinline__ void operator()(const f32x4 (&acc)[2][2][4][2], const Unit& u, int wr, int wc, int fr, int fq) const {
;     ...
;             FOR_AI_M {
;                 const int row = 256 * u.pm + 128 * ai + 64 * wr + 16 * m + fr;
;                 f32x4 x[2][2]; float ss = 0.f;
; #pragma unroll
;                 for (int bj = 0; bj < 2; ++bj)
; #pragma unroll
;                     for (int n = 0; n < 2; ++n) { x[bj][n] = acc[ai][bj][m][n]; ss += (x[bj][n][0] * x[bj][n][0] + x[bj][n][1] * x[bj][n][1]) + (x[bj][n][2] * x[bj][n][2] + x[bj][n][3] * x[bj][n][3]); }
;                 ss += shx<16>(ss); ss = sum_x32(ss);
;                 const float rinv = rsqrtf(ss * (1.0f / 64.0f) + EPS);
; #pragma unroll
;                 for (int bj = 0; bj < 2; ++bj)
; #pragma unroll
;                     for (int n = 0; n < 2; ++n) x[bj][n] = x[bj][n] * rinv * g[bj][n];
;                 if (!isctx) {
;                     const int t = row & (SEQ - 1); const int p = (fq < 2) ? (t >> 6) : (t & 63);
;                     const float* tp = tab + (p * 16 + 8 * (fq & 1)) * 2;
; #pragma unroll
;                     for (int n = 0; n < 2; ++n) {
;                         const f32x4 cs0 = *(const f32x4*)(tp + 8 * n), cs1 = *(const f32x4*)(tp + 8 * n + 4);
;                         const float c[4] = {cs0[0], cs0[2], cs1[0], cs1[2]}, s[4] = {cs0[1], cs0[3], cs1[1], cs1[3]};
; #pragma unroll
;                         for (int e = 0; e < 4; ++e) { const float lo = x[0][n][e], hi = x[1][n][e]; x[0][n][e] = lo * c[e] - hi * s[e]; x[1][n][e] = hi * c[e] + lo * s[e]; }
;                     }
;                 }
; #pragma unroll
;                 for (int bj = 0; bj < 2; ++bj) {
;                     u32x4 w; w.x = cvt_pk_bf16(x[bj][0][0] * qs, x[bj][0][1] * qs); w.y = cvt_pk_bf16(x[bj][0][2] * qs, x[bj][0][3] * qs);
;                     w.z = cvt_pk_bf16(x[bj][1][0] * qs, x[bj][1][1] * qs); w.w = cvt_pk_bf16(x[bj][1][2] * qs, x[bj][1][3] * qs);
;                     *(u32x4*)(dst + (size_t)row * pitch + colbase + 32 * bj + 8 * fq) = w;
;                 }
.LBB0_541:
	v_ashrrev_i32_e32 v109, 31, v116
	v_mul_lo_u32 v117, s25, v116
	v_mul_lo_u32 v109, s24, v109
	v_mad_u64_u32 v[110:111], s[2:3], s24, v116, 0
	v_add3_u32 v111, v111, v109, v117
	v_lshl_add_u64 v[116:117], v[110:111], 1, v[128:129]
	v_pk_mul_f32 v[110:111], s[96:97], v[112:113]
	v_pk_mul_f32 v[112:113], s[96:97], v[114:115]
	v_pk_mul_f32 v[104:105], s[96:97], v[104:105]
	v_cvt_pk_bf16_f32 v110, v110, v111
	v_cvt_pk_bf16_f32 v111, v112, v113
	v_cvt_pk_bf16_f32 v112, v104, v105
	v_pk_mul_f32 v[104:105], s[96:97], v[106:107]
	v_pk_mul_f32 v[106:107], v[92:93], v[92:93]
	v_cvt_pk_bf16_f32 v113, v104, v105
	v_pk_mul_f32 v[104:105], v[94:95], v[94:95]
	global_store_dwordx4 v[116:117], v[110:113], off
	v_pk_mul_f32 v[98:99], s[96:97], v[98:99]
	s_mov_b32 s2, 0x800000
	v_pk_mov_b32 v[110:111], v[106:107], v[104:105] op_sel:[1,0]
	v_mov_b32_e32 v107, v105
	v_pk_add_f32 v[104:105], v[110:111], v[106:107]
	v_pk_mul_f32 v[106:107], v[90:91], v[90:91]
	v_pk_add_f32 v[104:105], v[104:105], v[104:105] op_sel_hi:[0,1]
	v_pk_mul_f32 v[110:111], v[88:89], v[88:89]
	v_mul_f32_e32 v104, v84, v84
	v_pk_mov_b32 v[112:113], v[110:111], v[106:107] op_sel:[1,0]
	v_mov_b32_e32 v111, v107
	v_pk_add_f32 v[106:107], v[112:113], v[110:111]
	v_pk_fma_f32 v[110:111], v[84:85], v[84:85], v[104:105] op_sel_hi:[1,1,0]
	v_mul_f32_e32 v104, v86, v86
	v_pk_add_f32 v[106:107], v[106:107], v[106:107] op_sel_hi:[0,1]
	v_pk_fma_f32 v[112:113], v[86:87], v[86:87], v[104:105] op_sel_hi:[1,1,0]
	v_mul_f32_e32 v110, v80, v80
	v_mul_f32_e32 v112, v81, v81
	v_mul_f32_e32 v106, v82, v82
	v_mul_f32_e32 v104, v83, v83
	v_pk_add_f32 v[110:111], v[110:111], v[112:113]
	v_pk_add_f32 v[104:105], v[106:107], v[104:105]
	v_pk_mul_f32 v[96:97], s[96:97], v[96:97]
	v_pk_add_f32 v[104:105], v[110:111], v[104:105]
	v_pk_mul_f32 v[102:103], s[96:97], v[102:103]
	v_add_f32_e32 v105, v104, v105
	ds_swizzle_b32 v106, v105 offset:swizzle(SWAP,16)
	v_cvt_pk_bf16_f32 v104, v98, v99
	v_pk_mul_f32 v[100:101], s[96:97], v[100:101]
	v_cvt_pk_bf16_f32 v102, v102, v103
	v_cvt_pk_bf16_f32 v103, v100, v101
	s_waitcnt lgkmcnt(0)
	v_add_f32_e32 v98, v105, v106
	v_mov_b32_e32 v99, v98
	s_nop 1
	v_permlane32_swap_b32_e32 v98, v99
	v_add_f32_e32 v98, v98, v99
	v_fmamk_f32 v98, v98, 0x3c800000, v226
	v_mul_f32_e32 v99, 0x4b800000, v98
	v_cmp_gt_f32_e32 vcc, s2, v98
	v_cvt_pk_bf16_f32 v105, v96, v97
	v_add_u32_e32 v108, 48, v209
	v_cndmask_b32_e32 v98, v98, v99, vcc
	v_rsq_f32_e32 v98, v98
	v_and_b32_e32 v108, 63, v108
	global_store_dwordx4 v[116:117], v[102:105], off offset:64
	v_mul_f32_e32 v96, 0x45800000, v98
	v_cndmask_b32_e32 v100, v98, v96, vcc
	v_pk_mul_f32 v[92:93], v[92:93], v[100:101] op_sel_hi:[1,0]
	v_pk_mul_f32 v[94:95], v[94:95], v[100:101] op_sel_hi:[1,0]
	v_pk_mul_f32 v[96:97], v[60:61], v[92:93]
	v_pk_mul_f32 v[92:93], v[84:85], v[100:101] op_sel_hi:[1,0]
	v_pk_mul_f32 v[88:89], v[88:89], v[100:101] op_sel_hi:[1,0]
	v_pk_mul_f32 v[90:91], v[90:91], v[100:101] op_sel_hi:[1,0]
	v_pk_mul_f32 v[84:85], v[86:87], v[100:101] op_sel_hi:[1,0]
	v_pk_mul_f32 v[86:87], v[56:57], v[92:93]
	v_pk_mul_f32 v[92:93], v[80:81], v[100:101] op_sel_hi:[1,0]
	v_pk_mul_f32 v[80:81], v[82:83], v[100:101] op_sel_hi:[1,0]
	v_pk_mul_f32 v[98:99], v[62:63], v[94:95]
	v_pk_mul_f32 v[90:91], v[54:55], v[90:91]
	v_pk_mul_f32 v[88:89], v[52:53], v[88:89]
	v_pk_mul_f32 v[84:85], v[58:59], v[84:85]
	v_pk_mul_f32 v[80:81], v[50:51], v[80:81]
	v_pk_mul_f32 v[82:83], v[48:49], v[92:93]
	s_and_b64 vcc, exec, s[8:9]
	v_add_u32_e32 v100, 48, v150
	s_cbranch_vccnz .LBB0_543
	v_bfe_u32 v92, v100, 6, 7
	v_cndmask_b32_e64 v92, v108, v92, s[6:7]
	v_lshl_or_b32 v192, v92, 7, v151
	v_lshl_add_u64 v[106:107], s[10:11], 0, v[192:193]
	global_load_dwordx4 v[102:105], v[106:107], off
	global_load_dwordx4 v[110:113], v[106:107], off offset:16
	s_waitcnt vmcnt(0) lgkmcnt(0)
	v_mov_b32_e32 v92, v102
	v_mul_f32_e32 v102, v98, v110
	v_mul_f32_e32 v114, v84, v111
	v_mul_f32_e32 v110, v84, v110
	v_mov_b32_e32 v84, v99
	v_mov_b32_e32 v93, v104
	v_mov_b32_e32 v104, v103
	v_pk_mul_f32 v[118:119], v[84:85], v[112:113]
	v_pk_mul_f32 v[94:95], v[86:87], v[104:105]
	v_pk_mul_f32 v[86:87], v[86:87], v[92:93]
	v_mul_f32_e32 v116, v98, v111
	v_mov_b32_e32 v103, v118
	v_mov_b32_e32 v115, v119
	v_mov_b32_e32 v98, v85
	v_pk_fma_f32 v[94:95], v[96:97], v[92:93], v[94:95] neg_lo:[0,0,1] neg_hi:[0,0,1]
	v_pk_add_f32 v[92:93], v[102:103], v[114:115] neg_lo:[0,1] neg_hi:[0,1]
	v_pk_mul_f32 v[84:85], v[98:99], v[112:113]
	v_pk_fma_f32 v[86:87], v[96:97], v[104:105], v[86:87]
	global_load_dwordx4 v[96:99], v[106:107], off offset:32
	global_load_dwordx4 v[102:105], v[106:107], off offset:48
	v_mov_b32_e32 v117, v85
	v_mov_b32_e32 v111, v84
	v_pk_add_f32 v[84:85], v[116:117], v[110:111]
	s_waitcnt vmcnt(0) lgkmcnt(0)
	v_mov_b32_e32 v107, v98
	v_mul_f32_e32 v110, v90, v102
	v_mul_f32_e32 v112, v80, v103
	v_mul_f32_e32 v102, v80, v102
	v_mov_b32_e32 v80, v91
	v_mov_b32_e32 v98, v97
	v_mul_f32_e32 v114, v90, v103
	v_pk_mul_f32 v[116:117], v[80:81], v[104:105]
	v_mov_b32_e32 v90, v81
	v_mov_b32_e32 v106, v96
	v_pk_mul_f32 v[96:97], v[82:83], v[98:99]
	v_mov_b32_e32 v111, v116
	v_mov_b32_e32 v113, v117
	v_pk_mul_f32 v[80:81], v[90:91], v[104:105]
	v_pk_mul_f32 v[82:83], v[82:83], v[106:107]
	v_pk_fma_f32 v[96:97], v[88:89], v[106:107], v[96:97] neg_lo:[0,0,1] neg_hi:[0,0,1]
	v_pk_add_f32 v[106:107], v[110:111], v[112:113] neg_lo:[0,1] neg_hi:[0,1]
	v_mov_b32_e32 v115, v81
	v_mov_b32_e32 v103, v80
	v_pk_fma_f32 v[82:83], v[88:89], v[98:99], v[82:83]
	v_pk_add_f32 v[80:81], v[114:115], v[102:103]
	v_mov_b32_e32 v88, v96
	v_mov_b32_e32 v89, v97
	v_mov_b32_e32 v90, v106
	v_mov_b32_e32 v91, v107
	v_mov_b32_e32 v96, v94
	v_mov_b32_e32 v97, v95
	v_mov_b32_e32 v98, v92
	v_mov_b32_e32 v99, v93
; __device__ __forceinline__ unsigned cvt_pk_bf16(float lo, float hi) { f32x2 v = {lo, hi}; bf16x2_t b = __builtin_convertvector(v, bf16x2_t); return __builtin_bit_cast(unsigned, b); }
; #define FOR_AI_M _Pragma("unroll") for (int ai = 0; ai < 2; ++ai) _Pragma("unroll") for (int m = 0; m < 4; ++m)
;     __device__ __forceinline__ void operator()(const f32x4 (&acc)[2][2][4][2], const Unit& u, int wr, int wc, int fr, int fq) const {
;     ...
;             FOR_AI_M {
;                 const int row = 256 * u.pm + 128 * ai + 64 * wr + 16 * m + fr;
;                 f32x4 x[2][2]; float ss = 0.f;
; #pragma unroll
;                 for (int bj = 0; bj < 2; ++bj)
; #pragma unroll
;                     for (int n = 0; n < 2; ++n) { x[bj][n] = acc[ai][bj][m][n]; ss += (x[bj][n][0] * x[bj][n][0] + x[bj][n][1] * x[bj][n][1]) + (x[bj][n][2] * x[bj][n][2] + x[bj][n][3] * x[bj][n][3]); }
;                 ss += shx<16>(ss); ss = sum_x32(ss);
;                 const float rinv = rsqrtf(ss * (1.0f / 64.0f) + EPS);
; #pragma unroll
;                 for (int bj = 0; bj < 2; ++bj)
; #pragma unroll
;                     for (int n = 0; n < 2; ++n) x[bj][n] = x[bj][n] * rinv * g[bj][n];
;                 if (!isctx) {
;                     const int t = row & (SEQ - 1); const int p = (fq < 2) ? (t >> 6) : (t & 63);
;                     const float* tp = tab + (p * 16 + 8 * (fq & 1)) * 2;
; #pragma unroll
;                     for (int n = 0; n < 2; ++n) {
;                         const f32x4 cs0 = *(const f32x4*)(tp + 8 * n), cs1 = *(const f32x4*)(tp + 8 * n + 4);
;                         const float c[4] = {cs0[0], cs0[2], cs1[0], cs1[2]}, s[4] = {cs0[1], cs0[3], cs1[1], cs1[3]};
; #pragma unroll
;                         for (int e = 0; e < 4; ++e) { const float lo = x[0][n][e], hi = x[1][n][e]; x[0][n][e] = lo * c[e] - hi * s[e]; x[1][n][e] = hi * c[e] + lo * s[e]; }
;                     }
;                 }
; #pragma unroll
;                 for (int bj = 0; bj < 2; ++bj) {
;                     u32x4 w; w.x = cvt_pk_bf16(x[bj][0][0] * qs, x[bj][0][1] * qs); w.y = cvt_pk_bf16(x[bj][0][2] * qs, x[bj][0][3] * qs);
;                     w.z = cvt_pk_bf16(x[bj][1][0] * qs, x[bj][1][1] * qs); w.w = cvt_pk_bf16(x[bj][1][2] * qs, x[bj][1][3] * qs);
;                     *(u32x4*)(dst + (size_t)row * pitch + colbase + 32 * bj + 8 * fq) = w;
;                 }
.LBB0_543:
	v_ashrrev_i32_e32 v92, 31, v100
	v_mul_lo_u32 v94, s25, v100
	v_mul_lo_u32 v95, s24, v92
	v_mad_u64_u32 v[92:93], s[2:3], s24, v100, 0
	v_add3_u32 v93, v93, v95, v94
	v_lshl_add_u64 v[100:101], v[92:93], 1, v[128:129]
	v_pk_mul_f32 v[92:93], s[96:97], v[96:97]
	v_pk_mul_f32 v[94:95], s[96:97], v[98:99]
	v_pk_mul_f32 v[88:89], s[96:97], v[88:89]
	v_cvt_pk_bf16_f32 v92, v92, v93
	v_cvt_pk_bf16_f32 v93, v94, v95
	v_cvt_pk_bf16_f32 v94, v88, v89
	v_pk_mul_f32 v[88:89], s[96:97], v[90:91]
	v_pk_mul_f32 v[90:91], v[76:77], v[76:77]
	v_cvt_pk_bf16_f32 v95, v88, v89
	v_pk_mul_f32 v[88:89], v[78:79], v[78:79]
	global_store_dwordx4 v[100:101], v[92:95], off
	v_pk_mul_f32 v[82:83], s[96:97], v[82:83]
	s_mov_b32 s2, 0x800000
	v_pk_mov_b32 v[92:93], v[90:91], v[88:89] op_sel:[1,0]
	v_mov_b32_e32 v91, v89
	v_pk_add_f32 v[88:89], v[92:93], v[90:91]
	v_pk_mul_f32 v[90:91], v[74:75], v[74:75]
	v_pk_add_f32 v[88:89], v[88:89], v[88:89] op_sel_hi:[0,1]
	v_pk_mul_f32 v[92:93], v[72:73], v[72:73]
	v_mul_f32_e32 v88, v68, v68
	v_pk_mov_b32 v[94:95], v[92:93], v[90:91] op_sel:[1,0]
	v_mov_b32_e32 v93, v91
	v_pk_add_f32 v[90:91], v[94:95], v[92:93]
	v_pk_fma_f32 v[92:93], v[68:69], v[68:69], v[88:89] op_sel_hi:[1,1,0]
	v_mul_f32_e32 v88, v70, v70
	v_pk_add_f32 v[90:91], v[90:91], v[90:91] op_sel_hi:[0,1]
	v_pk_fma_f32 v[94:95], v[70:71], v[70:71], v[88:89] op_sel_hi:[1,1,0]
	v_mul_f32_e32 v92, v64, v64
	v_mul_f32_e32 v94, v65, v65
	v_mul_f32_e32 v90, v66, v66
	v_mul_f32_e32 v88, v67, v67
	v_pk_add_f32 v[92:93], v[92:93], v[94:95]
	v_pk_add_f32 v[88:89], v[90:91], v[88:89]
	v_pk_mul_f32 v[86:87], s[96:97], v[86:87]
	v_pk_add_f32 v[88:89], v[92:93], v[88:89]
	v_pk_mul_f32 v[84:85], s[96:97], v[84:85]
	v_add_f32_e32 v89, v88, v89
	ds_swizzle_b32 v90, v89 offset:swizzle(SWAP,16)
	v_cvt_pk_bf16_f32 v88, v82, v83
	v_pk_mul_f32 v[80:81], s[96:97], v[80:81]
	v_cvt_pk_bf16_f32 v86, v86, v87
	v_cvt_pk_bf16_f32 v87, v84, v85
	s_waitcnt lgkmcnt(0)
	v_add_f32_e32 v82, v89, v90
	v_mov_b32_e32 v83, v82
	s_nop 1
	v_permlane32_swap_b32_e32 v82, v83
	v_add_f32_e32 v82, v82, v83
	v_fmamk_f32 v82, v82, 0x3c800000, v226
	v_mul_f32_e32 v83, 0x4b800000, v82
	v_cmp_gt_f32_e32 vcc, s2, v82
	v_cvt_pk_bf16_f32 v89, v80, v81
	global_store_dwordx4 v[100:101], v[86:89], off offset:64
	v_cndmask_b32_e32 v82, v82, v83, vcc
	v_rsq_f32_e32 v82, v82
	v_add_u32_e32 v84, 0x80, v150
	v_mul_f32_e32 v80, 0x45800000, v82
	v_cndmask_b32_e32 v86, v82, v80, vcc
	v_pk_mul_f32 v[76:77], v[76:77], v[86:87] op_sel_hi:[1,0]
	v_pk_mul_f32 v[78:79], v[78:79], v[86:87] op_sel_hi:[1,0]
	v_pk_mul_f32 v[80:81], v[60:61], v[76:77]
	v_pk_mul_f32 v[76:77], v[68:69], v[86:87] op_sel_hi:[1,0]
	v_pk_mul_f32 v[72:73], v[72:73], v[86:87] op_sel_hi:[1,0]
	v_pk_mul_f32 v[74:75], v[74:75], v[86:87] op_sel_hi:[1,0]
	v_pk_mul_f32 v[68:69], v[70:71], v[86:87] op_sel_hi:[1,0]
	v_pk_mul_f32 v[70:71], v[56:57], v[76:77]
	v_pk_mul_f32 v[76:77], v[64:65], v[86:87] op_sel_hi:[1,0]
	v_pk_mul_f32 v[64:65], v[66:67], v[86:87] op_sel_hi:[1,0]
	v_pk_mul_f32 v[82:83], v[62:63], v[78:79]
	v_pk_mul_f32 v[74:75], v[54:55], v[74:75]
	v_pk_mul_f32 v[72:73], v[52:53], v[72:73]
	v_pk_mul_f32 v[68:69], v[58:59], v[68:69]
	v_pk_mul_f32 v[64:65], v[50:51], v[64:65]
	s_and_b64 vcc, exec, s[8:9]
	v_pk_mul_f32 v[66:67], v[48:49], v[76:77]
	s_cbranch_vccnz .LBB0_545
	v_bfe_u32 v76, v84, 6, 7
	v_cndmask_b32_e64 v76, v152, v76, s[6:7]
	v_lshl_or_b32 v192, v76, 7, v151
	v_lshl_add_u64 v[94:95], s[10:11], 0, v[192:193]
	global_load_dwordx4 v[86:89], v[94:95], off
	global_load_dwordx4 v[90:93], v[94:95], off offset:16
	s_waitcnt vmcnt(0) lgkmcnt(0)
	v_mov_b32_e32 v76, v86
	v_mul_f32_e32 v86, v82, v90
	v_mul_f32_e32 v96, v68, v91
	v_mul_f32_e32 v90, v68, v90
	v_mov_b32_e32 v68, v83
	v_mov_b32_e32 v77, v88
	v_mov_b32_e32 v88, v87
	v_pk_mul_f32 v[100:101], v[68:69], v[92:93]
	v_pk_mul_f32 v[78:79], v[70:71], v[88:89]
	v_pk_mul_f32 v[70:71], v[70:71], v[76:77]
	v_mul_f32_e32 v98, v82, v91
	v_mov_b32_e32 v87, v100
	v_mov_b32_e32 v97, v101
	v_mov_b32_e32 v82, v69
	v_pk_fma_f32 v[78:79], v[80:81], v[76:77], v[78:79] neg_lo:[0,0,1] neg_hi:[0,0,1]
	v_pk_add_f32 v[76:77], v[86:87], v[96:97] neg_lo:[0,1] neg_hi:[0,1]
	v_pk_mul_f32 v[68:69], v[82:83], v[92:93]
	v_pk_fma_f32 v[70:71], v[80:81], v[88:89], v[70:71]
	global_load_dwordx4 v[80:83], v[94:95], off offset:32
	global_load_dwordx4 v[86:89], v[94:95], off offset:48
	v_mov_b32_e32 v99, v69
	v_mov_b32_e32 v91, v68
	v_pk_add_f32 v[68:69], v[98:99], v[90:91]
	s_waitcnt vmcnt(0) lgkmcnt(0)
	v_mov_b32_e32 v91, v82
	v_mul_f32_e32 v92, v74, v86
	v_mul_f32_e32 v94, v64, v87
	v_mul_f32_e32 v86, v64, v86
	v_mov_b32_e32 v64, v75
	v_mov_b32_e32 v82, v81
	v_mul_f32_e32 v96, v74, v87
	v_pk_mul_f32 v[98:99], v[64:65], v[88:89]
	v_mov_b32_e32 v74, v65
	v_mov_b32_e32 v90, v80
	v_pk_mul_f32 v[80:81], v[66:67], v[82:83]
	v_mov_b32_e32 v93, v98
	v_mov_b32_e32 v95, v99
	v_pk_mul_f32 v[64:65], v[74:75], v[88:89]
	v_pk_mul_f32 v[66:67], v[66:67], v[90:91]
	v_pk_fma_f32 v[80:81], v[72:73], v[90:91], v[80:81] neg_lo:[0,0,1] neg_hi:[0,0,1]
	v_pk_add_f32 v[90:91], v[92:93], v[94:95] neg_lo:[0,1] neg_hi:[0,1]
	v_mov_b32_e32 v97, v65
	v_mov_b32_e32 v87, v64
	v_pk_fma_f32 v[66:67], v[72:73], v[82:83], v[66:67]
	v_pk_add_f32 v[64:65], v[96:97], v[86:87]
	v_mov_b32_e32 v72, v80
	v_mov_b32_e32 v73, v81
	v_mov_b32_e32 v74, v90
	v_mov_b32_e32 v75, v91
	v_mov_b32_e32 v80, v78
	v_mov_b32_e32 v81, v79
	v_mov_b32_e32 v82, v76
	v_mov_b32_e32 v83, v77
; __device__ __forceinline__ unsigned cvt_pk_bf16(float lo, float hi) { f32x2 v = {lo, hi}; bf16x2_t b = __builtin_convertvector(v, bf16x2_t); return __builtin_bit_cast(unsigned, b); }
; #define FOR_AI_M _Pragma("unroll") for (int ai = 0; ai < 2; ++ai) _Pragma("unroll") for (int m = 0; m < 4; ++m)
;     __device__ __forceinline__ void operator()(const f32x4 (&acc)[2][2][4][2], const Unit& u, int wr, int wc, int fr, int fq) const {
;     ...
;             FOR_AI_M {
;                 const int row = 256 * u.pm + 128 * ai + 64 * wr + 16 * m + fr;
;                 f32x4 x[2][2]; float ss = 0.f;
; #pragma unroll
;                 for (int bj = 0; bj < 2; ++bj)
; #pragma unroll
;                     for (int n = 0; n < 2; ++n) { x[bj][n] = acc[ai][bj][m][n]; ss += (x[bj][n][0] * x[bj][n][0] + x[bj][n][1] * x[bj][n][1]) + (x[bj][n][2] * x[bj][n][2] + x[bj][n][3] * x[bj][n][3]); }
;                 ss += shx<16>(ss); ss = sum_x32(ss);
;                 const float rinv = rsqrtf(ss * (1.0f / 64.0f) + EPS);
; #pragma unroll
;                 for (int bj = 0; bj < 2; ++bj)
; #pragma unroll
;                     for (int n = 0; n < 2; ++n) x[bj][n] = x[bj][n] * rinv * g[bj][n];
;                 if (!isctx) {
;                     const int t = row & (SEQ - 1); const int p = (fq < 2) ? (t >> 6) : (t & 63);
;                     const float* tp = tab + (p * 16 + 8 * (fq & 1)) * 2;
; #pragma unroll
;                     for (int n = 0; n < 2; ++n) {
;                         const f32x4 cs0 = *(const f32x4*)(tp + 8 * n), cs1 = *(const f32x4*)(tp + 8 * n + 4);
;                         const float c[4] = {cs0[0], cs0[2], cs1[0], cs1[2]}, s[4] = {cs0[1], cs0[3], cs1[1], cs1[3]};
; #pragma unroll
;                         for (int e = 0; e < 4; ++e) { const float lo = x[0][n][e], hi = x[1][n][e]; x[0][n][e] = lo * c[e] - hi * s[e]; x[1][n][e] = hi * c[e] + lo * s[e]; }
;                     }
;                 }
; #pragma unroll
;                 for (int bj = 0; bj < 2; ++bj) {
;                     u32x4 w; w.x = cvt_pk_bf16(x[bj][0][0] * qs, x[bj][0][1] * qs); w.y = cvt_pk_bf16(x[bj][0][2] * qs, x[bj][0][3] * qs);
;                     w.z = cvt_pk_bf16(x[bj][1][0] * qs, x[bj][1][1] * qs); w.w = cvt_pk_bf16(x[bj][1][2] * qs, x[bj][1][3] * qs);
;                     *(u32x4*)(dst + (size_t)row * pitch + colbase + 32 * bj + 8 * fq) = w;
;                 }
.LBB0_545:
	v_ashrrev_i32_e32 v76, 31, v84
	v_mul_lo_u32 v78, s25, v84
	v_mul_lo_u32 v79, s24, v76
	v_mad_u64_u32 v[76:77], s[2:3], s24, v84, 0
	v_add3_u32 v77, v77, v79, v78
	v_lshl_add_u64 v[84:85], v[76:77], 1, v[128:129]
	v_pk_mul_f32 v[76:77], s[96:97], v[80:81]
	v_pk_mul_f32 v[78:79], s[96:97], v[82:83]
	v_pk_mul_f32 v[72:73], s[96:97], v[72:73]
	v_cvt_pk_bf16_f32 v76, v76, v77
	v_cvt_pk_bf16_f32 v77, v78, v79
	v_cvt_pk_bf16_f32 v78, v72, v73
	v_pk_mul_f32 v[72:73], s[96:97], v[74:75]
	v_pk_mul_f32 v[74:75], v[44:45], v[44:45]
	v_cvt_pk_bf16_f32 v79, v72, v73
	v_pk_mul_f32 v[72:73], v[46:47], v[46:47]
	global_store_dwordx4 v[84:85], v[76:79], off
	v_pk_mul_f32 v[66:67], s[96:97], v[66:67]
	s_mov_b32 s2, 0x800000
	v_pk_mov_b32 v[76:77], v[74:75], v[72:73] op_sel:[1,0]
	v_mov_b32_e32 v75, v73
	v_pk_add_f32 v[72:73], v[76:77], v[74:75]
	v_pk_mul_f32 v[74:75], v[42:43], v[42:43]
	v_pk_add_f32 v[72:73], v[72:73], v[72:73] op_sel_hi:[0,1]
	v_pk_mul_f32 v[76:77], v[40:41], v[40:41]
	v_mul_f32_e32 v72, v36, v36
	v_pk_mov_b32 v[78:79], v[76:77], v[74:75] op_sel:[1,0]
	v_mov_b32_e32 v77, v75
	v_pk_add_f32 v[74:75], v[78:79], v[76:77]
	v_pk_fma_f32 v[76:77], v[36:37], v[36:37], v[72:73] op_sel_hi:[1,1,0]
	v_mul_f32_e32 v72, v38, v38
	v_pk_add_f32 v[74:75], v[74:75], v[74:75] op_sel_hi:[0,1]
	v_pk_fma_f32 v[78:79], v[38:39], v[38:39], v[72:73] op_sel_hi:[1,1,0]
	v_mul_f32_e32 v76, v32, v32
	v_mul_f32_e32 v78, v33, v33
	v_mul_f32_e32 v74, v34, v34
	v_mul_f32_e32 v72, v35, v35
	v_pk_add_f32 v[76:77], v[76:77], v[78:79]
	v_pk_add_f32 v[72:73], v[74:75], v[72:73]
	v_pk_mul_f32 v[64:65], s[96:97], v[64:65]
	v_pk_add_f32 v[72:73], v[76:77], v[72:73]
	v_pk_mul_f32 v[70:71], s[96:97], v[70:71]
	v_add_f32_e32 v73, v72, v73
	ds_swizzle_b32 v74, v73 offset:swizzle(SWAP,16)
	v_cvt_pk_bf16_f32 v72, v66, v67
	v_pk_mul_f32 v[68:69], s[96:97], v[68:69]
	v_cvt_pk_bf16_f32 v70, v70, v71
	v_cvt_pk_bf16_f32 v71, v68, v69
	s_waitcnt lgkmcnt(0)
	v_add_f32_e32 v66, v73, v74
	v_mov_b32_e32 v67, v66
	s_nop 1
	v_permlane32_swap_b32_e32 v66, v67
	v_add_f32_e32 v66, v66, v67
	v_fmamk_f32 v66, v66, 0x3c800000, v226
	v_mul_f32_e32 v67, 0x4b800000, v66
	v_cmp_gt_f32_e32 vcc, s2, v66
	v_cvt_pk_bf16_f32 v73, v64, v65
	global_store_dwordx4 v[84:85], v[70:73], off offset:64
	v_cndmask_b32_e32 v66, v66, v67, vcc
	v_rsq_f32_e32 v66, v66
	s_nop 0
	v_mul_f32_e32 v64, 0x45800000, v66
	v_cndmask_b32_e32 v68, v66, v64, vcc
	v_pk_mul_f32 v[44:45], v[44:45], v[68:69] op_sel_hi:[1,0]
	v_pk_mul_f32 v[46:47], v[46:47], v[68:69] op_sel_hi:[1,0]
	v_pk_mul_f32 v[64:65], v[60:61], v[44:45]
	v_pk_mul_f32 v[44:45], v[36:37], v[68:69] op_sel_hi:[1,0]
	v_pk_mul_f32 v[40:41], v[40:41], v[68:69] op_sel_hi:[1,0]
	v_pk_mul_f32 v[42:43], v[42:43], v[68:69] op_sel_hi:[1,0]
	v_pk_mul_f32 v[36:37], v[38:39], v[68:69] op_sel_hi:[1,0]
	v_pk_mul_f32 v[38:39], v[56:57], v[44:45]
	v_pk_mul_f32 v[44:45], v[32:33], v[68:69] op_sel_hi:[1,0]
	v_pk_mul_f32 v[32:33], v[34:35], v[68:69] op_sel_hi:[1,0]
	v_pk_mul_f32 v[66:67], v[62:63], v[46:47]
	v_pk_mul_f32 v[42:43], v[54:55], v[42:43]
	v_pk_mul_f32 v[40:41], v[52:53], v[40:41]
	v_pk_mul_f32 v[36:37], v[58:59], v[36:37]
	v_pk_mul_f32 v[32:33], v[50:51], v[32:33]
	v_pk_mul_f32 v[34:35], v[48:49], v[44:45]
	s_and_b64 vcc, exec, s[8:9]
	v_add_u32_e32 v68, 0x90, v150
	s_cbranch_vccnz .LBB0_547
	v_bfe_u32 v44, v68, 6, 7
	v_cndmask_b32_e64 v44, v142, v44, s[6:7]
	v_lshl_or_b32 v192, v44, 7, v151
	v_lshl_add_u64 v[78:79], s[10:11], 0, v[192:193]
	global_load_dwordx4 v[70:73], v[78:79], off
	global_load_dwordx4 v[74:77], v[78:79], off offset:16
	s_waitcnt vmcnt(0) lgkmcnt(0)
	v_mov_b32_e32 v44, v70
	v_mul_f32_e32 v70, v66, v74
	v_mul_f32_e32 v80, v36, v75
	v_mul_f32_e32 v74, v36, v74
	v_mov_b32_e32 v36, v67
	v_mov_b32_e32 v45, v72
	v_mov_b32_e32 v72, v71
	v_pk_mul_f32 v[84:85], v[36:37], v[76:77]
	v_pk_mul_f32 v[46:47], v[38:39], v[72:73]
	v_pk_mul_f32 v[38:39], v[38:39], v[44:45]
	v_mul_f32_e32 v82, v66, v75
	v_mov_b32_e32 v71, v84
	v_mov_b32_e32 v81, v85
	v_mov_b32_e32 v66, v37
	v_pk_fma_f32 v[46:47], v[64:65], v[44:45], v[46:47] neg_lo:[0,0,1] neg_hi:[0,0,1]
	v_pk_add_f32 v[44:45], v[70:71], v[80:81] neg_lo:[0,1] neg_hi:[0,1]
	v_pk_mul_f32 v[36:37], v[66:67], v[76:77]
	v_pk_fma_f32 v[38:39], v[64:65], v[72:73], v[38:39]
	global_load_dwordx4 v[64:67], v[78:79], off offset:32
	global_load_dwordx4 v[70:73], v[78:79], off offset:48
	v_mov_b32_e32 v83, v37
	v_mov_b32_e32 v75, v36
	v_pk_add_f32 v[36:37], v[82:83], v[74:75]
	s_waitcnt vmcnt(0) lgkmcnt(0)
	v_mov_b32_e32 v75, v66
	v_mul_f32_e32 v76, v42, v70
	v_mul_f32_e32 v78, v32, v71
	v_mul_f32_e32 v70, v32, v70
	v_mov_b32_e32 v32, v43
	v_mov_b32_e32 v66, v65
	v_mul_f32_e32 v80, v42, v71
	v_pk_mul_f32 v[82:83], v[32:33], v[72:73]
	v_mov_b32_e32 v42, v33
	v_mov_b32_e32 v74, v64
	v_pk_mul_f32 v[64:65], v[34:35], v[66:67]
	v_mov_b32_e32 v77, v82
	v_mov_b32_e32 v79, v83
	v_pk_mul_f32 v[32:33], v[42:43], v[72:73]
	v_pk_mul_f32 v[34:35], v[34:35], v[74:75]
	v_pk_fma_f32 v[64:65], v[40:41], v[74:75], v[64:65] neg_lo:[0,0,1] neg_hi:[0,0,1]
	v_pk_add_f32 v[74:75], v[76:77], v[78:79] neg_lo:[0,1] neg_hi:[0,1]
	v_mov_b32_e32 v81, v33
	v_mov_b32_e32 v71, v32
	v_pk_fma_f32 v[34:35], v[40:41], v[66:67], v[34:35]
	v_pk_add_f32 v[32:33], v[80:81], v[70:71]
	v_mov_b32_e32 v40, v64
	v_mov_b32_e32 v41, v65
	v_mov_b32_e32 v42, v74
	v_mov_b32_e32 v43, v75
	v_mov_b32_e32 v64, v46
	v_mov_b32_e32 v65, v47
	v_mov_b32_e32 v66, v44
	v_mov_b32_e32 v67, v45
; __device__ __forceinline__ unsigned cvt_pk_bf16(float lo, float hi) { f32x2 v = {lo, hi}; bf16x2_t b = __builtin_convertvector(v, bf16x2_t); return __builtin_bit_cast(unsigned, b); }
; #define FOR_AI_M _Pragma("unroll") for (int ai = 0; ai < 2; ++ai) _Pragma("unroll") for (int m = 0; m < 4; ++m)
;     __device__ __forceinline__ void operator()(const f32x4 (&acc)[2][2][4][2], const Unit& u, int wr, int wc, int fr, int fq) const {
;     ...
;             FOR_AI_M {
;                 const int row = 256 * u.pm + 128 * ai + 64 * wr + 16 * m + fr;
;                 f32x4 x[2][2]; float ss = 0.f;
; #pragma unroll
;                 for (int bj = 0; bj < 2; ++bj)
; #pragma unroll
;                     for (int n = 0; n < 2; ++n) { x[bj][n] = acc[ai][bj][m][n]; ss += (x[bj][n][0] * x[bj][n][0] + x[bj][n][1] * x[bj][n][1]) + (x[bj][n][2] * x[bj][n][2] + x[bj][n][3] * x[bj][n][3]); }
;                 ss += shx<16>(ss); ss = sum_x32(ss);
;                 const float rinv = rsqrtf(ss * (1.0f / 64.0f) + EPS);
; #pragma unroll
;                 for (int bj = 0; bj < 2; ++bj)
; #pragma unroll
;                     for (int n = 0; n < 2; ++n) x[bj][n] = x[bj][n] * rinv * g[bj][n];
;                 if (!isctx) {
;                     const int t = row & (SEQ - 1); const int p = (fq < 2) ? (t >> 6) : (t & 63);
;                     const float* tp = tab + (p * 16 + 8 * (fq & 1)) * 2;
; #pragma unroll
;                     for (int n = 0; n < 2; ++n) {
;                         const f32x4 cs0 = *(const f32x4*)(tp + 8 * n), cs1 = *(const f32x4*)(tp + 8 * n + 4);
;                         const float c[4] = {cs0[0], cs0[2], cs1[0], cs1[2]}, s[4] = {cs0[1], cs0[3], cs1[1], cs1[3]};
; #pragma unroll
;                         for (int e = 0; e < 4; ++e) { const float lo = x[0][n][e], hi = x[1][n][e]; x[0][n][e] = lo * c[e] - hi * s[e]; x[1][n][e] = hi * c[e] + lo * s[e]; }
;                     }
;                 }
; #pragma unroll
;                 for (int bj = 0; bj < 2; ++bj) {
;                     u32x4 w; w.x = cvt_pk_bf16(x[bj][0][0] * qs, x[bj][0][1] * qs); w.y = cvt_pk_bf16(x[bj][0][2] * qs, x[bj][0][3] * qs);
;                     w.z = cvt_pk_bf16(x[bj][1][0] * qs, x[bj][1][1] * qs); w.w = cvt_pk_bf16(x[bj][1][2] * qs, x[bj][1][3] * qs);
;                     *(u32x4*)(dst + (size_t)row * pitch + colbase + 32 * bj + 8 * fq) = w;
;                 }
.LBB0_547:
	v_ashrrev_i32_e32 v44, 31, v68
	v_mul_lo_u32 v46, s25, v68
	v_mul_lo_u32 v47, s24, v44
	v_mad_u64_u32 v[44:45], s[2:3], s24, v68, 0
	v_add3_u32 v45, v45, v47, v46
	v_lshl_add_u64 v[68:69], v[44:45], 1, v[128:129]
	v_pk_mul_f32 v[44:45], s[96:97], v[64:65]
	v_pk_mul_f32 v[46:47], s[96:97], v[66:67]
	v_pk_mul_f32 v[40:41], s[96:97], v[40:41]
	v_cvt_pk_bf16_f32 v44, v44, v45
	v_cvt_pk_bf16_f32 v45, v46, v47
	v_cvt_pk_bf16_f32 v46, v40, v41
	v_pk_mul_f32 v[40:41], s[96:97], v[42:43]
	v_pk_mul_f32 v[42:43], v[28:29], v[28:29]
	v_cvt_pk_bf16_f32 v47, v40, v41
	v_pk_mul_f32 v[40:41], v[30:31], v[30:31]
	global_store_dwordx4 v[68:69], v[44:47], off
	v_pk_mul_f32 v[34:35], s[96:97], v[34:35]
	s_mov_b32 s2, 0x800000
	v_pk_mov_b32 v[44:45], v[42:43], v[40:41] op_sel:[1,0]
	v_mov_b32_e32 v43, v41
	v_pk_add_f32 v[40:41], v[44:45], v[42:43]
	v_pk_mul_f32 v[42:43], v[26:27], v[26:27]
	v_pk_add_f32 v[40:41], v[40:41], v[40:41] op_sel_hi:[0,1]
	v_pk_mul_f32 v[44:45], v[24:25], v[24:25]
	v_mul_f32_e32 v40, v20, v20
	v_pk_mov_b32 v[46:47], v[44:45], v[42:43] op_sel:[1,0]
	v_mov_b32_e32 v45, v43
	v_pk_add_f32 v[42:43], v[46:47], v[44:45]
	v_pk_fma_f32 v[44:45], v[20:21], v[20:21], v[40:41] op_sel_hi:[1,1,0]
	v_mul_f32_e32 v40, v22, v22
	v_pk_add_f32 v[42:43], v[42:43], v[42:43] op_sel_hi:[0,1]
	v_pk_fma_f32 v[46:47], v[22:23], v[22:23], v[40:41] op_sel_hi:[1,1,0]
	v_mul_f32_e32 v44, v16, v16
	v_mul_f32_e32 v46, v17, v17
	v_mul_f32_e32 v42, v18, v18
	v_mul_f32_e32 v40, v19, v19
	v_pk_add_f32 v[44:45], v[44:45], v[46:47]
	v_pk_add_f32 v[40:41], v[42:43], v[40:41]
	v_pk_mul_f32 v[32:33], s[96:97], v[32:33]
	v_pk_add_f32 v[40:41], v[44:45], v[40:41]
	v_pk_mul_f32 v[38:39], s[96:97], v[38:39]
	v_add_f32_e32 v41, v40, v41
	ds_swizzle_b32 v42, v41 offset:swizzle(SWAP,16)
	v_cvt_pk_bf16_f32 v40, v34, v35
	v_pk_mul_f32 v[36:37], s[96:97], v[36:37]
	v_cvt_pk_bf16_f32 v38, v38, v39
	v_cvt_pk_bf16_f32 v39, v36, v37
	s_waitcnt lgkmcnt(0)
	v_add_f32_e32 v34, v41, v42
	v_mov_b32_e32 v35, v34
	s_nop 1
	v_permlane32_swap_b32_e32 v34, v35
	v_add_f32_e32 v34, v34, v35
	v_fmamk_f32 v34, v34, 0x3c800000, v226
	v_mul_f32_e32 v35, 0x4b800000, v34
	v_cmp_gt_f32_e32 vcc, s2, v34
	v_cvt_pk_bf16_f32 v41, v32, v33
	global_store_dwordx4 v[68:69], v[38:41], off offset:64
	v_cndmask_b32_e32 v34, v34, v35, vcc
	v_rsq_f32_e32 v34, v34
	s_nop 0
	v_mul_f32_e32 v32, 0x45800000, v34
	v_cndmask_b32_e32 v36, v34, v32, vcc
	v_pk_mul_f32 v[28:29], v[28:29], v[36:37] op_sel_hi:[1,0]
	v_pk_mul_f32 v[30:31], v[30:31], v[36:37] op_sel_hi:[1,0]
	v_pk_mul_f32 v[32:33], v[60:61], v[28:29]
	v_pk_mul_f32 v[28:29], v[20:21], v[36:37] op_sel_hi:[1,0]
	v_pk_mul_f32 v[24:25], v[24:25], v[36:37] op_sel_hi:[1,0]
	v_pk_mul_f32 v[26:27], v[26:27], v[36:37] op_sel_hi:[1,0]
	v_pk_mul_f32 v[20:21], v[22:23], v[36:37] op_sel_hi:[1,0]
	v_pk_mul_f32 v[22:23], v[56:57], v[28:29]
	v_pk_mul_f32 v[28:29], v[16:17], v[36:37] op_sel_hi:[1,0]
	v_pk_mul_f32 v[16:17], v[18:19], v[36:37] op_sel_hi:[1,0]
	v_pk_mul_f32 v[34:35], v[62:63], v[30:31]
	v_pk_mul_f32 v[26:27], v[54:55], v[26:27]
	v_pk_mul_f32 v[24:25], v[52:53], v[24:25]
	v_pk_mul_f32 v[20:21], v[58:59], v[20:21]
	v_pk_mul_f32 v[16:17], v[50:51], v[16:17]
	v_pk_mul_f32 v[18:19], v[48:49], v[28:29]
	s_and_b64 vcc, exec, s[8:9]
	v_add_u32_e32 v36, 0xa0, v150
	s_cbranch_vccnz .LBB0_549
	v_bfe_u32 v28, v36, 6, 7
	v_cndmask_b32_e64 v28, v124, v28, s[6:7]
	v_lshl_or_b32 v192, v28, 7, v151
	v_lshl_add_u64 v[46:47], s[10:11], 0, v[192:193]
	global_load_dwordx4 v[38:41], v[46:47], off
	global_load_dwordx4 v[42:45], v[46:47], off offset:16
	s_waitcnt vmcnt(0) lgkmcnt(0)
	v_mov_b32_e32 v28, v38
	v_mul_f32_e32 v38, v34, v42
	v_mul_f32_e32 v64, v20, v43
	v_mul_f32_e32 v42, v20, v42
	v_mov_b32_e32 v20, v35
	v_mov_b32_e32 v29, v40
	v_mov_b32_e32 v40, v39
	v_pk_mul_f32 v[68:69], v[20:21], v[44:45]
	v_pk_mul_f32 v[30:31], v[22:23], v[40:41]
	v_pk_mul_f32 v[22:23], v[22:23], v[28:29]
	v_mul_f32_e32 v66, v34, v43
	v_mov_b32_e32 v39, v68
	v_mov_b32_e32 v65, v69
	v_mov_b32_e32 v34, v21
	v_pk_fma_f32 v[30:31], v[32:33], v[28:29], v[30:31] neg_lo:[0,0,1] neg_hi:[0,0,1]
	v_pk_add_f32 v[28:29], v[38:39], v[64:65] neg_lo:[0,1] neg_hi:[0,1]
	v_pk_mul_f32 v[20:21], v[34:35], v[44:45]
	v_pk_fma_f32 v[22:23], v[32:33], v[40:41], v[22:23]
	global_load_dwordx4 v[32:35], v[46:47], off offset:32
	global_load_dwordx4 v[38:41], v[46:47], off offset:48
	v_mov_b32_e32 v67, v21
	v_mov_b32_e32 v43, v20
	v_pk_add_f32 v[20:21], v[66:67], v[42:43]
	s_waitcnt vmcnt(0) lgkmcnt(0)
	v_mov_b32_e32 v43, v34
	v_mul_f32_e32 v44, v26, v38
	v_mul_f32_e32 v46, v16, v39
	v_mul_f32_e32 v38, v16, v38
	v_mov_b32_e32 v16, v27
	v_mov_b32_e32 v34, v33
	v_mul_f32_e32 v64, v26, v39
	v_pk_mul_f32 v[66:67], v[16:17], v[40:41]
	v_mov_b32_e32 v26, v17
	v_mov_b32_e32 v42, v32
	v_pk_mul_f32 v[32:33], v[18:19], v[34:35]
	v_mov_b32_e32 v45, v66
	v_mov_b32_e32 v47, v67
	v_pk_mul_f32 v[16:17], v[26:27], v[40:41]
	v_pk_mul_f32 v[18:19], v[18:19], v[42:43]
	v_pk_fma_f32 v[32:33], v[24:25], v[42:43], v[32:33] neg_lo:[0,0,1] neg_hi:[0,0,1]
	v_pk_add_f32 v[42:43], v[44:45], v[46:47] neg_lo:[0,1] neg_hi:[0,1]
	v_mov_b32_e32 v65, v17
	v_mov_b32_e32 v39, v16
	v_pk_fma_f32 v[18:19], v[24:25], v[34:35], v[18:19]
	v_pk_add_f32 v[16:17], v[64:65], v[38:39]
	v_mov_b32_e32 v24, v32
	v_mov_b32_e32 v25, v33
	v_mov_b32_e32 v26, v42
	v_mov_b32_e32 v27, v43
	v_mov_b32_e32 v32, v30
	v_mov_b32_e32 v33, v31
	v_mov_b32_e32 v34, v28
	v_mov_b32_e32 v35, v29
; __device__ __forceinline__ unsigned cvt_pk_bf16(float lo, float hi) { f32x2 v = {lo, hi}; bf16x2_t b = __builtin_convertvector(v, bf16x2_t); return __builtin_bit_cast(unsigned, b); }
; #define FOR_AI_M _Pragma("unroll") for (int ai = 0; ai < 2; ++ai) _Pragma("unroll") for (int m = 0; m < 4; ++m)
;     __device__ __forceinline__ void operator()(const f32x4 (&acc)[2][2][4][2], const Unit& u, int wr, int wc, int fr, int fq) const {
;     ...
;             FOR_AI_M {
;                 const int row = 256 * u.pm + 128 * ai + 64 * wr + 16 * m + fr;
;                 f32x4 x[2][2]; float ss = 0.f;
; #pragma unroll
;                 for (int bj = 0; bj < 2; ++bj)
; #pragma unroll
;                     for (int n = 0; n < 2; ++n) { x[bj][n] = acc[ai][bj][m][n]; ss += (x[bj][n][0] * x[bj][n][0] + x[bj][n][1] * x[bj][n][1]) + (x[bj][n][2] * x[bj][n][2] + x[bj][n][3] * x[bj][n][3]); }
;                 ss += shx<16>(ss); ss = sum_x32(ss);
;                 const float rinv = rsqrtf(ss * (1.0f / 64.0f) + EPS);
; #pragma unroll
;                 for (int bj = 0; bj < 2; ++bj)
; #pragma unroll
;                     for (int n = 0; n < 2; ++n) x[bj][n] = x[bj][n] * rinv * g[bj][n];
;                 if (!isctx) {
;                     const int t = row & (SEQ - 1); const int p = (fq < 2) ? (t >> 6) : (t & 63);
;                     const float* tp = tab + (p * 16 + 8 * (fq & 1)) * 2;
; #pragma unroll
;                     for (int n = 0; n < 2; ++n) {
;                         const f32x4 cs0 = *(const f32x4*)(tp + 8 * n), cs1 = *(const f32x4*)(tp + 8 * n + 4);
;                         const float c[4] = {cs0[0], cs0[2], cs1[0], cs1[2]}, s[4] = {cs0[1], cs0[3], cs1[1], cs1[3]};
; #pragma unroll
;                         for (int e = 0; e < 4; ++e) { const float lo = x[0][n][e], hi = x[1][n][e]; x[0][n][e] = lo * c[e] - hi * s[e]; x[1][n][e] = hi * c[e] + lo * s[e]; }
;                     }
;                 }
; #pragma unroll
;                 for (int bj = 0; bj < 2; ++bj) {
;                     u32x4 w; w.x = cvt_pk_bf16(x[bj][0][0] * qs, x[bj][0][1] * qs); w.y = cvt_pk_bf16(x[bj][0][2] * qs, x[bj][0][3] * qs);
;                     w.z = cvt_pk_bf16(x[bj][1][0] * qs, x[bj][1][1] * qs); w.w = cvt_pk_bf16(x[bj][1][2] * qs, x[bj][1][3] * qs);
;                     *(u32x4*)(dst + (size_t)row * pitch + colbase + 32 * bj + 8 * fq) = w;
;                 }
.LBB0_549:
	v_ashrrev_i32_e32 v28, 31, v36
	v_mul_lo_u32 v30, s25, v36
	v_mul_lo_u32 v31, s24, v28
	v_mad_u64_u32 v[28:29], s[2:3], s24, v36, 0
	v_add3_u32 v29, v29, v31, v30
	v_lshl_add_u64 v[36:37], v[28:29], 1, v[128:129]
	v_pk_mul_f32 v[28:29], s[96:97], v[32:33]
	v_pk_mul_f32 v[30:31], s[96:97], v[34:35]
	v_pk_mul_f32 v[24:25], s[96:97], v[24:25]
	v_cvt_pk_bf16_f32 v28, v28, v29
	v_cvt_pk_bf16_f32 v29, v30, v31
	v_cvt_pk_bf16_f32 v30, v24, v25
	v_pk_mul_f32 v[24:25], s[96:97], v[26:27]
	v_pk_mul_f32 v[26:27], v[12:13], v[12:13]
	v_cvt_pk_bf16_f32 v31, v24, v25
	v_pk_mul_f32 v[24:25], v[14:15], v[14:15]
	global_store_dwordx4 v[36:37], v[28:31], off
	v_pk_mul_f32 v[18:19], s[96:97], v[18:19]
	s_mov_b32 s2, 0x800000
	v_pk_mov_b32 v[28:29], v[26:27], v[24:25] op_sel:[1,0]
	v_mov_b32_e32 v27, v25
	v_pk_add_f32 v[24:25], v[28:29], v[26:27]
	v_pk_mul_f32 v[26:27], v[10:11], v[10:11]
	v_pk_add_f32 v[24:25], v[24:25], v[24:25] op_sel_hi:[0,1]
	v_pk_mul_f32 v[28:29], v[8:9], v[8:9]
	v_mul_f32_e32 v24, v4, v4
	v_pk_mov_b32 v[30:31], v[28:29], v[26:27] op_sel:[1,0]
	v_mov_b32_e32 v29, v27
	v_pk_add_f32 v[26:27], v[30:31], v[28:29]
	v_pk_fma_f32 v[28:29], v[4:5], v[4:5], v[24:25] op_sel_hi:[1,1,0]
	v_mul_f32_e32 v24, v6, v6
	v_pk_add_f32 v[26:27], v[26:27], v[26:27] op_sel_hi:[0,1]
	v_pk_fma_f32 v[30:31], v[6:7], v[6:7], v[24:25] op_sel_hi:[1,1,0]
	v_mul_f32_e32 v28, v0, v0
	v_mul_f32_e32 v30, v1, v1
	v_mul_f32_e32 v26, v2, v2
	v_mul_f32_e32 v24, v3, v3
	v_pk_add_f32 v[28:29], v[28:29], v[30:31]
	v_pk_add_f32 v[24:25], v[26:27], v[24:25]
	v_pk_mul_f32 v[16:17], s[96:97], v[16:17]
	v_pk_add_f32 v[24:25], v[28:29], v[24:25]
	v_pk_mul_f32 v[22:23], s[96:97], v[22:23]
	v_add_f32_e32 v25, v24, v25
	ds_swizzle_b32 v26, v25 offset:swizzle(SWAP,16)
	v_cvt_pk_bf16_f32 v24, v18, v19
	v_pk_mul_f32 v[20:21], s[96:97], v[20:21]
	v_cvt_pk_bf16_f32 v22, v22, v23
	v_cvt_pk_bf16_f32 v23, v20, v21
	s_waitcnt lgkmcnt(0)
	v_add_f32_e32 v18, v25, v26
	v_mov_b32_e32 v19, v18
	s_nop 1
	v_permlane32_swap_b32_e32 v18, v19
	v_add_f32_e32 v18, v18, v19
	v_fmamk_f32 v18, v18, 0x3c800000, v226
	v_mul_f32_e32 v19, 0x4b800000, v18
	v_cmp_gt_f32_e32 vcc, s2, v18
	v_cvt_pk_bf16_f32 v25, v16, v17
	global_store_dwordx4 v[36:37], v[22:25], off offset:64
	v_cndmask_b32_e32 v18, v18, v19, vcc
	v_rsq_f32_e32 v18, v18
	s_nop 0
	v_mul_f32_e32 v16, 0x45800000, v18
	v_cndmask_b32_e32 v20, v18, v16, vcc
	v_pk_mul_f32 v[12:13], v[12:13], v[20:21] op_sel_hi:[1,0]
	v_pk_mul_f32 v[14:15], v[14:15], v[20:21] op_sel_hi:[1,0]
	v_pk_mul_f32 v[16:17], v[60:61], v[12:13]
	v_pk_mul_f32 v[12:13], v[4:5], v[20:21] op_sel_hi:[1,0]
	v_pk_mul_f32 v[8:9], v[8:9], v[20:21] op_sel_hi:[1,0]
	v_pk_mul_f32 v[10:11], v[10:11], v[20:21] op_sel_hi:[1,0]
	v_pk_mul_f32 v[4:5], v[6:7], v[20:21] op_sel_hi:[1,0]
	v_pk_mul_f32 v[6:7], v[56:57], v[12:13]
	v_pk_mul_f32 v[12:13], v[0:1], v[20:21] op_sel_hi:[1,0]
	v_pk_mul_f32 v[0:1], v[2:3], v[20:21] op_sel_hi:[1,0]
	v_pk_mul_f32 v[18:19], v[62:63], v[14:15]
	v_pk_mul_f32 v[10:11], v[54:55], v[10:11]
	v_pk_mul_f32 v[8:9], v[52:53], v[8:9]
	v_pk_mul_f32 v[4:5], v[58:59], v[4:5]
	v_pk_mul_f32 v[0:1], v[50:51], v[0:1]
	v_pk_mul_f32 v[12:13], v[48:49], v[12:13]
	s_and_b64 vcc, exec, s[8:9]
	v_add_u32_e32 v20, 0xb0, v150
	s_cbranch_vccnz .LBB0_551
	v_bfe_u32 v2, v20, 6, 7
	v_cndmask_b32_e64 v2, v108, v2, s[6:7]
	v_lshl_or_b32 v192, v2, 7, v151
	v_lshl_add_u64 v[30:31], s[10:11], 0, v[192:193]
	global_load_dwordx4 v[22:25], v[30:31], off
	global_load_dwordx4 v[26:29], v[30:31], off offset:16
	s_waitcnt vmcnt(0) lgkmcnt(0)
	v_mov_b32_e32 v2, v22
	v_mul_f32_e32 v22, v18, v26
	v_mul_f32_e32 v32, v4, v27
	v_mul_f32_e32 v26, v4, v26
	v_mov_b32_e32 v4, v19
	v_mov_b32_e32 v3, v24
	v_mov_b32_e32 v24, v23
	v_pk_mul_f32 v[36:37], v[4:5], v[28:29]
	v_pk_mul_f32 v[14:15], v[6:7], v[24:25]
	v_pk_mul_f32 v[6:7], v[6:7], v[2:3]
	v_mul_f32_e32 v34, v18, v27
	v_mov_b32_e32 v23, v36
	v_mov_b32_e32 v33, v37
	v_mov_b32_e32 v18, v5
	v_pk_fma_f32 v[14:15], v[16:17], v[2:3], v[14:15] neg_lo:[0,0,1] neg_hi:[0,0,1]
	v_pk_add_f32 v[2:3], v[22:23], v[32:33] neg_lo:[0,1] neg_hi:[0,1]
	v_pk_mul_f32 v[4:5], v[18:19], v[28:29]
	v_pk_fma_f32 v[6:7], v[16:17], v[24:25], v[6:7]
	global_load_dwordx4 v[16:19], v[30:31], off offset:32
	global_load_dwordx4 v[22:25], v[30:31], off offset:48
	v_mov_b32_e32 v35, v5
	v_mov_b32_e32 v27, v4
	v_pk_add_f32 v[4:5], v[34:35], v[26:27]
	s_waitcnt vmcnt(0) lgkmcnt(0)
	v_mov_b32_e32 v27, v18
	v_mul_f32_e32 v28, v10, v22
	v_mul_f32_e32 v30, v0, v23
	v_mul_f32_e32 v22, v0, v22
	v_mov_b32_e32 v0, v11
	v_mov_b32_e32 v18, v17
	v_mul_f32_e32 v32, v10, v23
	v_pk_mul_f32 v[34:35], v[0:1], v[24:25]
	v_mov_b32_e32 v10, v1
	v_mov_b32_e32 v26, v16
	v_pk_mul_f32 v[16:17], v[12:13], v[18:19]
	v_mov_b32_e32 v29, v34
	v_mov_b32_e32 v31, v35
	v_pk_mul_f32 v[0:1], v[10:11], v[24:25]
	v_pk_mul_f32 v[12:13], v[12:13], v[26:27]
	v_pk_fma_f32 v[16:17], v[8:9], v[26:27], v[16:17] neg_lo:[0,0,1] neg_hi:[0,0,1]
	v_pk_add_f32 v[26:27], v[28:29], v[30:31] neg_lo:[0,1] neg_hi:[0,1]
	v_mov_b32_e32 v33, v1
	v_mov_b32_e32 v23, v0
	v_pk_fma_f32 v[12:13], v[8:9], v[18:19], v[12:13]
	v_pk_add_f32 v[0:1], v[32:33], v[22:23]
	v_mov_b32_e32 v8, v16
	v_mov_b32_e32 v9, v17
	v_mov_b32_e32 v10, v26
	v_mov_b32_e32 v11, v27
	v_mov_b32_e32 v16, v14
	v_mov_b32_e32 v17, v15
	v_mov_b32_e32 v18, v2
	v_mov_b32_e32 v19, v3
.LBB0_551:
	v_ashrrev_i32_e32 v2, 31, v20
	v_mul_lo_u32 v14, s25, v20
	v_mul_lo_u32 v15, s24, v2
	v_mad_u64_u32 v[2:3], s[2:3], s24, v20, 0
	v_add3_u32 v3, v3, v15, v14
	v_lshl_add_u64 v[20:21], v[2:3], 1, v[128:129]
	v_pk_mul_f32 v[2:3], s[96:97], v[16:17]
	v_pk_mul_f32 v[4:5], s[96:97], v[4:5]
	v_cvt_pk_bf16_f32 v14, v2, v3
	v_pk_mul_f32 v[2:3], s[96:97], v[18:19]
	v_pk_mul_f32 v[0:1], s[96:97], v[0:1]
	v_cvt_pk_bf16_f32 v15, v2, v3
	v_pk_mul_f32 v[2:3], s[96:97], v[8:9]
	s_nop 0
	v_cvt_pk_bf16_f32 v16, v2, v3
	v_pk_mul_f32 v[2:3], s[96:97], v[10:11]
	s_nop 0
	v_cvt_pk_bf16_f32 v17, v2, v3
	v_pk_mul_f32 v[2:3], s[96:97], v[6:7]
	global_store_dwordx4 v[20:21], v[14:17], off
	v_cvt_pk_bf16_f32 v2, v2, v3
	v_cvt_pk_bf16_f32 v3, v4, v5
	v_pk_mul_f32 v[4:5], s[96:97], v[12:13]
	s_nop 0
	v_cvt_pk_bf16_f32 v4, v4, v5
	v_cvt_pk_bf16_f32 v5, v0, v1
	global_store_dwordx4 v[20:21], v[2:5], off offset:64
	s_andn2_b64 vcc, exec, s[12:13]
	s_mov_b64 s[6:7], -1
	s_cbranch_vccnz .LBB0_511
	s_branch .LBB0_560

; __device__ __forceinline__ unsigned cvt_pk_bf16(float lo, float hi) { f32x2 v = {lo, hi}; bf16x2_t b = __builtin_convertvector(v, bf16x2_t); return __builtin_bit_cast(unsigned, b); }
; #define FOR_AI_M _Pragma("unroll") for (int ai = 0; ai < 2; ++ai) _Pragma("unroll") for (int m = 0; m < 4; ++m)
;     __device__ __forceinline__ void operator()(const f32x4 (&acc)[2][2][4][2], const Unit& u, int wr, int wc, int fr, int fq) const {
;     ...
;         } else if (kind == 2) {
;             FOR_AI_M {
;                 const int row = 256 * u.pm + 128 * ai + 64 * wr + 16 * m + fr;
; #pragma unroll
;                 for (int bj = 0; bj < 2; ++bj) {
;                     const f32x4 a = acc[ai][bj][m][0], b = acc[ai][bj][m][1];
;                     u32x4 w; w.x = cvt_pk_bf16(a[0], a[1]); w.y = cvt_pk_bf16(a[2], a[3]); w.z = cvt_pk_bf16(b[0], b[1]); w.w = cvt_pk_bf16(b[2], b[3]);
;                     *(u32x4*)(dst + (size_t)row * pitch + colbase + 32 * bj + 8 * fq) = w;
;                 }
;             }
;         } else {
;             FOR_AI_M {
;                 const int row = 256 * u.pm + 128 * ai + 64 * wr + 16 * m + fr;
; #pragma unroll
;                 for (int bj = 0; bj < 2; ++bj) {
;                     const int g = 16 * (pn - 3) + 4 * wc + 2 * bj + (fq >> 1);
;                     const f32x4 a = acc[ai][bj][m][0], b = acc[ai][bj][m][1];
;                     u32x4 w; w.x = cvt_pk_bf16(a[0], a[1]); w.y = cvt_pk_bf16(a[2], a[3]); w.z = cvt_pk_bf16(b[0], b[1]); w.w = cvt_pk_bf16(b[2], b[3]);
;                     *(u32x4*)(UC + ((size_t)g * CHPAD + (row >> 5)) * 768 + (row & 31) * 16 + 8 * (fq & 1)) = w;
;                 }
;             }
.LBB0_553:
	s_andn2_b64 vcc, exec, s[28:29]
	s_mov_b64 s[28:29], -1
	s_cbranch_vccz .LBB0_534
	s_lshl_b32 s3, s6, 8
	s_add_i32 s3, s3, s61
	s_xor_b64 s[28:29], s[18:19], -1
	v_add_u32_e32 v218, s3, v209
	s_mov_b64 s[18:19], -1
	s_andn2_b64 vcc, exec, s[28:29]
	v_add_u32_e32 v217, 16, v218
	v_add_u32_e32 v216, 32, v218
	v_add_u32_e32 v215, 48, v218
	v_add_u32_e32 v212, 0x80, v218
	v_add_u32_e32 v211, 0x90, v218
	v_cvt_pk_bf16_f32 v188, v140, v141
	v_cvt_pk_bf16_f32 v189, v142, v143
	v_cvt_pk_bf16_f32 v190, v136, v137
	v_cvt_pk_bf16_f32 v191, v138, v139
	v_cvt_pk_bf16_f32 v184, v132, v133
	v_cvt_pk_bf16_f32 v185, v134, v135
	v_cvt_pk_bf16_f32 v186, v128, v129
	v_cvt_pk_bf16_f32 v187, v130, v131
	v_cvt_pk_bf16_f32 v180, v124, v125
	v_cvt_pk_bf16_f32 v181, v126, v127
	v_cvt_pk_bf16_f32 v182, v120, v121
	v_cvt_pk_bf16_f32 v183, v122, v123
	v_cvt_pk_bf16_f32 v176, v116, v117
	v_cvt_pk_bf16_f32 v177, v118, v119
	v_cvt_pk_bf16_f32 v178, v112, v113
	v_cvt_pk_bf16_f32 v179, v114, v115
	v_cvt_pk_bf16_f32 v172, v108, v109
	v_cvt_pk_bf16_f32 v173, v110, v111
	v_cvt_pk_bf16_f32 v174, v104, v105
	v_cvt_pk_bf16_f32 v175, v106, v107
	v_cvt_pk_bf16_f32 v168, v100, v101
	v_cvt_pk_bf16_f32 v169, v102, v103
	v_cvt_pk_bf16_f32 v170, v96, v97
	v_cvt_pk_bf16_f32 v171, v98, v99
	v_cvt_pk_bf16_f32 v164, v92, v93
	v_cvt_pk_bf16_f32 v165, v94, v95
	v_cvt_pk_bf16_f32 v166, v88, v89
	v_cvt_pk_bf16_f32 v167, v90, v91
	v_cvt_pk_bf16_f32 v160, v84, v85
	v_cvt_pk_bf16_f32 v161, v86, v87
	v_cvt_pk_bf16_f32 v162, v80, v81
	v_cvt_pk_bf16_f32 v163, v82, v83
	v_cvt_pk_bf16_f32 v156, v76, v77
	v_cvt_pk_bf16_f32 v157, v78, v79
	v_cvt_pk_bf16_f32 v158, v72, v73
	v_cvt_pk_bf16_f32 v159, v74, v75
	v_cvt_pk_bf16_f32 v152, v68, v69
	v_cvt_pk_bf16_f32 v153, v70, v71
	v_cvt_pk_bf16_f32 v154, v64, v65
	v_cvt_pk_bf16_f32 v155, v66, v67
	v_cvt_pk_bf16_f32 v148, v44, v45
	v_cvt_pk_bf16_f32 v149, v46, v47
	v_cvt_pk_bf16_f32 v150, v40, v41
	v_cvt_pk_bf16_f32 v151, v42, v43
	v_cvt_pk_bf16_f32 v144, v36, v37
	v_cvt_pk_bf16_f32 v145, v38, v39
	v_cvt_pk_bf16_f32 v146, v32, v33
	v_cvt_pk_bf16_f32 v147, v34, v35
	v_add_u32_e32 v214, 0xa0, v218
	v_cvt_pk_bf16_f32 v60, v28, v29
	v_cvt_pk_bf16_f32 v61, v30, v31
	v_cvt_pk_bf16_f32 v62, v24, v25
	v_cvt_pk_bf16_f32 v63, v26, v27
	v_cvt_pk_bf16_f32 v56, v20, v21
	v_cvt_pk_bf16_f32 v57, v22, v23
	v_cvt_pk_bf16_f32 v58, v16, v17
	v_cvt_pk_bf16_f32 v59, v18, v19
	v_add_u32_e32 v213, 0xb0, v218
	v_cvt_pk_bf16_f32 v52, v12, v13
	v_cvt_pk_bf16_f32 v53, v14, v15
	v_cvt_pk_bf16_f32 v54, v8, v9
	v_cvt_pk_bf16_f32 v55, v10, v11
	v_cvt_pk_bf16_f32 v48, v4, v5
	v_cvt_pk_bf16_f32 v49, v6, v7
	v_cvt_pk_bf16_f32 v50, v0, v1
	v_cvt_pk_bf16_f32 v51, v2, v3
	s_cbranch_vccnz .LBB0_556
	s_lshl_b32 s2, s2, 4
	v_readlane_b32 s3, v254, 63
	v_ashrrev_i32_e32 v192, 1, v210
	s_add_i32 s2, s3, s2
	v_ashrrev_i32_e32 v220, 5, v218
	v_add_u32_e32 v219, s2, v192
	v_ashrrev_i32_e32 v221, 31, v220
	v_mad_i64_i32 v[222:223], s[2:3], v219, s33, v[220:221]
	v_readlane_b32 s2, v254, 47
	v_readlane_b32 s3, v254, 48
	s_movk_i32 s7, 0x600
	v_lshlrev_b32_e32 v192, 5, v209
	v_mov_b64_e32 v[224:225], s[2:3]
	v_mad_u64_u32 v[230:231], s[2:3], v222, s7, v[224:225]
	v_mad_i32_i24 v231, v223, s7, v231
	v_and_b32_e32 v192, 0x3e0, v192
	v_lshl_add_u64 v[222:223], v[230:231], 0, v[192:193]
	v_lshlrev_b32_e32 v230, 4, v210
	v_and_b32_e32 v230, 16, v230
	v_mov_b32_e32 v231, v193
	v_add_u32_e32 v234, 2, v219
	v_lshl_add_u64 v[222:223], v[222:223], 0, v[230:231]
	v_mad_i64_i32 v[220:221], s[2:3], v234, s33, v[220:221]
	global_store_dwordx4 v[222:223], v[188:191], off
	v_mad_u64_u32 v[222:223], s[2:3], v220, s7, v[224:225]
	v_mad_i32_i24 v223, v221, s7, v223
	v_lshl_add_u64 v[220:221], v[222:223], 0, v[192:193]
	v_lshl_add_u64 v[220:221], v[220:221], 0, v[230:231]
	global_store_dwordx4 v[220:221], v[184:187], off
	v_ashrrev_i32_e32 v220, 5, v217
	v_ashrrev_i32_e32 v221, 31, v220
	v_mad_i64_i32 v[222:223], s[2:3], v219, s33, v[220:221]
	v_mad_u64_u32 v[232:233], s[2:3], v222, s7, v[224:225]
	v_lshlrev_b32_e32 v222, 5, v217
	v_mad_i32_i24 v233, v223, s7, v233
	v_and_b32_e32 v222, 0x3e0, v222
	v_mov_b32_e32 v223, v193
	v_lshl_add_u64 v[232:233], v[232:233], 0, v[222:223]
	v_lshl_add_u64 v[232:233], v[232:233], 0, v[230:231]
	v_mad_i64_i32 v[220:221], s[2:3], v234, s33, v[220:221]
	global_store_dwordx4 v[232:233], v[180:183], off
	v_mad_u64_u32 v[232:233], s[2:3], v220, s7, v[224:225]
	v_mad_i32_i24 v233, v221, s7, v233
	v_lshl_add_u64 v[220:221], v[232:233], 0, v[222:223]
	v_lshl_add_u64 v[220:221], v[220:221], 0, v[230:231]
	global_store_dwordx4 v[220:221], v[176:179], off
	v_ashrrev_i32_e32 v220, 5, v216
	v_ashrrev_i32_e32 v221, 31, v220
	v_mad_i64_i32 v[222:223], s[2:3], v219, s33, v[220:221]
	v_mad_u64_u32 v[232:233], s[2:3], v222, s7, v[224:225]
	v_mad_i32_i24 v233, v223, s7, v233
	v_lshl_add_u64 v[222:223], v[232:233], 0, v[192:193]
	v_lshl_add_u64 v[222:223], v[222:223], 0, v[230:231]
	v_mad_i64_i32 v[220:221], s[2:3], v234, s33, v[220:221]
	global_store_dwordx4 v[222:223], v[172:175], off
	v_mad_u64_u32 v[222:223], s[2:3], v220, s7, v[224:225]
	v_mad_i32_i24 v223, v221, s7, v223
	v_lshl_add_u64 v[220:221], v[222:223], 0, v[192:193]
	v_lshl_add_u64 v[220:221], v[220:221], 0, v[230:231]
	global_store_dwordx4 v[220:221], v[168:171], off
	v_ashrrev_i32_e32 v220, 5, v215
	v_ashrrev_i32_e32 v221, 31, v220
	v_mad_i64_i32 v[222:223], s[2:3], v219, s33, v[220:221]
	v_mad_u64_u32 v[232:233], s[2:3], v222, s7, v[224:225]
	v_lshlrev_b32_e32 v222, 5, v215
	v_mad_i32_i24 v233, v223, s7, v233
	v_and_b32_e32 v222, 0x3e0, v222
	v_mov_b32_e32 v223, v193
	v_lshl_add_u64 v[232:233], v[232:233], 0, v[222:223]
; __device__ __forceinline__ unsigned cvt_pk_bf16(float lo, float hi) { f32x2 v = {lo, hi}; bf16x2_t b = __builtin_convertvector(v, bf16x2_t); return __builtin_bit_cast(unsigned, b); }
; #define FOR_AI_M _Pragma("unroll") for (int ai = 0; ai < 2; ++ai) _Pragma("unroll") for (int m = 0; m < 4; ++m)
;     __device__ __forceinline__ void operator()(const f32x4 (&acc)[2][2][4][2], const Unit& u, int wr, int wc, int fr, int fq) const {
;     ...
;         } else if (kind == 2) {
;             FOR_AI_M {
;                 const int row = 256 * u.pm + 128 * ai + 64 * wr + 16 * m + fr;
; #pragma unroll
;                 for (int bj = 0; bj < 2; ++bj) {
;                     const f32x4 a = acc[ai][bj][m][0], b = acc[ai][bj][m][1];
;                     u32x4 w; w.x = cvt_pk_bf16(a[0], a[1]); w.y = cvt_pk_bf16(a[2], a[3]); w.z = cvt_pk_bf16(b[0], b[1]); w.w = cvt_pk_bf16(b[2], b[3]);
;                     *(u32x4*)(dst + (size_t)row * pitch + colbase + 32 * bj + 8 * fq) = w;
;                 }
;             }
;         } else {
;             FOR_AI_M {
;                 const int row = 256 * u.pm + 128 * ai + 64 * wr + 16 * m + fr;
; #pragma unroll
;                 for (int bj = 0; bj < 2; ++bj) {
;                     const int g = 16 * (pn - 3) + 4 * wc + 2 * bj + (fq >> 1);
;                     const f32x4 a = acc[ai][bj][m][0], b = acc[ai][bj][m][1];
;                     u32x4 w; w.x = cvt_pk_bf16(a[0], a[1]); w.y = cvt_pk_bf16(a[2], a[3]); w.z = cvt_pk_bf16(b[0], b[1]); w.w = cvt_pk_bf16(b[2], b[3]);
;                     *(u32x4*)(UC + ((size_t)g * CHPAD + (row >> 5)) * 768 + (row & 31) * 16 + 8 * (fq & 1)) = w;
;                 }
;             }
	v_lshl_add_u64 v[232:233], v[232:233], 0, v[230:231]
	v_mad_i64_i32 v[220:221], s[2:3], v234, s33, v[220:221]
	global_store_dwordx4 v[232:233], v[164:167], off
	v_mad_u64_u32 v[232:233], s[2:3], v220, s7, v[224:225]
	v_mad_i32_i24 v233, v221, s7, v233
	v_lshl_add_u64 v[220:221], v[232:233], 0, v[222:223]
	v_lshl_add_u64 v[220:221], v[220:221], 0, v[230:231]
	global_store_dwordx4 v[220:221], v[160:163], off
	v_ashrrev_i32_e32 v220, 5, v212
	v_ashrrev_i32_e32 v221, 31, v220
	v_mad_i64_i32 v[222:223], s[2:3], v219, s33, v[220:221]
	v_mad_u64_u32 v[232:233], s[2:3], v222, s7, v[224:225]
	v_mad_i32_i24 v233, v223, s7, v233
	v_lshl_add_u64 v[222:223], v[232:233], 0, v[192:193]
	v_lshl_add_u64 v[222:223], v[222:223], 0, v[230:231]
	v_mad_i64_i32 v[220:221], s[2:3], v234, s33, v[220:221]
	global_store_dwordx4 v[222:223], v[156:159], off
	v_mad_u64_u32 v[222:223], s[2:3], v220, s7, v[224:225]
	v_mad_i32_i24 v223, v221, s7, v223
	v_lshl_add_u64 v[220:221], v[222:223], 0, v[192:193]
	v_lshl_add_u64 v[220:221], v[220:221], 0, v[230:231]
	global_store_dwordx4 v[220:221], v[152:155], off
	v_ashrrev_i32_e32 v220, 5, v211
	v_ashrrev_i32_e32 v221, 31, v220
	v_mad_i64_i32 v[222:223], s[2:3], v219, s33, v[220:221]
	v_mad_u64_u32 v[232:233], s[2:3], v222, s7, v[224:225]
	v_lshlrev_b32_e32 v222, 5, v211
	v_mad_i32_i24 v233, v223, s7, v233
	v_and_b32_e32 v222, 0x3e0, v222
	v_mov_b32_e32 v223, v193
	v_lshl_add_u64 v[232:233], v[232:233], 0, v[222:223]
	v_lshl_add_u64 v[232:233], v[232:233], 0, v[230:231]
	v_mad_i64_i32 v[220:221], s[2:3], v234, s33, v[220:221]
	global_store_dwordx4 v[232:233], v[148:151], off
	v_mad_u64_u32 v[232:233], s[2:3], v220, s7, v[224:225]
	v_mad_i32_i24 v233, v221, s7, v233
	v_lshl_add_u64 v[220:221], v[232:233], 0, v[222:223]
	v_lshl_add_u64 v[220:221], v[220:221], 0, v[230:231]
	global_store_dwordx4 v[220:221], v[144:147], off
	v_ashrrev_i32_e32 v220, 5, v214
	v_ashrrev_i32_e32 v221, 31, v220
	v_mad_i64_i32 v[222:223], s[2:3], v219, s33, v[220:221]
	v_mad_u64_u32 v[232:233], s[2:3], v222, s7, v[224:225]
	v_mad_i32_i24 v233, v223, s7, v233
	v_lshl_add_u64 v[222:223], v[232:233], 0, v[192:193]
	v_lshl_add_u64 v[222:223], v[222:223], 0, v[230:231]
	v_mad_i64_i32 v[220:221], s[2:3], v234, s33, v[220:221]
	global_store_dwordx4 v[222:223], v[60:63], off
	v_mad_u64_u32 v[222:223], s[2:3], v220, s7, v[224:225]
	v_mad_i32_i24 v223, v221, s7, v223
	v_lshl_add_u64 v[220:221], v[222:223], 0, v[192:193]
	v_lshl_add_u64 v[220:221], v[220:221], 0, v[230:231]
	global_store_dwordx4 v[220:221], v[56:59], off
	v_ashrrev_i32_e32 v220, 5, v213
	v_ashrrev_i32_e32 v221, 31, v220
	v_mad_i64_i32 v[222:223], s[2:3], v219, s33, v[220:221]
	v_mad_u64_u32 v[232:233], s[2:3], v222, s7, v[224:225]
	v_lshlrev_b32_e32 v192, 5, v213
	v_mad_i32_i24 v233, v223, s7, v233
	v_and_b32_e32 v192, 0x3e0, v192
	v_lshl_add_u64 v[222:223], v[232:233], 0, v[192:193]
	v_lshl_add_u64 v[222:223], v[222:223], 0, v[230:231]
	v_mad_i64_i32 v[220:221], s[2:3], v234, s33, v[220:221]
	global_store_dwordx4 v[222:223], v[52:55], off
	v_mad_u64_u32 v[222:223], s[2:3], v220, s7, v[224:225]
	v_mad_i32_i24 v223, v221, s7, v223
	v_lshl_add_u64 v[220:221], v[222:223], 0, v[192:193]
	s_movk_i32 s90, 0x600
	v_lshl_add_u64 v[220:221], v[220:221], 0, v[230:231]
	s_mov_b64 s[18:19], 0
	global_store_dwordx4 v[220:221], v[48:51], off
.LBB0_556:
	s_andn2_b64 vcc, exec, s[18:19]
	s_cbranch_vccnz .LBB0_558
	s_ashr_i32 s9, s8, 31
	s_lshl_b64 s[2:3], s[8:9], 1
	s_add_u32 s2, s16, s2
	v_lshlrev_b32_e32 v220, 3, v210
	s_addc_u32 s3, s17, s3
	v_ashrrev_i32_e32 v221, 31, v220
	v_ashrrev_i32_e32 v192, 31, v218
	v_lshl_add_u64 v[220:221], v[220:221], 1, s[2:3]
	v_mul_lo_u32 v222, s25, v218
	v_mul_lo_u32 v192, s24, v192
	v_mad_u64_u32 v[218:219], s[2:3], s24, v218, 0
	v_add3_u32 v219, v219, v192, v222
	v_lshl_add_u64 v[218:219], v[218:219], 1, v[220:221]
	global_store_dwordx4 v[218:219], v[188:191], off
	global_store_dwordx4 v[218:219], v[184:187], off offset:64
	s_nop 1
	v_ashrrev_i32_e32 v184, 31, v217
	v_mul_lo_u32 v186, s24, v184
	v_mul_lo_u32 v187, s25, v217
	v_mad_u64_u32 v[184:185], s[2:3], s24, v217, 0
	v_add3_u32 v185, v185, v186, v187
	v_lshl_add_u64 v[184:185], v[184:185], 1, v[220:221]
	global_store_dwordx4 v[184:185], v[180:183], off
	global_store_dwordx4 v[184:185], v[176:179], off offset:64
	s_nop 1
	v_ashrrev_i32_e32 v176, 31, v216
	v_mul_lo_u32 v178, s24, v176
	v_mul_lo_u32 v179, s25, v216
	v_mad_u64_u32 v[176:177], s[2:3], s24, v216, 0
	v_add3_u32 v177, v177, v178, v179
	v_lshl_add_u64 v[176:177], v[176:177], 1, v[220:221]
	global_store_dwordx4 v[176:177], v[172:175], off
	global_store_dwordx4 v[176:177], v[168:171], off offset:64
	s_nop 1
	v_ashrrev_i32_e32 v168, 31, v215
	v_mul_lo_u32 v170, s24, v168
	v_mul_lo_u32 v171, s25, v215
	v_mad_u64_u32 v[168:169], s[2:3], s24, v215, 0
	v_add3_u32 v169, v169, v170, v171
	v_lshl_add_u64 v[168:169], v[168:169], 1, v[220:221]
	global_store_dwordx4 v[168:169], v[164:167], off
	global_store_dwordx4 v[168:169], v[160:163], off offset:64
	s_nop 1
	v_ashrrev_i32_e32 v160, 31, v212
	v_mul_lo_u32 v162, s24, v160
	v_mul_lo_u32 v163, s25, v212
	v_mad_u64_u32 v[160:161], s[2:3], s24, v212, 0
	v_add3_u32 v161, v161, v162, v163
	v_lshl_add_u64 v[160:161], v[160:161], 1, v[220:221]
	global_store_dwordx4 v[160:161], v[156:159], off
	global_store_dwordx4 v[160:161], v[152:155], off offset:64
	s_nop 1
	v_ashrrev_i32_e32 v152, 31, v211
	v_mul_lo_u32 v154, s24, v152
	v_mul_lo_u32 v155, s25, v211
	v_mad_u64_u32 v[152:153], s[2:3], s24, v211, 0
	v_add3_u32 v153, v153, v154, v155
	v_lshl_add_u64 v[152:153], v[152:153], 1, v[220:221]
	global_store_dwordx4 v[152:153], v[148:151], off
	global_store_dwordx4 v[152:153], v[144:147], off offset:64
	s_nop 1
	v_ashrrev_i32_e32 v144, 31, v214
	v_mul_lo_u32 v146, s24, v144
	v_mul_lo_u32 v147, s25, v214
	v_mad_u64_u32 v[144:145], s[2:3], s24, v214, 0
	v_add3_u32 v145, v145, v146, v147
	v_lshl_add_u64 v[144:145], v[144:145], 1, v[220:221]
	global_store_dwordx4 v[144:145], v[60:63], off
	global_store_dwordx4 v[144:145], v[56:59], off offset:64
	s_nop 1
	v_ashrrev_i32_e32 v56, 31, v213
	v_mul_lo_u32 v58, s24, v56
	v_mul_lo_u32 v59, s25, v213
	v_mad_u64_u32 v[56:57], s[2:3], s24, v213, 0
	v_add3_u32 v57, v57, v58, v59
	v_lshl_add_u64 v[56:57], v[56:57], 1, v[220:221]
	global_store_dwordx4 v[56:57], v[52:55], off
	global_store_dwordx4 v[56:57], v[48:51], off offset:64
